# all 13 eight-phase GEMM k-loops: pairs of pipeline phases merged (32 MFMA per barrier interval)
# speedup vs baseline: 1.0136x; 1.0067x over previous
; #define PG8_STAGE(bufoff, gbase, voff) do { _Pragma("unroll") for (int _i = 0; _i < 2; ++_i) \
;         __builtin_amdgcn_global_load_lds((const unsigned*)((const char*)(gbase) + (voff)[_i]), (LAS unsigned*)(lds + (bufoff) + ldsw + _i * 8192), 16, 0, 0); } while (0)
; #define PG8_LDA(dst, b, h) do { _Pragma("unroll") for (int m = 0; m < 4; ++m) _Pragma("unroll") for (int k = 0; k < 2; ++k) dst[m][k] = *(const LAS bf16x8*)(lds + PG8_SA(b, h) + aoff + m * 2048 + k * 1024); } while (0)
; #define PG8_LDB(dst, b, h) do { _Pragma("unroll") for (int n = 0; n < 2; ++n) _Pragma("unroll") for (int k = 0; k < 2; ++k) dst[n][k] = *(const LAS bf16x8*)(lds + PG8_SB(b, h) + boff + n * 2048 + k * 1024); } while (0)
; #define PG8_MMA(ai, bj, At, Bt) do { __builtin_amdgcn_s_setprio(1); _Pragma("unroll") for (int m = 0; m < 4; ++m) _Pragma("unroll") for (int n = 0; n < 2; ++n) _Pragma("unroll") for (int k = 0; k < 2; ++k) \
;         acc[ai][bj][m][n] = __builtin_amdgcn_mfma_f32_16x16x32_bf16(Bt[n][k], At[m][k], acc[ai][bj][m][n], 0, 0, 0); __builtin_amdgcn_s_setprio(0); } while (0)
; #define PG8_WAIT_V(n) asm volatile("s_waitcnt vmcnt(" #n ")" ::: "memory")
; #define PG8_WAIT_L(n) asm volatile("s_waitcnt lgkmcnt(" #n ")" ::: "memory")
; template <class Epi>
; __device__ __forceinline__ void gemm_phase(LAS unsigned char* lds, const Gemm g, const StaticOrder& S, const Epi& E) {
;     ...
;         for (int t = 0; t < nt; t += 2) {
;             const bool last = (t == nt - 2);
;             const char* a1 = cA + (size_t)(t + 1) * kstep;
;             const char* a2 = last ? nA : cA + (size_t)(t + 2) * kstep; const char* b2 = last ? nB : cB + (size_t)(t + 2) * kstep;
;             const char* a3 = a2 + kstep; const char* b3 = b2 + kstep;
;             PG8_LDB(B0, 0, 0); PG8_SCHED; PG8_LDA(At, 0, 0); PG8_STAGE(PG8_SA(1, 1), a1 + hstepA, voffA);
;             PG8_WAIT_L(8); PG8_BAR; PG8_WAIT_L(0); PG8_MMA(0, 0, At, B0); PG8_BAR; PG8_SCHED;
;             PG8_LDB(B1, 0, 1); PG8_STAGE(PG8_SB(0, 0), b2, voffB);
;             PG8_BAR; PG8_WAIT_L(0); PG8_MMA(0, 1, At, B1); PG8_BAR;
;             PG8_LDA(At, 0, 1); PG8_STAGE(PG8_SA(0, 0), a2, voffA);
;             PG8_BAR; PG8_WAIT_L(0); PG8_MMA(1, 0, At, B0); PG8_BAR; PG8_SCHED;
;             PG8_STAGE(PG8_SB(0, 1), b2 + hstepB, voffB);
;             PG8_WAIT_V(6); PG8_BAR; PG8_MMA(1, 1, At, B1); PG8_BAR;
.LBB0_411:
	ds_read_b128 v[140:143], v149
	ds_read_b128 v[152:155], v149 offset:1024
	ds_read_b128 v[156:159], v149 offset:2048
	ds_read_b128 v[160:163], v149 offset:3072
	s_add_u32 s28, s26, 0x100
	s_addc_u32 s29, s27, 0
	s_cmp_eq_u32 s68, 40
	s_cselect_b32 s35, s11, s29
	s_cselect_b32 s34, s10, s28
	s_cselect_b32 s31, s13, s63
	s_cselect_b32 s30, s12, s49
	v_lshl_add_u64 v[144:145], s[26:27], 0, v[132:133]
	s_add_i32 m0, s36, 0xc000
	ds_read_b128 v[164:167], v150
	ds_read_b128 v[168:171], v150 offset:1024
	ds_read_b128 v[172:175], v150 offset:2048
	ds_read_b128 v[176:179], v150 offset:3072
	ds_read_b128 v[180:183], v150 offset:4096
	ds_read_b128 v[184:187], v150 offset:5120
	ds_read_b128 v[188:191], v150 offset:6144
	ds_read_b128 v[192:195], v150 offset:7168
	global_load_lds_dwordx4 v[144:145], off
	v_lshl_add_u64 v[144:145], s[26:27], 0, v[134:135]
	s_add_i32 m0, s36, 0xe000
	s_nop 0
	global_load_lds_dwordx4 v[144:145], off
	ds_read_b128 v[196:199], v151
	ds_read_b128 v[200:203], v151 offset:1024
	ds_read_b128 v[204:207], v151 offset:2048
	ds_read_b128 v[208:211], v151 offset:3072
	s_waitcnt lgkmcnt(0)
	s_barrier
	s_setprio 1
	v_mfma_f32_16x16x32_bf16 v[124:127], v[140:143], v[164:167], v[124:127]
	v_mfma_f32_16x16x32_bf16 v[120:123], v[156:159], v[164:167], v[120:123]
	v_mfma_f32_16x16x32_bf16 v[112:115], v[140:143], v[172:175], v[112:115]
	v_mfma_f32_16x16x32_bf16 v[104:107], v[156:159], v[172:175], v[104:107]
	v_mfma_f32_16x16x32_bf16 v[92:95], v[140:143], v[180:183], v[92:95]
	v_mfma_f32_16x16x32_bf16 v[88:91], v[156:159], v[180:183], v[88:91]
	v_mfma_f32_16x16x32_bf16 v[80:83], v[140:143], v[188:191], v[80:83]
	v_mfma_f32_16x16x32_bf16 v[72:75], v[156:159], v[188:191], v[72:75]
	v_mfma_f32_16x16x32_bf16 v[124:127], v[152:155], v[168:171], v[124:127]
	v_mfma_f32_16x16x32_bf16 v[120:123], v[160:163], v[168:171], v[120:123]
	v_mfma_f32_16x16x32_bf16 v[112:115], v[152:155], v[176:179], v[112:115]
	v_mfma_f32_16x16x32_bf16 v[104:107], v[160:163], v[176:179], v[104:107]
	v_mfma_f32_16x16x32_bf16 v[92:95], v[152:155], v[184:187], v[92:95]
	v_mfma_f32_16x16x32_bf16 v[88:91], v[160:163], v[184:187], v[88:91]
	v_mfma_f32_16x16x32_bf16 v[80:83], v[152:155], v[192:195], v[80:83]
	v_mfma_f32_16x16x32_bf16 v[72:75], v[160:163], v[192:195], v[72:75]
	v_mfma_f32_16x16x32_bf16 v[116:119], v[196:199], v[164:167], v[116:119]
	v_mfma_f32_16x16x32_bf16 v[108:111], v[204:207], v[164:167], v[108:111]
	v_mfma_f32_16x16x32_bf16 v[100:103], v[196:199], v[172:175], v[100:103]
	v_mfma_f32_16x16x32_bf16 v[96:99], v[204:207], v[172:175], v[96:99]
	v_mfma_f32_16x16x32_bf16 v[84:87], v[196:199], v[180:183], v[84:87]
	v_mfma_f32_16x16x32_bf16 v[76:79], v[204:207], v[180:183], v[76:79]
	v_mfma_f32_16x16x32_bf16 v[68:71], v[196:199], v[188:191], v[68:71]
	v_mfma_f32_16x16x32_bf16 v[64:67], v[204:207], v[188:191], v[64:67]
	v_mfma_f32_16x16x32_bf16 v[116:119], v[200:203], v[168:171], v[116:119]
	v_mfma_f32_16x16x32_bf16 v[108:111], v[208:211], v[168:171], v[108:111]
	v_mfma_f32_16x16x32_bf16 v[100:103], v[200:203], v[176:179], v[100:103]
	v_mfma_f32_16x16x32_bf16 v[96:99], v[208:211], v[176:179], v[96:99]
	v_mfma_f32_16x16x32_bf16 v[84:87], v[200:203], v[184:187], v[84:87]
	v_mfma_f32_16x16x32_bf16 v[76:79], v[208:211], v[184:187], v[76:79]
	v_mfma_f32_16x16x32_bf16 v[68:71], v[200:203], v[192:195], v[68:71]
	v_mfma_f32_16x16x32_bf16 v[64:67], v[208:211], v[192:195], v[64:67]
	s_setprio 0
	s_barrier
	s_nop 1
	ds_read_b128 v[164:167], v150 offset:16384
	ds_read_b128 v[168:171], v150 offset:17408
	ds_read_b128 v[172:175], v150 offset:18432
	ds_read_b128 v[176:179], v150 offset:19456
	ds_read_b128 v[180:183], v150 offset:20480
	ds_read_b128 v[184:187], v150 offset:21504
	ds_read_b128 v[188:191], v150 offset:22528
	ds_read_b128 v[192:195], v150 offset:23552
	s_add_i32 s26, s43, s7
	v_lshl_add_u64 v[144:145], s[30:31], 0, v[128:129]
	s_mov_b32 m0, s26
	s_nop 0
	global_load_lds_dwordx4 v[144:145], off
	v_lshl_add_u64 v[212:213], s[30:31], 0, v[130:131]
	s_add_i32 m0, s26, 0x2000
	s_nop 0
	global_load_lds_dwordx4 v[212:213], off
	s_mov_b32 m0, s36
	v_lshl_add_u64 v[214:215], s[34:35], 0, v[128:129]
	global_load_lds_dwordx4 v[214:215], off
	v_lshl_add_u64 v[216:217], s[34:35], 0, v[130:131]
	s_mov_b32 m0, s37
	s_nop 0
	global_load_lds_dwordx4 v[216:217], off
	s_add_u32 s26, s30, 0xb0000
	s_addc_u32 s27, s31, 0
	s_add_i32 s69, s44, s7
	v_lshl_add_u64 v[254:255], s[26:27], 0, v[128:129]
	s_mov_b32 m0, s69
	s_nop 0
	global_load_lds_dwordx4 v[254:255], off
	v_lshl_add_u64 v[254:255], s[26:27], 0, v[130:131]
	s_add_i32 m0, s69, 0x2000
	s_nop 0
	global_load_lds_dwordx4 v[254:255], off
	s_waitcnt vmcnt(6)
	s_waitcnt lgkmcnt(0)
	s_barrier
; #define PG8_STAGE(bufoff, gbase, voff) do { _Pragma("unroll") for (int _i = 0; _i < 2; ++_i) \
;         __builtin_amdgcn_global_load_lds((const unsigned*)((const char*)(gbase) + (voff)[_i]), (LAS unsigned*)(lds + (bufoff) + ldsw + _i * 8192), 16, 0, 0); } while (0)
; #define PG8_LDA(dst, b, h) do { _Pragma("unroll") for (int m = 0; m < 4; ++m) _Pragma("unroll") for (int k = 0; k < 2; ++k) dst[m][k] = *(const LAS bf16x8*)(lds + PG8_SA(b, h) + aoff + m * 2048 + k * 1024); } while (0)
; #define PG8_LDB(dst, b, h) do { _Pragma("unroll") for (int n = 0; n < 2; ++n) _Pragma("unroll") for (int k = 0; k < 2; ++k) dst[n][k] = *(const LAS bf16x8*)(lds + PG8_SB(b, h) + boff + n * 2048 + k * 1024); } while (0)
; #define PG8_MMA(ai, bj, At, Bt) do { __builtin_amdgcn_s_setprio(1); _Pragma("unroll") for (int m = 0; m < 4; ++m) _Pragma("unroll") for (int n = 0; n < 2; ++n) _Pragma("unroll") for (int k = 0; k < 2; ++k) \
;         acc[ai][bj][m][n] = __builtin_amdgcn_mfma_f32_16x16x32_bf16(Bt[n][k], At[m][k], acc[ai][bj][m][n], 0, 0, 0); __builtin_amdgcn_s_setprio(0); } while (0)
; #define PG8_WAIT_V(n) asm volatile("s_waitcnt vmcnt(" #n ")" ::: "memory")
; #define PG8_WAIT_L(n) asm volatile("s_waitcnt lgkmcnt(" #n ")" ::: "memory")
; #define PG8_BAR __builtin_amdgcn_s_barrier()
; #define PG8_SCHED __builtin_amdgcn_sched_barrier(0)
; template <class Epi>
; __device__ __forceinline__ void gemm_phase(LAS unsigned char* lds, const Gemm g, const StaticOrder& S, const Epi& E) {
;     ...
;             PG8_BAR; PG8_WAIT_L(0); PG8_MMA(1, 0, At, B0); PG8_BAR; PG8_SCHED;
;             PG8_STAGE(PG8_SB(0, 1), b2 + hstepB, voffB);
;             PG8_WAIT_V(6); PG8_BAR; PG8_MMA(1, 1, At, B1); PG8_BAR;
;             PG8_LDB(B0, 1, 0); PG8_SCHED; PG8_LDA(At, 1, 0); PG8_STAGE(PG8_SA(0, 1), a2 + hstepA, voffA);
;             PG8_WAIT_L(8); PG8_BAR; PG8_WAIT_L(0); PG8_MMA(0, 0, At, B0); PG8_BAR; PG8_SCHED;
;             PG8_LDB(B1, 1, 1); PG8_STAGE(PG8_SB(1, 0), b3, voffB);
;             PG8_BAR; PG8_WAIT_L(0); PG8_MMA(0, 1, At, B1); PG8_BAR;
	s_setprio 1
	v_mfma_f32_16x16x32_bf16 v[60:63], v[140:143], v[164:167], v[60:63]
	v_mfma_f32_16x16x32_bf16 v[56:59], v[156:159], v[164:167], v[56:59]
	v_mfma_f32_16x16x32_bf16 v[48:51], v[140:143], v[172:175], v[48:51]
	v_mfma_f32_16x16x32_bf16 v[40:43], v[156:159], v[172:175], v[40:43]
	v_mfma_f32_16x16x32_bf16 v[28:31], v[140:143], v[180:183], v[28:31]
	v_mfma_f32_16x16x32_bf16 v[24:27], v[156:159], v[180:183], v[24:27]
	v_mfma_f32_16x16x32_bf16 v[16:19], v[140:143], v[188:191], v[16:19]
	v_mfma_f32_16x16x32_bf16 v[8:11], v[156:159], v[188:191], v[8:11]
	v_mfma_f32_16x16x32_bf16 v[60:63], v[152:155], v[168:171], v[60:63]
	v_mfma_f32_16x16x32_bf16 v[56:59], v[160:163], v[168:171], v[56:59]
	v_mfma_f32_16x16x32_bf16 v[48:51], v[152:155], v[176:179], v[48:51]
	v_mfma_f32_16x16x32_bf16 v[40:43], v[160:163], v[176:179], v[40:43]
	v_mfma_f32_16x16x32_bf16 v[28:31], v[152:155], v[184:187], v[28:31]
	v_mfma_f32_16x16x32_bf16 v[24:27], v[160:163], v[184:187], v[24:27]
	v_mfma_f32_16x16x32_bf16 v[16:19], v[152:155], v[192:195], v[16:19]
	v_mfma_f32_16x16x32_bf16 v[8:11], v[160:163], v[192:195], v[8:11]
	v_mfma_f32_16x16x32_bf16 v[52:55], v[196:199], v[164:167], v[52:55]
	v_mfma_f32_16x16x32_bf16 v[44:47], v[204:207], v[164:167], v[44:47]
	v_mfma_f32_16x16x32_bf16 v[36:39], v[196:199], v[172:175], v[36:39]
	v_mfma_f32_16x16x32_bf16 v[32:35], v[204:207], v[172:175], v[32:35]
	v_mfma_f32_16x16x32_bf16 v[20:23], v[196:199], v[180:183], v[20:23]
	v_mfma_f32_16x16x32_bf16 v[12:15], v[204:207], v[180:183], v[12:15]
	v_mfma_f32_16x16x32_bf16 v[4:7], v[196:199], v[188:191], v[4:7]
	v_mfma_f32_16x16x32_bf16 v[0:3], v[204:207], v[188:191], v[0:3]
	v_mfma_f32_16x16x32_bf16 v[52:55], v[200:203], v[168:171], v[52:55]
	v_mfma_f32_16x16x32_bf16 v[44:47], v[208:211], v[168:171], v[44:47]
	v_mfma_f32_16x16x32_bf16 v[36:39], v[200:203], v[176:179], v[36:39]
	v_mfma_f32_16x16x32_bf16 v[32:35], v[208:211], v[176:179], v[32:35]
	v_mfma_f32_16x16x32_bf16 v[20:23], v[200:203], v[184:187], v[20:23]
	v_mfma_f32_16x16x32_bf16 v[12:15], v[208:211], v[184:187], v[12:15]
	v_mfma_f32_16x16x32_bf16 v[4:7], v[200:203], v[192:195], v[4:7]
	v_mfma_f32_16x16x32_bf16 v[0:3], v[208:211], v[192:195], v[0:3]
	s_setprio 0
	s_add_i32 s69, 0, 0x18000
	v_add_u32_e32 v160, s69, v147
	s_barrier
	ds_read_b128 v[140:143], v160
	ds_read_b128 v[152:155], v160 offset:1024
	ds_read_b128 v[156:159], v160 offset:2048
	ds_read_b128 v[160:163], v160 offset:3072
	s_add_u32 s26, s34, 0xb0000
	s_addc_u32 s27, s35, 0
	s_mov_b32 m0, s38
	v_lshl_add_u64 v[196:197], s[26:27], 0, v[128:129]
	ds_read_b128 v[164:167], v150 offset:32768
	ds_read_b128 v[168:171], v150 offset:33792
	ds_read_b128 v[172:175], v150 offset:34816
	ds_read_b128 v[176:179], v150 offset:35840
	ds_read_b128 v[180:183], v150 offset:36864
	ds_read_b128 v[184:187], v150 offset:37888
	ds_read_b128 v[188:191], v150 offset:38912
	ds_read_b128 v[192:195], v150 offset:39936
	global_load_lds_dwordx4 v[196:197], off
	v_lshl_add_u64 v[196:197], s[26:27], 0, v[130:131]
	s_mov_b32 m0, s39
	s_nop 0
	global_load_lds_dwordx4 v[196:197], off
	s_add_i32 s34, 0, 0x1c000
	v_add_u32_e32 v208, s34, v147
	ds_read_b128 v[196:199], v208
	ds_read_b128 v[200:203], v208 offset:1024
	ds_read_b128 v[204:207], v208 offset:2048
	ds_read_b128 v[208:211], v208 offset:3072
	s_waitcnt lgkmcnt(0)
	s_barrier
	s_setprio 1
	v_mfma_f32_16x16x32_bf16 v[124:127], v[140:143], v[164:167], v[124:127]
	v_mfma_f32_16x16x32_bf16 v[120:123], v[156:159], v[164:167], v[120:123]
	v_mfma_f32_16x16x32_bf16 v[112:115], v[140:143], v[172:175], v[112:115]
	v_mfma_f32_16x16x32_bf16 v[104:107], v[156:159], v[172:175], v[104:107]
	v_mfma_f32_16x16x32_bf16 v[92:95], v[140:143], v[180:183], v[92:95]
	v_mfma_f32_16x16x32_bf16 v[88:91], v[156:159], v[180:183], v[88:91]
	v_mfma_f32_16x16x32_bf16 v[80:83], v[140:143], v[188:191], v[80:83]
	v_mfma_f32_16x16x32_bf16 v[72:75], v[156:159], v[188:191], v[72:75]
	v_mfma_f32_16x16x32_bf16 v[124:127], v[152:155], v[168:171], v[124:127]
	v_mfma_f32_16x16x32_bf16 v[120:123], v[160:163], v[168:171], v[120:123]
	v_mfma_f32_16x16x32_bf16 v[112:115], v[152:155], v[176:179], v[112:115]
	v_mfma_f32_16x16x32_bf16 v[104:107], v[160:163], v[176:179], v[104:107]
	v_mfma_f32_16x16x32_bf16 v[92:95], v[152:155], v[184:187], v[92:95]
	v_mfma_f32_16x16x32_bf16 v[88:91], v[160:163], v[184:187], v[88:91]
	v_mfma_f32_16x16x32_bf16 v[80:83], v[152:155], v[192:195], v[80:83]
	v_mfma_f32_16x16x32_bf16 v[72:75], v[160:163], v[192:195], v[72:75]
	v_mfma_f32_16x16x32_bf16 v[116:119], v[196:199], v[164:167], v[116:119]
	v_mfma_f32_16x16x32_bf16 v[108:111], v[204:207], v[164:167], v[108:111]
	v_mfma_f32_16x16x32_bf16 v[100:103], v[196:199], v[172:175], v[100:103]
	v_mfma_f32_16x16x32_bf16 v[96:99], v[204:207], v[172:175], v[96:99]
	v_mfma_f32_16x16x32_bf16 v[84:87], v[196:199], v[180:183], v[84:87]
	v_mfma_f32_16x16x32_bf16 v[76:79], v[204:207], v[180:183], v[76:79]
	v_mfma_f32_16x16x32_bf16 v[68:71], v[196:199], v[188:191], v[68:71]
	v_mfma_f32_16x16x32_bf16 v[64:67], v[204:207], v[188:191], v[64:67]
	v_mfma_f32_16x16x32_bf16 v[116:119], v[200:203], v[168:171], v[116:119]
	v_mfma_f32_16x16x32_bf16 v[108:111], v[208:211], v[168:171], v[108:111]
	v_mfma_f32_16x16x32_bf16 v[100:103], v[200:203], v[176:179], v[100:103]
	v_mfma_f32_16x16x32_bf16 v[96:99], v[208:211], v[176:179], v[96:99]
	v_mfma_f32_16x16x32_bf16 v[84:87], v[200:203], v[184:187], v[84:87]
	v_mfma_f32_16x16x32_bf16 v[76:79], v[208:211], v[184:187], v[76:79]
	v_mfma_f32_16x16x32_bf16 v[68:71], v[200:203], v[192:195], v[68:71]
	v_mfma_f32_16x16x32_bf16 v[64:67], v[208:211], v[192:195], v[64:67]
	s_setprio 0
	s_barrier
; #define PG8_STAGE(bufoff, gbase, voff) do { _Pragma("unroll") for (int _i = 0; _i < 2; ++_i) \
;         __builtin_amdgcn_global_load_lds((const unsigned*)((const char*)(gbase) + (voff)[_i]), (LAS unsigned*)(lds + (bufoff) + ldsw + _i * 8192), 16, 0, 0); } while (0)
; #define PG8_LDA(dst, b, h) do { _Pragma("unroll") for (int m = 0; m < 4; ++m) _Pragma("unroll") for (int k = 0; k < 2; ++k) dst[m][k] = *(const LAS bf16x8*)(lds + PG8_SA(b, h) + aoff + m * 2048 + k * 1024); } while (0)
; #define PG8_LDB(dst, b, h) do { _Pragma("unroll") for (int n = 0; n < 2; ++n) _Pragma("unroll") for (int k = 0; k < 2; ++k) dst[n][k] = *(const LAS bf16x8*)(lds + PG8_SB(b, h) + boff + n * 2048 + k * 1024); } while (0)
; template <class Epi>
; __device__ __forceinline__ void gemm_phase(LAS unsigned char* lds, const Gemm g, const StaticOrder& S, const Epi& E) {
;     ...
;             PG8_LDB(B1, 1, 1); PG8_STAGE(PG8_SB(1, 0), b3, voffB);
;             PG8_BAR; PG8_WAIT_L(0); PG8_MMA(0, 1, At, B1); PG8_BAR;
;             PG8_LDA(At, 1, 1); PG8_STAGE(PG8_SA(1, 0), a3, voffA);
;             PG8_BAR; PG8_WAIT_L(0); PG8_MMA(1, 0, At, B0); PG8_BAR; PG8_SCHED;
;             PG8_STAGE(PG8_SB(1, 1), b3 + hstepB, voffB);
;             PG8_WAIT_V(6); PG8_BAR; PG8_MMA(1, 1, At, B1); PG8_BAR;
;     __device__ __forceinline__ void operator()(AccRef acc, const Unit& u, int wr, int wc, int fr, int fq) const {
;         const int row0 = u.pm * 256 + wr * 64 + fr, col0 = u.pn * 256 + wc * 32 + 4 * fq;
;         f32x4 sv[2][2], bv[2][2];
; #pragma unroll
;         for (int bj = 0; bj < 2; ++bj)
; #pragma unroll
;             for (int n = 0; n < 2; ++n) {
;                 sv[bj][n] = scale ? *(const f32x4*)(scale + col0 + bj * 128 + n * 16) : (f32x4){1.f, 1.f, 1.f, 1.f};
;                 bv[bj][n] = bias ? *(const f32x4*)(bias + col0 + bj * 128 + n * 16) : (f32x4){0.f, 0.f, 0.f, 0.f}; }
; #pragma unroll
;         for (int ai = 0; ai < 2; ++ai)
; #pragma unroll
;             for (int mh = 0; mh < 2; ++mh) {
;                 f32x4 bs[2][2][2];
; #pragma unroll
;                 for (int m = 0; m < 2; ++m)
; #pragma unroll
;                     for (int bj = 0; bj < 2; ++bj)
; #pragma unroll
;                         for (int n = 0; n < 2; ++n) bs[m][bj][n] = *(const f32x4*)(base + (size_t)(row0 + ai * 128 + (2 * mh + m) * 16) * D + col0 + bj * 128 + n * 16);
	s_nop 1
	ds_read_b128 v[164:167], v150 offset:49152
	ds_read_b128 v[168:171], v150 offset:50176
	ds_read_b128 v[172:175], v150 offset:51200
	ds_read_b128 v[176:179], v150 offset:52224
	ds_read_b128 v[180:183], v150 offset:53248
	ds_read_b128 v[184:187], v150 offset:54272
	ds_read_b128 v[188:191], v150 offset:55296
	ds_read_b128 v[192:195], v150 offset:56320
	s_add_i32 s26, s69, s7
	v_lshl_add_u64 v[254:255], v[144:145], 0, s[16:17]
	s_mov_b32 m0, s26
	s_nop 0
	global_load_lds_dwordx4 v[254:255], off
	v_lshl_add_u64 v[254:255], v[212:213], 0, s[16:17]
	s_add_i32 m0, s26, 0x2000
	s_nop 0
	global_load_lds_dwordx4 v[254:255], off
	s_mov_b32 m0, s41
	v_lshl_add_u64 v[254:255], v[214:215], 0, s[16:17]
	global_load_lds_dwordx4 v[254:255], off
	v_lshl_add_u64 v[144:145], v[216:217], 0, s[16:17]
	s_mov_b32 m0, s42
	s_nop 0
	global_load_lds_dwordx4 v[144:145], off
	s_add_u32 s26, s30, 0xb0080
	s_addc_u32 s27, s31, 0
	s_add_i32 s30, s34, s7
	v_lshl_add_u64 v[254:255], s[26:27], 0, v[128:129]
	s_mov_b32 m0, s30
	s_nop 0
	global_load_lds_dwordx4 v[254:255], off
	v_lshl_add_u64 v[254:255], s[26:27], 0, v[130:131]
	s_add_i32 m0, s30, 0x2000
	s_nop 0
	global_load_lds_dwordx4 v[254:255], off
	s_waitcnt vmcnt(6)
	s_waitcnt lgkmcnt(0)
	s_barrier
	s_setprio 1
	v_mfma_f32_16x16x32_bf16 v[60:63], v[140:143], v[164:167], v[60:63]
	v_mfma_f32_16x16x32_bf16 v[56:59], v[156:159], v[164:167], v[56:59]
	v_mfma_f32_16x16x32_bf16 v[48:51], v[140:143], v[172:175], v[48:51]
	v_mfma_f32_16x16x32_bf16 v[40:43], v[156:159], v[172:175], v[40:43]
	v_mfma_f32_16x16x32_bf16 v[28:31], v[140:143], v[180:183], v[28:31]
	v_mfma_f32_16x16x32_bf16 v[24:27], v[156:159], v[180:183], v[24:27]
	v_mfma_f32_16x16x32_bf16 v[16:19], v[140:143], v[188:191], v[16:19]
	v_mfma_f32_16x16x32_bf16 v[8:11], v[156:159], v[188:191], v[8:11]
	v_mfma_f32_16x16x32_bf16 v[60:63], v[152:155], v[168:171], v[60:63]
	v_mfma_f32_16x16x32_bf16 v[56:59], v[160:163], v[168:171], v[56:59]
	v_mfma_f32_16x16x32_bf16 v[48:51], v[152:155], v[176:179], v[48:51]
	v_mfma_f32_16x16x32_bf16 v[40:43], v[160:163], v[176:179], v[40:43]
	v_mfma_f32_16x16x32_bf16 v[28:31], v[152:155], v[184:187], v[28:31]
	v_mfma_f32_16x16x32_bf16 v[24:27], v[160:163], v[184:187], v[24:27]
	v_mfma_f32_16x16x32_bf16 v[16:19], v[152:155], v[192:195], v[16:19]
	v_mfma_f32_16x16x32_bf16 v[8:11], v[160:163], v[192:195], v[8:11]
	v_mfma_f32_16x16x32_bf16 v[52:55], v[196:199], v[164:167], v[52:55]
	v_mfma_f32_16x16x32_bf16 v[44:47], v[204:207], v[164:167], v[44:47]
	v_mfma_f32_16x16x32_bf16 v[36:39], v[196:199], v[172:175], v[36:39]
	v_mfma_f32_16x16x32_bf16 v[32:35], v[204:207], v[172:175], v[32:35]
	v_mfma_f32_16x16x32_bf16 v[20:23], v[196:199], v[180:183], v[20:23]
	v_mfma_f32_16x16x32_bf16 v[12:15], v[204:207], v[180:183], v[12:15]
	v_mfma_f32_16x16x32_bf16 v[4:7], v[196:199], v[188:191], v[4:7]
	v_mfma_f32_16x16x32_bf16 v[0:3], v[204:207], v[188:191], v[0:3]
	v_mfma_f32_16x16x32_bf16 v[52:55], v[200:203], v[168:171], v[52:55]
	v_mfma_f32_16x16x32_bf16 v[44:47], v[208:211], v[168:171], v[44:47]
	v_mfma_f32_16x16x32_bf16 v[36:39], v[200:203], v[176:179], v[36:39]
	v_mfma_f32_16x16x32_bf16 v[32:35], v[208:211], v[176:179], v[32:35]
	v_mfma_f32_16x16x32_bf16 v[20:23], v[200:203], v[184:187], v[20:23]
	v_mfma_f32_16x16x32_bf16 v[12:15], v[208:211], v[184:187], v[12:15]
	v_mfma_f32_16x16x32_bf16 v[4:7], v[200:203], v[192:195], v[4:7]
	v_mfma_f32_16x16x32_bf16 v[0:3], v[208:211], v[192:195], v[0:3]
	s_setprio 0
	s_add_i32 s68, s68, 2
	s_add_u32 s49, s49, 0x100
	s_addc_u32 s63, s63, 0
	s_cmp_gt_u32 s68, 41
	s_mov_b64 s[26:27], s[28:29]
	s_barrier
	s_cbranch_scc0 .LBB0_411
	v_lshl_or_b32 v140, s47, 8, v148
	v_ashrrev_i32_e32 v141, 31, v140
	v_lshl_add_u32 v184, s48, 8, v146
	v_lshlrev_b64 v[140:141], 2, v[140:141]
	v_ashrrev_i32_e32 v185, 31, v184
	v_or_b32_e32 v168, 16, v184
	v_lshl_add_u64 v[142:143], s[52:53], 0, v[140:141]
	v_lshlrev_b64 v[144:145], 12, v[184:185]
	v_ashrrev_i32_e32 v169, 31, v168
	v_lshl_add_u64 v[164:165], v[142:143], 0, v[144:145]
	v_lshlrev_b64 v[186:187], 12, v[168:169]
	global_load_dwordx4 v[152:155], v[164:165], off
	global_load_dwordx4 v[156:159], v[164:165], off offset:64
	global_load_dwordx4 v[160:163], v[164:165], off offset:512
	s_nop 0
	global_load_dwordx4 v[164:167], v[164:165], off offset:576
	v_lshl_add_u64 v[180:181], v[142:143], 0, v[186:187]
	global_load_dwordx4 v[168:171], v[180:181], off
	global_load_dwordx4 v[172:175], v[180:181], off offset:64
	global_load_dwordx4 v[176:179], v[180:181], off offset:512
	s_nop 0
	global_load_dwordx4 v[180:183], v[180:181], off offset:576
	v_pk_add_f32 v[198:199], v[96:97], 0 op_sel_hi:[1,0]
	v_or_b32_e32 v96, 32, v184
	v_ashrrev_i32_e32 v97, 31, v96
	v_pk_add_f32 v[126:127], v[126:127], 0 op_sel_hi:[1,0]
	v_pk_add_f32 v[124:125], v[124:125], 0 op_sel_hi:[1,0]
	v_pk_add_f32 v[108:109], v[108:109], 0 op_sel_hi:[1,0]
	v_pk_add_f32 v[196:197], v[98:99], 0 op_sel_hi:[1,0]
	v_lshl_add_u64 v[98:99], s[52:53], 0, v[144:145]
	v_lshlrev_b64 v[200:201], 12, v[96:97]
	v_lshl_add_u64 v[96:97], s[52:53], 0, v[186:187]
	v_pk_add_f32 v[122:123], v[122:123], 0 op_sel_hi:[1,0]
	v_pk_add_f32 v[120:121], v[120:121], 0 op_sel_hi:[1,0]
	v_pk_add_f32 v[118:119], v[118:119], 0 op_sel_hi:[1,0]
	v_pk_add_f32 v[116:117], v[116:117], 0 op_sel_hi:[1,0]
	v_pk_add_f32 v[110:111], v[110:111], 0 op_sel_hi:[1,0]
	v_pk_add_f32 v[114:115], v[114:115], 0 op_sel_hi:[1,0]
	v_pk_add_f32 v[112:113], v[112:113], 0 op_sel_hi:[1,0]
	v_pk_add_f32 v[188:189], v[106:107], 0 op_sel_hi:[1,0]
	v_pk_add_f32 v[190:191], v[104:105], 0 op_sel_hi:[1,0]
	v_pk_add_f32 v[192:193], v[102:103], 0 op_sel_hi:[1,0]
;     __device__ __forceinline__ void operator()(AccRef acc, const Unit& u, int wr, int wc, int fr, int fq) const {
;     ...
;         for (int ai = 0; ai < 2; ++ai)
; #pragma unroll
;             for (int mh = 0; mh < 2; ++mh) {
;                 f32x4 bs[2][2][2];
; #pragma unroll
;                 for (int m = 0; m < 2; ++m)
; #pragma unroll
;                     for (int bj = 0; bj < 2; ++bj)
; #pragma unroll
;                         for (int n = 0; n < 2; ++n) bs[m][bj][n] = *(const f32x4*)(base + (size_t)(row0 + ai * 128 + (2 * mh + m) * 16) * D + col0 + bj * 128 + n * 16);
; #pragma unroll
;                 for (int m = 0; m < 2; ++m)
; #pragma unroll
;                     for (int bj = 0; bj < 2; ++bj)
; #pragma unroll
;                         for (int n = 0; n < 2; ++n) *(f32x4*)(out + (size_t)(row0 + ai * 128 + (2 * mh + m) * 16) * D + col0 + bj * 128 + n * 16) = bs[m][bj][n] + sv[bj][n] * (acc[ai][bj][2 * mh + m][n] + bv[bj][n]);
;                 asm volatile("" ::: "memory"); }
	v_pk_add_f32 v[194:195], v[100:101], 0 op_sel_hi:[1,0]
	v_lshl_add_u64 v[202:203], v[98:99], 0, v[140:141]
	v_lshl_add_u64 v[204:205], v[96:97], 0, v[140:141]
	v_lshl_add_u64 v[186:187], v[142:143], 0, v[200:201]
	v_pk_add_f32 v[94:95], v[94:95], 0 op_sel_hi:[1,0]
	v_pk_add_f32 v[92:93], v[92:93], 0 op_sel_hi:[1,0]
	v_pk_add_f32 v[90:91], v[90:91], 0 op_sel_hi:[1,0]
	v_pk_add_f32 v[88:89], v[88:89], 0 op_sel_hi:[1,0]
	v_pk_add_f32 v[86:87], v[86:87], 0 op_sel_hi:[1,0]
	v_pk_add_f32 v[84:85], v[84:85], 0 op_sel_hi:[1,0]
	v_pk_add_f32 v[78:79], v[78:79], 0 op_sel_hi:[1,0]
	v_pk_add_f32 v[76:77], v[76:77], 0 op_sel_hi:[1,0]
	v_pk_add_f32 v[82:83], v[82:83], 0 op_sel_hi:[1,0]
	v_pk_add_f32 v[80:81], v[80:81], 0 op_sel_hi:[1,0]
	v_pk_add_f32 v[62:63], v[62:63], 0 op_sel_hi:[1,0]
	v_pk_add_f32 v[60:61], v[60:61], 0 op_sel_hi:[1,0]
	v_pk_add_f32 v[58:59], v[58:59], 0 op_sel_hi:[1,0]
	v_pk_add_f32 v[56:57], v[56:57], 0 op_sel_hi:[1,0]
	v_pk_add_f32 v[54:55], v[54:55], 0 op_sel_hi:[1,0]
	v_pk_add_f32 v[52:53], v[52:53], 0 op_sel_hi:[1,0]
	v_pk_add_f32 v[46:47], v[46:47], 0 op_sel_hi:[1,0]
	v_pk_add_f32 v[44:45], v[44:45], 0 op_sel_hi:[1,0]
	v_pk_add_f32 v[50:51], v[50:51], 0 op_sel_hi:[1,0]
	v_pk_add_f32 v[48:49], v[48:49], 0 op_sel_hi:[1,0]
	v_pk_add_f32 v[30:31], v[30:31], 0 op_sel_hi:[1,0]
	v_pk_add_f32 v[28:29], v[28:29], 0 op_sel_hi:[1,0]
	v_pk_add_f32 v[26:27], v[26:27], 0 op_sel_hi:[1,0]
	v_pk_add_f32 v[24:25], v[24:25], 0 op_sel_hi:[1,0]
	v_pk_add_f32 v[22:23], v[22:23], 0 op_sel_hi:[1,0]
	v_pk_add_f32 v[20:21], v[20:21], 0 op_sel_hi:[1,0]
	v_pk_add_f32 v[14:15], v[14:15], 0 op_sel_hi:[1,0]
	v_pk_add_f32 v[12:13], v[12:13], 0 op_sel_hi:[1,0]
	v_pk_add_f32 v[18:19], v[18:19], 0 op_sel_hi:[1,0]
	v_pk_add_f32 v[16:17], v[16:17], 0 op_sel_hi:[1,0]
	s_and_b64 vcc, exec, s[8:9]
	s_mov_b32 s47, s45
	s_mov_b32 s48, s46
	s_mov_b64 s[28:29], s[12:13]
	s_mov_b64 s[26:27], s[10:11]
	s_waitcnt vmcnt(0)
	v_pk_add_f32 v[98:99], v[126:127], v[154:155]
	v_pk_add_f32 v[96:97], v[124:125], v[152:153]
	v_pk_add_f32 v[102:103], v[122:123], v[158:159]
	v_pk_add_f32 v[108:109], v[108:109], v[164:165]
	v_pk_add_f32 v[100:101], v[120:121], v[156:157]
	v_pk_add_f32 v[106:107], v[118:119], v[162:163]
	v_pk_add_f32 v[104:105], v[116:117], v[160:161]
	v_pk_add_f32 v[110:111], v[110:111], v[166:167]
	v_pk_add_f32 v[114:115], v[114:115], v[170:171]
	v_pk_add_f32 v[112:113], v[112:113], v[168:169]
	v_pk_add_f32 v[118:119], v[188:189], v[174:175]
	v_pk_add_f32 v[116:117], v[190:191], v[172:173]
	v_pk_add_f32 v[122:123], v[192:193], v[178:179]
	v_pk_add_f32 v[120:121], v[194:195], v[176:177]
	v_pk_add_f32 v[126:127], v[196:197], v[182:183]
	v_pk_add_f32 v[124:125], v[198:199], v[180:181]
	global_store_dwordx4 v[202:203], v[96:99], off
	global_store_dwordx4 v[202:203], v[100:103], off offset:64
	global_store_dwordx4 v[202:203], v[104:107], off offset:512
	global_store_dwordx4 v[202:203], v[108:111], off offset:576
	global_store_dwordx4 v[204:205], v[112:115], off
	global_store_dwordx4 v[204:205], v[116:119], off offset:64
	global_store_dwordx4 v[204:205], v[120:123], off offset:512
	global_store_dwordx4 v[204:205], v[124:127], off offset:576
	v_or_b32_e32 v108, 48, v184
	v_ashrrev_i32_e32 v109, 31, v108
	v_lshlrev_b64 v[152:153], 12, v[108:109]
	global_load_dwordx4 v[96:99], v[186:187], off
	global_load_dwordx4 v[100:103], v[186:187], off offset:64
	v_lshl_add_u64 v[124:125], v[142:143], 0, v[152:153]
	global_load_dwordx4 v[104:107], v[186:187], off offset:512
	global_load_dwordx4 v[108:111], v[186:187], off offset:576
	global_load_dwordx4 v[112:115], v[124:125], off
	global_load_dwordx4 v[116:119], v[124:125], off offset:64
	global_load_dwordx4 v[120:123], v[124:125], off offset:512
	s_nop 0
	global_load_dwordx4 v[124:127], v[124:125], off offset:576
	v_pk_add_f32 v[162:163], v[66:67], 0 op_sel_hi:[1,0]
	v_pk_add_f32 v[164:165], v[64:65], 0 op_sel_hi:[1,0]
	v_lshl_add_u64 v[64:65], s[52:53], 0, v[200:201]
	v_lshl_add_u64 v[66:67], s[52:53], 0, v[152:153]
	v_pk_add_f32 v[154:155], v[74:75], 0 op_sel_hi:[1,0]
	v_pk_add_f32 v[156:157], v[72:73], 0 op_sel_hi:[1,0]
	v_pk_add_f32 v[158:159], v[70:71], 0 op_sel_hi:[1,0]
	v_pk_add_f32 v[160:161], v[68:69], 0 op_sel_hi:[1,0]
	v_lshl_add_u64 v[168:169], v[64:65], 0, v[140:141]
	v_lshl_add_u64 v[170:171], v[66:67], 0, v[140:141]
	v_lshl_add_u64 v[166:167], v[144:145], 0, s[18:19]
	v_lshl_add_u64 v[152:153], v[142:143], 0, v[166:167]
	s_waitcnt vmcnt(0)
; #define PG8_WAIT_V(n) asm volatile("s_waitcnt vmcnt(" #n ")" ::: "memory")
; #define PG8_BAR __builtin_amdgcn_s_barrier()
; template <class Epi>
; __device__ __forceinline__ void gemm_phase(LAS unsigned char* lds, const Gemm g, const StaticOrder& S, const Epi& E) {
;     ...
;         if (!has_next) break;
;         {
; #pragma unroll
;         for (int a = 0; a < 2; ++a)
; #pragma unroll
;             for (int b = 0; b < 2; ++b)
; #pragma unroll
;                 for (int m = 0; m < 4; ++m)
; #pragma unroll
;                     for (int n = 0; n < 2; ++n) acc[a][b][m][n] = (f32x4){0.f, 0.f, 0.f, 0.f};
;         }
;         cur = nxt; cA = nA; cB = nB; ++ui;
;     }
;     PG8_WAIT_V(0);
;     if (wr == 0) PG8_BAR;
;     __device__ __forceinline__ void operator()(AccRef acc, const Unit& u, int wr, int wc, int fr, int fq) const {
;     ...
;         for (int ai = 0; ai < 2; ++ai)
; #pragma unroll
;             for (int mh = 0; mh < 2; ++mh) {
;                 f32x4 bs[2][2][2];
; #pragma unroll
;                 for (int m = 0; m < 2; ++m)
; #pragma unroll
;                     for (int bj = 0; bj < 2; ++bj)
; #pragma unroll
;                         for (int n = 0; n < 2; ++n) bs[m][bj][n] = *(const f32x4*)(base + (size_t)(row0 + ai * 128 + (2 * mh + m) * 16) * D + col0 + bj * 128 + n * 16);
; #pragma unroll
;                 for (int m = 0; m < 2; ++m)
; #pragma unroll
;                     for (int bj = 0; bj < 2; ++bj)
; #pragma unroll
;                         for (int n = 0; n < 2; ++n) *(f32x4*)(out + (size_t)(row0 + ai * 128 + (2 * mh + m) * 16) * D + col0 + bj * 128 + n * 16) = bs[m][bj][n] + sv[bj][n] * (acc[ai][bj][2 * mh + m][n] + bv[bj][n]);
;                 asm volatile("" ::: "memory"); }
	v_pk_add_f32 v[66:67], v[94:95], v[98:99]
	v_pk_add_f32 v[64:65], v[92:93], v[96:97]
	v_pk_add_f32 v[70:71], v[90:91], v[102:103]
	v_pk_add_f32 v[68:69], v[88:89], v[100:101]
	v_pk_add_f32 v[74:75], v[86:87], v[106:107]
	v_pk_add_f32 v[72:73], v[84:85], v[104:105]
	v_pk_add_f32 v[78:79], v[78:79], v[110:111]
	v_pk_add_f32 v[76:77], v[76:77], v[108:109]
	v_pk_add_f32 v[82:83], v[82:83], v[114:115]
	v_pk_add_f32 v[80:81], v[80:81], v[112:113]
	v_pk_add_f32 v[86:87], v[154:155], v[118:119]
	v_pk_add_f32 v[84:85], v[156:157], v[116:117]
	v_pk_add_f32 v[90:91], v[158:159], v[122:123]
	v_pk_add_f32 v[88:89], v[160:161], v[120:121]
	v_pk_add_f32 v[94:95], v[162:163], v[126:127]
	v_pk_add_f32 v[92:93], v[164:165], v[124:125]
	global_store_dwordx4 v[168:169], v[64:67], off
	global_store_dwordx4 v[168:169], v[68:71], off offset:64
	global_store_dwordx4 v[168:169], v[72:75], off offset:512
	global_store_dwordx4 v[168:169], v[76:79], off offset:576
	global_store_dwordx4 v[170:171], v[80:83], off
	global_store_dwordx4 v[170:171], v[84:87], off offset:64
	global_store_dwordx4 v[170:171], v[88:91], off offset:512
	global_store_dwordx4 v[170:171], v[92:95], off offset:576
	v_lshl_add_u64 v[96:97], v[144:145], 0, s[22:23]
	global_load_dwordx4 v[64:67], v[152:153], off
	global_load_dwordx4 v[68:71], v[152:153], off offset:64
	global_load_dwordx4 v[72:75], v[152:153], off offset:512
	v_lshl_add_u64 v[92:93], v[142:143], 0, v[96:97]
	global_load_dwordx4 v[76:79], v[152:153], off offset:576
	global_load_dwordx4 v[80:83], v[92:93], off
	global_load_dwordx4 v[84:87], v[92:93], off offset:64
	global_load_dwordx4 v[88:91], v[92:93], off offset:512
	s_nop 0
	global_load_dwordx4 v[92:95], v[92:93], off offset:576
	v_pk_add_f32 v[106:107], v[34:35], 0 op_sel_hi:[1,0]
	v_pk_add_f32 v[108:109], v[32:33], 0 op_sel_hi:[1,0]
	v_lshl_add_u64 v[32:33], s[52:53], 0, v[166:167]
	v_lshl_add_u64 v[34:35], s[52:53], 0, v[96:97]
	v_pk_add_f32 v[98:99], v[42:43], 0 op_sel_hi:[1,0]
	v_pk_add_f32 v[100:101], v[40:41], 0 op_sel_hi:[1,0]
	v_pk_add_f32 v[102:103], v[38:39], 0 op_sel_hi:[1,0]
	v_pk_add_f32 v[104:105], v[36:37], 0 op_sel_hi:[1,0]
	v_lshl_add_u64 v[112:113], v[32:33], 0, v[140:141]
	v_lshl_add_u64 v[114:115], v[34:35], 0, v[140:141]
	v_lshl_add_u64 v[110:111], v[144:145], 0, s[24:25]
	v_lshl_add_u64 v[96:97], v[142:143], 0, v[110:111]
	s_waitcnt vmcnt(0)
	v_pk_add_f32 v[34:35], v[62:63], v[66:67]
	v_pk_add_f32 v[32:33], v[60:61], v[64:65]
	v_pk_add_f32 v[38:39], v[58:59], v[70:71]
	v_pk_add_f32 v[36:37], v[56:57], v[68:69]
	v_pk_add_f32 v[42:43], v[54:55], v[74:75]
	v_pk_add_f32 v[40:41], v[52:53], v[72:73]
	v_pk_add_f32 v[46:47], v[46:47], v[78:79]
	v_pk_add_f32 v[44:45], v[44:45], v[76:77]
	v_pk_add_f32 v[50:51], v[50:51], v[82:83]
	v_pk_add_f32 v[48:49], v[48:49], v[80:81]
	v_pk_add_f32 v[54:55], v[98:99], v[86:87]
	v_pk_add_f32 v[52:53], v[100:101], v[84:85]
	v_pk_add_f32 v[58:59], v[102:103], v[90:91]
	v_pk_add_f32 v[56:57], v[104:105], v[88:89]
	v_pk_add_f32 v[62:63], v[106:107], v[94:95]
	v_pk_add_f32 v[60:61], v[108:109], v[92:93]
	global_store_dwordx4 v[112:113], v[32:35], off
	global_store_dwordx4 v[112:113], v[36:39], off offset:64
	global_store_dwordx4 v[112:113], v[40:43], off offset:512
	global_store_dwordx4 v[112:113], v[44:47], off offset:576
	global_store_dwordx4 v[114:115], v[48:51], off
	global_store_dwordx4 v[114:115], v[52:55], off offset:64
	global_store_dwordx4 v[114:115], v[56:59], off offset:512
	global_store_dwordx4 v[114:115], v[60:63], off offset:576
	v_lshl_add_u64 v[64:65], v[144:145], 0, s[14:15]
	global_load_dwordx4 v[32:35], v[96:97], off
	global_load_dwordx4 v[36:39], v[96:97], off offset:64
	global_load_dwordx4 v[40:43], v[96:97], off offset:512
	v_lshl_add_u64 v[60:61], v[142:143], 0, v[64:65]
	global_load_dwordx4 v[44:47], v[96:97], off offset:576
	global_load_dwordx4 v[48:51], v[60:61], off
	global_load_dwordx4 v[52:55], v[60:61], off offset:64
	global_load_dwordx4 v[56:59], v[60:61], off offset:512
	s_nop 0
	global_load_dwordx4 v[60:63], v[60:61], off offset:576
	v_pk_add_f32 v[74:75], v[2:3], 0 op_sel_hi:[1,0]
	v_pk_add_f32 v[76:77], v[0:1], 0 op_sel_hi:[1,0]
	v_lshl_add_u64 v[0:1], s[52:53], 0, v[110:111]
	v_lshl_add_u64 v[2:3], s[52:53], 0, v[64:65]
	v_pk_add_f32 v[66:67], v[10:11], 0 op_sel_hi:[1,0]
	v_pk_add_f32 v[68:69], v[8:9], 0 op_sel_hi:[1,0]
	v_pk_add_f32 v[70:71], v[6:7], 0 op_sel_hi:[1,0]
	v_pk_add_f32 v[72:73], v[4:5], 0 op_sel_hi:[1,0]
	v_lshl_add_u64 v[64:65], v[0:1], 0, v[140:141]
	v_lshl_add_u64 v[78:79], v[2:3], 0, v[140:141]
	s_waitcnt vmcnt(0)
	v_pk_add_f32 v[2:3], v[30:31], v[34:35]
	v_pk_add_f32 v[0:1], v[28:29], v[32:33]
	v_pk_add_f32 v[6:7], v[26:27], v[38:39]
	v_pk_add_f32 v[4:5], v[24:25], v[36:37]
	v_pk_add_f32 v[10:11], v[22:23], v[42:43]
	v_pk_add_f32 v[8:9], v[20:21], v[40:41]
	v_pk_add_f32 v[14:15], v[14:15], v[46:47]
	v_pk_add_f32 v[12:13], v[12:13], v[44:45]
	v_pk_add_f32 v[18:19], v[18:19], v[50:51]
	v_pk_add_f32 v[16:17], v[16:17], v[48:49]
	v_pk_add_f32 v[22:23], v[66:67], v[54:55]
	v_pk_add_f32 v[20:21], v[68:69], v[52:53]
	v_pk_add_f32 v[26:27], v[70:71], v[58:59]
	v_pk_add_f32 v[24:25], v[72:73], v[56:57]
	v_pk_add_f32 v[30:31], v[74:75], v[62:63]
	v_pk_add_f32 v[28:29], v[76:77], v[60:61]
	global_store_dwordx4 v[64:65], v[0:3], off
	global_store_dwordx4 v[64:65], v[4:7], off offset:64
	global_store_dwordx4 v[64:65], v[8:11], off offset:512
	global_store_dwordx4 v[64:65], v[12:15], off offset:576
	global_store_dwordx4 v[78:79], v[16:19], off
	global_store_dwordx4 v[78:79], v[20:23], off offset:64
	global_store_dwordx4 v[78:79], v[24:27], off offset:512
	global_store_dwordx4 v[78:79], v[28:31], off offset:576
	s_cbranch_vccz .LBB0_400
	s_waitcnt vmcnt(0)
	s_cmpk_gt_u32 s4, 0xff
	s_cbranch_scc1 .LBB0_415
	s_barrier

; #define PG8_STAGE(bufoff, gbase, voff) do { _Pragma("unroll") for (int _i = 0; _i < 2; ++_i) \
;         __builtin_amdgcn_global_load_lds((const unsigned*)((const char*)(gbase) + (voff)[_i]), (LAS unsigned*)(lds + (bufoff) + ldsw + _i * 8192), 16, 0, 0); } while (0)
; #define PG8_LDA(dst, b, h) do { _Pragma("unroll") for (int m = 0; m < 4; ++m) _Pragma("unroll") for (int k = 0; k < 2; ++k) dst[m][k] = *(const LAS bf16x8*)(lds + PG8_SA(b, h) + aoff + m * 2048 + k * 1024); } while (0)
; #define PG8_LDB(dst, b, h) do { _Pragma("unroll") for (int n = 0; n < 2; ++n) _Pragma("unroll") for (int k = 0; k < 2; ++k) dst[n][k] = *(const LAS bf16x8*)(lds + PG8_SB(b, h) + boff + n * 2048 + k * 1024); } while (0)
; #define PG8_MMA(ai, bj, At, Bt) do { __builtin_amdgcn_s_setprio(1); _Pragma("unroll") for (int m = 0; m < 4; ++m) _Pragma("unroll") for (int n = 0; n < 2; ++n) _Pragma("unroll") for (int k = 0; k < 2; ++k) \
;         acc[ai][bj][m][n] = __builtin_amdgcn_mfma_f32_16x16x32_bf16(Bt[n][k], At[m][k], acc[ai][bj][m][n], 0, 0, 0); __builtin_amdgcn_s_setprio(0); } while (0)
; #define PG8_WAIT_V(n) asm volatile("s_waitcnt vmcnt(" #n ")" ::: "memory")
; #define PG8_WAIT_L(n) asm volatile("s_waitcnt lgkmcnt(" #n ")" ::: "memory")
; template <class Epi>
; __device__ __forceinline__ void gemm_phase(LAS unsigned char* lds, const Gemm g, const StaticOrder& S, const Epi& E) {
;     ...
;         for (int t = 0; t < nt; t += 2) {
;             const bool last = (t == nt - 2);
;             const char* a1 = cA + (size_t)(t + 1) * kstep;
;             const char* a2 = last ? nA : cA + (size_t)(t + 2) * kstep; const char* b2 = last ? nB : cB + (size_t)(t + 2) * kstep;
;             const char* a3 = a2 + kstep; const char* b3 = b2 + kstep;
;             PG8_LDB(B0, 0, 0); PG8_SCHED; PG8_LDA(At, 0, 0); PG8_STAGE(PG8_SA(1, 1), a1 + hstepA, voffA);
;             PG8_WAIT_L(8); PG8_BAR; PG8_WAIT_L(0); PG8_MMA(0, 0, At, B0); PG8_BAR; PG8_SCHED;
;             PG8_LDB(B1, 0, 1); PG8_STAGE(PG8_SB(0, 0), b2, voffB);
;             PG8_BAR; PG8_WAIT_L(0); PG8_MMA(0, 1, At, B1); PG8_BAR;
;             PG8_LDA(At, 0, 1); PG8_STAGE(PG8_SA(0, 0), a2, voffA);
;             PG8_BAR; PG8_WAIT_L(0); PG8_MMA(1, 0, At, B0); PG8_BAR; PG8_SCHED;
;             PG8_STAGE(PG8_SB(0, 1), b2 + hstepB, voffB);
;             PG8_WAIT_V(6); PG8_BAR; PG8_MMA(1, 1, At, B1); PG8_BAR;
.LBB0_638:
	ds_read_b128 v[128:131], v185
	ds_read_b128 v[132:135], v185 offset:1024
	ds_read_b128 v[136:139], v185 offset:2048
	ds_read_b128 v[140:143], v185 offset:3072
	s_add_u32 s42, s40, 0xfffc0080
	s_addc_u32 s43, s41, -1
	s_cmp_eq_u32 s76, 12
	s_cselect_b32 s45, s31, s43
	s_cselect_b32 s44, s72, s42
	s_cselect_b32 s43, s29, s75
	s_cselect_b32 s42, s73, s74
	v_lshl_add_u64 v[180:181], s[40:41], 0, v[164:165]
	s_add_i32 m0, s39, 0xc000
	ds_read_b128 v[144:147], v186
	ds_read_b128 v[148:151], v186 offset:1024
	ds_read_b128 v[152:155], v186 offset:2048
	ds_read_b128 v[172:175], v186 offset:3072
	ds_read_b128 v[176:179], v186 offset:4096
	ds_read_b128 v[188:191], v186 offset:5120
	ds_read_b128 v[192:195], v186 offset:6144
	ds_read_b128 v[196:199], v186 offset:7168
	global_load_lds_dwordx4 v[180:181], off
	v_lshl_add_u64 v[180:181], s[40:41], 0, v[166:167]
	s_add_i32 m0, s39, 0xe000
	s_nop 0
	global_load_lds_dwordx4 v[180:181], off
	ds_read_b128 v[200:203], v187
	ds_read_b128 v[204:207], v187 offset:1024
	ds_read_b128 v[208:211], v187 offset:2048
	ds_read_b128 v[212:215], v187 offset:3072
	s_waitcnt lgkmcnt(0)
	s_barrier
	s_setprio 1
	v_mfma_f32_16x16x32_bf16 v[124:127], v[128:131], v[144:147], v[124:127]
	v_mfma_f32_16x16x32_bf16 v[116:119], v[136:139], v[144:147], v[116:119]
	v_mfma_f32_16x16x32_bf16 v[108:111], v[128:131], v[152:155], v[108:111]
	v_mfma_f32_16x16x32_bf16 v[100:103], v[136:139], v[152:155], v[100:103]
	v_mfma_f32_16x16x32_bf16 v[92:95], v[128:131], v[176:179], v[92:95]
	v_mfma_f32_16x16x32_bf16 v[84:87], v[136:139], v[176:179], v[84:87]
	v_mfma_f32_16x16x32_bf16 v[76:79], v[128:131], v[192:195], v[76:79]
	v_mfma_f32_16x16x32_bf16 v[68:71], v[136:139], v[192:195], v[68:71]
	v_mfma_f32_16x16x32_bf16 v[124:127], v[132:135], v[148:151], v[124:127]
	v_mfma_f32_16x16x32_bf16 v[116:119], v[140:143], v[148:151], v[116:119]
	v_mfma_f32_16x16x32_bf16 v[108:111], v[132:135], v[172:175], v[108:111]
	v_mfma_f32_16x16x32_bf16 v[100:103], v[140:143], v[172:175], v[100:103]
	v_mfma_f32_16x16x32_bf16 v[92:95], v[132:135], v[188:191], v[92:95]
	v_mfma_f32_16x16x32_bf16 v[84:87], v[140:143], v[188:191], v[84:87]
	v_mfma_f32_16x16x32_bf16 v[76:79], v[132:135], v[196:199], v[76:79]
	v_mfma_f32_16x16x32_bf16 v[68:71], v[140:143], v[196:199], v[68:71]
	v_mfma_f32_16x16x32_bf16 v[120:123], v[200:203], v[144:147], v[120:123]
	v_mfma_f32_16x16x32_bf16 v[112:115], v[208:211], v[144:147], v[112:115]
	v_mfma_f32_16x16x32_bf16 v[104:107], v[200:203], v[152:155], v[104:107]
	v_mfma_f32_16x16x32_bf16 v[96:99], v[208:211], v[152:155], v[96:99]
	v_mfma_f32_16x16x32_bf16 v[88:91], v[200:203], v[176:179], v[88:91]
	v_mfma_f32_16x16x32_bf16 v[80:83], v[208:211], v[176:179], v[80:83]
	v_mfma_f32_16x16x32_bf16 v[72:75], v[200:203], v[192:195], v[72:75]
	v_mfma_f32_16x16x32_bf16 v[64:67], v[208:211], v[192:195], v[64:67]
	v_mfma_f32_16x16x32_bf16 v[120:123], v[204:207], v[148:151], v[120:123]
	v_mfma_f32_16x16x32_bf16 v[112:115], v[212:215], v[148:151], v[112:115]
	v_mfma_f32_16x16x32_bf16 v[104:107], v[204:207], v[172:175], v[104:107]
	v_mfma_f32_16x16x32_bf16 v[96:99], v[212:215], v[172:175], v[96:99]
	v_mfma_f32_16x16x32_bf16 v[88:91], v[204:207], v[188:191], v[88:91]
	v_mfma_f32_16x16x32_bf16 v[80:83], v[212:215], v[188:191], v[80:83]
	v_mfma_f32_16x16x32_bf16 v[72:75], v[204:207], v[196:199], v[72:75]
	v_mfma_f32_16x16x32_bf16 v[64:67], v[212:215], v[196:199], v[64:67]
	s_setprio 0
	s_barrier
	s_nop 1
	ds_read_b128 v[144:147], v186 offset:16384
	ds_read_b128 v[148:151], v186 offset:17408
	ds_read_b128 v[152:155], v186 offset:18432
	ds_read_b128 v[172:175], v186 offset:19456
	ds_read_b128 v[176:179], v186 offset:20480
	ds_read_b128 v[188:191], v186 offset:21504
	ds_read_b128 v[192:195], v186 offset:22528
	ds_read_b128 v[196:199], v186 offset:23552
	s_add_i32 s77, s69, s7
	v_lshl_add_u64 v[180:181], s[42:43], 0, v[158:159]
	s_mov_b32 m0, s77
	s_nop 0
	global_load_lds_dwordx4 v[180:181], off
	v_lshl_add_u64 v[216:217], s[42:43], 0, v[162:163]
	s_add_i32 m0, s77, 0x2000
	s_nop 0
	global_load_lds_dwordx4 v[216:217], off
	s_mov_b32 m0, s39
	v_lshl_add_u64 v[220:221], s[44:45], 0, v[156:157]
	global_load_lds_dwordx4 v[220:221], off
	v_lshl_add_u64 v[222:223], s[44:45], 0, v[160:161]
	s_mov_b32 m0, s46
	s_nop 0
	global_load_lds_dwordx4 v[222:223], off
	s_add_u32 s78, s42, 0x40000
	s_addc_u32 s79, s43, 0
	s_add_i32 s77, s70, s7
	v_lshl_add_u64 v[254:255], s[78:79], 0, v[158:159]
	s_mov_b32 m0, s77
	s_nop 0
	global_load_lds_dwordx4 v[254:255], off
	v_lshl_add_u64 v[254:255], s[78:79], 0, v[162:163]
	s_add_i32 m0, s77, 0x2000
	s_nop 0
	global_load_lds_dwordx4 v[254:255], off
	s_waitcnt vmcnt(6)
	s_waitcnt lgkmcnt(0)
	s_barrier
; #define PG8_STAGE(bufoff, gbase, voff) do { _Pragma("unroll") for (int _i = 0; _i < 2; ++_i) \
;         __builtin_amdgcn_global_load_lds((const unsigned*)((const char*)(gbase) + (voff)[_i]), (LAS unsigned*)(lds + (bufoff) + ldsw + _i * 8192), 16, 0, 0); } while (0)
; #define PG8_LDA(dst, b, h) do { _Pragma("unroll") for (int m = 0; m < 4; ++m) _Pragma("unroll") for (int k = 0; k < 2; ++k) dst[m][k] = *(const LAS bf16x8*)(lds + PG8_SA(b, h) + aoff + m * 2048 + k * 1024); } while (0)
; #define PG8_LDB(dst, b, h) do { _Pragma("unroll") for (int n = 0; n < 2; ++n) _Pragma("unroll") for (int k = 0; k < 2; ++k) dst[n][k] = *(const LAS bf16x8*)(lds + PG8_SB(b, h) + boff + n * 2048 + k * 1024); } while (0)
; #define PG8_MMA(ai, bj, At, Bt) do { __builtin_amdgcn_s_setprio(1); _Pragma("unroll") for (int m = 0; m < 4; ++m) _Pragma("unroll") for (int n = 0; n < 2; ++n) _Pragma("unroll") for (int k = 0; k < 2; ++k) \
;         acc[ai][bj][m][n] = __builtin_amdgcn_mfma_f32_16x16x32_bf16(Bt[n][k], At[m][k], acc[ai][bj][m][n], 0, 0, 0); __builtin_amdgcn_s_setprio(0); } while (0)
; #define PG8_WAIT_V(n) asm volatile("s_waitcnt vmcnt(" #n ")" ::: "memory")
; #define PG8_WAIT_L(n) asm volatile("s_waitcnt lgkmcnt(" #n ")" ::: "memory")
; #define PG8_BAR __builtin_amdgcn_s_barrier()
; #define PG8_SCHED __builtin_amdgcn_sched_barrier(0)
; template <class Epi>
; __device__ __forceinline__ void gemm_phase(LAS unsigned char* lds, const Gemm g, const StaticOrder& S, const Epi& E) {
;     ...
;             PG8_BAR; PG8_WAIT_L(0); PG8_MMA(1, 0, At, B0); PG8_BAR; PG8_SCHED;
;             PG8_STAGE(PG8_SB(0, 1), b2 + hstepB, voffB);
;             PG8_WAIT_V(6); PG8_BAR; PG8_MMA(1, 1, At, B1); PG8_BAR;
;             PG8_LDB(B0, 1, 0); PG8_SCHED; PG8_LDA(At, 1, 0); PG8_STAGE(PG8_SA(0, 1), a2 + hstepA, voffA);
;             PG8_WAIT_L(8); PG8_BAR; PG8_WAIT_L(0); PG8_MMA(0, 0, At, B0); PG8_BAR; PG8_SCHED;
;             PG8_LDB(B1, 1, 1); PG8_STAGE(PG8_SB(1, 0), b3, voffB);
;             PG8_BAR; PG8_WAIT_L(0); PG8_MMA(0, 1, At, B1); PG8_BAR;
	s_setprio 1
	v_mfma_f32_16x16x32_bf16 v[60:63], v[128:131], v[144:147], v[60:63]
	v_mfma_f32_16x16x32_bf16 v[52:55], v[136:139], v[144:147], v[52:55]
	v_mfma_f32_16x16x32_bf16 v[44:47], v[128:131], v[152:155], v[44:47]
	v_mfma_f32_16x16x32_bf16 v[36:39], v[136:139], v[152:155], v[36:39]
	v_mfma_f32_16x16x32_bf16 v[28:31], v[128:131], v[176:179], v[28:31]
	v_mfma_f32_16x16x32_bf16 v[20:23], v[136:139], v[176:179], v[20:23]
	v_mfma_f32_16x16x32_bf16 v[12:15], v[128:131], v[192:195], v[12:15]
	v_mfma_f32_16x16x32_bf16 v[4:7], v[136:139], v[192:195], v[4:7]
	v_mfma_f32_16x16x32_bf16 v[60:63], v[132:135], v[148:151], v[60:63]
	v_mfma_f32_16x16x32_bf16 v[52:55], v[140:143], v[148:151], v[52:55]
	v_mfma_f32_16x16x32_bf16 v[44:47], v[132:135], v[172:175], v[44:47]
	v_mfma_f32_16x16x32_bf16 v[36:39], v[140:143], v[172:175], v[36:39]
	v_mfma_f32_16x16x32_bf16 v[28:31], v[132:135], v[188:191], v[28:31]
	v_mfma_f32_16x16x32_bf16 v[20:23], v[140:143], v[188:191], v[20:23]
	v_mfma_f32_16x16x32_bf16 v[12:15], v[132:135], v[196:199], v[12:15]
	v_mfma_f32_16x16x32_bf16 v[4:7], v[140:143], v[196:199], v[4:7]
	v_mfma_f32_16x16x32_bf16 v[56:59], v[200:203], v[144:147], v[56:59]
	v_mfma_f32_16x16x32_bf16 v[48:51], v[208:211], v[144:147], v[48:51]
	v_mfma_f32_16x16x32_bf16 v[40:43], v[200:203], v[152:155], v[40:43]
	v_mfma_f32_16x16x32_bf16 v[32:35], v[208:211], v[152:155], v[32:35]
	v_mfma_f32_16x16x32_bf16 v[24:27], v[200:203], v[176:179], v[24:27]
	v_mfma_f32_16x16x32_bf16 v[16:19], v[208:211], v[176:179], v[16:19]
	v_mfma_f32_16x16x32_bf16 v[8:11], v[200:203], v[192:195], v[8:11]
	v_mfma_f32_16x16x32_bf16 v[0:3], v[208:211], v[192:195], v[0:3]
	v_mfma_f32_16x16x32_bf16 v[56:59], v[204:207], v[148:151], v[56:59]
	v_mfma_f32_16x16x32_bf16 v[48:51], v[212:215], v[148:151], v[48:51]
	v_mfma_f32_16x16x32_bf16 v[40:43], v[204:207], v[172:175], v[40:43]
	v_mfma_f32_16x16x32_bf16 v[32:35], v[212:215], v[172:175], v[32:35]
	v_mfma_f32_16x16x32_bf16 v[24:27], v[204:207], v[188:191], v[24:27]
	v_mfma_f32_16x16x32_bf16 v[16:19], v[212:215], v[188:191], v[16:19]
	v_mfma_f32_16x16x32_bf16 v[8:11], v[204:207], v[196:199], v[8:11]
	v_mfma_f32_16x16x32_bf16 v[0:3], v[212:215], v[196:199], v[0:3]
	s_setprio 0
	s_add_i32 s77, 0, 0x18000
	v_add_u32_e32 v140, s77, v183
	s_barrier
	ds_read_b128 v[128:131], v140
	ds_read_b128 v[132:135], v140 offset:1024
	ds_read_b128 v[136:139], v140 offset:2048
	ds_read_b128 v[140:143], v140 offset:3072
	s_add_u32 s44, s44, 0x40000
	s_addc_u32 s45, s45, 0
	s_mov_b32 m0, s47
	v_lshl_add_u64 v[200:201], s[44:45], 0, v[156:157]
	ds_read_b128 v[144:147], v186 offset:32768
	ds_read_b128 v[148:151], v186 offset:33792
	ds_read_b128 v[152:155], v186 offset:34816
	ds_read_b128 v[172:175], v186 offset:35840
	ds_read_b128 v[176:179], v186 offset:36864
	ds_read_b128 v[188:191], v186 offset:37888
	ds_read_b128 v[192:195], v186 offset:38912
	ds_read_b128 v[196:199], v186 offset:39936
	global_load_lds_dwordx4 v[200:201], off
	v_lshl_add_u64 v[200:201], s[44:45], 0, v[160:161]
	s_mov_b32 m0, s48
	s_nop 0
	global_load_lds_dwordx4 v[200:201], off
	s_add_i32 s44, 0, 0x1c000
	v_add_u32_e32 v212, s44, v183
	ds_read_b128 v[200:203], v212
	ds_read_b128 v[204:207], v212 offset:1024
	ds_read_b128 v[208:211], v212 offset:2048
	ds_read_b128 v[212:215], v212 offset:3072
	s_waitcnt lgkmcnt(0)
	s_barrier
	s_setprio 1
	v_mfma_f32_16x16x32_bf16 v[124:127], v[128:131], v[144:147], v[124:127]
	v_mfma_f32_16x16x32_bf16 v[116:119], v[136:139], v[144:147], v[116:119]
	v_mfma_f32_16x16x32_bf16 v[108:111], v[128:131], v[152:155], v[108:111]
	v_mfma_f32_16x16x32_bf16 v[100:103], v[136:139], v[152:155], v[100:103]
	v_mfma_f32_16x16x32_bf16 v[92:95], v[128:131], v[176:179], v[92:95]
	v_mfma_f32_16x16x32_bf16 v[84:87], v[136:139], v[176:179], v[84:87]
	v_mfma_f32_16x16x32_bf16 v[76:79], v[128:131], v[192:195], v[76:79]
	v_mfma_f32_16x16x32_bf16 v[68:71], v[136:139], v[192:195], v[68:71]
	v_mfma_f32_16x16x32_bf16 v[124:127], v[132:135], v[148:151], v[124:127]
	v_mfma_f32_16x16x32_bf16 v[116:119], v[140:143], v[148:151], v[116:119]
	v_mfma_f32_16x16x32_bf16 v[108:111], v[132:135], v[172:175], v[108:111]
	v_mfma_f32_16x16x32_bf16 v[100:103], v[140:143], v[172:175], v[100:103]
	v_mfma_f32_16x16x32_bf16 v[92:95], v[132:135], v[188:191], v[92:95]
	v_mfma_f32_16x16x32_bf16 v[84:87], v[140:143], v[188:191], v[84:87]
	v_mfma_f32_16x16x32_bf16 v[76:79], v[132:135], v[196:199], v[76:79]
	v_mfma_f32_16x16x32_bf16 v[68:71], v[140:143], v[196:199], v[68:71]
	v_mfma_f32_16x16x32_bf16 v[120:123], v[200:203], v[144:147], v[120:123]
	v_mfma_f32_16x16x32_bf16 v[112:115], v[208:211], v[144:147], v[112:115]
	v_mfma_f32_16x16x32_bf16 v[104:107], v[200:203], v[152:155], v[104:107]
	v_mfma_f32_16x16x32_bf16 v[96:99], v[208:211], v[152:155], v[96:99]
	v_mfma_f32_16x16x32_bf16 v[88:91], v[200:203], v[176:179], v[88:91]
	v_mfma_f32_16x16x32_bf16 v[80:83], v[208:211], v[176:179], v[80:83]
	v_mfma_f32_16x16x32_bf16 v[72:75], v[200:203], v[192:195], v[72:75]
	v_mfma_f32_16x16x32_bf16 v[64:67], v[208:211], v[192:195], v[64:67]
	v_mfma_f32_16x16x32_bf16 v[120:123], v[204:207], v[148:151], v[120:123]
	v_mfma_f32_16x16x32_bf16 v[112:115], v[212:215], v[148:151], v[112:115]
	v_mfma_f32_16x16x32_bf16 v[104:107], v[204:207], v[172:175], v[104:107]
	v_mfma_f32_16x16x32_bf16 v[96:99], v[212:215], v[172:175], v[96:99]
	v_mfma_f32_16x16x32_bf16 v[88:91], v[204:207], v[188:191], v[88:91]
	v_mfma_f32_16x16x32_bf16 v[80:83], v[212:215], v[188:191], v[80:83]
	v_mfma_f32_16x16x32_bf16 v[72:75], v[204:207], v[196:199], v[72:75]
	v_mfma_f32_16x16x32_bf16 v[64:67], v[212:215], v[196:199], v[64:67]
	s_setprio 0
	s_barrier
; #define PG8_STAGE(bufoff, gbase, voff) do { _Pragma("unroll") for (int _i = 0; _i < 2; ++_i) \
;         __builtin_amdgcn_global_load_lds((const unsigned*)((const char*)(gbase) + (voff)[_i]), (LAS unsigned*)(lds + (bufoff) + ldsw + _i * 8192), 16, 0, 0); } while (0)
; #define PG8_LDA(dst, b, h) do { _Pragma("unroll") for (int m = 0; m < 4; ++m) _Pragma("unroll") for (int k = 0; k < 2; ++k) dst[m][k] = *(const LAS bf16x8*)(lds + PG8_SA(b, h) + aoff + m * 2048 + k * 1024); } while (0)
; #define PG8_LDB(dst, b, h) do { _Pragma("unroll") for (int n = 0; n < 2; ++n) _Pragma("unroll") for (int k = 0; k < 2; ++k) dst[n][k] = *(const LAS bf16x8*)(lds + PG8_SB(b, h) + boff + n * 2048 + k * 1024); } while (0)
; #define PG8_MMA(ai, bj, At, Bt) do { __builtin_amdgcn_s_setprio(1); _Pragma("unroll") for (int m = 0; m < 4; ++m) _Pragma("unroll") for (int n = 0; n < 2; ++n) _Pragma("unroll") for (int k = 0; k < 2; ++k) \
;         acc[ai][bj][m][n] = __builtin_amdgcn_mfma_f32_16x16x32_bf16(Bt[n][k], At[m][k], acc[ai][bj][m][n], 0, 0, 0); __builtin_amdgcn_s_setprio(0); } while (0)
; #define PG8_BAR __builtin_amdgcn_s_barrier()
; template <class Epi>
; __device__ __forceinline__ void gemm_phase(LAS unsigned char* lds, const Gemm g, const StaticOrder& S, const Epi& E) {
;     ...
;             PG8_LDB(B1, 1, 1); PG8_STAGE(PG8_SB(1, 0), b3, voffB);
;             PG8_BAR; PG8_WAIT_L(0); PG8_MMA(0, 1, At, B1); PG8_BAR;
;             PG8_LDA(At, 1, 1); PG8_STAGE(PG8_SA(1, 0), a3, voffA);
;             PG8_BAR; PG8_WAIT_L(0); PG8_MMA(1, 0, At, B0); PG8_BAR; PG8_SCHED;
;             PG8_STAGE(PG8_SB(1, 1), b3 + hstepB, voffB);
;             PG8_WAIT_V(6); PG8_BAR; PG8_MMA(1, 1, At, B1); PG8_BAR;
;     __device__ __forceinline__ void operator()(AccRef acc, const Unit& u, int wr, int wc, int fr, int fq) const {
;         const int row0 = u.pm * 256 + wr * 64 + fr, col0 = u.pn * 128 + wc * 32 + 8 * fq;
;         f32x4 bv[2], bg[2];
; #pragma unroll
;         for (int n = 0; n < 2; ++n) { bv[n] = *(const f32x4*)(bias + col0 + 4 * n); bg[n] = *(const f32x4*)(bias + D + col0 + 4 * n); }
; #pragma unroll
;         for (int ai = 0; ai < 2; ++ai) {
;             f32x4 xs[4][2];
; #pragma unroll
;             for (int m = 0; m < 4; ++m)
; #pragma unroll
;                 for (int n = 0; n < 2; ++n) xs[m][n] = *(const f32x4*)(x + (size_t)(row0 + ai * 128 + m * 16) * D + col0 + 4 * n);
	s_nop 1
	ds_read_b128 v[144:147], v186 offset:49152
	ds_read_b128 v[148:151], v186 offset:50176
	ds_read_b128 v[152:155], v186 offset:51200
	ds_read_b128 v[172:175], v186 offset:52224
	ds_read_b128 v[176:179], v186 offset:53248
	ds_read_b128 v[188:191], v186 offset:54272
	ds_read_b128 v[192:195], v186 offset:55296
	ds_read_b128 v[196:199], v186 offset:56320
	s_add_i32 s45, s77, s7
	v_lshl_add_u64 v[254:255], v[180:181], 0, s[12:13]
	s_mov_b32 m0, s45
	s_nop 0
	global_load_lds_dwordx4 v[254:255], off
	v_lshl_add_u64 v[254:255], v[216:217], 0, s[12:13]
	s_add_i32 m0, s45, 0x2000
	s_nop 0
	global_load_lds_dwordx4 v[254:255], off
	s_mov_b32 m0, s63
	v_lshl_add_u64 v[254:255], v[220:221], 0, s[12:13]
	global_load_lds_dwordx4 v[254:255], off
	v_lshl_add_u64 v[180:181], v[222:223], 0, s[12:13]
	s_mov_b32 m0, s68
	s_nop 0
	global_load_lds_dwordx4 v[180:181], off
	s_add_u32 s42, s42, 0x40080
	s_addc_u32 s43, s43, 0
	s_add_i32 s44, s44, s7
	v_lshl_add_u64 v[254:255], s[42:43], 0, v[158:159]
	s_mov_b32 m0, s44
	s_nop 0
	global_load_lds_dwordx4 v[254:255], off
	v_lshl_add_u64 v[254:255], s[42:43], 0, v[162:163]
	s_add_i32 m0, s44, 0x2000
	s_nop 0
	global_load_lds_dwordx4 v[254:255], off
	s_waitcnt vmcnt(6)
	s_waitcnt lgkmcnt(0)
	s_barrier
	s_setprio 1
	v_mfma_f32_16x16x32_bf16 v[60:63], v[128:131], v[144:147], v[60:63]
	v_mfma_f32_16x16x32_bf16 v[52:55], v[136:139], v[144:147], v[52:55]
	v_mfma_f32_16x16x32_bf16 v[44:47], v[128:131], v[152:155], v[44:47]
	v_mfma_f32_16x16x32_bf16 v[36:39], v[136:139], v[152:155], v[36:39]
	v_mfma_f32_16x16x32_bf16 v[28:31], v[128:131], v[176:179], v[28:31]
	v_mfma_f32_16x16x32_bf16 v[20:23], v[136:139], v[176:179], v[20:23]
	v_mfma_f32_16x16x32_bf16 v[12:15], v[128:131], v[192:195], v[12:15]
	v_mfma_f32_16x16x32_bf16 v[4:7], v[136:139], v[192:195], v[4:7]
	v_mfma_f32_16x16x32_bf16 v[60:63], v[132:135], v[148:151], v[60:63]
	v_mfma_f32_16x16x32_bf16 v[52:55], v[140:143], v[148:151], v[52:55]
	v_mfma_f32_16x16x32_bf16 v[44:47], v[132:135], v[172:175], v[44:47]
	v_mfma_f32_16x16x32_bf16 v[36:39], v[140:143], v[172:175], v[36:39]
	v_mfma_f32_16x16x32_bf16 v[28:31], v[132:135], v[188:191], v[28:31]
	v_mfma_f32_16x16x32_bf16 v[20:23], v[140:143], v[188:191], v[20:23]
	v_mfma_f32_16x16x32_bf16 v[12:15], v[132:135], v[196:199], v[12:15]
	v_mfma_f32_16x16x32_bf16 v[4:7], v[140:143], v[196:199], v[4:7]
	v_mfma_f32_16x16x32_bf16 v[56:59], v[200:203], v[144:147], v[56:59]
	v_mfma_f32_16x16x32_bf16 v[48:51], v[208:211], v[144:147], v[48:51]
	v_mfma_f32_16x16x32_bf16 v[40:43], v[200:203], v[152:155], v[40:43]
	v_mfma_f32_16x16x32_bf16 v[32:35], v[208:211], v[152:155], v[32:35]
	v_mfma_f32_16x16x32_bf16 v[24:27], v[200:203], v[176:179], v[24:27]
	v_mfma_f32_16x16x32_bf16 v[16:19], v[208:211], v[176:179], v[16:19]
	v_mfma_f32_16x16x32_bf16 v[8:11], v[200:203], v[192:195], v[8:11]
	v_mfma_f32_16x16x32_bf16 v[0:3], v[208:211], v[192:195], v[0:3]
	v_mfma_f32_16x16x32_bf16 v[56:59], v[204:207], v[148:151], v[56:59]
	v_mfma_f32_16x16x32_bf16 v[48:51], v[212:215], v[148:151], v[48:51]
	v_mfma_f32_16x16x32_bf16 v[40:43], v[204:207], v[172:175], v[40:43]
	v_mfma_f32_16x16x32_bf16 v[32:35], v[212:215], v[172:175], v[32:35]
	v_mfma_f32_16x16x32_bf16 v[24:27], v[204:207], v[188:191], v[24:27]
	v_mfma_f32_16x16x32_bf16 v[16:19], v[212:215], v[188:191], v[16:19]
	v_mfma_f32_16x16x32_bf16 v[8:11], v[204:207], v[196:199], v[8:11]
	v_mfma_f32_16x16x32_bf16 v[0:3], v[212:215], v[196:199], v[0:3]
	s_setprio 0
	s_add_i32 s76, s76, 2
	s_add_u32 s40, s40, 0x100
	s_addc_u32 s41, s41, 0
	s_add_u32 s74, s74, 0x100
	s_addc_u32 s75, s75, 0
	s_cmp_gt_u32 s76, 13
	s_barrier
	s_cbranch_scc0 .LBB0_638
	v_lshl_or_b32 v128, s71, 7, v184
	v_ashrrev_i32_e32 v129, 31, v128
	v_lshlrev_b64 v[172:173], 2, v[128:129]
	v_lshl_add_u64 v[128:129], s[14:15], 0, v[172:173]
	global_load_dwordx4 v[140:143], v[128:129], off
	v_lshl_add_u64 v[130:131], s[10:11], 0, v[172:173]
	global_load_dwordx4 v[136:139], v[130:131], off
	global_load_dwordx4 v[132:135], v[128:129], off offset:16
	s_nop 0
	global_load_dwordx4 v[128:131], v[130:131], off offset:16
	v_lshl_add_u32 v144, s38, 8, v182
	v_ashrrev_i32_e32 v145, 31, v144
	v_lshlrev_b64 v[176:177], 12, v[144:145]
	v_lshl_add_u64 v[174:175], s[52:53], 0, v[172:173]
	v_lshl_add_u64 v[146:147], v[174:175], 0, v[176:177]
	global_load_dwordx4 v[188:191], v[146:147], off
	global_load_dwordx4 v[192:195], v[146:147], off offset:16
	v_or_b32_e32 v146, 16, v144
	v_or_b32_e32 v148, 32, v144
	v_or_b32_e32 v144, 48, v144
	v_ashrrev_i32_e32 v147, 31, v146
	v_ashrrev_i32_e32 v149, 31, v148
	v_ashrrev_i32_e32 v145, 31, v144
	v_lshlrev_b64 v[208:209], 12, v[146:147]
	v_lshlrev_b64 v[180:181], 12, v[148:149]
	v_lshlrev_b64 v[178:179], 12, v[144:145]
	v_lshl_add_u64 v[146:147], v[174:175], 0, v[208:209]
	v_lshl_add_u64 v[144:145], s[52:53], 0, v[176:177]
	global_load_dwordx4 v[196:199], v[146:147], off offset:16
	global_load_dwordx4 v[200:203], v[146:147], off
	v_lshl_add_u64 v[146:147], v[174:175], 0, v[180:181]
	v_lshl_add_u64 v[148:149], v[174:175], 0, v[178:179]
	v_lshl_add_u64 v[210:211], v[144:145], 0, v[172:173]
	global_load_dwordx4 v[152:155], v[146:147], off offset:16
	global_load_dwordx4 v[204:207], v[146:147], off
	s_nop 0
	global_load_dwordx4 v[144:147], v[148:149], off offset:16
	s_nop 0
	global_load_dwordx4 v[148:151], v[148:149], off
	s_and_b64 vcc, exec, s[8:9]
	s_mov_b32 s71, s28
	s_mov_b32 s38, s30
	s_mov_b64 s[42:43], s[36:37]
	s_mov_b64 s[40:41], s[34:35]
	s_waitcnt vmcnt(0)
; __device__ __forceinline__ float sigmoidf_(float x) { return __builtin_amdgcn_rcpf(1.0f + __expf(-x)); }
;     __device__ __forceinline__ void operator()(AccRef acc, const Unit& u, int wr, int wc, int fr, int fq) const {
;     ...
; #pragma unroll
;             for (int m = 0; m < 4; ++m)
; #pragma unroll
;                 for (int n = 0; n < 2; ++n) { f32x4 xv = xs[m][n]; const f32x4 v = acc[ai][0][m][n] + bv[n], gt = acc[ai][1][m][n] + bg[n];
; #pragma unroll
;                     for (int j = 0; j < 4; ++j) xv[j] += v[j] * sigmoidf_(gt[j]);
;                     *(f32x4*)(x + (size_t)(row0 + ai * 128 + m * 16) * D + col0 + 4 * n) = xv; }
	v_pk_add_f32 v[108:109], v[108:109], v[136:137]
	v_add_f32_e32 v212, v120, v140
	v_add_f32_e32 v213, v121, v141
	v_add_f32_e32 v214, v122, v142
	v_add_f32_e32 v215, v123, v143
	v_pk_add_f32 v[120:121], v[126:127], v[138:139]
	v_pk_add_f32 v[122:123], v[124:125], v[136:137]
	v_add_f32_e32 v112, v112, v132
	v_add_f32_e32 v113, v113, v133
	v_add_f32_e32 v104, v104, v140
	v_mul_f32_e32 v124, 0xbfb8aa3b, v212
	v_mul_f32_e32 v125, 0xbfb8aa3b, v213
	v_mul_f32_e32 v126, 0xbfb8aa3b, v214
	v_mul_f32_e32 v127, 0xbfb8aa3b, v215
	v_mul_f32_e32 v112, 0xbfb8aa3b, v112
	v_mul_f32_e32 v113, 0xbfb8aa3b, v113
	v_mul_f32_e32 v104, 0xbfb8aa3b, v104
	v_exp_f32_e32 v124, v124
	v_exp_f32_e32 v125, v125
	v_exp_f32_e32 v126, v126
	v_exp_f32_e32 v127, v127
	v_exp_f32_e32 v112, v112
	v_exp_f32_e32 v113, v113
	v_exp_f32_e32 v104, v104
	v_add_f32_e32 v114, v114, v134
	v_add_f32_e32 v115, v115, v135
	v_add_f32_e32 v105, v105, v141
	v_mul_f32_e32 v114, 0xbfb8aa3b, v114
	v_mul_f32_e32 v115, 0xbfb8aa3b, v115
	v_mul_f32_e32 v105, 0xbfb8aa3b, v105
	v_exp_f32_e32 v114, v114
	v_exp_f32_e32 v115, v115
	v_exp_f32_e32 v213, v105
	v_add_f32_e32 v105, 1.0, v124
	v_add_f32_e32 v124, 1.0, v125
	v_add_f32_e32 v125, 1.0, v126
	v_add_f32_e32 v126, 1.0, v127
	v_add_f32_e32 v127, 1.0, v112
	v_add_f32_e32 v212, 1.0, v113
	v_add_f32_e32 v214, 1.0, v104
	v_rcp_f32_e32 v104, v105
	v_rcp_f32_e32 v105, v124
	v_rcp_f32_e32 v112, v125
	v_rcp_f32_e32 v113, v126
	v_add_f32_e32 v114, 1.0, v114
	v_add_f32_e32 v115, 1.0, v115
	v_add_f32_e32 v106, v106, v142
	v_rcp_f32_e32 v124, v127
	v_rcp_f32_e32 v126, v114
	v_rcp_f32_e32 v127, v115
	v_pk_fma_f32 v[114:115], v[120:121], v[112:113], v[190:191]
	v_pk_fma_f32 v[112:113], v[122:123], v[104:105], v[188:189]
	v_add_f32_e32 v104, v107, v143
	v_add_f32_e32 v88, v88, v140
	v_add_f32_e32 v89, v89, v141
	v_add_f32_e32 v72, v72, v140
	v_add_f32_e32 v73, v73, v141
	v_mul_f32_e32 v106, 0xbfb8aa3b, v106
	v_mul_f32_e32 v104, 0xbfb8aa3b, v104
	v_add_f32_e32 v96, v96, v132
	v_add_f32_e32 v97, v97, v133
	v_add_f32_e32 v98, v98, v134
	v_add_f32_e32 v99, v99, v135
	v_mul_f32_e32 v88, 0xbfb8aa3b, v88
	v_mul_f32_e32 v89, 0xbfb8aa3b, v89
	v_add_f32_e32 v90, v90, v142
	v_add_f32_e32 v91, v91, v143
	v_add_f32_e32 v80, v80, v132
	v_add_f32_e32 v81, v81, v133
	v_add_f32_e32 v82, v82, v134
	v_add_f32_e32 v83, v83, v135
	v_mul_f32_e32 v72, 0xbfb8aa3b, v72
	v_mul_f32_e32 v73, 0xbfb8aa3b, v73
	v_add_f32_e32 v74, v74, v142
	v_add_f32_e32 v75, v75, v143
	v_add_f32_e32 v64, v64, v132
	v_add_f32_e32 v65, v65, v133
	v_add_f32_e32 v66, v66, v134
	v_add_f32_e32 v67, v67, v135
	v_exp_f32_e32 v106, v106
	v_exp_f32_e32 v105, v104
	v_mul_f32_e32 v96, 0xbfb8aa3b, v96
	v_mul_f32_e32 v97, 0xbfb8aa3b, v97
	v_mul_f32_e32 v98, 0xbfb8aa3b, v98
	v_mul_f32_e32 v99, 0xbfb8aa3b, v99
	v_exp_f32_e32 v88, v88
	v_exp_f32_e32 v89, v89
	v_mul_f32_e32 v90, 0xbfb8aa3b, v90
	v_mul_f32_e32 v91, 0xbfb8aa3b, v91
	v_mul_f32_e32 v80, 0xbfb8aa3b, v80
	v_mul_f32_e32 v81, 0xbfb8aa3b, v81
	v_mul_f32_e32 v82, 0xbfb8aa3b, v82
	v_mul_f32_e32 v83, 0xbfb8aa3b, v83
	v_exp_f32_e32 v72, v72
	v_exp_f32_e32 v73, v73
	v_mul_f32_e32 v74, 0xbfb8aa3b, v74
	v_mul_f32_e32 v75, 0xbfb8aa3b, v75
	v_mul_f32_e32 v64, 0xbfb8aa3b, v64
	v_mul_f32_e32 v65, 0xbfb8aa3b, v65
	v_mul_f32_e32 v66, 0xbfb8aa3b, v66
	v_mul_f32_e32 v67, 0xbfb8aa3b, v67
	v_exp_f32_e32 v96, v96
	v_exp_f32_e32 v97, v97
	v_exp_f32_e32 v98, v98
	v_exp_f32_e32 v99, v99
	v_exp_f32_e32 v90, v90
	v_exp_f32_e32 v91, v91
	v_exp_f32_e32 v80, v80
	v_exp_f32_e32 v81, v81
	v_exp_f32_e32 v82, v82
	v_exp_f32_e32 v83, v83
	v_exp_f32_e32 v74, v74
	v_exp_f32_e32 v75, v75
	v_exp_f32_e32 v64, v64
	v_exp_f32_e32 v65, v65
	v_exp_f32_e32 v66, v66
	v_exp_f32_e32 v67, v67
	v_add_f32_e32 v107, 1.0, v213
	v_add_f32_e32 v104, 1.0, v106
	v_add_f32_e32 v105, 1.0, v105
	v_add_f32_e32 v88, 1.0, v88
	v_add_f32_e32 v89, 1.0, v89
	v_add_f32_e32 v72, 1.0, v72
	v_add_f32_e32 v73, 1.0, v73
	v_rcp_f32_e32 v125, v212
	v_rcp_f32_e32 v212, v214
	v_rcp_f32_e32 v104, v104
	v_rcp_f32_e32 v105, v105
	v_rcp_f32_e32 v213, v107
	v_add_f32_e32 v96, 1.0, v96
	v_add_f32_e32 v97, 1.0, v97
	v_add_f32_e32 v98, 1.0, v98
	v_add_f32_e32 v99, 1.0, v99
	v_rcp_f32_e32 v88, v88
	v_add_f32_e32 v90, 1.0, v90
	v_add_f32_e32 v91, 1.0, v91
	v_rcp_f32_e32 v89, v89
	v_add_f32_e32 v80, 1.0, v80
	v_add_f32_e32 v81, 1.0, v81
	v_add_f32_e32 v82, 1.0, v82
	v_add_f32_e32 v83, 1.0, v83
	v_rcp_f32_e32 v72, v72
	v_add_f32_e32 v74, 1.0, v74
	v_add_f32_e32 v75, 1.0, v75
	v_rcp_f32_e32 v73, v73
	v_add_f32_e32 v64, 1.0, v64
	v_add_f32_e32 v65, 1.0, v65
	v_add_f32_e32 v66, 1.0, v66
	v_add_f32_e32 v67, 1.0, v67
	v_rcp_f32_e32 v96, v96
	v_rcp_f32_e32 v97, v97
	v_rcp_f32_e32 v98, v98
	v_rcp_f32_e32 v99, v99
	v_rcp_f32_e32 v90, v90
	v_rcp_f32_e32 v91, v91
	v_rcp_f32_e32 v80, v80
	v_rcp_f32_e32 v81, v81
	v_rcp_f32_e32 v82, v82
	v_rcp_f32_e32 v83, v83
	v_rcp_f32_e32 v74, v74
	v_rcp_f32_e32 v75, v75
	v_rcp_f32_e32 v64, v64
	v_rcp_f32_e32 v66, v66
	v_rcp_f32_e32 v67, v67
	v_rcp_f32_e32 v65, v65
	v_pk_add_f32 v[106:107], v[110:111], v[138:139]
	v_pk_add_f32 v[92:93], v[92:93], v[136:137]
	v_pk_add_f32 v[76:77], v[76:77], v[136:137]
	v_pk_fma_f32 v[106:107], v[106:107], v[104:105], v[202:203]
	v_pk_fma_f32 v[104:105], v[108:109], v[212:213], v[200:201]
	v_lshl_add_u64 v[108:109], s[52:53], 0, v[208:209]
	v_pk_add_f32 v[102:103], v[102:103], v[130:131]
	v_pk_add_f32 v[100:101], v[100:101], v[128:129]
	v_pk_add_f32 v[94:95], v[94:95], v[138:139]
	v_pk_fma_f32 v[88:89], v[92:93], v[88:89], v[204:205]
	v_lshl_add_u64 v[92:93], s[52:53], 0, v[180:181]
	v_pk_add_f32 v[86:87], v[86:87], v[130:131]
	v_pk_add_f32 v[84:85], v[84:85], v[128:129]
	v_pk_add_f32 v[78:79], v[78:79], v[138:139]
; __device__ __forceinline__ float sigmoidf_(float x) { return __builtin_amdgcn_rcpf(1.0f + __expf(-x)); }
;     __device__ __forceinline__ void operator()(AccRef acc, const Unit& u, int wr, int wc, int fr, int fq) const {
;     ...
;         for (int ai = 0; ai < 2; ++ai) {
;             f32x4 xs[4][2];
; #pragma unroll
;             for (int m = 0; m < 4; ++m)
; #pragma unroll
;                 for (int n = 0; n < 2; ++n) xs[m][n] = *(const f32x4*)(x + (size_t)(row0 + ai * 128 + m * 16) * D + col0 + 4 * n);
; #pragma unroll
;             for (int m = 0; m < 4; ++m)
; #pragma unroll
;                 for (int n = 0; n < 2; ++n) { f32x4 xv = xs[m][n]; const f32x4 v = acc[ai][0][m][n] + bv[n], gt = acc[ai][1][m][n] + bg[n];
; #pragma unroll
;                     for (int j = 0; j < 4; ++j) xv[j] += v[j] * sigmoidf_(gt[j]);
;                     *(f32x4*)(x + (size_t)(row0 + ai * 128 + m * 16) * D + col0 + 4 * n) = xv; }
	v_pk_fma_f32 v[72:73], v[76:77], v[72:73], v[148:149]
	v_lshl_add_u64 v[76:77], s[52:53], 0, v[178:179]
	v_pk_add_f32 v[70:71], v[70:71], v[130:131]
	v_pk_add_f32 v[68:69], v[68:69], v[128:129]
	v_pk_add_f32 v[118:119], v[118:119], v[130:131]
	v_pk_add_f32 v[116:117], v[116:117], v[128:129]
	v_lshl_add_u64 v[108:109], v[108:109], 0, v[172:173]
	v_pk_fma_f32 v[98:99], v[102:103], v[98:99], v[198:199]
	v_pk_fma_f32 v[96:97], v[100:101], v[96:97], v[196:197]
	v_pk_fma_f32 v[90:91], v[94:95], v[90:91], v[206:207]
	v_lshl_add_u64 v[92:93], v[92:93], 0, v[172:173]
	v_pk_fma_f32 v[82:83], v[86:87], v[82:83], v[154:155]
	v_pk_fma_f32 v[80:81], v[84:85], v[80:81], v[152:153]
	v_pk_fma_f32 v[74:75], v[78:79], v[74:75], v[150:151]
	v_lshl_add_u64 v[76:77], v[76:77], 0, v[172:173]
	v_pk_fma_f32 v[66:67], v[70:71], v[66:67], v[146:147]
	v_pk_fma_f32 v[64:65], v[68:69], v[64:65], v[144:145]
	v_pk_fma_f32 v[118:119], v[118:119], v[126:127], v[194:195]
	v_pk_fma_f32 v[116:117], v[116:117], v[124:125], v[192:193]
	global_store_dwordx4 v[210:211], v[112:115], off
	global_store_dwordx4 v[210:211], v[116:119], off offset:16
	global_store_dwordx4 v[108:109], v[104:107], off
	global_store_dwordx4 v[108:109], v[96:99], off offset:16
	global_store_dwordx4 v[92:93], v[88:91], off
	global_store_dwordx4 v[92:93], v[80:83], off offset:16
	global_store_dwordx4 v[76:77], v[72:75], off
	global_store_dwordx4 v[76:77], v[64:67], off offset:16
	v_lshl_add_u64 v[98:99], v[176:177], 0, s[18:19]
	v_lshl_add_u64 v[100:101], v[176:177], 0, s[22:23]
	v_lshl_add_u64 v[64:65], v[174:175], 0, v[98:99]
	global_load_dwordx4 v[78:81], v[64:65], off
	global_load_dwordx4 v[82:85], v[64:65], off offset:16
	v_lshl_add_u64 v[64:65], v[174:175], 0, v[100:101]
	v_lshl_add_u64 v[102:103], v[176:177], 0, s[24:25]
	v_lshl_add_u64 v[76:77], v[176:177], 0, s[26:27]
	global_load_dwordx4 v[86:89], v[64:65], off offset:16
	global_load_dwordx4 v[90:93], v[64:65], off
	v_lshl_add_u64 v[64:65], v[174:175], 0, v[102:103]
	v_lshl_add_u64 v[68:69], v[174:175], 0, v[76:77]
	global_load_dwordx4 v[72:75], v[64:65], off offset:16
	global_load_dwordx4 v[94:97], v[64:65], off
	s_nop 0
	global_load_dwordx4 v[64:67], v[68:69], off offset:16
	s_nop 0
	global_load_dwordx4 v[68:71], v[68:69], off
	v_add_f32_e32 v56, v56, v140
	v_add_f32_e32 v57, v57, v141
	v_add_f32_e32 v40, v40, v140
	v_add_f32_e32 v41, v41, v141
	v_add_f32_e32 v24, v24, v140
	v_add_f32_e32 v25, v25, v141
	v_add_f32_e32 v8, v8, v140
	v_add_f32_e32 v9, v9, v141
	v_mul_f32_e32 v56, 0xbfb8aa3b, v56
	v_mul_f32_e32 v57, 0xbfb8aa3b, v57
	v_add_f32_e32 v58, v58, v142
	v_add_f32_e32 v59, v59, v143
	v_add_f32_e32 v48, v48, v132
	v_add_f32_e32 v49, v49, v133
	v_add_f32_e32 v50, v50, v134
	v_add_f32_e32 v51, v51, v135
	v_mul_f32_e32 v40, 0xbfb8aa3b, v40
	v_mul_f32_e32 v41, 0xbfb8aa3b, v41
	v_add_f32_e32 v42, v42, v142
	v_add_f32_e32 v43, v43, v143
	v_add_f32_e32 v32, v32, v132
	v_add_f32_e32 v33, v33, v133
	v_add_f32_e32 v34, v34, v134
	v_add_f32_e32 v35, v35, v135
	v_mul_f32_e32 v24, 0xbfb8aa3b, v24
	v_mul_f32_e32 v25, 0xbfb8aa3b, v25
	v_add_f32_e32 v26, v26, v142
	v_add_f32_e32 v27, v27, v143
	v_add_f32_e32 v16, v16, v132
	v_add_f32_e32 v17, v17, v133
	v_add_f32_e32 v18, v18, v134
	v_add_f32_e32 v19, v19, v135
	v_mul_f32_e32 v8, 0xbfb8aa3b, v8
	v_mul_f32_e32 v9, 0xbfb8aa3b, v9
	v_add_f32_e32 v10, v10, v142
	v_add_f32_e32 v11, v11, v143
	v_add_f32_e32 v0, v0, v132
	v_add_f32_e32 v1, v1, v133
	v_add_f32_e32 v2, v2, v134
	v_add_f32_e32 v3, v3, v135
	v_exp_f32_e32 v56, v56
	v_exp_f32_e32 v57, v57
	v_mul_f32_e32 v58, 0xbfb8aa3b, v58
	v_mul_f32_e32 v59, 0xbfb8aa3b, v59
	v_mul_f32_e32 v48, 0xbfb8aa3b, v48
	v_mul_f32_e32 v49, 0xbfb8aa3b, v49
	v_mul_f32_e32 v50, 0xbfb8aa3b, v50
	v_mul_f32_e32 v51, 0xbfb8aa3b, v51
	v_exp_f32_e32 v40, v40
	v_exp_f32_e32 v41, v41
	v_mul_f32_e32 v42, 0xbfb8aa3b, v42
	v_mul_f32_e32 v43, 0xbfb8aa3b, v43
	v_mul_f32_e32 v32, 0xbfb8aa3b, v32
	v_mul_f32_e32 v33, 0xbfb8aa3b, v33
	v_mul_f32_e32 v34, 0xbfb8aa3b, v34
	v_mul_f32_e32 v35, 0xbfb8aa3b, v35
	v_exp_f32_e32 v24, v24
	v_exp_f32_e32 v25, v25
	v_mul_f32_e32 v26, 0xbfb8aa3b, v26
	v_mul_f32_e32 v27, 0xbfb8aa3b, v27
	v_mul_f32_e32 v16, 0xbfb8aa3b, v16
	v_mul_f32_e32 v17, 0xbfb8aa3b, v17
	v_mul_f32_e32 v18, 0xbfb8aa3b, v18
	v_mul_f32_e32 v19, 0xbfb8aa3b, v19
	v_exp_f32_e32 v8, v8
	v_exp_f32_e32 v9, v9
	v_mul_f32_e32 v10, 0xbfb8aa3b, v10
	v_mul_f32_e32 v11, 0xbfb8aa3b, v11
	v_mul_f32_e32 v0, 0xbfb8aa3b, v0
	v_mul_f32_e32 v1, 0xbfb8aa3b, v1
	v_mul_f32_e32 v2, 0xbfb8aa3b, v2
	v_mul_f32_e32 v3, 0xbfb8aa3b, v3
	v_exp_f32_e32 v58, v58
	v_exp_f32_e32 v59, v59
	v_exp_f32_e32 v48, v48
	v_exp_f32_e32 v49, v49
	v_exp_f32_e32 v50, v50
	v_exp_f32_e32 v51, v51
	v_exp_f32_e32 v42, v42
	v_exp_f32_e32 v43, v43
	v_exp_f32_e32 v32, v32
	v_exp_f32_e32 v33, v33
	v_exp_f32_e32 v34, v34
	v_exp_f32_e32 v35, v35
	v_exp_f32_e32 v26, v26
	v_exp_f32_e32 v27, v27
	v_exp_f32_e32 v16, v16
	v_exp_f32_e32 v17, v17
	v_exp_f32_e32 v18, v18
	v_exp_f32_e32 v19, v19
	v_exp_f32_e32 v10, v10
	v_exp_f32_e32 v11, v11
	v_exp_f32_e32 v0, v0
	v_exp_f32_e32 v1, v1
	v_exp_f32_e32 v2, v2
	v_exp_f32_e32 v3, v3
	v_add_f32_e32 v56, 1.0, v56
	v_add_f32_e32 v57, 1.0, v57
	v_add_f32_e32 v40, 1.0, v40
	v_add_f32_e32 v41, 1.0, v41
	v_add_f32_e32 v24, 1.0, v24
	v_add_f32_e32 v25, 1.0, v25
	v_add_f32_e32 v8, 1.0, v8
	v_add_f32_e32 v9, 1.0, v9
	v_rcp_f32_e32 v56, v56
	v_rcp_f32_e32 v57, v57
	v_add_f32_e32 v58, 1.0, v58
	v_add_f32_e32 v59, 1.0, v59
	v_add_f32_e32 v48, 1.0, v48
	v_add_f32_e32 v49, 1.0, v49
	v_add_f32_e32 v50, 1.0, v50
	v_add_f32_e32 v51, 1.0, v51
	v_rcp_f32_e32 v40, v40
	v_rcp_f32_e32 v41, v41
	v_add_f32_e32 v42, 1.0, v42
	v_add_f32_e32 v43, 1.0, v43
	v_add_f32_e32 v32, 1.0, v32
	v_add_f32_e32 v33, 1.0, v33
	v_add_f32_e32 v34, 1.0, v34
	v_add_f32_e32 v35, 1.0, v35
	v_rcp_f32_e32 v24, v24
	v_rcp_f32_e32 v25, v25
	v_add_f32_e32 v26, 1.0, v26
	v_add_f32_e32 v27, 1.0, v27
	v_add_f32_e32 v16, 1.0, v16
	v_add_f32_e32 v17, 1.0, v17
	v_add_f32_e32 v18, 1.0, v18
	v_add_f32_e32 v19, 1.0, v19
	v_rcp_f32_e32 v8, v8
	v_rcp_f32_e32 v9, v9
	v_add_f32_e32 v10, 1.0, v10
	v_add_f32_e32 v11, 1.0, v11
	v_add_f32_e32 v0, 1.0, v0
	v_add_f32_e32 v1, 1.0, v1
	v_add_f32_e32 v2, 1.0, v2
	v_add_f32_e32 v3, 1.0, v3
	v_rcp_f32_e32 v58, v58
	v_rcp_f32_e32 v59, v59
	v_rcp_f32_e32 v48, v48
	v_rcp_f32_e32 v49, v49
	v_rcp_f32_e32 v50, v50
	v_rcp_f32_e32 v51, v51
	v_rcp_f32_e32 v42, v42
	v_rcp_f32_e32 v43, v43
	v_rcp_f32_e32 v32, v32
	v_rcp_f32_e32 v33, v33
	v_rcp_f32_e32 v34, v34
	v_rcp_f32_e32 v35, v35
	v_rcp_f32_e32 v26, v26
	v_rcp_f32_e32 v27, v27
	v_rcp_f32_e32 v16, v16
	v_rcp_f32_e32 v17, v17
	v_rcp_f32_e32 v18, v18
	v_rcp_f32_e32 v19, v19
	v_rcp_f32_e32 v10, v10
	v_rcp_f32_e32 v11, v11
	v_rcp_f32_e32 v0, v0
	v_rcp_f32_e32 v1, v1
	v_rcp_f32_e32 v2, v2
	v_rcp_f32_e32 v3, v3
	v_pk_add_f32 v[60:61], v[60:61], v[136:137]
	v_pk_add_f32 v[44:45], v[44:45], v[136:137]
	v_pk_add_f32 v[28:29], v[28:29], v[136:137]
	v_pk_add_f32 v[12:13], v[12:13], v[136:137]
	v_pk_add_f32 v[62:63], v[62:63], v[138:139]
	s_waitcnt vmcnt(0)
; __device__ __forceinline__ float sigmoidf_(float x) { return __builtin_amdgcn_rcpf(1.0f + __expf(-x)); }
; #define PG8_WAIT_V(n) asm volatile("s_waitcnt vmcnt(" #n ")" ::: "memory")
; #define PG8_BAR __builtin_amdgcn_s_barrier()
; template <class Epi>
; __device__ __forceinline__ void gemm_phase(LAS unsigned char* lds, const Gemm g, const StaticOrder& S, const Epi& E) {
;     ...
;         if (!has_next) break;
;         {
; #pragma unroll
;         for (int a = 0; a < 2; ++a)
; #pragma unroll
;             for (int b = 0; b < 2; ++b)
; #pragma unroll
;                 for (int m = 0; m < 4; ++m)
; #pragma unroll
;                     for (int n = 0; n < 2; ++n) acc[a][b][m][n] = (f32x4){0.f, 0.f, 0.f, 0.f};
;         }
;         cur = nxt; cA = nA; cB = nB; ++ui;
;     }
;     PG8_WAIT_V(0);
;     if (wr == 0) PG8_BAR;
;     PG8_BAR;
;     __device__ __forceinline__ void operator()(AccRef acc, const Unit& u, int wr, int wc, int fr, int fq) const {
;     ...
;                 for (int n = 0; n < 2; ++n) { f32x4 xv = xs[m][n]; const f32x4 v = acc[ai][0][m][n] + bv[n], gt = acc[ai][1][m][n] + bg[n];
; #pragma unroll
;                     for (int j = 0; j < 4; ++j) xv[j] += v[j] * sigmoidf_(gt[j]);
;                     *(f32x4*)(x + (size_t)(row0 + ai * 128 + m * 16) * D + col0 + 4 * n) = xv; }
	v_pk_fma_f32 v[56:57], v[60:61], v[56:57], v[78:79]
	v_lshl_add_u64 v[60:61], s[52:53], 0, v[98:99]
	v_pk_add_f32 v[54:55], v[54:55], v[130:131]
	v_pk_add_f32 v[52:53], v[52:53], v[128:129]
	v_pk_add_f32 v[46:47], v[46:47], v[138:139]
	v_pk_fma_f32 v[40:41], v[44:45], v[40:41], v[90:91]
	v_lshl_add_u64 v[44:45], s[52:53], 0, v[100:101]
	v_pk_add_f32 v[38:39], v[38:39], v[130:131]
	v_pk_add_f32 v[36:37], v[36:37], v[128:129]
	v_pk_add_f32 v[30:31], v[30:31], v[138:139]
	v_pk_fma_f32 v[24:25], v[28:29], v[24:25], v[94:95]
	v_lshl_add_u64 v[28:29], s[52:53], 0, v[102:103]
	v_pk_add_f32 v[22:23], v[22:23], v[130:131]
	v_pk_add_f32 v[20:21], v[20:21], v[128:129]
	v_pk_add_f32 v[14:15], v[14:15], v[138:139]
	v_pk_fma_f32 v[8:9], v[12:13], v[8:9], v[68:69]
	v_lshl_add_u64 v[12:13], s[52:53], 0, v[76:77]
	v_pk_add_f32 v[6:7], v[6:7], v[130:131]
	v_pk_add_f32 v[4:5], v[4:5], v[128:129]
	v_pk_fma_f32 v[58:59], v[62:63], v[58:59], v[80:81]
	v_lshl_add_u64 v[60:61], v[60:61], 0, v[172:173]
	v_pk_fma_f32 v[48:49], v[52:53], v[48:49], v[82:83]
	v_pk_fma_f32 v[50:51], v[54:55], v[50:51], v[84:85]
	v_pk_fma_f32 v[42:43], v[46:47], v[42:43], v[92:93]
	v_lshl_add_u64 v[44:45], v[44:45], 0, v[172:173]
	v_pk_fma_f32 v[32:33], v[36:37], v[32:33], v[86:87]
	v_pk_fma_f32 v[34:35], v[38:39], v[34:35], v[88:89]
	v_pk_fma_f32 v[26:27], v[30:31], v[26:27], v[96:97]
	v_lshl_add_u64 v[28:29], v[28:29], 0, v[172:173]
	v_pk_fma_f32 v[16:17], v[20:21], v[16:17], v[72:73]
	v_pk_fma_f32 v[18:19], v[22:23], v[18:19], v[74:75]
	v_pk_fma_f32 v[10:11], v[14:15], v[10:11], v[70:71]
	v_lshl_add_u64 v[12:13], v[12:13], 0, v[172:173]
	v_pk_fma_f32 v[0:1], v[4:5], v[0:1], v[64:65]
	v_pk_fma_f32 v[2:3], v[6:7], v[2:3], v[66:67]
	global_store_dwordx4 v[60:61], v[56:59], off
	global_store_dwordx4 v[60:61], v[48:51], off offset:16
	global_store_dwordx4 v[44:45], v[40:43], off
	global_store_dwordx4 v[44:45], v[32:35], off offset:16
	global_store_dwordx4 v[28:29], v[24:27], off
	global_store_dwordx4 v[28:29], v[16:19], off offset:16
	global_store_dwordx4 v[12:13], v[8:11], off
	global_store_dwordx4 v[12:13], v[0:3], off offset:16
	s_cbranch_vccz .LBB0_631
	s_waitcnt vmcnt(0)
	s_cmpk_gt_u32 s4, 0xff
	s_cbranch_scc1 .LBB0_642
	s_barrier

; #define PG8_STAGE(bufoff, gbase, voff) do { _Pragma("unroll") for (int _i = 0; _i < 2; ++_i) \
;         __builtin_amdgcn_global_load_lds((const unsigned*)((const char*)(gbase) + (voff)[_i]), (LAS unsigned*)(lds + (bufoff) + ldsw + _i * 8192), 16, 0, 0); } while (0)
; #define PG8_LDA(dst, b, h) do { _Pragma("unroll") for (int m = 0; m < 4; ++m) _Pragma("unroll") for (int k = 0; k < 2; ++k) dst[m][k] = *(const LAS bf16x8*)(lds + PG8_SA(b, h) + aoff + m * 2048 + k * 1024); } while (0)
; #define PG8_LDB(dst, b, h) do { _Pragma("unroll") for (int n = 0; n < 2; ++n) _Pragma("unroll") for (int k = 0; k < 2; ++k) dst[n][k] = *(const LAS bf16x8*)(lds + PG8_SB(b, h) + boff + n * 2048 + k * 1024); } while (0)
; #define PG8_MMA(ai, bj, At, Bt) do { __builtin_amdgcn_s_setprio(1); _Pragma("unroll") for (int m = 0; m < 4; ++m) _Pragma("unroll") for (int n = 0; n < 2; ++n) _Pragma("unroll") for (int k = 0; k < 2; ++k) \
;         acc[ai][bj][m][n] = __builtin_amdgcn_mfma_f32_16x16x32_bf16(Bt[n][k], At[m][k], acc[ai][bj][m][n], 0, 0, 0); __builtin_amdgcn_s_setprio(0); } while (0)
; #define PG8_WAIT_V(n) asm volatile("s_waitcnt vmcnt(" #n ")" ::: "memory")
; #define PG8_WAIT_L(n) asm volatile("s_waitcnt lgkmcnt(" #n ")" ::: "memory")
; #define PG8_BAR __builtin_amdgcn_s_barrier()
; #define PG8_SCHED __builtin_amdgcn_sched_barrier(0)
; template <class Epi>
; __device__ __forceinline__ void gemm_phase(LAS unsigned char* lds, const Gemm g, const StaticOrder& S, const Epi& E) {
;     ...
;             PG8_LDB(B0, 0, 0); PG8_SCHED; PG8_LDA(At, 0, 0); PG8_STAGE(PG8_SA(1, 1), a1 + hstepA, voffA);
;             PG8_WAIT_L(8); PG8_BAR; PG8_WAIT_L(0); PG8_MMA(0, 0, At, B0); PG8_BAR; PG8_SCHED;
;             PG8_LDB(B1, 0, 1); PG8_STAGE(PG8_SB(0, 0), b2, voffB);
;             PG8_BAR; PG8_WAIT_L(0); PG8_MMA(0, 1, At, B1); PG8_BAR;
;             PG8_LDA(At, 0, 1); PG8_STAGE(PG8_SA(0, 0), a2, voffA);
;             PG8_BAR; PG8_WAIT_L(0); PG8_MMA(1, 0, At, B0); PG8_BAR; PG8_SCHED;
;             PG8_STAGE(PG8_SB(0, 1), b2 + hstepB, voffB);
;             PG8_WAIT_V(6); PG8_BAR; PG8_MMA(1, 1, At, B1); PG8_BAR;
.LBB0_860:
	ds_read_b128 v[140:143], v149
	ds_read_b128 v[152:155], v149 offset:1024
	ds_read_b128 v[156:159], v149 offset:2048
	ds_read_b128 v[160:163], v149 offset:3072
	s_add_u32 s30, s28, 0x100
	s_addc_u32 s31, s29, 0
	s_cmp_eq_u32 s68, 40
	s_cselect_b32 s37, s13, s31
	s_cselect_b32 s36, s12, s30
	s_cselect_b32 s35, s15, s63
	s_cselect_b32 s34, s14, s49
	v_lshl_add_u64 v[144:145], s[28:29], 0, v[132:133]
	s_add_i32 m0, s8, 0xc000
	ds_read_b128 v[164:167], v150
	ds_read_b128 v[168:171], v150 offset:1024
	ds_read_b128 v[172:175], v150 offset:2048
	ds_read_b128 v[176:179], v150 offset:3072
	ds_read_b128 v[180:183], v150 offset:4096
	ds_read_b128 v[184:187], v150 offset:5120
	ds_read_b128 v[188:191], v150 offset:6144
	ds_read_b128 v[192:195], v150 offset:7168
	global_load_lds_dwordx4 v[144:145], off
	v_lshl_add_u64 v[144:145], s[28:29], 0, v[134:135]
	s_add_i32 m0, s8, 0xe000
	s_nop 0
	global_load_lds_dwordx4 v[144:145], off
	ds_read_b128 v[196:199], v151
	ds_read_b128 v[200:203], v151 offset:1024
	ds_read_b128 v[204:207], v151 offset:2048
	ds_read_b128 v[208:211], v151 offset:3072
	s_waitcnt lgkmcnt(0)
	s_barrier
	s_setprio 1
	v_mfma_f32_16x16x32_bf16 v[124:127], v[140:143], v[164:167], v[124:127]
	v_mfma_f32_16x16x32_bf16 v[120:123], v[156:159], v[164:167], v[120:123]
	v_mfma_f32_16x16x32_bf16 v[112:115], v[140:143], v[172:175], v[112:115]
	v_mfma_f32_16x16x32_bf16 v[104:107], v[156:159], v[172:175], v[104:107]
	v_mfma_f32_16x16x32_bf16 v[92:95], v[140:143], v[180:183], v[92:95]
	v_mfma_f32_16x16x32_bf16 v[88:91], v[156:159], v[180:183], v[88:91]
	v_mfma_f32_16x16x32_bf16 v[80:83], v[140:143], v[188:191], v[80:83]
	v_mfma_f32_16x16x32_bf16 v[72:75], v[156:159], v[188:191], v[72:75]
	v_mfma_f32_16x16x32_bf16 v[124:127], v[152:155], v[168:171], v[124:127]
	v_mfma_f32_16x16x32_bf16 v[120:123], v[160:163], v[168:171], v[120:123]
	v_mfma_f32_16x16x32_bf16 v[112:115], v[152:155], v[176:179], v[112:115]
	v_mfma_f32_16x16x32_bf16 v[104:107], v[160:163], v[176:179], v[104:107]
	v_mfma_f32_16x16x32_bf16 v[92:95], v[152:155], v[184:187], v[92:95]
	v_mfma_f32_16x16x32_bf16 v[88:91], v[160:163], v[184:187], v[88:91]
	v_mfma_f32_16x16x32_bf16 v[80:83], v[152:155], v[192:195], v[80:83]
	v_mfma_f32_16x16x32_bf16 v[72:75], v[160:163], v[192:195], v[72:75]
	v_mfma_f32_16x16x32_bf16 v[116:119], v[196:199], v[164:167], v[116:119]
	v_mfma_f32_16x16x32_bf16 v[108:111], v[204:207], v[164:167], v[108:111]
	v_mfma_f32_16x16x32_bf16 v[100:103], v[196:199], v[172:175], v[100:103]
	v_mfma_f32_16x16x32_bf16 v[96:99], v[204:207], v[172:175], v[96:99]
	v_mfma_f32_16x16x32_bf16 v[84:87], v[196:199], v[180:183], v[84:87]
	v_mfma_f32_16x16x32_bf16 v[76:79], v[204:207], v[180:183], v[76:79]
	v_mfma_f32_16x16x32_bf16 v[68:71], v[196:199], v[188:191], v[68:71]
	v_mfma_f32_16x16x32_bf16 v[64:67], v[204:207], v[188:191], v[64:67]
	v_mfma_f32_16x16x32_bf16 v[116:119], v[200:203], v[168:171], v[116:119]
	v_mfma_f32_16x16x32_bf16 v[108:111], v[208:211], v[168:171], v[108:111]
	v_mfma_f32_16x16x32_bf16 v[100:103], v[200:203], v[176:179], v[100:103]
	v_mfma_f32_16x16x32_bf16 v[96:99], v[208:211], v[176:179], v[96:99]
	v_mfma_f32_16x16x32_bf16 v[84:87], v[200:203], v[184:187], v[84:87]
	v_mfma_f32_16x16x32_bf16 v[76:79], v[208:211], v[184:187], v[76:79]
	v_mfma_f32_16x16x32_bf16 v[68:71], v[200:203], v[192:195], v[68:71]
	v_mfma_f32_16x16x32_bf16 v[64:67], v[208:211], v[192:195], v[64:67]
	s_setprio 0
	s_barrier
	s_nop 1
	ds_read_b128 v[164:167], v150 offset:16384
	ds_read_b128 v[168:171], v150 offset:17408
	ds_read_b128 v[172:175], v150 offset:18432
	ds_read_b128 v[176:179], v150 offset:19456
	ds_read_b128 v[180:183], v150 offset:20480
	ds_read_b128 v[184:187], v150 offset:21504
	ds_read_b128 v[188:191], v150 offset:22528
	ds_read_b128 v[192:195], v150 offset:23552
	s_add_i32 s28, s43, s7
	v_lshl_add_u64 v[144:145], s[34:35], 0, v[128:129]
	s_mov_b32 m0, s28
	s_nop 0
	global_load_lds_dwordx4 v[144:145], off
	v_lshl_add_u64 v[212:213], s[34:35], 0, v[130:131]
	s_add_i32 m0, s28, 0x2000
	s_nop 0
	global_load_lds_dwordx4 v[212:213], off
	s_mov_b32 m0, s8
	v_lshl_add_u64 v[214:215], s[36:37], 0, v[128:129]
	global_load_lds_dwordx4 v[214:215], off
	v_lshl_add_u64 v[216:217], s[36:37], 0, v[130:131]
	s_mov_b32 m0, s9
	s_nop 0
	global_load_lds_dwordx4 v[216:217], off
	s_add_u32 s28, s34, 0xb0000
	s_addc_u32 s29, s35, 0
	s_add_i32 s69, s44, s7
	v_lshl_add_u64 v[254:255], s[28:29], 0, v[128:129]
	s_mov_b32 m0, s69
	s_nop 0
	global_load_lds_dwordx4 v[254:255], off
	v_lshl_add_u64 v[254:255], s[28:29], 0, v[130:131]
	s_add_i32 m0, s69, 0x2000
	s_nop 0
	global_load_lds_dwordx4 v[254:255], off
	s_waitcnt vmcnt(6)
	s_waitcnt lgkmcnt(0)
	s_barrier
; #define PG8_STAGE(bufoff, gbase, voff) do { _Pragma("unroll") for (int _i = 0; _i < 2; ++_i) \
;         __builtin_amdgcn_global_load_lds((const unsigned*)((const char*)(gbase) + (voff)[_i]), (LAS unsigned*)(lds + (bufoff) + ldsw + _i * 8192), 16, 0, 0); } while (0)
; #define PG8_LDA(dst, b, h) do { _Pragma("unroll") for (int m = 0; m < 4; ++m) _Pragma("unroll") for (int k = 0; k < 2; ++k) dst[m][k] = *(const LAS bf16x8*)(lds + PG8_SA(b, h) + aoff + m * 2048 + k * 1024); } while (0)
; #define PG8_LDB(dst, b, h) do { _Pragma("unroll") for (int n = 0; n < 2; ++n) _Pragma("unroll") for (int k = 0; k < 2; ++k) dst[n][k] = *(const LAS bf16x8*)(lds + PG8_SB(b, h) + boff + n * 2048 + k * 1024); } while (0)
; #define PG8_MMA(ai, bj, At, Bt) do { __builtin_amdgcn_s_setprio(1); _Pragma("unroll") for (int m = 0; m < 4; ++m) _Pragma("unroll") for (int n = 0; n < 2; ++n) _Pragma("unroll") for (int k = 0; k < 2; ++k) \
;         acc[ai][bj][m][n] = __builtin_amdgcn_mfma_f32_16x16x32_bf16(Bt[n][k], At[m][k], acc[ai][bj][m][n], 0, 0, 0); __builtin_amdgcn_s_setprio(0); } while (0)
; #define PG8_WAIT_V(n) asm volatile("s_waitcnt vmcnt(" #n ")" ::: "memory")
; #define PG8_WAIT_L(n) asm volatile("s_waitcnt lgkmcnt(" #n ")" ::: "memory")
; #define PG8_BAR __builtin_amdgcn_s_barrier()
; #define PG8_SCHED __builtin_amdgcn_sched_barrier(0)
; template <class Epi>
; __device__ __forceinline__ void gemm_phase(LAS unsigned char* lds, const Gemm g, const StaticOrder& S, const Epi& E) {
;     ...
;             PG8_WAIT_V(6); PG8_BAR; PG8_MMA(1, 1, At, B1); PG8_BAR;
;             PG8_LDB(B0, 1, 0); PG8_SCHED; PG8_LDA(At, 1, 0); PG8_STAGE(PG8_SA(0, 1), a2 + hstepA, voffA);
;             PG8_WAIT_L(8); PG8_BAR; PG8_WAIT_L(0); PG8_MMA(0, 0, At, B0); PG8_BAR; PG8_SCHED;
;             PG8_LDB(B1, 1, 1); PG8_STAGE(PG8_SB(1, 0), b3, voffB);
;             PG8_BAR; PG8_WAIT_L(0); PG8_MMA(0, 1, At, B1); PG8_BAR;
;             PG8_LDA(At, 1, 1); PG8_STAGE(PG8_SA(1, 0), a3, voffA);
;             PG8_BAR; PG8_WAIT_L(0); PG8_MMA(1, 0, At, B0); PG8_BAR; PG8_SCHED;
	s_setprio 1
	v_mfma_f32_16x16x32_bf16 v[60:63], v[140:143], v[164:167], v[60:63]
	v_mfma_f32_16x16x32_bf16 v[56:59], v[156:159], v[164:167], v[56:59]
	v_mfma_f32_16x16x32_bf16 v[48:51], v[140:143], v[172:175], v[48:51]
	v_mfma_f32_16x16x32_bf16 v[40:43], v[156:159], v[172:175], v[40:43]
	v_mfma_f32_16x16x32_bf16 v[28:31], v[140:143], v[180:183], v[28:31]
	v_mfma_f32_16x16x32_bf16 v[24:27], v[156:159], v[180:183], v[24:27]
	v_mfma_f32_16x16x32_bf16 v[16:19], v[140:143], v[188:191], v[16:19]
	v_mfma_f32_16x16x32_bf16 v[8:11], v[156:159], v[188:191], v[8:11]
	v_mfma_f32_16x16x32_bf16 v[60:63], v[152:155], v[168:171], v[60:63]
	v_mfma_f32_16x16x32_bf16 v[56:59], v[160:163], v[168:171], v[56:59]
	v_mfma_f32_16x16x32_bf16 v[48:51], v[152:155], v[176:179], v[48:51]
	v_mfma_f32_16x16x32_bf16 v[40:43], v[160:163], v[176:179], v[40:43]
	v_mfma_f32_16x16x32_bf16 v[28:31], v[152:155], v[184:187], v[28:31]
	v_mfma_f32_16x16x32_bf16 v[24:27], v[160:163], v[184:187], v[24:27]
	v_mfma_f32_16x16x32_bf16 v[16:19], v[152:155], v[192:195], v[16:19]
	v_mfma_f32_16x16x32_bf16 v[8:11], v[160:163], v[192:195], v[8:11]
	v_mfma_f32_16x16x32_bf16 v[52:55], v[196:199], v[164:167], v[52:55]
	v_mfma_f32_16x16x32_bf16 v[44:47], v[204:207], v[164:167], v[44:47]
	v_mfma_f32_16x16x32_bf16 v[36:39], v[196:199], v[172:175], v[36:39]
	v_mfma_f32_16x16x32_bf16 v[32:35], v[204:207], v[172:175], v[32:35]
	v_mfma_f32_16x16x32_bf16 v[20:23], v[196:199], v[180:183], v[20:23]
	v_mfma_f32_16x16x32_bf16 v[12:15], v[204:207], v[180:183], v[12:15]
	v_mfma_f32_16x16x32_bf16 v[4:7], v[196:199], v[188:191], v[4:7]
	v_mfma_f32_16x16x32_bf16 v[0:3], v[204:207], v[188:191], v[0:3]
	v_mfma_f32_16x16x32_bf16 v[52:55], v[200:203], v[168:171], v[52:55]
	v_mfma_f32_16x16x32_bf16 v[44:47], v[208:211], v[168:171], v[44:47]
	v_mfma_f32_16x16x32_bf16 v[36:39], v[200:203], v[176:179], v[36:39]
	v_mfma_f32_16x16x32_bf16 v[32:35], v[208:211], v[176:179], v[32:35]
	v_mfma_f32_16x16x32_bf16 v[20:23], v[200:203], v[184:187], v[20:23]
	v_mfma_f32_16x16x32_bf16 v[12:15], v[208:211], v[184:187], v[12:15]
	v_mfma_f32_16x16x32_bf16 v[4:7], v[200:203], v[192:195], v[4:7]
	v_mfma_f32_16x16x32_bf16 v[0:3], v[208:211], v[192:195], v[0:3]
	s_setprio 0
	s_add_i32 s69, 0, 0x18000
	v_add_u32_e32 v160, s69, v147
	s_barrier
	ds_read_b128 v[140:143], v160
	ds_read_b128 v[152:155], v160 offset:1024
	ds_read_b128 v[156:159], v160 offset:2048
	ds_read_b128 v[160:163], v160 offset:3072
	s_add_u32 s28, s36, 0xb0000
	s_addc_u32 s29, s37, 0
	s_mov_b32 m0, s38
	v_lshl_add_u64 v[196:197], s[28:29], 0, v[128:129]
	ds_read_b128 v[164:167], v150 offset:32768
	ds_read_b128 v[168:171], v150 offset:33792
	ds_read_b128 v[172:175], v150 offset:34816
	ds_read_b128 v[176:179], v150 offset:35840
	ds_read_b128 v[180:183], v150 offset:36864
	ds_read_b128 v[184:187], v150 offset:37888
	ds_read_b128 v[188:191], v150 offset:38912
	ds_read_b128 v[192:195], v150 offset:39936
	global_load_lds_dwordx4 v[196:197], off
	v_lshl_add_u64 v[196:197], s[28:29], 0, v[130:131]
	s_mov_b32 m0, s39
	s_nop 0
	global_load_lds_dwordx4 v[196:197], off
	s_add_i32 s36, 0, 0x1c000
	v_add_u32_e32 v208, s36, v147
	ds_read_b128 v[196:199], v208
	ds_read_b128 v[200:203], v208 offset:1024
	ds_read_b128 v[204:207], v208 offset:2048
	ds_read_b128 v[208:211], v208 offset:3072
	s_waitcnt lgkmcnt(0)
	s_barrier
	s_setprio 1
	v_mfma_f32_16x16x32_bf16 v[124:127], v[140:143], v[164:167], v[124:127]
	v_mfma_f32_16x16x32_bf16 v[120:123], v[156:159], v[164:167], v[120:123]
	v_mfma_f32_16x16x32_bf16 v[112:115], v[140:143], v[172:175], v[112:115]
	v_mfma_f32_16x16x32_bf16 v[104:107], v[156:159], v[172:175], v[104:107]
	v_mfma_f32_16x16x32_bf16 v[92:95], v[140:143], v[180:183], v[92:95]
	v_mfma_f32_16x16x32_bf16 v[88:91], v[156:159], v[180:183], v[88:91]
	v_mfma_f32_16x16x32_bf16 v[80:83], v[140:143], v[188:191], v[80:83]
	v_mfma_f32_16x16x32_bf16 v[72:75], v[156:159], v[188:191], v[72:75]
	v_mfma_f32_16x16x32_bf16 v[124:127], v[152:155], v[168:171], v[124:127]
	v_mfma_f32_16x16x32_bf16 v[120:123], v[160:163], v[168:171], v[120:123]
	v_mfma_f32_16x16x32_bf16 v[112:115], v[152:155], v[176:179], v[112:115]
	v_mfma_f32_16x16x32_bf16 v[104:107], v[160:163], v[176:179], v[104:107]
	v_mfma_f32_16x16x32_bf16 v[92:95], v[152:155], v[184:187], v[92:95]
	v_mfma_f32_16x16x32_bf16 v[88:91], v[160:163], v[184:187], v[88:91]
	v_mfma_f32_16x16x32_bf16 v[80:83], v[152:155], v[192:195], v[80:83]
	v_mfma_f32_16x16x32_bf16 v[72:75], v[160:163], v[192:195], v[72:75]
	v_mfma_f32_16x16x32_bf16 v[116:119], v[196:199], v[164:167], v[116:119]
	v_mfma_f32_16x16x32_bf16 v[108:111], v[204:207], v[164:167], v[108:111]
	v_mfma_f32_16x16x32_bf16 v[100:103], v[196:199], v[172:175], v[100:103]
	v_mfma_f32_16x16x32_bf16 v[96:99], v[204:207], v[172:175], v[96:99]
	v_mfma_f32_16x16x32_bf16 v[84:87], v[196:199], v[180:183], v[84:87]
	v_mfma_f32_16x16x32_bf16 v[76:79], v[204:207], v[180:183], v[76:79]
	v_mfma_f32_16x16x32_bf16 v[68:71], v[196:199], v[188:191], v[68:71]
	v_mfma_f32_16x16x32_bf16 v[64:67], v[204:207], v[188:191], v[64:67]
	v_mfma_f32_16x16x32_bf16 v[116:119], v[200:203], v[168:171], v[116:119]
	v_mfma_f32_16x16x32_bf16 v[108:111], v[208:211], v[168:171], v[108:111]
	v_mfma_f32_16x16x32_bf16 v[100:103], v[200:203], v[176:179], v[100:103]
	v_mfma_f32_16x16x32_bf16 v[96:99], v[208:211], v[176:179], v[96:99]
	v_mfma_f32_16x16x32_bf16 v[84:87], v[200:203], v[184:187], v[84:87]
	v_mfma_f32_16x16x32_bf16 v[76:79], v[208:211], v[184:187], v[76:79]
	v_mfma_f32_16x16x32_bf16 v[68:71], v[200:203], v[192:195], v[68:71]
	v_mfma_f32_16x16x32_bf16 v[64:67], v[208:211], v[192:195], v[64:67]
	s_setprio 0
	s_barrier
; #define PG8_STAGE(bufoff, gbase, voff) do { _Pragma("unroll") for (int _i = 0; _i < 2; ++_i) \
;         __builtin_amdgcn_global_load_lds((const unsigned*)((const char*)(gbase) + (voff)[_i]), (LAS unsigned*)(lds + (bufoff) + ldsw + _i * 8192), 16, 0, 0); } while (0)
; #define PG8_LDA(dst, b, h) do { _Pragma("unroll") for (int m = 0; m < 4; ++m) _Pragma("unroll") for (int k = 0; k < 2; ++k) dst[m][k] = *(const LAS bf16x8*)(lds + PG8_SA(b, h) + aoff + m * 2048 + k * 1024); } while (0)
; #define PG8_LDB(dst, b, h) do { _Pragma("unroll") for (int n = 0; n < 2; ++n) _Pragma("unroll") for (int k = 0; k < 2; ++k) dst[n][k] = *(const LAS bf16x8*)(lds + PG8_SB(b, h) + boff + n * 2048 + k * 1024); } while (0)
; template <class Epi>
; __device__ __forceinline__ void gemm_phase(LAS unsigned char* lds, const Gemm g, const StaticOrder& S, const Epi& E) {
;     ...
;             PG8_LDB(B1, 1, 1); PG8_STAGE(PG8_SB(1, 0), b3, voffB);
;             PG8_BAR; PG8_WAIT_L(0); PG8_MMA(0, 1, At, B1); PG8_BAR;
;             PG8_LDA(At, 1, 1); PG8_STAGE(PG8_SA(1, 0), a3, voffA);
;             PG8_BAR; PG8_WAIT_L(0); PG8_MMA(1, 0, At, B0); PG8_BAR; PG8_SCHED;
;             PG8_STAGE(PG8_SB(1, 1), b3 + hstepB, voffB);
;             PG8_WAIT_V(6); PG8_BAR; PG8_MMA(1, 1, At, B1); PG8_BAR;
;     __device__ __forceinline__ void operator()(AccRef acc, const Unit& u, int wr, int wc, int fr, int fq) const {
;         const int row0 = u.pm * 256 + wr * 64 + fr, col0 = u.pn * 256 + wc * 32 + 4 * fq;
;         f32x4 sv[2][2], bv[2][2];
; #pragma unroll
;         for (int bj = 0; bj < 2; ++bj)
; #pragma unroll
;             for (int n = 0; n < 2; ++n) {
;                 sv[bj][n] = scale ? *(const f32x4*)(scale + col0 + bj * 128 + n * 16) : (f32x4){1.f, 1.f, 1.f, 1.f};
;                 bv[bj][n] = bias ? *(const f32x4*)(bias + col0 + bj * 128 + n * 16) : (f32x4){0.f, 0.f, 0.f, 0.f}; }
; #pragma unroll
;         for (int ai = 0; ai < 2; ++ai)
; #pragma unroll
;             for (int mh = 0; mh < 2; ++mh) {
;                 f32x4 bs[2][2][2];
; #pragma unroll
;                 for (int m = 0; m < 2; ++m)
; #pragma unroll
;                     for (int bj = 0; bj < 2; ++bj)
; #pragma unroll
;                         for (int n = 0; n < 2; ++n) bs[m][bj][n] = *(const f32x4*)(base + (size_t)(row0 + ai * 128 + (2 * mh + m) * 16) * D + col0 + bj * 128 + n * 16);
	s_nop 1
	ds_read_b128 v[164:167], v150 offset:49152
	ds_read_b128 v[168:171], v150 offset:50176
	ds_read_b128 v[172:175], v150 offset:51200
	ds_read_b128 v[176:179], v150 offset:52224
	ds_read_b128 v[180:183], v150 offset:53248
	ds_read_b128 v[184:187], v150 offset:54272
	ds_read_b128 v[188:191], v150 offset:55296
	ds_read_b128 v[192:195], v150 offset:56320
	s_add_i32 s28, s69, s7
	v_lshl_add_u64 v[254:255], v[144:145], 0, s[20:21]
	s_mov_b32 m0, s28
	s_nop 0
	global_load_lds_dwordx4 v[254:255], off
	v_lshl_add_u64 v[254:255], v[212:213], 0, s[20:21]
	s_add_i32 m0, s28, 0x2000
	s_nop 0
	global_load_lds_dwordx4 v[254:255], off
	s_mov_b32 m0, s41
	v_lshl_add_u64 v[254:255], v[214:215], 0, s[20:21]
	global_load_lds_dwordx4 v[254:255], off
	v_lshl_add_u64 v[144:145], v[216:217], 0, s[20:21]
	s_mov_b32 m0, s42
	s_nop 0
	global_load_lds_dwordx4 v[144:145], off
	s_add_u32 s28, s34, 0xb0080
	s_addc_u32 s29, s35, 0
	s_add_i32 s34, s36, s7
	v_lshl_add_u64 v[254:255], s[28:29], 0, v[128:129]
	s_mov_b32 m0, s34
	s_nop 0
	global_load_lds_dwordx4 v[254:255], off
	v_lshl_add_u64 v[254:255], s[28:29], 0, v[130:131]
	s_add_i32 m0, s34, 0x2000
	s_nop 0
	global_load_lds_dwordx4 v[254:255], off
	s_waitcnt vmcnt(6)
	s_waitcnt lgkmcnt(0)
	s_barrier
	s_setprio 1
	v_mfma_f32_16x16x32_bf16 v[60:63], v[140:143], v[164:167], v[60:63]
	v_mfma_f32_16x16x32_bf16 v[56:59], v[156:159], v[164:167], v[56:59]
	v_mfma_f32_16x16x32_bf16 v[48:51], v[140:143], v[172:175], v[48:51]
	v_mfma_f32_16x16x32_bf16 v[40:43], v[156:159], v[172:175], v[40:43]
	v_mfma_f32_16x16x32_bf16 v[28:31], v[140:143], v[180:183], v[28:31]
	v_mfma_f32_16x16x32_bf16 v[24:27], v[156:159], v[180:183], v[24:27]
	v_mfma_f32_16x16x32_bf16 v[16:19], v[140:143], v[188:191], v[16:19]
	v_mfma_f32_16x16x32_bf16 v[8:11], v[156:159], v[188:191], v[8:11]
	v_mfma_f32_16x16x32_bf16 v[60:63], v[152:155], v[168:171], v[60:63]
	v_mfma_f32_16x16x32_bf16 v[56:59], v[160:163], v[168:171], v[56:59]
	v_mfma_f32_16x16x32_bf16 v[48:51], v[152:155], v[176:179], v[48:51]
	v_mfma_f32_16x16x32_bf16 v[40:43], v[160:163], v[176:179], v[40:43]
	v_mfma_f32_16x16x32_bf16 v[28:31], v[152:155], v[184:187], v[28:31]
	v_mfma_f32_16x16x32_bf16 v[24:27], v[160:163], v[184:187], v[24:27]
	v_mfma_f32_16x16x32_bf16 v[16:19], v[152:155], v[192:195], v[16:19]
	v_mfma_f32_16x16x32_bf16 v[8:11], v[160:163], v[192:195], v[8:11]
	v_mfma_f32_16x16x32_bf16 v[52:55], v[196:199], v[164:167], v[52:55]
	v_mfma_f32_16x16x32_bf16 v[44:47], v[204:207], v[164:167], v[44:47]
	v_mfma_f32_16x16x32_bf16 v[36:39], v[196:199], v[172:175], v[36:39]
	v_mfma_f32_16x16x32_bf16 v[32:35], v[204:207], v[172:175], v[32:35]
	v_mfma_f32_16x16x32_bf16 v[20:23], v[196:199], v[180:183], v[20:23]
	v_mfma_f32_16x16x32_bf16 v[12:15], v[204:207], v[180:183], v[12:15]
	v_mfma_f32_16x16x32_bf16 v[4:7], v[196:199], v[188:191], v[4:7]
	v_mfma_f32_16x16x32_bf16 v[0:3], v[204:207], v[188:191], v[0:3]
	v_mfma_f32_16x16x32_bf16 v[52:55], v[200:203], v[168:171], v[52:55]
	v_mfma_f32_16x16x32_bf16 v[44:47], v[208:211], v[168:171], v[44:47]
	v_mfma_f32_16x16x32_bf16 v[36:39], v[200:203], v[176:179], v[36:39]
	v_mfma_f32_16x16x32_bf16 v[32:35], v[208:211], v[176:179], v[32:35]
	v_mfma_f32_16x16x32_bf16 v[20:23], v[200:203], v[184:187], v[20:23]
	v_mfma_f32_16x16x32_bf16 v[12:15], v[208:211], v[184:187], v[12:15]
	v_mfma_f32_16x16x32_bf16 v[4:7], v[200:203], v[192:195], v[4:7]
	v_mfma_f32_16x16x32_bf16 v[0:3], v[208:211], v[192:195], v[0:3]
	s_setprio 0
	s_add_i32 s68, s68, 2
	s_add_u32 s49, s49, 0x100
	s_addc_u32 s63, s63, 0
	s_cmp_gt_u32 s68, 41
	s_mov_b64 s[28:29], s[30:31]
	s_barrier
	s_cbranch_scc0 .LBB0_860
	v_lshl_or_b32 v140, s47, 8, v148
	v_ashrrev_i32_e32 v141, 31, v140
	v_lshl_add_u32 v184, s48, 8, v146
	v_lshlrev_b64 v[140:141], 2, v[140:141]
	v_ashrrev_i32_e32 v185, 31, v184
	v_or_b32_e32 v168, 16, v184
	v_lshl_add_u64 v[142:143], s[52:53], 0, v[140:141]
	v_lshlrev_b64 v[144:145], 12, v[184:185]
	v_ashrrev_i32_e32 v169, 31, v168
	v_lshl_add_u64 v[164:165], v[142:143], 0, v[144:145]
	v_lshlrev_b64 v[186:187], 12, v[168:169]
	global_load_dwordx4 v[152:155], v[164:165], off
	global_load_dwordx4 v[156:159], v[164:165], off offset:64
	global_load_dwordx4 v[160:163], v[164:165], off offset:512
	s_nop 0
	global_load_dwordx4 v[164:167], v[164:165], off offset:576
	v_lshl_add_u64 v[180:181], v[142:143], 0, v[186:187]
	global_load_dwordx4 v[168:171], v[180:181], off
	global_load_dwordx4 v[172:175], v[180:181], off offset:64
	global_load_dwordx4 v[176:179], v[180:181], off offset:512
	s_nop 0
	global_load_dwordx4 v[180:183], v[180:181], off offset:576
	v_pk_add_f32 v[198:199], v[96:97], 0 op_sel_hi:[1,0]
	v_or_b32_e32 v96, 32, v184
	v_ashrrev_i32_e32 v97, 31, v96
	v_pk_add_f32 v[126:127], v[126:127], 0 op_sel_hi:[1,0]
	v_pk_add_f32 v[124:125], v[124:125], 0 op_sel_hi:[1,0]
	v_pk_add_f32 v[108:109], v[108:109], 0 op_sel_hi:[1,0]
	v_pk_add_f32 v[196:197], v[98:99], 0 op_sel_hi:[1,0]
	v_lshl_add_u64 v[98:99], s[52:53], 0, v[144:145]
	v_lshlrev_b64 v[200:201], 12, v[96:97]
	v_lshl_add_u64 v[96:97], s[52:53], 0, v[186:187]
	v_pk_add_f32 v[122:123], v[122:123], 0 op_sel_hi:[1,0]
	v_pk_add_f32 v[120:121], v[120:121], 0 op_sel_hi:[1,0]
	v_pk_add_f32 v[118:119], v[118:119], 0 op_sel_hi:[1,0]
	v_pk_add_f32 v[116:117], v[116:117], 0 op_sel_hi:[1,0]
	v_pk_add_f32 v[110:111], v[110:111], 0 op_sel_hi:[1,0]
	v_pk_add_f32 v[114:115], v[114:115], 0 op_sel_hi:[1,0]
	v_pk_add_f32 v[112:113], v[112:113], 0 op_sel_hi:[1,0]
	v_pk_add_f32 v[188:189], v[106:107], 0 op_sel_hi:[1,0]
	v_pk_add_f32 v[190:191], v[104:105], 0 op_sel_hi:[1,0]
	v_pk_add_f32 v[192:193], v[102:103], 0 op_sel_hi:[1,0]
;     __device__ __forceinline__ void operator()(AccRef acc, const Unit& u, int wr, int wc, int fr, int fq) const {
;     ...
;         for (int ai = 0; ai < 2; ++ai)
; #pragma unroll
;             for (int mh = 0; mh < 2; ++mh) {
;                 f32x4 bs[2][2][2];
; #pragma unroll
;                 for (int m = 0; m < 2; ++m)
; #pragma unroll
;                     for (int bj = 0; bj < 2; ++bj)
; #pragma unroll
;                         for (int n = 0; n < 2; ++n) bs[m][bj][n] = *(const f32x4*)(base + (size_t)(row0 + ai * 128 + (2 * mh + m) * 16) * D + col0 + bj * 128 + n * 16);
; #pragma unroll
;                 for (int m = 0; m < 2; ++m)
; #pragma unroll
;                     for (int bj = 0; bj < 2; ++bj)
; #pragma unroll
;                         for (int n = 0; n < 2; ++n) *(f32x4*)(out + (size_t)(row0 + ai * 128 + (2 * mh + m) * 16) * D + col0 + bj * 128 + n * 16) = bs[m][bj][n] + sv[bj][n] * (acc[ai][bj][2 * mh + m][n] + bv[bj][n]);
;                 asm volatile("" ::: "memory"); }
	v_pk_add_f32 v[194:195], v[100:101], 0 op_sel_hi:[1,0]
	v_lshl_add_u64 v[202:203], v[98:99], 0, v[140:141]
	v_lshl_add_u64 v[204:205], v[96:97], 0, v[140:141]
	v_lshl_add_u64 v[186:187], v[142:143], 0, v[200:201]
	v_pk_add_f32 v[94:95], v[94:95], 0 op_sel_hi:[1,0]
	v_pk_add_f32 v[92:93], v[92:93], 0 op_sel_hi:[1,0]
	v_pk_add_f32 v[90:91], v[90:91], 0 op_sel_hi:[1,0]
	v_pk_add_f32 v[88:89], v[88:89], 0 op_sel_hi:[1,0]
	v_pk_add_f32 v[86:87], v[86:87], 0 op_sel_hi:[1,0]
	v_pk_add_f32 v[84:85], v[84:85], 0 op_sel_hi:[1,0]
	v_pk_add_f32 v[78:79], v[78:79], 0 op_sel_hi:[1,0]
	v_pk_add_f32 v[76:77], v[76:77], 0 op_sel_hi:[1,0]
	v_pk_add_f32 v[82:83], v[82:83], 0 op_sel_hi:[1,0]
	v_pk_add_f32 v[80:81], v[80:81], 0 op_sel_hi:[1,0]
	v_pk_add_f32 v[62:63], v[62:63], 0 op_sel_hi:[1,0]
	v_pk_add_f32 v[60:61], v[60:61], 0 op_sel_hi:[1,0]
	v_pk_add_f32 v[58:59], v[58:59], 0 op_sel_hi:[1,0]
	v_pk_add_f32 v[56:57], v[56:57], 0 op_sel_hi:[1,0]
	v_pk_add_f32 v[54:55], v[54:55], 0 op_sel_hi:[1,0]
	v_pk_add_f32 v[52:53], v[52:53], 0 op_sel_hi:[1,0]
	v_pk_add_f32 v[46:47], v[46:47], 0 op_sel_hi:[1,0]
	v_pk_add_f32 v[44:45], v[44:45], 0 op_sel_hi:[1,0]
	v_pk_add_f32 v[50:51], v[50:51], 0 op_sel_hi:[1,0]
	v_pk_add_f32 v[48:49], v[48:49], 0 op_sel_hi:[1,0]
	v_pk_add_f32 v[30:31], v[30:31], 0 op_sel_hi:[1,0]
	v_pk_add_f32 v[28:29], v[28:29], 0 op_sel_hi:[1,0]
	v_pk_add_f32 v[26:27], v[26:27], 0 op_sel_hi:[1,0]
	v_pk_add_f32 v[24:25], v[24:25], 0 op_sel_hi:[1,0]
	v_pk_add_f32 v[22:23], v[22:23], 0 op_sel_hi:[1,0]
	v_pk_add_f32 v[20:21], v[20:21], 0 op_sel_hi:[1,0]
	v_pk_add_f32 v[14:15], v[14:15], 0 op_sel_hi:[1,0]
	v_pk_add_f32 v[12:13], v[12:13], 0 op_sel_hi:[1,0]
	v_pk_add_f32 v[18:19], v[18:19], 0 op_sel_hi:[1,0]
	v_pk_add_f32 v[16:17], v[16:17], 0 op_sel_hi:[1,0]
	s_and_b64 vcc, exec, s[10:11]
	s_mov_b32 s47, s45
	s_mov_b32 s48, s46
	s_mov_b64 s[30:31], s[14:15]
	s_mov_b64 s[28:29], s[12:13]
	s_waitcnt vmcnt(0)
	v_pk_add_f32 v[98:99], v[126:127], v[154:155]
	v_pk_add_f32 v[96:97], v[124:125], v[152:153]
	v_pk_add_f32 v[102:103], v[122:123], v[158:159]
	v_pk_add_f32 v[108:109], v[108:109], v[164:165]
	v_pk_add_f32 v[100:101], v[120:121], v[156:157]
	v_pk_add_f32 v[106:107], v[118:119], v[162:163]
	v_pk_add_f32 v[104:105], v[116:117], v[160:161]
	v_pk_add_f32 v[110:111], v[110:111], v[166:167]
	v_pk_add_f32 v[114:115], v[114:115], v[170:171]
	v_pk_add_f32 v[112:113], v[112:113], v[168:169]
	v_pk_add_f32 v[118:119], v[188:189], v[174:175]
	v_pk_add_f32 v[116:117], v[190:191], v[172:173]
	v_pk_add_f32 v[122:123], v[192:193], v[178:179]
	v_pk_add_f32 v[120:121], v[194:195], v[176:177]
	v_pk_add_f32 v[126:127], v[196:197], v[182:183]
	v_pk_add_f32 v[124:125], v[198:199], v[180:181]
	global_store_dwordx4 v[202:203], v[96:99], off
	global_store_dwordx4 v[202:203], v[100:103], off offset:64
	global_store_dwordx4 v[202:203], v[104:107], off offset:512
	global_store_dwordx4 v[202:203], v[108:111], off offset:576
	global_store_dwordx4 v[204:205], v[112:115], off
	global_store_dwordx4 v[204:205], v[116:119], off offset:64
	global_store_dwordx4 v[204:205], v[120:123], off offset:512
	global_store_dwordx4 v[204:205], v[124:127], off offset:576
	v_or_b32_e32 v108, 48, v184
	v_ashrrev_i32_e32 v109, 31, v108
	v_lshlrev_b64 v[152:153], 12, v[108:109]
	global_load_dwordx4 v[96:99], v[186:187], off
	global_load_dwordx4 v[100:103], v[186:187], off offset:64
	v_lshl_add_u64 v[124:125], v[142:143], 0, v[152:153]
	global_load_dwordx4 v[104:107], v[186:187], off offset:512
	global_load_dwordx4 v[108:111], v[186:187], off offset:576
	global_load_dwordx4 v[112:115], v[124:125], off
	global_load_dwordx4 v[116:119], v[124:125], off offset:64
	global_load_dwordx4 v[120:123], v[124:125], off offset:512
	s_nop 0
	global_load_dwordx4 v[124:127], v[124:125], off offset:576
	v_pk_add_f32 v[162:163], v[66:67], 0 op_sel_hi:[1,0]
	v_pk_add_f32 v[164:165], v[64:65], 0 op_sel_hi:[1,0]
	v_lshl_add_u64 v[64:65], s[52:53], 0, v[200:201]
	v_lshl_add_u64 v[66:67], s[52:53], 0, v[152:153]
	v_pk_add_f32 v[154:155], v[74:75], 0 op_sel_hi:[1,0]
	v_pk_add_f32 v[156:157], v[72:73], 0 op_sel_hi:[1,0]
	v_pk_add_f32 v[158:159], v[70:71], 0 op_sel_hi:[1,0]
	v_pk_add_f32 v[160:161], v[68:69], 0 op_sel_hi:[1,0]
	v_lshl_add_u64 v[168:169], v[64:65], 0, v[140:141]
	v_lshl_add_u64 v[170:171], v[66:67], 0, v[140:141]
	v_lshl_add_u64 v[166:167], v[144:145], 0, s[22:23]
	v_lshl_add_u64 v[152:153], v[142:143], 0, v[166:167]
	s_waitcnt vmcnt(0)
; #define PG8_WAIT_V(n) asm volatile("s_waitcnt vmcnt(" #n ")" ::: "memory")
; #define PG8_BAR __builtin_amdgcn_s_barrier()
; template <class Epi>
; __device__ __forceinline__ void gemm_phase(LAS unsigned char* lds, const Gemm g, const StaticOrder& S, const Epi& E) {
;     ...
;         if (!has_next) break;
;         {
; #pragma unroll
;         for (int a = 0; a < 2; ++a)
; #pragma unroll
;             for (int b = 0; b < 2; ++b)
; #pragma unroll
;                 for (int m = 0; m < 4; ++m)
; #pragma unroll
;                     for (int n = 0; n < 2; ++n) acc[a][b][m][n] = (f32x4){0.f, 0.f, 0.f, 0.f};
;         }
;         cur = nxt; cA = nA; cB = nB; ++ui;
;     }
;     PG8_WAIT_V(0);
;     if (wr == 0) PG8_BAR;
;     PG8_BAR;
;     __device__ __forceinline__ void operator()(AccRef acc, const Unit& u, int wr, int wc, int fr, int fq) const {
;     ...
;                         for (int n = 0; n < 2; ++n) bs[m][bj][n] = *(const f32x4*)(base + (size_t)(row0 + ai * 128 + (2 * mh + m) * 16) * D + col0 + bj * 128 + n * 16);
; #pragma unroll
;                 for (int m = 0; m < 2; ++m)
; #pragma unroll
;                     for (int bj = 0; bj < 2; ++bj)
; #pragma unroll
;                         for (int n = 0; n < 2; ++n) *(f32x4*)(out + (size_t)(row0 + ai * 128 + (2 * mh + m) * 16) * D + col0 + bj * 128 + n * 16) = bs[m][bj][n] + sv[bj][n] * (acc[ai][bj][2 * mh + m][n] + bv[bj][n]);
;                 asm volatile("" ::: "memory"); }
	v_pk_add_f32 v[66:67], v[94:95], v[98:99]
	v_pk_add_f32 v[64:65], v[92:93], v[96:97]
	v_pk_add_f32 v[70:71], v[90:91], v[102:103]
	v_pk_add_f32 v[68:69], v[88:89], v[100:101]
	v_pk_add_f32 v[74:75], v[86:87], v[106:107]
	v_pk_add_f32 v[72:73], v[84:85], v[104:105]
	v_pk_add_f32 v[78:79], v[78:79], v[110:111]
	v_pk_add_f32 v[76:77], v[76:77], v[108:109]
	v_pk_add_f32 v[82:83], v[82:83], v[114:115]
	v_pk_add_f32 v[80:81], v[80:81], v[112:113]
	v_pk_add_f32 v[86:87], v[154:155], v[118:119]
	v_pk_add_f32 v[84:85], v[156:157], v[116:117]
	v_pk_add_f32 v[90:91], v[158:159], v[122:123]
	v_pk_add_f32 v[88:89], v[160:161], v[120:121]
	v_pk_add_f32 v[94:95], v[162:163], v[126:127]
	v_pk_add_f32 v[92:93], v[164:165], v[124:125]
	global_store_dwordx4 v[168:169], v[64:67], off
	global_store_dwordx4 v[168:169], v[68:71], off offset:64
	global_store_dwordx4 v[168:169], v[72:75], off offset:512
	global_store_dwordx4 v[168:169], v[76:79], off offset:576
	global_store_dwordx4 v[170:171], v[80:83], off
	global_store_dwordx4 v[170:171], v[84:87], off offset:64
	global_store_dwordx4 v[170:171], v[88:91], off offset:512
	global_store_dwordx4 v[170:171], v[92:95], off offset:576
	v_lshl_add_u64 v[96:97], v[144:145], 0, s[24:25]
	global_load_dwordx4 v[64:67], v[152:153], off
	global_load_dwordx4 v[68:71], v[152:153], off offset:64
	global_load_dwordx4 v[72:75], v[152:153], off offset:512
	v_lshl_add_u64 v[92:93], v[142:143], 0, v[96:97]
	global_load_dwordx4 v[76:79], v[152:153], off offset:576
	global_load_dwordx4 v[80:83], v[92:93], off
	global_load_dwordx4 v[84:87], v[92:93], off offset:64
	global_load_dwordx4 v[88:91], v[92:93], off offset:512
	s_nop 0
	global_load_dwordx4 v[92:95], v[92:93], off offset:576
	v_pk_add_f32 v[106:107], v[34:35], 0 op_sel_hi:[1,0]
	v_pk_add_f32 v[108:109], v[32:33], 0 op_sel_hi:[1,0]
	v_lshl_add_u64 v[32:33], s[52:53], 0, v[166:167]
	v_lshl_add_u64 v[34:35], s[52:53], 0, v[96:97]
	v_pk_add_f32 v[98:99], v[42:43], 0 op_sel_hi:[1,0]
	v_pk_add_f32 v[100:101], v[40:41], 0 op_sel_hi:[1,0]
	v_pk_add_f32 v[102:103], v[38:39], 0 op_sel_hi:[1,0]
	v_pk_add_f32 v[104:105], v[36:37], 0 op_sel_hi:[1,0]
	v_lshl_add_u64 v[112:113], v[32:33], 0, v[140:141]
	v_lshl_add_u64 v[114:115], v[34:35], 0, v[140:141]
	v_lshl_add_u64 v[110:111], v[144:145], 0, s[26:27]
	v_lshl_add_u64 v[96:97], v[142:143], 0, v[110:111]
	s_waitcnt vmcnt(0)
	v_pk_add_f32 v[34:35], v[62:63], v[66:67]
	v_pk_add_f32 v[32:33], v[60:61], v[64:65]
	v_pk_add_f32 v[38:39], v[58:59], v[70:71]
	v_pk_add_f32 v[36:37], v[56:57], v[68:69]
	v_pk_add_f32 v[42:43], v[54:55], v[74:75]
	v_pk_add_f32 v[40:41], v[52:53], v[72:73]
	v_pk_add_f32 v[46:47], v[46:47], v[78:79]
	v_pk_add_f32 v[44:45], v[44:45], v[76:77]
	v_pk_add_f32 v[50:51], v[50:51], v[82:83]
	v_pk_add_f32 v[48:49], v[48:49], v[80:81]
	v_pk_add_f32 v[54:55], v[98:99], v[86:87]
	v_pk_add_f32 v[52:53], v[100:101], v[84:85]
	v_pk_add_f32 v[58:59], v[102:103], v[90:91]
	v_pk_add_f32 v[56:57], v[104:105], v[88:89]
	v_pk_add_f32 v[62:63], v[106:107], v[94:95]
	v_pk_add_f32 v[60:61], v[108:109], v[92:93]
	global_store_dwordx4 v[112:113], v[32:35], off
	global_store_dwordx4 v[112:113], v[36:39], off offset:64
	global_store_dwordx4 v[112:113], v[40:43], off offset:512
	global_store_dwordx4 v[112:113], v[44:47], off offset:576
	global_store_dwordx4 v[114:115], v[48:51], off
	global_store_dwordx4 v[114:115], v[52:55], off offset:64
	global_store_dwordx4 v[114:115], v[56:59], off offset:512
	global_store_dwordx4 v[114:115], v[60:63], off offset:576
	v_lshl_add_u64 v[64:65], v[144:145], 0, s[18:19]
	global_load_dwordx4 v[32:35], v[96:97], off
	global_load_dwordx4 v[36:39], v[96:97], off offset:64
	global_load_dwordx4 v[40:43], v[96:97], off offset:512
	v_lshl_add_u64 v[60:61], v[142:143], 0, v[64:65]
	global_load_dwordx4 v[44:47], v[96:97], off offset:576
	global_load_dwordx4 v[48:51], v[60:61], off
	global_load_dwordx4 v[52:55], v[60:61], off offset:64
	global_load_dwordx4 v[56:59], v[60:61], off offset:512
	s_nop 0
	global_load_dwordx4 v[60:63], v[60:61], off offset:576
	v_pk_add_f32 v[74:75], v[2:3], 0 op_sel_hi:[1,0]
	v_pk_add_f32 v[76:77], v[0:1], 0 op_sel_hi:[1,0]
	v_lshl_add_u64 v[0:1], s[52:53], 0, v[110:111]
	v_lshl_add_u64 v[2:3], s[52:53], 0, v[64:65]
	v_pk_add_f32 v[66:67], v[10:11], 0 op_sel_hi:[1,0]
	v_pk_add_f32 v[68:69], v[8:9], 0 op_sel_hi:[1,0]
	v_pk_add_f32 v[70:71], v[6:7], 0 op_sel_hi:[1,0]
	v_pk_add_f32 v[72:73], v[4:5], 0 op_sel_hi:[1,0]
	v_lshl_add_u64 v[64:65], v[0:1], 0, v[140:141]
	v_lshl_add_u64 v[78:79], v[2:3], 0, v[140:141]
	s_waitcnt vmcnt(0)
	v_pk_add_f32 v[2:3], v[30:31], v[34:35]
	v_pk_add_f32 v[0:1], v[28:29], v[32:33]
	v_pk_add_f32 v[6:7], v[26:27], v[38:39]
	v_pk_add_f32 v[4:5], v[24:25], v[36:37]
	v_pk_add_f32 v[10:11], v[22:23], v[42:43]
	v_pk_add_f32 v[8:9], v[20:21], v[40:41]
	v_pk_add_f32 v[14:15], v[14:15], v[46:47]
	v_pk_add_f32 v[12:13], v[12:13], v[44:45]
	v_pk_add_f32 v[18:19], v[18:19], v[50:51]
	v_pk_add_f32 v[16:17], v[16:17], v[48:49]
	v_pk_add_f32 v[22:23], v[66:67], v[54:55]
	v_pk_add_f32 v[20:21], v[68:69], v[52:53]
	v_pk_add_f32 v[26:27], v[70:71], v[58:59]
	v_pk_add_f32 v[24:25], v[72:73], v[56:57]
	v_pk_add_f32 v[30:31], v[74:75], v[62:63]
	v_pk_add_f32 v[28:29], v[76:77], v[60:61]
	global_store_dwordx4 v[64:65], v[0:3], off
	global_store_dwordx4 v[64:65], v[4:7], off offset:64
	global_store_dwordx4 v[64:65], v[8:11], off offset:512
	global_store_dwordx4 v[64:65], v[12:15], off offset:576
	global_store_dwordx4 v[78:79], v[16:19], off
	global_store_dwordx4 v[78:79], v[20:23], off offset:64
	global_store_dwordx4 v[78:79], v[24:27], off offset:512
	global_store_dwordx4 v[78:79], v[28:31], off offset:576
	s_cbranch_vccz .LBB0_849
	s_waitcnt vmcnt(0)
	s_cmpk_gt_u32 s4, 0xff
	s_cbranch_scc1 .LBB0_864
	s_barrier

; #define PG8_STAGE(bufoff, gbase, voff) do { _Pragma("unroll") for (int _i = 0; _i < 2; ++_i) \
;         __builtin_amdgcn_global_load_lds((const unsigned*)((const char*)(gbase) + (voff)[_i]), (LAS unsigned*)(lds + (bufoff) + ldsw + _i * 8192), 16, 0, 0); } while (0)
; #define PG8_LDA(dst, b, h) do { _Pragma("unroll") for (int m = 0; m < 4; ++m) _Pragma("unroll") for (int k = 0; k < 2; ++k) dst[m][k] = *(const LAS bf16x8*)(lds + PG8_SA(b, h) + aoff + m * 2048 + k * 1024); } while (0)
; #define PG8_LDB(dst, b, h) do { _Pragma("unroll") for (int n = 0; n < 2; ++n) _Pragma("unroll") for (int k = 0; k < 2; ++k) dst[n][k] = *(const LAS bf16x8*)(lds + PG8_SB(b, h) + boff + n * 2048 + k * 1024); } while (0)
; #define PG8_MMA(ai, bj, At, Bt) do { __builtin_amdgcn_s_setprio(1); _Pragma("unroll") for (int m = 0; m < 4; ++m) _Pragma("unroll") for (int n = 0; n < 2; ++n) _Pragma("unroll") for (int k = 0; k < 2; ++k) \
;         acc[ai][bj][m][n] = __builtin_amdgcn_mfma_f32_16x16x32_bf16(Bt[n][k], At[m][k], acc[ai][bj][m][n], 0, 0, 0); __builtin_amdgcn_s_setprio(0); } while (0)
; #define PG8_WAIT_V(n) asm volatile("s_waitcnt vmcnt(" #n ")" ::: "memory")
; #define PG8_WAIT_L(n) asm volatile("s_waitcnt lgkmcnt(" #n ")" ::: "memory")
; #define PG8_BAR __builtin_amdgcn_s_barrier()
; #define PG8_SCHED __builtin_amdgcn_sched_barrier(0)
; template <class Epi>
; __device__ __forceinline__ void gemm_phase(LAS unsigned char* lds, const Gemm g, const StaticOrder& S, const Epi& E) {
;     ...
;             PG8_LDB(B0, 0, 0); PG8_SCHED; PG8_LDA(At, 0, 0); PG8_STAGE(PG8_SA(1, 1), a1 + hstepA, voffA);
;             PG8_WAIT_L(8); PG8_BAR; PG8_WAIT_L(0); PG8_MMA(0, 0, At, B0); PG8_BAR; PG8_SCHED;
;             PG8_LDB(B1, 0, 1); PG8_STAGE(PG8_SB(0, 0), b2, voffB);
;             PG8_BAR; PG8_WAIT_L(0); PG8_MMA(0, 1, At, B1); PG8_BAR;
;             PG8_LDA(At, 0, 1); PG8_STAGE(PG8_SA(0, 0), a2, voffA);
;             PG8_BAR; PG8_WAIT_L(0); PG8_MMA(1, 0, At, B0); PG8_BAR; PG8_SCHED;
;             PG8_STAGE(PG8_SB(0, 1), b2 + hstepB, voffB);
;             PG8_WAIT_V(6); PG8_BAR; PG8_MMA(1, 1, At, B1); PG8_BAR;
.LBB0_990:
	ds_read_b128 v[128:131], v214
	ds_read_b128 v[132:135], v214 offset:1024
	ds_read_b128 v[136:139], v214 offset:2048
	ds_read_b128 v[140:143], v214 offset:3072
	s_add_u32 s82, s80, 0x100
	s_addc_u32 s83, s81, 0
	s_cmp_eq_u32 s10, 12
	s_cselect_b32 s87, s71, s83
	s_cselect_b32 s86, s77, s82
	s_cselect_b32 s85, s69, vcc_hi
	s_cselect_b32 s84, s79, vcc_lo
	v_lshl_add_u64 v[160:161], s[80:81], 0, v[174:175]
	s_add_i32 m0, s91, 0xc000
	ds_read_b128 v[144:147], v215
	ds_read_b128 v[148:151], v215 offset:1024
	ds_read_b128 v[152:155], v215 offset:2048
	ds_read_b128 v[156:159], v215 offset:3072
	ds_read_b128 v[182:185], v215 offset:4096
	ds_read_b128 v[186:189], v215 offset:5120
	ds_read_b128 v[190:193], v215 offset:6144
	ds_read_b128 v[194:197], v215 offset:7168
	global_load_lds_dwordx4 v[160:161], off
	v_lshl_add_u64 v[160:161], s[80:81], 0, v[176:177]
	s_add_i32 m0, s91, 0xe000
	s_nop 0
	global_load_lds_dwordx4 v[160:161], off
	ds_read_b128 v[198:201], v216
	ds_read_b128 v[220:223], v216 offset:1024
	ds_read_b128 v[224:227], v216 offset:2048
	ds_read_b128 v[228:231], v216 offset:3072
	s_waitcnt lgkmcnt(0)
	s_barrier
	s_setprio 1
	v_mfma_f32_16x16x32_bf16 v[124:127], v[128:131], v[144:147], v[124:127]
	v_mfma_f32_16x16x32_bf16 v[120:123], v[136:139], v[144:147], v[120:123]
	v_mfma_f32_16x16x32_bf16 v[108:111], v[128:131], v[152:155], v[108:111]
	v_mfma_f32_16x16x32_bf16 v[104:107], v[136:139], v[152:155], v[104:107]
	v_mfma_f32_16x16x32_bf16 v[92:95], v[128:131], v[182:185], v[92:95]
	v_mfma_f32_16x16x32_bf16 v[88:91], v[136:139], v[182:185], v[88:91]
	v_mfma_f32_16x16x32_bf16 v[76:79], v[128:131], v[190:193], v[76:79]
	v_mfma_f32_16x16x32_bf16 v[72:75], v[136:139], v[190:193], v[72:75]
	v_mfma_f32_16x16x32_bf16 v[124:127], v[132:135], v[148:151], v[124:127]
	v_mfma_f32_16x16x32_bf16 v[120:123], v[140:143], v[148:151], v[120:123]
	v_mfma_f32_16x16x32_bf16 v[108:111], v[132:135], v[156:159], v[108:111]
	v_mfma_f32_16x16x32_bf16 v[104:107], v[140:143], v[156:159], v[104:107]
	v_mfma_f32_16x16x32_bf16 v[92:95], v[132:135], v[186:189], v[92:95]
	v_mfma_f32_16x16x32_bf16 v[88:91], v[140:143], v[186:189], v[88:91]
	v_mfma_f32_16x16x32_bf16 v[76:79], v[132:135], v[194:197], v[76:79]
	v_mfma_f32_16x16x32_bf16 v[72:75], v[140:143], v[194:197], v[72:75]
	v_mfma_f32_16x16x32_bf16 v[116:119], v[198:201], v[144:147], v[116:119]
	v_mfma_f32_16x16x32_bf16 v[112:115], v[224:227], v[144:147], v[112:115]
	v_mfma_f32_16x16x32_bf16 v[100:103], v[198:201], v[152:155], v[100:103]
	v_mfma_f32_16x16x32_bf16 v[96:99], v[224:227], v[152:155], v[96:99]
	v_mfma_f32_16x16x32_bf16 v[84:87], v[198:201], v[182:185], v[84:87]
	v_mfma_f32_16x16x32_bf16 v[80:83], v[224:227], v[182:185], v[80:83]
	v_mfma_f32_16x16x32_bf16 v[68:71], v[198:201], v[190:193], v[68:71]
	v_mfma_f32_16x16x32_bf16 v[64:67], v[224:227], v[190:193], v[64:67]
	v_mfma_f32_16x16x32_bf16 v[116:119], v[220:223], v[148:151], v[116:119]
	v_mfma_f32_16x16x32_bf16 v[112:115], v[228:231], v[148:151], v[112:115]
	v_mfma_f32_16x16x32_bf16 v[100:103], v[220:223], v[156:159], v[100:103]
	v_mfma_f32_16x16x32_bf16 v[96:99], v[228:231], v[156:159], v[96:99]
	v_mfma_f32_16x16x32_bf16 v[84:87], v[220:223], v[186:189], v[84:87]
	v_mfma_f32_16x16x32_bf16 v[80:83], v[228:231], v[186:189], v[80:83]
	v_mfma_f32_16x16x32_bf16 v[68:71], v[220:223], v[194:197], v[68:71]
	v_mfma_f32_16x16x32_bf16 v[64:67], v[228:231], v[194:197], v[64:67]
	s_setprio 0
	s_barrier
	s_nop 1
	ds_read_b128 v[144:147], v215 offset:16384
	ds_read_b128 v[148:151], v215 offset:17408
	ds_read_b128 v[152:155], v215 offset:18432
	ds_read_b128 v[156:159], v215 offset:19456
	ds_read_b128 v[182:185], v215 offset:20480
	ds_read_b128 v[186:189], v215 offset:21504
	ds_read_b128 v[190:193], v215 offset:22528
	ds_read_b128 v[194:197], v215 offset:23552
	s_add_i32 s11, s93, s90
	v_lshl_add_u64 v[160:161], s[84:85], 0, v[164:165]
	s_mov_b32 m0, s11
	s_nop 0
	global_load_lds_dwordx4 v[160:161], off
	v_lshl_add_u64 v[202:203], s[84:85], 0, v[168:169]
	s_add_i32 m0, s11, 0x2000
	s_nop 0
	global_load_lds_dwordx4 v[202:203], off
	s_mov_b32 m0, s91
	v_lshl_add_u64 v[232:233], s[86:87], 0, v[162:163]
	global_load_lds_dwordx4 v[232:233], off
	v_lshl_add_u64 v[236:237], s[86:87], 0, v[166:167]
	s_mov_b32 m0, s97
	s_nop 0
	global_load_lds_dwordx4 v[236:237], off
	s_add_u32 s80, s84, 0x40000
	s_addc_u32 s81, s85, 0
	s_add_i32 s11, s96, s90
	v_lshl_add_u64 v[254:255], s[80:81], 0, v[164:165]
	s_mov_b32 m0, s11
	s_nop 0
	global_load_lds_dwordx4 v[254:255], off
	v_lshl_add_u64 v[254:255], s[80:81], 0, v[168:169]
	s_add_i32 m0, s11, 0x2000
	s_nop 0
	global_load_lds_dwordx4 v[254:255], off
	s_waitcnt vmcnt(6)
	s_waitcnt lgkmcnt(0)
	s_barrier
; #define PG8_STAGE(bufoff, gbase, voff) do { _Pragma("unroll") for (int _i = 0; _i < 2; ++_i) \
;         __builtin_amdgcn_global_load_lds((const unsigned*)((const char*)(gbase) + (voff)[_i]), (LAS unsigned*)(lds + (bufoff) + ldsw + _i * 8192), 16, 0, 0); } while (0)
; #define PG8_LDA(dst, b, h) do { _Pragma("unroll") for (int m = 0; m < 4; ++m) _Pragma("unroll") for (int k = 0; k < 2; ++k) dst[m][k] = *(const LAS bf16x8*)(lds + PG8_SA(b, h) + aoff + m * 2048 + k * 1024); } while (0)
; #define PG8_LDB(dst, b, h) do { _Pragma("unroll") for (int n = 0; n < 2; ++n) _Pragma("unroll") for (int k = 0; k < 2; ++k) dst[n][k] = *(const LAS bf16x8*)(lds + PG8_SB(b, h) + boff + n * 2048 + k * 1024); } while (0)
; #define PG8_MMA(ai, bj, At, Bt) do { __builtin_amdgcn_s_setprio(1); _Pragma("unroll") for (int m = 0; m < 4; ++m) _Pragma("unroll") for (int n = 0; n < 2; ++n) _Pragma("unroll") for (int k = 0; k < 2; ++k) \
;         acc[ai][bj][m][n] = __builtin_amdgcn_mfma_f32_16x16x32_bf16(Bt[n][k], At[m][k], acc[ai][bj][m][n], 0, 0, 0); __builtin_amdgcn_s_setprio(0); } while (0)
; #define PG8_WAIT_V(n) asm volatile("s_waitcnt vmcnt(" #n ")" ::: "memory")
; #define PG8_WAIT_L(n) asm volatile("s_waitcnt lgkmcnt(" #n ")" ::: "memory")
; #define PG8_BAR __builtin_amdgcn_s_barrier()
; #define PG8_SCHED __builtin_amdgcn_sched_barrier(0)
; template <class Epi>
; __device__ __forceinline__ void gemm_phase(LAS unsigned char* lds, const Gemm g, const StaticOrder& S, const Epi& E) {
;     ...
;             PG8_WAIT_V(6); PG8_BAR; PG8_MMA(1, 1, At, B1); PG8_BAR;
;             PG8_LDB(B0, 1, 0); PG8_SCHED; PG8_LDA(At, 1, 0); PG8_STAGE(PG8_SA(0, 1), a2 + hstepA, voffA);
;             PG8_WAIT_L(8); PG8_BAR; PG8_WAIT_L(0); PG8_MMA(0, 0, At, B0); PG8_BAR; PG8_SCHED;
;             PG8_LDB(B1, 1, 1); PG8_STAGE(PG8_SB(1, 0), b3, voffB);
;             PG8_BAR; PG8_WAIT_L(0); PG8_MMA(0, 1, At, B1); PG8_BAR;
;             PG8_LDA(At, 1, 1); PG8_STAGE(PG8_SA(1, 0), a3, voffA);
;             PG8_BAR; PG8_WAIT_L(0); PG8_MMA(1, 0, At, B0); PG8_BAR; PG8_SCHED;
	s_setprio 1
	v_mfma_f32_16x16x32_bf16 v[60:63], v[128:131], v[144:147], v[60:63]
	v_mfma_f32_16x16x32_bf16 v[56:59], v[136:139], v[144:147], v[56:59]
	v_mfma_f32_16x16x32_bf16 v[44:47], v[128:131], v[152:155], v[44:47]
	v_mfma_f32_16x16x32_bf16 v[40:43], v[136:139], v[152:155], v[40:43]
	v_mfma_f32_16x16x32_bf16 v[28:31], v[128:131], v[182:185], v[28:31]
	v_mfma_f32_16x16x32_bf16 v[24:27], v[136:139], v[182:185], v[24:27]
	v_mfma_f32_16x16x32_bf16 v[12:15], v[128:131], v[190:193], v[12:15]
	v_mfma_f32_16x16x32_bf16 v[8:11], v[136:139], v[190:193], v[8:11]
	v_mfma_f32_16x16x32_bf16 v[60:63], v[132:135], v[148:151], v[60:63]
	v_mfma_f32_16x16x32_bf16 v[56:59], v[140:143], v[148:151], v[56:59]
	v_mfma_f32_16x16x32_bf16 v[44:47], v[132:135], v[156:159], v[44:47]
	v_mfma_f32_16x16x32_bf16 v[40:43], v[140:143], v[156:159], v[40:43]
	v_mfma_f32_16x16x32_bf16 v[28:31], v[132:135], v[186:189], v[28:31]
	v_mfma_f32_16x16x32_bf16 v[24:27], v[140:143], v[186:189], v[24:27]
	v_mfma_f32_16x16x32_bf16 v[12:15], v[132:135], v[194:197], v[12:15]
	v_mfma_f32_16x16x32_bf16 v[8:11], v[140:143], v[194:197], v[8:11]
	v_mfma_f32_16x16x32_bf16 v[52:55], v[198:201], v[144:147], v[52:55]
	v_mfma_f32_16x16x32_bf16 v[48:51], v[224:227], v[144:147], v[48:51]
	v_mfma_f32_16x16x32_bf16 v[36:39], v[198:201], v[152:155], v[36:39]
	v_mfma_f32_16x16x32_bf16 v[32:35], v[224:227], v[152:155], v[32:35]
	v_mfma_f32_16x16x32_bf16 v[20:23], v[198:201], v[182:185], v[20:23]
	v_mfma_f32_16x16x32_bf16 v[16:19], v[224:227], v[182:185], v[16:19]
	v_mfma_f32_16x16x32_bf16 v[4:7], v[198:201], v[190:193], v[4:7]
	v_mfma_f32_16x16x32_bf16 v[0:3], v[224:227], v[190:193], v[0:3]
	v_mfma_f32_16x16x32_bf16 v[52:55], v[220:223], v[148:151], v[52:55]
	v_mfma_f32_16x16x32_bf16 v[48:51], v[228:231], v[148:151], v[48:51]
	v_mfma_f32_16x16x32_bf16 v[36:39], v[220:223], v[156:159], v[36:39]
	v_mfma_f32_16x16x32_bf16 v[32:35], v[228:231], v[156:159], v[32:35]
	v_mfma_f32_16x16x32_bf16 v[20:23], v[220:223], v[186:189], v[20:23]
	v_mfma_f32_16x16x32_bf16 v[16:19], v[228:231], v[186:189], v[16:19]
	v_mfma_f32_16x16x32_bf16 v[4:7], v[220:223], v[194:197], v[4:7]
	v_mfma_f32_16x16x32_bf16 v[0:3], v[228:231], v[194:197], v[0:3]
	s_setprio 0
	s_add_i32 s11, 0, 0x18000
	v_add_u32_e32 v140, s11, v173
	s_barrier
	ds_read_b128 v[128:131], v140
	ds_read_b128 v[132:135], v140 offset:1024
	ds_read_b128 v[136:139], v140 offset:2048
	ds_read_b128 v[140:143], v140 offset:3072
	s_add_u32 s80, s86, 0x40000
	s_addc_u32 s81, s87, 0
	s_mov_b32 m0, s8
	v_lshl_add_u64 v[198:199], s[80:81], 0, v[162:163]
	ds_read_b128 v[144:147], v215 offset:32768
	ds_read_b128 v[148:151], v215 offset:33792
	ds_read_b128 v[152:155], v215 offset:34816
	ds_read_b128 v[156:159], v215 offset:35840
	ds_read_b128 v[182:185], v215 offset:36864
	ds_read_b128 v[186:189], v215 offset:37888
	ds_read_b128 v[190:193], v215 offset:38912
	ds_read_b128 v[194:197], v215 offset:39936
	global_load_lds_dwordx4 v[198:199], off
	v_lshl_add_u64 v[198:199], s[80:81], 0, v[166:167]
	s_mov_b32 m0, s9
	s_nop 0
	global_load_lds_dwordx4 v[198:199], off
	s_add_i32 s86, 0, 0x1c000
	v_add_u32_e32 v170, s86, v173
	ds_read_b128 v[198:201], v170
	ds_read_b128 v[220:223], v170 offset:1024
	ds_read_b128 v[224:227], v170 offset:2048
	ds_read_b128 v[228:231], v170 offset:3072
	s_waitcnt lgkmcnt(0)
	s_barrier
	s_setprio 1
	v_mfma_f32_16x16x32_bf16 v[124:127], v[128:131], v[144:147], v[124:127]
	v_mfma_f32_16x16x32_bf16 v[120:123], v[136:139], v[144:147], v[120:123]
	v_mfma_f32_16x16x32_bf16 v[108:111], v[128:131], v[152:155], v[108:111]
	v_mfma_f32_16x16x32_bf16 v[104:107], v[136:139], v[152:155], v[104:107]
	v_mfma_f32_16x16x32_bf16 v[92:95], v[128:131], v[182:185], v[92:95]
	v_mfma_f32_16x16x32_bf16 v[88:91], v[136:139], v[182:185], v[88:91]
	v_mfma_f32_16x16x32_bf16 v[76:79], v[128:131], v[190:193], v[76:79]
	v_mfma_f32_16x16x32_bf16 v[72:75], v[136:139], v[190:193], v[72:75]
	v_mfma_f32_16x16x32_bf16 v[124:127], v[132:135], v[148:151], v[124:127]
	v_mfma_f32_16x16x32_bf16 v[120:123], v[140:143], v[148:151], v[120:123]
	v_mfma_f32_16x16x32_bf16 v[108:111], v[132:135], v[156:159], v[108:111]
	v_mfma_f32_16x16x32_bf16 v[104:107], v[140:143], v[156:159], v[104:107]
	v_mfma_f32_16x16x32_bf16 v[92:95], v[132:135], v[186:189], v[92:95]
	v_mfma_f32_16x16x32_bf16 v[88:91], v[140:143], v[186:189], v[88:91]
	v_mfma_f32_16x16x32_bf16 v[76:79], v[132:135], v[194:197], v[76:79]
	v_mfma_f32_16x16x32_bf16 v[72:75], v[140:143], v[194:197], v[72:75]
	v_mfma_f32_16x16x32_bf16 v[116:119], v[198:201], v[144:147], v[116:119]
	v_mfma_f32_16x16x32_bf16 v[112:115], v[224:227], v[144:147], v[112:115]
	v_mfma_f32_16x16x32_bf16 v[100:103], v[198:201], v[152:155], v[100:103]
	v_mfma_f32_16x16x32_bf16 v[96:99], v[224:227], v[152:155], v[96:99]
	v_mfma_f32_16x16x32_bf16 v[84:87], v[198:201], v[182:185], v[84:87]
	v_mfma_f32_16x16x32_bf16 v[80:83], v[224:227], v[182:185], v[80:83]
	v_mfma_f32_16x16x32_bf16 v[68:71], v[198:201], v[190:193], v[68:71]
	v_mfma_f32_16x16x32_bf16 v[64:67], v[224:227], v[190:193], v[64:67]
	v_mfma_f32_16x16x32_bf16 v[116:119], v[220:223], v[148:151], v[116:119]
	v_mfma_f32_16x16x32_bf16 v[112:115], v[228:231], v[148:151], v[112:115]
	v_mfma_f32_16x16x32_bf16 v[100:103], v[220:223], v[156:159], v[100:103]
	v_mfma_f32_16x16x32_bf16 v[96:99], v[228:231], v[156:159], v[96:99]
	v_mfma_f32_16x16x32_bf16 v[84:87], v[220:223], v[186:189], v[84:87]
	v_mfma_f32_16x16x32_bf16 v[80:83], v[228:231], v[186:189], v[80:83]
	v_mfma_f32_16x16x32_bf16 v[68:71], v[220:223], v[194:197], v[68:71]
	v_mfma_f32_16x16x32_bf16 v[64:67], v[228:231], v[194:197], v[64:67]
	s_setprio 0
	s_barrier
; #define LAS __attribute__((address_space(3)))
; __device__ __forceinline__ float gelu_tanh(float x) { const float k = 1.5957691216f * (x + 0.044715f * x * x * x); return x * __builtin_amdgcn_rcpf(1.0f + __expf(-k)); }
; #define PG8_STAGE(bufoff, gbase, voff) do { _Pragma("unroll") for (int _i = 0; _i < 2; ++_i) \
;         __builtin_amdgcn_global_load_lds((const unsigned*)((const char*)(gbase) + (voff)[_i]), (LAS unsigned*)(lds + (bufoff) + ldsw + _i * 8192), 16, 0, 0); } while (0)
; template <class Epi>
; __device__ __forceinline__ void gemm_phase(LAS unsigned char* lds, const Gemm g, const StaticOrder& S, const Epi& E) {
;     ...
;             PG8_LDB(B1, 1, 1); PG8_STAGE(PG8_SB(1, 0), b3, voffB);
;             PG8_BAR; PG8_WAIT_L(0); PG8_MMA(0, 1, At, B1); PG8_BAR;
;             PG8_LDA(At, 1, 1); PG8_STAGE(PG8_SA(1, 0), a3, voffA);
;             PG8_BAR; PG8_WAIT_L(0); PG8_MMA(1, 0, At, B0); PG8_BAR; PG8_SCHED;
;             PG8_STAGE(PG8_SB(1, 1), b3 + hstepB, voffB);
;             PG8_WAIT_V(6); PG8_BAR; PG8_MMA(1, 1, At, B1); PG8_BAR;
;     __device__ __forceinline__ void operator()(AccRef acc, const Unit& u, int wr, int wc, int fr, int fq) const {
;         const int row0 = u.pm * 256 + wr * 64 + 4 * fr, clb = wc * 32 + 8 * fq, col0 = (u.pn & 3) * 256 + clb;
;         if (u.pn < 4) {
; #pragma unroll
;             for (int ai = 0; ai < 2; ++ai)
; #pragma unroll
;                 for (int m = 0; m < 4; ++m) { bf16_t* rp = GG + (size_t)(row0 + ai * 128 + m) * D + col0;
; #pragma unroll
;                     for (int bj = 0; bj < 2; ++bj) { f32x4 v0 = acc[ai][bj][m][0], v1 = acc[ai][bj][m][1];
; #pragma unroll
;                         for (int j = 0; j < 4; ++j) { v0[j] = gelu_tanh(v0[j]); v1[j] = gelu_tanh(v1[j]); }
;                         u32x4 w; w.x = cvt_pk_bf16(v0[0], v0[1]); w.y = cvt_pk_bf16(v0[2], v0[3]); w.z = cvt_pk_bf16(v1[0], v1[1]); w.w = cvt_pk_bf16(v1[2], v1[3]);
;                         *(u32x4*)(rp + bj * 128) = w; } }
;             return;
;         }
;         if (fr == 15) {
; #pragma unroll
;             for (int ai = 0; ai < 2; ++ai)
; #pragma unroll
;                 for (int bj = 0; bj < 2; ++bj)
; #pragma unroll
;                     for (int n = 0; n < 2; ++n)
; #pragma unroll
;                         for (int q = 0; q < 3; ++q) *(LAS f32x4*)(xch + ((ai * 2 + wr) * 3 + q) * 256 + bj * 128 + clb + 4 * n) = acc[ai][bj][1 + q][n];
	s_nop 1
	ds_read_b128 v[144:147], v215 offset:49152
	ds_read_b128 v[148:151], v215 offset:50176
	ds_read_b128 v[152:155], v215 offset:51200
	ds_read_b128 v[156:159], v215 offset:52224
	ds_read_b128 v[182:185], v215 offset:53248
	ds_read_b128 v[186:189], v215 offset:54272
	ds_read_b128 v[190:193], v215 offset:55296
	ds_read_b128 v[194:197], v215 offset:56320
	s_add_i32 s11, s11, s90
	v_lshl_add_u64 v[254:255], v[160:161], 0, s[28:29]
	s_mov_b32 m0, s11
	s_nop 0
	global_load_lds_dwordx4 v[254:255], off
	v_lshl_add_u64 v[254:255], v[202:203], 0, s[28:29]
	s_add_i32 m0, s11, 0x2000
	s_nop 0
	global_load_lds_dwordx4 v[254:255], off
	s_mov_b32 m0, s4
	v_lshl_add_u64 v[254:255], v[232:233], 0, s[28:29]
	global_load_lds_dwordx4 v[254:255], off
	v_lshl_add_u64 v[160:161], v[236:237], 0, s[28:29]
	s_mov_b32 m0, s5
	s_nop 0
	global_load_lds_dwordx4 v[160:161], off
	s_add_u32 s80, s84, 0x40080
	s_addc_u32 s81, s85, 0
	s_add_i32 s11, s86, s90
	v_lshl_add_u64 v[254:255], s[80:81], 0, v[164:165]
	s_mov_b32 m0, s11
	s_nop 0
	global_load_lds_dwordx4 v[254:255], off
	v_lshl_add_u64 v[254:255], s[80:81], 0, v[168:169]
	s_add_i32 m0, s11, 0x2000
	s_nop 0
	global_load_lds_dwordx4 v[254:255], off
	s_waitcnt vmcnt(6)
	s_waitcnt lgkmcnt(0)
	s_barrier
	s_setprio 1
	v_mfma_f32_16x16x32_bf16 v[60:63], v[128:131], v[144:147], v[60:63]
	v_mfma_f32_16x16x32_bf16 v[56:59], v[136:139], v[144:147], v[56:59]
	v_mfma_f32_16x16x32_bf16 v[44:47], v[128:131], v[152:155], v[44:47]
	v_mfma_f32_16x16x32_bf16 v[40:43], v[136:139], v[152:155], v[40:43]
	v_mfma_f32_16x16x32_bf16 v[28:31], v[128:131], v[182:185], v[28:31]
	v_mfma_f32_16x16x32_bf16 v[24:27], v[136:139], v[182:185], v[24:27]
	v_mfma_f32_16x16x32_bf16 v[12:15], v[128:131], v[190:193], v[12:15]
	v_mfma_f32_16x16x32_bf16 v[8:11], v[136:139], v[190:193], v[8:11]
	v_mfma_f32_16x16x32_bf16 v[60:63], v[132:135], v[148:151], v[60:63]
	v_mfma_f32_16x16x32_bf16 v[56:59], v[140:143], v[148:151], v[56:59]
	v_mfma_f32_16x16x32_bf16 v[44:47], v[132:135], v[156:159], v[44:47]
	v_mfma_f32_16x16x32_bf16 v[40:43], v[140:143], v[156:159], v[40:43]
	v_mfma_f32_16x16x32_bf16 v[28:31], v[132:135], v[186:189], v[28:31]
	v_mfma_f32_16x16x32_bf16 v[24:27], v[140:143], v[186:189], v[24:27]
	v_mfma_f32_16x16x32_bf16 v[12:15], v[132:135], v[194:197], v[12:15]
	v_mfma_f32_16x16x32_bf16 v[8:11], v[140:143], v[194:197], v[8:11]
	v_mfma_f32_16x16x32_bf16 v[52:55], v[198:201], v[144:147], v[52:55]
	v_mfma_f32_16x16x32_bf16 v[48:51], v[224:227], v[144:147], v[48:51]
	v_mfma_f32_16x16x32_bf16 v[36:39], v[198:201], v[152:155], v[36:39]
	v_mfma_f32_16x16x32_bf16 v[32:35], v[224:227], v[152:155], v[32:35]
	v_mfma_f32_16x16x32_bf16 v[20:23], v[198:201], v[182:185], v[20:23]
	v_mfma_f32_16x16x32_bf16 v[16:19], v[224:227], v[182:185], v[16:19]
	v_mfma_f32_16x16x32_bf16 v[4:7], v[198:201], v[190:193], v[4:7]
	v_mfma_f32_16x16x32_bf16 v[0:3], v[224:227], v[190:193], v[0:3]
	v_mfma_f32_16x16x32_bf16 v[52:55], v[220:223], v[148:151], v[52:55]
	v_mfma_f32_16x16x32_bf16 v[48:51], v[228:231], v[148:151], v[48:51]
	v_mfma_f32_16x16x32_bf16 v[36:39], v[220:223], v[156:159], v[36:39]
	v_mfma_f32_16x16x32_bf16 v[32:35], v[228:231], v[156:159], v[32:35]
	v_mfma_f32_16x16x32_bf16 v[20:23], v[220:223], v[186:189], v[20:23]
	v_mfma_f32_16x16x32_bf16 v[16:19], v[228:231], v[186:189], v[16:19]
	v_mfma_f32_16x16x32_bf16 v[4:7], v[220:223], v[194:197], v[4:7]
	v_mfma_f32_16x16x32_bf16 v[0:3], v[228:231], v[194:197], v[0:3]
	s_setprio 0
	s_add_i32 s10, s10, 2
	s_add_u32 vcc_lo, vcc_lo, 0x100
	s_addc_u32 vcc_hi, vcc_hi, 0
	s_cmp_gt_u32 s10, 13
	s_mov_b64 s[80:81], s[82:83]
	s_barrier
	s_cbranch_scc0 .LBB0_990
	s_lshl_b32 s10, s78, 8
	s_and_b32 s10, s10, 0x300
	v_lshl_add_u32 v182, s76, 8, v204
	v_or_b32_e32 v220, s10, v172
	s_cmp_gt_i32 s78, 3
	s_mov_b64 s[80:81], -1
	s_cbranch_scc0 .LBB0_1015
	s_and_saveexec_b64 s[80:81], s[12:13]
	s_cbranch_execz .LBB0_994
	ds_write_b128 v205, v[108:111]
	ds_write_b128 v205, v[92:95] offset:1024
	ds_write_b128 v205, v[76:79] offset:2048
	ds_write_b128 v205, v[104:107] offset:16
	ds_write_b128 v205, v[88:91] offset:1040
	ds_write_b128 v205, v[72:75] offset:2064
	ds_write_b128 v205, v[100:103] offset:512
	ds_write_b128 v205, v[84:87] offset:1536
	ds_write_b128 v205, v[68:71] offset:2560
	ds_write_b128 v205, v[96:99] offset:528
	ds_write_b128 v205, v[80:83] offset:1552
	ds_write_b128 v205, v[64:67] offset:2576
	ds_write_b128 v205, v[44:47] offset:6144
	ds_write_b128 v205, v[28:31] offset:7168
	ds_write_b128 v205, v[12:15] offset:8192
	ds_write_b128 v205, v[40:43] offset:6160
	ds_write_b128 v205, v[24:27] offset:7184
	ds_write_b128 v205, v[8:11] offset:8208
	ds_write_b128 v205, v[36:39] offset:6656
	ds_write_b128 v205, v[20:23] offset:7680
	ds_write_b128 v205, v[4:7] offset:8704
	ds_write_b128 v205, v[32:35] offset:6672
	ds_write_b128 v205, v[16:19] offset:7696
	ds_write_b128 v205, v[0:3] offset:8720

; #define PG8_STAGE(bufoff, gbase, voff) do { _Pragma("unroll") for (int _i = 0; _i < 2; ++_i) \
;         __builtin_amdgcn_global_load_lds((const unsigned*)((const char*)(gbase) + (voff)[_i]), (LAS unsigned*)(lds + (bufoff) + ldsw + _i * 8192), 16, 0, 0); } while (0)
; #define PG8_LDA(dst, b, h) do { _Pragma("unroll") for (int m = 0; m < 4; ++m) _Pragma("unroll") for (int k = 0; k < 2; ++k) dst[m][k] = *(const LAS bf16x8*)(lds + PG8_SA(b, h) + aoff + m * 2048 + k * 1024); } while (0)
; #define PG8_LDB(dst, b, h) do { _Pragma("unroll") for (int n = 0; n < 2; ++n) _Pragma("unroll") for (int k = 0; k < 2; ++k) dst[n][k] = *(const LAS bf16x8*)(lds + PG8_SB(b, h) + boff + n * 2048 + k * 1024); } while (0)
; #define PG8_MMA(ai, bj, At, Bt) do { __builtin_amdgcn_s_setprio(1); _Pragma("unroll") for (int m = 0; m < 4; ++m) _Pragma("unroll") for (int n = 0; n < 2; ++n) _Pragma("unroll") for (int k = 0; k < 2; ++k) \
;         acc[ai][bj][m][n] = __builtin_amdgcn_mfma_f32_16x16x32_bf16(Bt[n][k], At[m][k], acc[ai][bj][m][n], 0, 0, 0); __builtin_amdgcn_s_setprio(0); } while (0)
; #define PG8_WAIT_V(n) asm volatile("s_waitcnt vmcnt(" #n ")" ::: "memory")
; #define PG8_WAIT_L(n) asm volatile("s_waitcnt lgkmcnt(" #n ")" ::: "memory")
; #define PG8_BAR __builtin_amdgcn_s_barrier()
; #define PG8_SCHED __builtin_amdgcn_sched_barrier(0)
; template <class Epi>
; __device__ __forceinline__ void gemm_phase(LAS unsigned char* lds, const Gemm g, const StaticOrder& S, const Epi& E) {
;     ...
;             PG8_LDB(B0, 0, 0); PG8_SCHED; PG8_LDA(At, 0, 0); PG8_STAGE(PG8_SA(1, 1), a1 + hstepA, voffA);
;             PG8_WAIT_L(8); PG8_BAR; PG8_WAIT_L(0); PG8_MMA(0, 0, At, B0); PG8_BAR; PG8_SCHED;
;             PG8_LDB(B1, 0, 1); PG8_STAGE(PG8_SB(0, 0), b2, voffB);
;             PG8_BAR; PG8_WAIT_L(0); PG8_MMA(0, 1, At, B1); PG8_BAR;
;             PG8_LDA(At, 0, 1); PG8_STAGE(PG8_SA(0, 0), a2, voffA);
;             PG8_BAR; PG8_WAIT_L(0); PG8_MMA(1, 0, At, B0); PG8_BAR; PG8_SCHED;
;             PG8_STAGE(PG8_SB(0, 1), b2 + hstepB, voffB);
;             PG8_WAIT_V(6); PG8_BAR; PG8_MMA(1, 1, At, B1); PG8_BAR;
.LBB0_1239:
	ds_read_b128 v[140:143], v149
	ds_read_b128 v[152:155], v149 offset:1024
	ds_read_b128 v[156:159], v149 offset:2048
	ds_read_b128 v[160:163], v149 offset:3072
	s_add_u32 s40, s38, 0xfffc0080
	s_addc_u32 s41, s39, -1
	s_cmp_eq_u32 s76, 12
	s_cselect_b32 s43, s29, s41
	s_cselect_b32 s42, s72, s40
	s_cselect_b32 s41, s27, s75
	s_cselect_b32 s40, s73, s74
	v_lshl_add_u64 v[144:145], s[38:39], 0, v[132:133]
	s_add_i32 m0, s8, 0xc000
	ds_read_b128 v[164:167], v150
	ds_read_b128 v[168:171], v150 offset:1024
	ds_read_b128 v[172:175], v150 offset:2048
	ds_read_b128 v[176:179], v150 offset:3072
	ds_read_b128 v[180:183], v150 offset:4096
	ds_read_b128 v[184:187], v150 offset:5120
	ds_read_b128 v[188:191], v150 offset:6144
	ds_read_b128 v[192:195], v150 offset:7168
	global_load_lds_dwordx4 v[144:145], off
	v_lshl_add_u64 v[144:145], s[38:39], 0, v[134:135]
	s_add_i32 m0, s8, 0xe000
	s_nop 0
	global_load_lds_dwordx4 v[144:145], off
	ds_read_b128 v[196:199], v151
	ds_read_b128 v[200:203], v151 offset:1024
	ds_read_b128 v[204:207], v151 offset:2048
	ds_read_b128 v[208:211], v151 offset:3072
	s_waitcnt lgkmcnt(0)
	s_barrier
	s_setprio 1
	v_mfma_f32_16x16x32_bf16 v[124:127], v[140:143], v[164:167], v[124:127]
	v_mfma_f32_16x16x32_bf16 v[120:123], v[156:159], v[164:167], v[120:123]
	v_mfma_f32_16x16x32_bf16 v[112:115], v[140:143], v[172:175], v[112:115]
	v_mfma_f32_16x16x32_bf16 v[104:107], v[156:159], v[172:175], v[104:107]
	v_mfma_f32_16x16x32_bf16 v[92:95], v[140:143], v[180:183], v[92:95]
	v_mfma_f32_16x16x32_bf16 v[88:91], v[156:159], v[180:183], v[88:91]
	v_mfma_f32_16x16x32_bf16 v[80:83], v[140:143], v[188:191], v[80:83]
	v_mfma_f32_16x16x32_bf16 v[72:75], v[156:159], v[188:191], v[72:75]
	v_mfma_f32_16x16x32_bf16 v[124:127], v[152:155], v[168:171], v[124:127]
	v_mfma_f32_16x16x32_bf16 v[120:123], v[160:163], v[168:171], v[120:123]
	v_mfma_f32_16x16x32_bf16 v[112:115], v[152:155], v[176:179], v[112:115]
	v_mfma_f32_16x16x32_bf16 v[104:107], v[160:163], v[176:179], v[104:107]
	v_mfma_f32_16x16x32_bf16 v[92:95], v[152:155], v[184:187], v[92:95]
	v_mfma_f32_16x16x32_bf16 v[88:91], v[160:163], v[184:187], v[88:91]
	v_mfma_f32_16x16x32_bf16 v[80:83], v[152:155], v[192:195], v[80:83]
	v_mfma_f32_16x16x32_bf16 v[72:75], v[160:163], v[192:195], v[72:75]
	v_mfma_f32_16x16x32_bf16 v[116:119], v[196:199], v[164:167], v[116:119]
	v_mfma_f32_16x16x32_bf16 v[108:111], v[204:207], v[164:167], v[108:111]
	v_mfma_f32_16x16x32_bf16 v[100:103], v[196:199], v[172:175], v[100:103]
	v_mfma_f32_16x16x32_bf16 v[96:99], v[204:207], v[172:175], v[96:99]
	v_mfma_f32_16x16x32_bf16 v[84:87], v[196:199], v[180:183], v[84:87]
	v_mfma_f32_16x16x32_bf16 v[76:79], v[204:207], v[180:183], v[76:79]
	v_mfma_f32_16x16x32_bf16 v[68:71], v[196:199], v[188:191], v[68:71]
	v_mfma_f32_16x16x32_bf16 v[64:67], v[204:207], v[188:191], v[64:67]
	v_mfma_f32_16x16x32_bf16 v[116:119], v[200:203], v[168:171], v[116:119]
	v_mfma_f32_16x16x32_bf16 v[108:111], v[208:211], v[168:171], v[108:111]
	v_mfma_f32_16x16x32_bf16 v[100:103], v[200:203], v[176:179], v[100:103]
	v_mfma_f32_16x16x32_bf16 v[96:99], v[208:211], v[176:179], v[96:99]
	v_mfma_f32_16x16x32_bf16 v[84:87], v[200:203], v[184:187], v[84:87]
	v_mfma_f32_16x16x32_bf16 v[76:79], v[208:211], v[184:187], v[76:79]
	v_mfma_f32_16x16x32_bf16 v[68:71], v[200:203], v[192:195], v[68:71]
	v_mfma_f32_16x16x32_bf16 v[64:67], v[208:211], v[192:195], v[64:67]
	s_setprio 0
	s_barrier
	s_nop 1
	ds_read_b128 v[164:167], v150 offset:16384
	ds_read_b128 v[168:171], v150 offset:17408
	ds_read_b128 v[172:175], v150 offset:18432
	ds_read_b128 v[176:179], v150 offset:19456
	ds_read_b128 v[180:183], v150 offset:20480
	ds_read_b128 v[184:187], v150 offset:21504
	ds_read_b128 v[188:191], v150 offset:22528
	ds_read_b128 v[192:195], v150 offset:23552
	s_add_i32 s77, s48, s7
	v_lshl_add_u64 v[144:145], s[40:41], 0, v[128:129]
	s_mov_b32 m0, s77
	s_nop 0
	global_load_lds_dwordx4 v[144:145], off
	v_lshl_add_u64 v[212:213], s[40:41], 0, v[130:131]
	s_add_i32 m0, s77, 0x2000
	s_nop 0
	global_load_lds_dwordx4 v[212:213], off
	s_mov_b32 m0, s8
	v_lshl_add_u64 v[214:215], s[42:43], 0, v[128:129]
	global_load_lds_dwordx4 v[214:215], off
	v_lshl_add_u64 v[216:217], s[42:43], 0, v[130:131]
	s_mov_b32 m0, s9
	s_nop 0
	global_load_lds_dwordx4 v[216:217], off
	s_add_u32 s78, s40, 0x40000
	s_addc_u32 s79, s41, 0
	s_add_i32 s77, s49, s7
	v_lshl_add_u64 v[254:255], s[78:79], 0, v[128:129]
	s_mov_b32 m0, s77
	s_nop 0
	global_load_lds_dwordx4 v[254:255], off
	v_lshl_add_u64 v[254:255], s[78:79], 0, v[130:131]
	s_add_i32 m0, s77, 0x2000
	s_nop 0
	global_load_lds_dwordx4 v[254:255], off
	s_waitcnt vmcnt(6)
	s_waitcnt lgkmcnt(0)
	s_barrier
; #define PG8_STAGE(bufoff, gbase, voff) do { _Pragma("unroll") for (int _i = 0; _i < 2; ++_i) \
;         __builtin_amdgcn_global_load_lds((const unsigned*)((const char*)(gbase) + (voff)[_i]), (LAS unsigned*)(lds + (bufoff) + ldsw + _i * 8192), 16, 0, 0); } while (0)
; #define PG8_LDA(dst, b, h) do { _Pragma("unroll") for (int m = 0; m < 4; ++m) _Pragma("unroll") for (int k = 0; k < 2; ++k) dst[m][k] = *(const LAS bf16x8*)(lds + PG8_SA(b, h) + aoff + m * 2048 + k * 1024); } while (0)
; #define PG8_LDB(dst, b, h) do { _Pragma("unroll") for (int n = 0; n < 2; ++n) _Pragma("unroll") for (int k = 0; k < 2; ++k) dst[n][k] = *(const LAS bf16x8*)(lds + PG8_SB(b, h) + boff + n * 2048 + k * 1024); } while (0)
; #define PG8_MMA(ai, bj, At, Bt) do { __builtin_amdgcn_s_setprio(1); _Pragma("unroll") for (int m = 0; m < 4; ++m) _Pragma("unroll") for (int n = 0; n < 2; ++n) _Pragma("unroll") for (int k = 0; k < 2; ++k) \
;         acc[ai][bj][m][n] = __builtin_amdgcn_mfma_f32_16x16x32_bf16(Bt[n][k], At[m][k], acc[ai][bj][m][n], 0, 0, 0); __builtin_amdgcn_s_setprio(0); } while (0)
; #define PG8_WAIT_V(n) asm volatile("s_waitcnt vmcnt(" #n ")" ::: "memory")
; #define PG8_WAIT_L(n) asm volatile("s_waitcnt lgkmcnt(" #n ")" ::: "memory")
; #define PG8_BAR __builtin_amdgcn_s_barrier()
; #define PG8_SCHED __builtin_amdgcn_sched_barrier(0)
; template <class Epi>
; __device__ __forceinline__ void gemm_phase(LAS unsigned char* lds, const Gemm g, const StaticOrder& S, const Epi& E) {
;     ...
;             PG8_WAIT_V(6); PG8_BAR; PG8_MMA(1, 1, At, B1); PG8_BAR;
;             PG8_LDB(B0, 1, 0); PG8_SCHED; PG8_LDA(At, 1, 0); PG8_STAGE(PG8_SA(0, 1), a2 + hstepA, voffA);
;             PG8_WAIT_L(8); PG8_BAR; PG8_WAIT_L(0); PG8_MMA(0, 0, At, B0); PG8_BAR; PG8_SCHED;
;             PG8_LDB(B1, 1, 1); PG8_STAGE(PG8_SB(1, 0), b3, voffB);
;             PG8_BAR; PG8_WAIT_L(0); PG8_MMA(0, 1, At, B1); PG8_BAR;
;             PG8_LDA(At, 1, 1); PG8_STAGE(PG8_SA(1, 0), a3, voffA);
;             PG8_BAR; PG8_WAIT_L(0); PG8_MMA(1, 0, At, B0); PG8_BAR; PG8_SCHED;
	s_setprio 1
	v_mfma_f32_16x16x32_bf16 v[60:63], v[140:143], v[164:167], v[60:63]
	v_mfma_f32_16x16x32_bf16 v[56:59], v[156:159], v[164:167], v[56:59]
	v_mfma_f32_16x16x32_bf16 v[48:51], v[140:143], v[172:175], v[48:51]
	v_mfma_f32_16x16x32_bf16 v[40:43], v[156:159], v[172:175], v[40:43]
	v_mfma_f32_16x16x32_bf16 v[28:31], v[140:143], v[180:183], v[28:31]
	v_mfma_f32_16x16x32_bf16 v[24:27], v[156:159], v[180:183], v[24:27]
	v_mfma_f32_16x16x32_bf16 v[16:19], v[140:143], v[188:191], v[16:19]
	v_mfma_f32_16x16x32_bf16 v[8:11], v[156:159], v[188:191], v[8:11]
	v_mfma_f32_16x16x32_bf16 v[60:63], v[152:155], v[168:171], v[60:63]
	v_mfma_f32_16x16x32_bf16 v[56:59], v[160:163], v[168:171], v[56:59]
	v_mfma_f32_16x16x32_bf16 v[48:51], v[152:155], v[176:179], v[48:51]
	v_mfma_f32_16x16x32_bf16 v[40:43], v[160:163], v[176:179], v[40:43]
	v_mfma_f32_16x16x32_bf16 v[28:31], v[152:155], v[184:187], v[28:31]
	v_mfma_f32_16x16x32_bf16 v[24:27], v[160:163], v[184:187], v[24:27]
	v_mfma_f32_16x16x32_bf16 v[16:19], v[152:155], v[192:195], v[16:19]
	v_mfma_f32_16x16x32_bf16 v[8:11], v[160:163], v[192:195], v[8:11]
	v_mfma_f32_16x16x32_bf16 v[52:55], v[196:199], v[164:167], v[52:55]
	v_mfma_f32_16x16x32_bf16 v[44:47], v[204:207], v[164:167], v[44:47]
	v_mfma_f32_16x16x32_bf16 v[36:39], v[196:199], v[172:175], v[36:39]
	v_mfma_f32_16x16x32_bf16 v[32:35], v[204:207], v[172:175], v[32:35]
	v_mfma_f32_16x16x32_bf16 v[20:23], v[196:199], v[180:183], v[20:23]
	v_mfma_f32_16x16x32_bf16 v[12:15], v[204:207], v[180:183], v[12:15]
	v_mfma_f32_16x16x32_bf16 v[4:7], v[196:199], v[188:191], v[4:7]
	v_mfma_f32_16x16x32_bf16 v[0:3], v[204:207], v[188:191], v[0:3]
	v_mfma_f32_16x16x32_bf16 v[52:55], v[200:203], v[168:171], v[52:55]
	v_mfma_f32_16x16x32_bf16 v[44:47], v[208:211], v[168:171], v[44:47]
	v_mfma_f32_16x16x32_bf16 v[36:39], v[200:203], v[176:179], v[36:39]
	v_mfma_f32_16x16x32_bf16 v[32:35], v[208:211], v[176:179], v[32:35]
	v_mfma_f32_16x16x32_bf16 v[20:23], v[200:203], v[184:187], v[20:23]
	v_mfma_f32_16x16x32_bf16 v[12:15], v[208:211], v[184:187], v[12:15]
	v_mfma_f32_16x16x32_bf16 v[4:7], v[200:203], v[192:195], v[4:7]
	v_mfma_f32_16x16x32_bf16 v[0:3], v[208:211], v[192:195], v[0:3]
	s_setprio 0
	s_add_i32 s77, 0, 0x18000
	v_add_u32_e32 v160, s77, v147
	s_barrier
	ds_read_b128 v[140:143], v160
	ds_read_b128 v[152:155], v160 offset:1024
	ds_read_b128 v[156:159], v160 offset:2048
	ds_read_b128 v[160:163], v160 offset:3072
	s_add_u32 s42, s42, 0x40000
	s_addc_u32 s43, s43, 0
	s_mov_b32 m0, s37
	v_lshl_add_u64 v[196:197], s[42:43], 0, v[128:129]
	ds_read_b128 v[164:167], v150 offset:32768
	ds_read_b128 v[168:171], v150 offset:33792
	ds_read_b128 v[172:175], v150 offset:34816
	ds_read_b128 v[176:179], v150 offset:35840
	ds_read_b128 v[180:183], v150 offset:36864
	ds_read_b128 v[184:187], v150 offset:37888
	ds_read_b128 v[188:191], v150 offset:38912
	ds_read_b128 v[192:195], v150 offset:39936
	global_load_lds_dwordx4 v[196:197], off
	v_lshl_add_u64 v[196:197], s[42:43], 0, v[130:131]
	s_mov_b32 m0, s44
	s_nop 0
	global_load_lds_dwordx4 v[196:197], off
	s_add_i32 s42, 0, 0x1c000
	v_add_u32_e32 v208, s42, v147
	ds_read_b128 v[196:199], v208
	ds_read_b128 v[200:203], v208 offset:1024
	ds_read_b128 v[204:207], v208 offset:2048
	ds_read_b128 v[208:211], v208 offset:3072
	s_waitcnt lgkmcnt(0)
	s_barrier
	s_setprio 1
	v_mfma_f32_16x16x32_bf16 v[124:127], v[140:143], v[164:167], v[124:127]
	v_mfma_f32_16x16x32_bf16 v[120:123], v[156:159], v[164:167], v[120:123]
	v_mfma_f32_16x16x32_bf16 v[112:115], v[140:143], v[172:175], v[112:115]
	v_mfma_f32_16x16x32_bf16 v[104:107], v[156:159], v[172:175], v[104:107]
	v_mfma_f32_16x16x32_bf16 v[92:95], v[140:143], v[180:183], v[92:95]
	v_mfma_f32_16x16x32_bf16 v[88:91], v[156:159], v[180:183], v[88:91]
	v_mfma_f32_16x16x32_bf16 v[80:83], v[140:143], v[188:191], v[80:83]
	v_mfma_f32_16x16x32_bf16 v[72:75], v[156:159], v[188:191], v[72:75]
	v_mfma_f32_16x16x32_bf16 v[124:127], v[152:155], v[168:171], v[124:127]
	v_mfma_f32_16x16x32_bf16 v[120:123], v[160:163], v[168:171], v[120:123]
	v_mfma_f32_16x16x32_bf16 v[112:115], v[152:155], v[176:179], v[112:115]
	v_mfma_f32_16x16x32_bf16 v[104:107], v[160:163], v[176:179], v[104:107]
	v_mfma_f32_16x16x32_bf16 v[92:95], v[152:155], v[184:187], v[92:95]
	v_mfma_f32_16x16x32_bf16 v[88:91], v[160:163], v[184:187], v[88:91]
	v_mfma_f32_16x16x32_bf16 v[80:83], v[152:155], v[192:195], v[80:83]
	v_mfma_f32_16x16x32_bf16 v[72:75], v[160:163], v[192:195], v[72:75]
	v_mfma_f32_16x16x32_bf16 v[116:119], v[196:199], v[164:167], v[116:119]
	v_mfma_f32_16x16x32_bf16 v[108:111], v[204:207], v[164:167], v[108:111]
	v_mfma_f32_16x16x32_bf16 v[100:103], v[196:199], v[172:175], v[100:103]
	v_mfma_f32_16x16x32_bf16 v[96:99], v[204:207], v[172:175], v[96:99]
	v_mfma_f32_16x16x32_bf16 v[84:87], v[196:199], v[180:183], v[84:87]
	v_mfma_f32_16x16x32_bf16 v[76:79], v[204:207], v[180:183], v[76:79]
	v_mfma_f32_16x16x32_bf16 v[68:71], v[196:199], v[188:191], v[68:71]
	v_mfma_f32_16x16x32_bf16 v[64:67], v[204:207], v[188:191], v[64:67]
	v_mfma_f32_16x16x32_bf16 v[116:119], v[200:203], v[168:171], v[116:119]
	v_mfma_f32_16x16x32_bf16 v[108:111], v[208:211], v[168:171], v[108:111]
	v_mfma_f32_16x16x32_bf16 v[100:103], v[200:203], v[176:179], v[100:103]
	v_mfma_f32_16x16x32_bf16 v[96:99], v[208:211], v[176:179], v[96:99]
	v_mfma_f32_16x16x32_bf16 v[84:87], v[200:203], v[184:187], v[84:87]
	v_mfma_f32_16x16x32_bf16 v[76:79], v[208:211], v[184:187], v[76:79]
	v_mfma_f32_16x16x32_bf16 v[68:71], v[200:203], v[192:195], v[68:71]
	v_mfma_f32_16x16x32_bf16 v[64:67], v[208:211], v[192:195], v[64:67]
	s_setprio 0
	s_barrier
; #define PG8_STAGE(bufoff, gbase, voff) do { _Pragma("unroll") for (int _i = 0; _i < 2; ++_i) \
;         __builtin_amdgcn_global_load_lds((const unsigned*)((const char*)(gbase) + (voff)[_i]), (LAS unsigned*)(lds + (bufoff) + ldsw + _i * 8192), 16, 0, 0); } while (0)
; #define PG8_LDA(dst, b, h) do { _Pragma("unroll") for (int m = 0; m < 4; ++m) _Pragma("unroll") for (int k = 0; k < 2; ++k) dst[m][k] = *(const LAS bf16x8*)(lds + PG8_SA(b, h) + aoff + m * 2048 + k * 1024); } while (0)
; #define PG8_LDB(dst, b, h) do { _Pragma("unroll") for (int n = 0; n < 2; ++n) _Pragma("unroll") for (int k = 0; k < 2; ++k) dst[n][k] = *(const LAS bf16x8*)(lds + PG8_SB(b, h) + boff + n * 2048 + k * 1024); } while (0)
; template <class Epi>
; __device__ __forceinline__ void gemm_phase(LAS unsigned char* lds, const Gemm g, const StaticOrder& S, const Epi& E) {
;     ...
;             PG8_LDB(B1, 1, 1); PG8_STAGE(PG8_SB(1, 0), b3, voffB);
;             PG8_BAR; PG8_WAIT_L(0); PG8_MMA(0, 1, At, B1); PG8_BAR;
;             PG8_LDA(At, 1, 1); PG8_STAGE(PG8_SA(1, 0), a3, voffA);
;             PG8_BAR; PG8_WAIT_L(0); PG8_MMA(1, 0, At, B0); PG8_BAR; PG8_SCHED;
;             PG8_STAGE(PG8_SB(1, 1), b3 + hstepB, voffB);
;             PG8_WAIT_V(6); PG8_BAR; PG8_MMA(1, 1, At, B1); PG8_BAR;
;     __device__ __forceinline__ void operator()(AccRef acc, const Unit& u, int wr, int wc, int fr, int fq) const {
;         const int row0 = u.pm * 256 + wr * 64 + fr, col0 = u.pn * 256 + wc * 32 + 4 * fq;
;         f32x4 sv[2][2], bv[2][2];
; #pragma unroll
;         for (int bj = 0; bj < 2; ++bj)
; #pragma unroll
;             for (int n = 0; n < 2; ++n) {
;                 sv[bj][n] = scale ? *(const f32x4*)(scale + col0 + bj * 128 + n * 16) : (f32x4){1.f, 1.f, 1.f, 1.f};
;                 bv[bj][n] = bias ? *(const f32x4*)(bias + col0 + bj * 128 + n * 16) : (f32x4){0.f, 0.f, 0.f, 0.f}; }
; #pragma unroll
;         for (int ai = 0; ai < 2; ++ai)
; #pragma unroll
;             for (int mh = 0; mh < 2; ++mh) {
;                 f32x4 bs[2][2][2];
; #pragma unroll
;                 for (int m = 0; m < 2; ++m)
; #pragma unroll
;                     for (int bj = 0; bj < 2; ++bj)
; #pragma unroll
;                         for (int n = 0; n < 2; ++n) bs[m][bj][n] = *(const f32x4*)(base + (size_t)(row0 + ai * 128 + (2 * mh + m) * 16) * D + col0 + bj * 128 + n * 16);
	s_nop 1
	ds_read_b128 v[164:167], v150 offset:49152
	ds_read_b128 v[168:171], v150 offset:50176
	ds_read_b128 v[172:175], v150 offset:51200
	ds_read_b128 v[176:179], v150 offset:52224
	ds_read_b128 v[180:183], v150 offset:53248
	ds_read_b128 v[184:187], v150 offset:54272
	ds_read_b128 v[188:191], v150 offset:55296
	ds_read_b128 v[192:195], v150 offset:56320
	s_add_i32 s43, s77, s7
	v_lshl_add_u64 v[254:255], v[144:145], 0, s[12:13]
	s_mov_b32 m0, s43
	s_nop 0
	global_load_lds_dwordx4 v[254:255], off
	v_lshl_add_u64 v[254:255], v[212:213], 0, s[12:13]
	s_add_i32 m0, s43, 0x2000
	s_nop 0
	global_load_lds_dwordx4 v[254:255], off
	s_mov_b32 m0, s46
	v_lshl_add_u64 v[254:255], v[214:215], 0, s[12:13]
	global_load_lds_dwordx4 v[254:255], off
	v_lshl_add_u64 v[144:145], v[216:217], 0, s[12:13]
	s_mov_b32 m0, s47
	s_nop 0
	global_load_lds_dwordx4 v[144:145], off
	s_add_u32 s40, s40, 0x40080
	s_addc_u32 s41, s41, 0
	s_add_i32 s42, s42, s7
	v_lshl_add_u64 v[254:255], s[40:41], 0, v[128:129]
	s_mov_b32 m0, s42
	s_nop 0
	global_load_lds_dwordx4 v[254:255], off
	v_lshl_add_u64 v[254:255], s[40:41], 0, v[130:131]
	s_add_i32 m0, s42, 0x2000
	s_nop 0
	global_load_lds_dwordx4 v[254:255], off
	s_waitcnt vmcnt(6)
	s_waitcnt lgkmcnt(0)
	s_barrier
	s_setprio 1
	v_mfma_f32_16x16x32_bf16 v[60:63], v[140:143], v[164:167], v[60:63]
	v_mfma_f32_16x16x32_bf16 v[56:59], v[156:159], v[164:167], v[56:59]
	v_mfma_f32_16x16x32_bf16 v[48:51], v[140:143], v[172:175], v[48:51]
	v_mfma_f32_16x16x32_bf16 v[40:43], v[156:159], v[172:175], v[40:43]
	v_mfma_f32_16x16x32_bf16 v[28:31], v[140:143], v[180:183], v[28:31]
	v_mfma_f32_16x16x32_bf16 v[24:27], v[156:159], v[180:183], v[24:27]
	v_mfma_f32_16x16x32_bf16 v[16:19], v[140:143], v[188:191], v[16:19]
	v_mfma_f32_16x16x32_bf16 v[8:11], v[156:159], v[188:191], v[8:11]
	v_mfma_f32_16x16x32_bf16 v[60:63], v[152:155], v[168:171], v[60:63]
	v_mfma_f32_16x16x32_bf16 v[56:59], v[160:163], v[168:171], v[56:59]
	v_mfma_f32_16x16x32_bf16 v[48:51], v[152:155], v[176:179], v[48:51]
	v_mfma_f32_16x16x32_bf16 v[40:43], v[160:163], v[176:179], v[40:43]
	v_mfma_f32_16x16x32_bf16 v[28:31], v[152:155], v[184:187], v[28:31]
	v_mfma_f32_16x16x32_bf16 v[24:27], v[160:163], v[184:187], v[24:27]
	v_mfma_f32_16x16x32_bf16 v[16:19], v[152:155], v[192:195], v[16:19]
	v_mfma_f32_16x16x32_bf16 v[8:11], v[160:163], v[192:195], v[8:11]
	v_mfma_f32_16x16x32_bf16 v[52:55], v[196:199], v[164:167], v[52:55]
	v_mfma_f32_16x16x32_bf16 v[44:47], v[204:207], v[164:167], v[44:47]
	v_mfma_f32_16x16x32_bf16 v[36:39], v[196:199], v[172:175], v[36:39]
	v_mfma_f32_16x16x32_bf16 v[32:35], v[204:207], v[172:175], v[32:35]
	v_mfma_f32_16x16x32_bf16 v[20:23], v[196:199], v[180:183], v[20:23]
	v_mfma_f32_16x16x32_bf16 v[12:15], v[204:207], v[180:183], v[12:15]
	v_mfma_f32_16x16x32_bf16 v[4:7], v[196:199], v[188:191], v[4:7]
	v_mfma_f32_16x16x32_bf16 v[0:3], v[204:207], v[188:191], v[0:3]
	v_mfma_f32_16x16x32_bf16 v[52:55], v[200:203], v[168:171], v[52:55]
	v_mfma_f32_16x16x32_bf16 v[44:47], v[208:211], v[168:171], v[44:47]
	v_mfma_f32_16x16x32_bf16 v[36:39], v[200:203], v[176:179], v[36:39]
	v_mfma_f32_16x16x32_bf16 v[32:35], v[208:211], v[176:179], v[32:35]
	v_mfma_f32_16x16x32_bf16 v[20:23], v[200:203], v[184:187], v[20:23]
	v_mfma_f32_16x16x32_bf16 v[12:15], v[208:211], v[184:187], v[12:15]
	v_mfma_f32_16x16x32_bf16 v[4:7], v[200:203], v[192:195], v[4:7]
	v_mfma_f32_16x16x32_bf16 v[0:3], v[208:211], v[192:195], v[0:3]
	s_setprio 0
	s_add_i32 s76, s76, 2
	s_add_u32 s38, s38, 0x100
	s_addc_u32 s39, s39, 0
	s_add_u32 s74, s74, 0x100
	s_addc_u32 s75, s75, 0
	s_cmp_gt_u32 s76, 13
	s_barrier
	s_cbranch_scc0 .LBB0_1239
	v_lshl_or_b32 v140, s63, 8, v148
	v_ashrrev_i32_e32 v141, 31, v140
	v_lshl_add_u32 v184, s36, 8, v146
	v_lshlrev_b64 v[140:141], 2, v[140:141]
	v_ashrrev_i32_e32 v185, 31, v184
	v_or_b32_e32 v168, 16, v184
	v_lshl_add_u64 v[142:143], s[52:53], 0, v[140:141]
	v_lshlrev_b64 v[144:145], 12, v[184:185]
	v_ashrrev_i32_e32 v169, 31, v168
	v_lshl_add_u64 v[164:165], v[142:143], 0, v[144:145]
	v_lshlrev_b64 v[186:187], 12, v[168:169]
	global_load_dwordx4 v[152:155], v[164:165], off
	global_load_dwordx4 v[156:159], v[164:165], off offset:64
	global_load_dwordx4 v[160:163], v[164:165], off offset:512
	s_nop 0
	global_load_dwordx4 v[164:167], v[164:165], off offset:576
	v_lshl_add_u64 v[180:181], v[142:143], 0, v[186:187]
	global_load_dwordx4 v[168:171], v[180:181], off
	global_load_dwordx4 v[172:175], v[180:181], off offset:64
	global_load_dwordx4 v[176:179], v[180:181], off offset:512
	s_nop 0
	global_load_dwordx4 v[180:183], v[180:181], off offset:576
	v_pk_add_f32 v[198:199], v[96:97], 0 op_sel_hi:[1,0]
	v_or_b32_e32 v96, 32, v184
	v_ashrrev_i32_e32 v97, 31, v96
	v_pk_add_f32 v[126:127], v[126:127], 0 op_sel_hi:[1,0]
	v_pk_add_f32 v[124:125], v[124:125], 0 op_sel_hi:[1,0]
	v_pk_add_f32 v[108:109], v[108:109], 0 op_sel_hi:[1,0]
	v_pk_add_f32 v[196:197], v[98:99], 0 op_sel_hi:[1,0]
	v_lshl_add_u64 v[98:99], s[52:53], 0, v[144:145]
	v_lshlrev_b64 v[200:201], 12, v[96:97]
	v_lshl_add_u64 v[96:97], s[52:53], 0, v[186:187]
	v_pk_add_f32 v[122:123], v[122:123], 0 op_sel_hi:[1,0]
	v_pk_add_f32 v[120:121], v[120:121], 0 op_sel_hi:[1,0]
	v_pk_add_f32 v[118:119], v[118:119], 0 op_sel_hi:[1,0]
	v_pk_add_f32 v[116:117], v[116:117], 0 op_sel_hi:[1,0]
	v_pk_add_f32 v[110:111], v[110:111], 0 op_sel_hi:[1,0]
	v_pk_add_f32 v[114:115], v[114:115], 0 op_sel_hi:[1,0]
	v_pk_add_f32 v[112:113], v[112:113], 0 op_sel_hi:[1,0]
	v_pk_add_f32 v[188:189], v[106:107], 0 op_sel_hi:[1,0]
	v_pk_add_f32 v[190:191], v[104:105], 0 op_sel_hi:[1,0]
	v_pk_add_f32 v[192:193], v[102:103], 0 op_sel_hi:[1,0]
;     __device__ __forceinline__ void operator()(AccRef acc, const Unit& u, int wr, int wc, int fr, int fq) const {
;     ...
;         for (int ai = 0; ai < 2; ++ai)
; #pragma unroll
;             for (int mh = 0; mh < 2; ++mh) {
;                 f32x4 bs[2][2][2];
; #pragma unroll
;                 for (int m = 0; m < 2; ++m)
; #pragma unroll
;                     for (int bj = 0; bj < 2; ++bj)
; #pragma unroll
;                         for (int n = 0; n < 2; ++n) bs[m][bj][n] = *(const f32x4*)(base + (size_t)(row0 + ai * 128 + (2 * mh + m) * 16) * D + col0 + bj * 128 + n * 16);
; #pragma unroll
;                 for (int m = 0; m < 2; ++m)
; #pragma unroll
;                     for (int bj = 0; bj < 2; ++bj)
; #pragma unroll
;                         for (int n = 0; n < 2; ++n) *(f32x4*)(out + (size_t)(row0 + ai * 128 + (2 * mh + m) * 16) * D + col0 + bj * 128 + n * 16) = bs[m][bj][n] + sv[bj][n] * (acc[ai][bj][2 * mh + m][n] + bv[bj][n]);
;                 asm volatile("" ::: "memory"); }
	v_pk_add_f32 v[194:195], v[100:101], 0 op_sel_hi:[1,0]
	v_lshl_add_u64 v[202:203], v[98:99], 0, v[140:141]
	v_lshl_add_u64 v[204:205], v[96:97], 0, v[140:141]
	v_lshl_add_u64 v[186:187], v[142:143], 0, v[200:201]
	v_pk_add_f32 v[94:95], v[94:95], 0 op_sel_hi:[1,0]
	v_pk_add_f32 v[92:93], v[92:93], 0 op_sel_hi:[1,0]
	v_pk_add_f32 v[90:91], v[90:91], 0 op_sel_hi:[1,0]
	v_pk_add_f32 v[88:89], v[88:89], 0 op_sel_hi:[1,0]
	v_pk_add_f32 v[86:87], v[86:87], 0 op_sel_hi:[1,0]
	v_pk_add_f32 v[84:85], v[84:85], 0 op_sel_hi:[1,0]
	v_pk_add_f32 v[78:79], v[78:79], 0 op_sel_hi:[1,0]
	v_pk_add_f32 v[76:77], v[76:77], 0 op_sel_hi:[1,0]
	v_pk_add_f32 v[82:83], v[82:83], 0 op_sel_hi:[1,0]
	v_pk_add_f32 v[80:81], v[80:81], 0 op_sel_hi:[1,0]
	v_pk_add_f32 v[62:63], v[62:63], 0 op_sel_hi:[1,0]
	v_pk_add_f32 v[60:61], v[60:61], 0 op_sel_hi:[1,0]
	v_pk_add_f32 v[58:59], v[58:59], 0 op_sel_hi:[1,0]
	v_pk_add_f32 v[56:57], v[56:57], 0 op_sel_hi:[1,0]
	v_pk_add_f32 v[54:55], v[54:55], 0 op_sel_hi:[1,0]
	v_pk_add_f32 v[52:53], v[52:53], 0 op_sel_hi:[1,0]
	v_pk_add_f32 v[46:47], v[46:47], 0 op_sel_hi:[1,0]
	v_pk_add_f32 v[44:45], v[44:45], 0 op_sel_hi:[1,0]
	v_pk_add_f32 v[50:51], v[50:51], 0 op_sel_hi:[1,0]
	v_pk_add_f32 v[48:49], v[48:49], 0 op_sel_hi:[1,0]
	v_pk_add_f32 v[30:31], v[30:31], 0 op_sel_hi:[1,0]
	v_pk_add_f32 v[28:29], v[28:29], 0 op_sel_hi:[1,0]
	v_pk_add_f32 v[26:27], v[26:27], 0 op_sel_hi:[1,0]
	v_pk_add_f32 v[24:25], v[24:25], 0 op_sel_hi:[1,0]
	v_pk_add_f32 v[22:23], v[22:23], 0 op_sel_hi:[1,0]
	v_pk_add_f32 v[20:21], v[20:21], 0 op_sel_hi:[1,0]
	v_pk_add_f32 v[14:15], v[14:15], 0 op_sel_hi:[1,0]
	v_pk_add_f32 v[12:13], v[12:13], 0 op_sel_hi:[1,0]
	v_pk_add_f32 v[18:19], v[18:19], 0 op_sel_hi:[1,0]
	v_pk_add_f32 v[16:17], v[16:17], 0 op_sel_hi:[1,0]
	s_and_b64 vcc, exec, s[10:11]
	s_mov_b32 s63, s26
	s_mov_b32 s36, s28
	s_mov_b64 s[40:41], s[34:35]
	s_mov_b64 s[38:39], s[30:31]
	s_waitcnt vmcnt(0)
	v_pk_add_f32 v[98:99], v[126:127], v[154:155]
	v_pk_add_f32 v[96:97], v[124:125], v[152:153]
	v_pk_add_f32 v[102:103], v[122:123], v[158:159]
	v_pk_add_f32 v[108:109], v[108:109], v[164:165]
	v_pk_add_f32 v[100:101], v[120:121], v[156:157]
	v_pk_add_f32 v[106:107], v[118:119], v[162:163]
	v_pk_add_f32 v[104:105], v[116:117], v[160:161]
	v_pk_add_f32 v[110:111], v[110:111], v[166:167]
	v_pk_add_f32 v[114:115], v[114:115], v[170:171]
	v_pk_add_f32 v[112:113], v[112:113], v[168:169]
	v_pk_add_f32 v[118:119], v[188:189], v[174:175]
	v_pk_add_f32 v[116:117], v[190:191], v[172:173]
	v_pk_add_f32 v[122:123], v[192:193], v[178:179]
	v_pk_add_f32 v[120:121], v[194:195], v[176:177]
	v_pk_add_f32 v[126:127], v[196:197], v[182:183]
	v_pk_add_f32 v[124:125], v[198:199], v[180:181]
	global_store_dwordx4 v[202:203], v[96:99], off
	global_store_dwordx4 v[202:203], v[100:103], off offset:64
	global_store_dwordx4 v[202:203], v[104:107], off offset:512
	global_store_dwordx4 v[202:203], v[108:111], off offset:576
	global_store_dwordx4 v[204:205], v[112:115], off
	global_store_dwordx4 v[204:205], v[116:119], off offset:64
	global_store_dwordx4 v[204:205], v[120:123], off offset:512
	global_store_dwordx4 v[204:205], v[124:127], off offset:576
	v_or_b32_e32 v108, 48, v184
	v_ashrrev_i32_e32 v109, 31, v108
	v_lshlrev_b64 v[152:153], 12, v[108:109]
	global_load_dwordx4 v[96:99], v[186:187], off
	global_load_dwordx4 v[100:103], v[186:187], off offset:64
	v_lshl_add_u64 v[124:125], v[142:143], 0, v[152:153]
	global_load_dwordx4 v[104:107], v[186:187], off offset:512
	global_load_dwordx4 v[108:111], v[186:187], off offset:576
	global_load_dwordx4 v[112:115], v[124:125], off
	global_load_dwordx4 v[116:119], v[124:125], off offset:64
	global_load_dwordx4 v[120:123], v[124:125], off offset:512
	s_nop 0
	global_load_dwordx4 v[124:127], v[124:125], off offset:576
	v_pk_add_f32 v[162:163], v[66:67], 0 op_sel_hi:[1,0]
	v_pk_add_f32 v[164:165], v[64:65], 0 op_sel_hi:[1,0]
	v_lshl_add_u64 v[64:65], s[52:53], 0, v[200:201]
	v_lshl_add_u64 v[66:67], s[52:53], 0, v[152:153]
	v_pk_add_f32 v[154:155], v[74:75], 0 op_sel_hi:[1,0]
	v_pk_add_f32 v[156:157], v[72:73], 0 op_sel_hi:[1,0]
	v_pk_add_f32 v[158:159], v[70:71], 0 op_sel_hi:[1,0]
	v_pk_add_f32 v[160:161], v[68:69], 0 op_sel_hi:[1,0]
	v_lshl_add_u64 v[168:169], v[64:65], 0, v[140:141]
	v_lshl_add_u64 v[170:171], v[66:67], 0, v[140:141]
	v_lshl_add_u64 v[166:167], v[144:145], 0, s[14:15]
	v_lshl_add_u64 v[152:153], v[142:143], 0, v[166:167]
	s_waitcnt vmcnt(0)
; #define PG8_WAIT_V(n) asm volatile("s_waitcnt vmcnt(" #n ")" ::: "memory")
; #define PG8_BAR __builtin_amdgcn_s_barrier()
; template <class Epi>
; __device__ __forceinline__ void gemm_phase(LAS unsigned char* lds, const Gemm g, const StaticOrder& S, const Epi& E) {
;     ...
;         if (!has_next) break;
;         {
; #pragma unroll
;         for (int a = 0; a < 2; ++a)
; #pragma unroll
;             for (int b = 0; b < 2; ++b)
; #pragma unroll
;                 for (int m = 0; m < 4; ++m)
; #pragma unroll
;                     for (int n = 0; n < 2; ++n) acc[a][b][m][n] = (f32x4){0.f, 0.f, 0.f, 0.f};
;         }
;         cur = nxt; cA = nA; cB = nB; ++ui;
;     }
;     PG8_WAIT_V(0);
;     if (wr == 0) PG8_BAR;
;     PG8_BAR;
;     __device__ __forceinline__ void operator()(AccRef acc, const Unit& u, int wr, int wc, int fr, int fq) const {
;     ...
;                         for (int n = 0; n < 2; ++n) bs[m][bj][n] = *(const f32x4*)(base + (size_t)(row0 + ai * 128 + (2 * mh + m) * 16) * D + col0 + bj * 128 + n * 16);
; #pragma unroll
;                 for (int m = 0; m < 2; ++m)
; #pragma unroll
;                     for (int bj = 0; bj < 2; ++bj)
; #pragma unroll
;                         for (int n = 0; n < 2; ++n) *(f32x4*)(out + (size_t)(row0 + ai * 128 + (2 * mh + m) * 16) * D + col0 + bj * 128 + n * 16) = bs[m][bj][n] + sv[bj][n] * (acc[ai][bj][2 * mh + m][n] + bv[bj][n]);
;                 asm volatile("" ::: "memory"); }
	v_pk_add_f32 v[66:67], v[94:95], v[98:99]
	v_pk_add_f32 v[64:65], v[92:93], v[96:97]
	v_pk_add_f32 v[70:71], v[90:91], v[102:103]
	v_pk_add_f32 v[68:69], v[88:89], v[100:101]
	v_pk_add_f32 v[74:75], v[86:87], v[106:107]
	v_pk_add_f32 v[72:73], v[84:85], v[104:105]
	v_pk_add_f32 v[78:79], v[78:79], v[110:111]
	v_pk_add_f32 v[76:77], v[76:77], v[108:109]
	v_pk_add_f32 v[82:83], v[82:83], v[114:115]
	v_pk_add_f32 v[80:81], v[80:81], v[112:113]
	v_pk_add_f32 v[86:87], v[154:155], v[118:119]
	v_pk_add_f32 v[84:85], v[156:157], v[116:117]
	v_pk_add_f32 v[90:91], v[158:159], v[122:123]
	v_pk_add_f32 v[88:89], v[160:161], v[120:121]
	v_pk_add_f32 v[94:95], v[162:163], v[126:127]
	v_pk_add_f32 v[92:93], v[164:165], v[124:125]
	global_store_dwordx4 v[168:169], v[64:67], off
	global_store_dwordx4 v[168:169], v[68:71], off offset:64
	global_store_dwordx4 v[168:169], v[72:75], off offset:512
	global_store_dwordx4 v[168:169], v[76:79], off offset:576
	global_store_dwordx4 v[170:171], v[80:83], off
	global_store_dwordx4 v[170:171], v[84:87], off offset:64
	global_store_dwordx4 v[170:171], v[88:91], off offset:512
	global_store_dwordx4 v[170:171], v[92:95], off offset:576
	v_lshl_add_u64 v[96:97], v[144:145], 0, s[16:17]
	global_load_dwordx4 v[64:67], v[152:153], off
	global_load_dwordx4 v[68:71], v[152:153], off offset:64
	global_load_dwordx4 v[72:75], v[152:153], off offset:512
	v_lshl_add_u64 v[92:93], v[142:143], 0, v[96:97]
	global_load_dwordx4 v[76:79], v[152:153], off offset:576
	global_load_dwordx4 v[80:83], v[92:93], off
	global_load_dwordx4 v[84:87], v[92:93], off offset:64
	global_load_dwordx4 v[88:91], v[92:93], off offset:512
	s_nop 0
	global_load_dwordx4 v[92:95], v[92:93], off offset:576
	v_pk_add_f32 v[106:107], v[34:35], 0 op_sel_hi:[1,0]
	v_pk_add_f32 v[108:109], v[32:33], 0 op_sel_hi:[1,0]
	v_lshl_add_u64 v[32:33], s[52:53], 0, v[166:167]
	v_lshl_add_u64 v[34:35], s[52:53], 0, v[96:97]
	v_pk_add_f32 v[98:99], v[42:43], 0 op_sel_hi:[1,0]
	v_pk_add_f32 v[100:101], v[40:41], 0 op_sel_hi:[1,0]
	v_pk_add_f32 v[102:103], v[38:39], 0 op_sel_hi:[1,0]
	v_pk_add_f32 v[104:105], v[36:37], 0 op_sel_hi:[1,0]
	v_lshl_add_u64 v[112:113], v[32:33], 0, v[140:141]
	v_lshl_add_u64 v[114:115], v[34:35], 0, v[140:141]
	v_lshl_add_u64 v[110:111], v[144:145], 0, s[22:23]
	v_lshl_add_u64 v[96:97], v[142:143], 0, v[110:111]
	s_waitcnt vmcnt(0)
	v_pk_add_f32 v[34:35], v[62:63], v[66:67]
	v_pk_add_f32 v[32:33], v[60:61], v[64:65]
	v_pk_add_f32 v[38:39], v[58:59], v[70:71]
	v_pk_add_f32 v[36:37], v[56:57], v[68:69]
	v_pk_add_f32 v[42:43], v[54:55], v[74:75]
	v_pk_add_f32 v[40:41], v[52:53], v[72:73]
	v_pk_add_f32 v[46:47], v[46:47], v[78:79]
	v_pk_add_f32 v[44:45], v[44:45], v[76:77]
	v_pk_add_f32 v[50:51], v[50:51], v[82:83]
	v_pk_add_f32 v[48:49], v[48:49], v[80:81]
	v_pk_add_f32 v[54:55], v[98:99], v[86:87]
	v_pk_add_f32 v[52:53], v[100:101], v[84:85]
	v_pk_add_f32 v[58:59], v[102:103], v[90:91]
	v_pk_add_f32 v[56:57], v[104:105], v[88:89]
	v_pk_add_f32 v[62:63], v[106:107], v[94:95]
	v_pk_add_f32 v[60:61], v[108:109], v[92:93]
	global_store_dwordx4 v[112:113], v[32:35], off
	global_store_dwordx4 v[112:113], v[36:39], off offset:64
	global_store_dwordx4 v[112:113], v[40:43], off offset:512
	global_store_dwordx4 v[112:113], v[44:47], off offset:576
	global_store_dwordx4 v[114:115], v[48:51], off
	global_store_dwordx4 v[114:115], v[52:55], off offset:64
	global_store_dwordx4 v[114:115], v[56:59], off offset:512
	global_store_dwordx4 v[114:115], v[60:63], off offset:576
	v_lshl_add_u64 v[64:65], v[144:145], 0, s[24:25]
	global_load_dwordx4 v[32:35], v[96:97], off
	global_load_dwordx4 v[36:39], v[96:97], off offset:64
	global_load_dwordx4 v[40:43], v[96:97], off offset:512
	v_lshl_add_u64 v[60:61], v[142:143], 0, v[64:65]
	global_load_dwordx4 v[44:47], v[96:97], off offset:576
	global_load_dwordx4 v[48:51], v[60:61], off
	global_load_dwordx4 v[52:55], v[60:61], off offset:64
	global_load_dwordx4 v[56:59], v[60:61], off offset:512
	s_nop 0
	global_load_dwordx4 v[60:63], v[60:61], off offset:576
	v_pk_add_f32 v[74:75], v[2:3], 0 op_sel_hi:[1,0]
	v_pk_add_f32 v[76:77], v[0:1], 0 op_sel_hi:[1,0]
	v_lshl_add_u64 v[0:1], s[52:53], 0, v[110:111]
	v_lshl_add_u64 v[2:3], s[52:53], 0, v[64:65]
	v_pk_add_f32 v[66:67], v[10:11], 0 op_sel_hi:[1,0]
	v_pk_add_f32 v[68:69], v[8:9], 0 op_sel_hi:[1,0]
	v_pk_add_f32 v[70:71], v[6:7], 0 op_sel_hi:[1,0]
	v_pk_add_f32 v[72:73], v[4:5], 0 op_sel_hi:[1,0]
	v_lshl_add_u64 v[64:65], v[0:1], 0, v[140:141]
	v_lshl_add_u64 v[78:79], v[2:3], 0, v[140:141]
	s_waitcnt vmcnt(0)
	v_pk_add_f32 v[2:3], v[30:31], v[34:35]
	v_pk_add_f32 v[0:1], v[28:29], v[32:33]
	v_pk_add_f32 v[6:7], v[26:27], v[38:39]
	v_pk_add_f32 v[4:5], v[24:25], v[36:37]
	v_pk_add_f32 v[10:11], v[22:23], v[42:43]
	v_pk_add_f32 v[8:9], v[20:21], v[40:41]
	v_pk_add_f32 v[14:15], v[14:15], v[46:47]
	v_pk_add_f32 v[12:13], v[12:13], v[44:45]
	v_pk_add_f32 v[18:19], v[18:19], v[50:51]
	v_pk_add_f32 v[16:17], v[16:17], v[48:49]
	v_pk_add_f32 v[22:23], v[66:67], v[54:55]
	v_pk_add_f32 v[20:21], v[68:69], v[52:53]
	v_pk_add_f32 v[26:27], v[70:71], v[58:59]
	v_pk_add_f32 v[24:25], v[72:73], v[56:57]
	v_pk_add_f32 v[30:31], v[74:75], v[62:63]
	v_pk_add_f32 v[28:29], v[76:77], v[60:61]
	global_store_dwordx4 v[64:65], v[0:3], off
	global_store_dwordx4 v[64:65], v[4:7], off offset:64
	global_store_dwordx4 v[64:65], v[8:11], off offset:512
	global_store_dwordx4 v[64:65], v[12:15], off offset:576
	global_store_dwordx4 v[78:79], v[16:19], off
	global_store_dwordx4 v[78:79], v[20:23], off offset:64
	global_store_dwordx4 v[78:79], v[24:27], off offset:512
	global_store_dwordx4 v[78:79], v[28:31], off offset:576
	s_cbranch_vccz .LBB0_1232
	s_waitcnt vmcnt(0)
	s_cmpk_gt_u32 s4, 0xff
	s_cbranch_scc1 .LBB0_1243
	s_barrier

; #define PG8_STAGE(bufoff, gbase, voff) do { _Pragma("unroll") for (int _i = 0; _i < 2; ++_i) \
;         __builtin_amdgcn_global_load_lds((const unsigned*)((const char*)(gbase) + (voff)[_i]), (LAS unsigned*)(lds + (bufoff) + ldsw + _i * 8192), 16, 0, 0); } while (0)
; #define PG8_LDA(dst, b, h) do { _Pragma("unroll") for (int m = 0; m < 4; ++m) _Pragma("unroll") for (int k = 0; k < 2; ++k) dst[m][k] = *(const LAS bf16x8*)(lds + PG8_SA(b, h) + aoff + m * 2048 + k * 1024); } while (0)
; #define PG8_LDB(dst, b, h) do { _Pragma("unroll") for (int n = 0; n < 2; ++n) _Pragma("unroll") for (int k = 0; k < 2; ++k) dst[n][k] = *(const LAS bf16x8*)(lds + PG8_SB(b, h) + boff + n * 2048 + k * 1024); } while (0)
; #define PG8_MMA(ai, bj, At, Bt) do { __builtin_amdgcn_s_setprio(1); _Pragma("unroll") for (int m = 0; m < 4; ++m) _Pragma("unroll") for (int n = 0; n < 2; ++n) _Pragma("unroll") for (int k = 0; k < 2; ++k) \
;         acc[ai][bj][m][n] = __builtin_amdgcn_mfma_f32_16x16x32_bf16(Bt[n][k], At[m][k], acc[ai][bj][m][n], 0, 0, 0); __builtin_amdgcn_s_setprio(0); } while (0)
; #define PG8_WAIT_V(n) asm volatile("s_waitcnt vmcnt(" #n ")" ::: "memory")
; #define PG8_WAIT_L(n) asm volatile("s_waitcnt lgkmcnt(" #n ")" ::: "memory")
; #define PG8_BAR __builtin_amdgcn_s_barrier()
; #define PG8_SCHED __builtin_amdgcn_sched_barrier(0)
; template <class Epi>
; __device__ __forceinline__ void gemm_phase(LAS unsigned char* lds, const Gemm g, const StaticOrder& S, const Epi& E) {
;     ...
;             PG8_LDB(B0, 0, 0); PG8_SCHED; PG8_LDA(At, 0, 0); PG8_STAGE(PG8_SA(1, 1), a1 + hstepA, voffA);
;             PG8_WAIT_L(8); PG8_BAR; PG8_WAIT_L(0); PG8_MMA(0, 0, At, B0); PG8_BAR; PG8_SCHED;
;             PG8_LDB(B1, 0, 1); PG8_STAGE(PG8_SB(0, 0), b2, voffB);
;             PG8_BAR; PG8_WAIT_L(0); PG8_MMA(0, 1, At, B1); PG8_BAR;
;             PG8_LDA(At, 0, 1); PG8_STAGE(PG8_SA(0, 0), a2, voffA);
;             PG8_BAR; PG8_WAIT_L(0); PG8_MMA(1, 0, At, B0); PG8_BAR; PG8_SCHED;
;             PG8_STAGE(PG8_SB(0, 1), b2 + hstepB, voffB);
;             PG8_WAIT_V(6); PG8_BAR; PG8_MMA(1, 1, At, B1); PG8_BAR;
.LBB0_1461:
	ds_read_b128 v[140:143], v149
	ds_read_b128 v[152:155], v149 offset:1024
	ds_read_b128 v[156:159], v149 offset:2048
	ds_read_b128 v[160:163], v149 offset:3072
	s_add_u32 s34, s30, 0x100
	s_addc_u32 s35, s31, 0
	s_cmp_eq_u32 s74, 40
	s_cselect_b32 s39, s13, s35
	s_cselect_b32 s38, s12, s34
	s_cselect_b32 s37, s15, s73
	s_cselect_b32 s36, s14, s72
	v_lshl_add_u64 v[144:145], s[30:31], 0, v[132:133]
	s_add_i32 m0, s8, 0xc000
	ds_read_b128 v[164:167], v150
	ds_read_b128 v[168:171], v150 offset:1024
	ds_read_b128 v[172:175], v150 offset:2048
	ds_read_b128 v[176:179], v150 offset:3072
	ds_read_b128 v[180:183], v150 offset:4096
	ds_read_b128 v[184:187], v150 offset:5120
	ds_read_b128 v[188:191], v150 offset:6144
	ds_read_b128 v[192:195], v150 offset:7168
	global_load_lds_dwordx4 v[144:145], off
	v_lshl_add_u64 v[144:145], s[30:31], 0, v[134:135]
	s_add_i32 m0, s8, 0xe000
	s_nop 0
	global_load_lds_dwordx4 v[144:145], off
	ds_read_b128 v[196:199], v151
	ds_read_b128 v[200:203], v151 offset:1024
	ds_read_b128 v[204:207], v151 offset:2048
	ds_read_b128 v[208:211], v151 offset:3072
	s_waitcnt lgkmcnt(0)
	s_barrier
	s_setprio 1
	v_mfma_f32_16x16x32_bf16 v[124:127], v[140:143], v[164:167], v[124:127]
	v_mfma_f32_16x16x32_bf16 v[120:123], v[156:159], v[164:167], v[120:123]
	v_mfma_f32_16x16x32_bf16 v[112:115], v[140:143], v[172:175], v[112:115]
	v_mfma_f32_16x16x32_bf16 v[104:107], v[156:159], v[172:175], v[104:107]
	v_mfma_f32_16x16x32_bf16 v[92:95], v[140:143], v[180:183], v[92:95]
	v_mfma_f32_16x16x32_bf16 v[88:91], v[156:159], v[180:183], v[88:91]
	v_mfma_f32_16x16x32_bf16 v[80:83], v[140:143], v[188:191], v[80:83]
	v_mfma_f32_16x16x32_bf16 v[72:75], v[156:159], v[188:191], v[72:75]
	v_mfma_f32_16x16x32_bf16 v[124:127], v[152:155], v[168:171], v[124:127]
	v_mfma_f32_16x16x32_bf16 v[120:123], v[160:163], v[168:171], v[120:123]
	v_mfma_f32_16x16x32_bf16 v[112:115], v[152:155], v[176:179], v[112:115]
	v_mfma_f32_16x16x32_bf16 v[104:107], v[160:163], v[176:179], v[104:107]
	v_mfma_f32_16x16x32_bf16 v[92:95], v[152:155], v[184:187], v[92:95]
	v_mfma_f32_16x16x32_bf16 v[88:91], v[160:163], v[184:187], v[88:91]
	v_mfma_f32_16x16x32_bf16 v[80:83], v[152:155], v[192:195], v[80:83]
	v_mfma_f32_16x16x32_bf16 v[72:75], v[160:163], v[192:195], v[72:75]
	v_mfma_f32_16x16x32_bf16 v[116:119], v[196:199], v[164:167], v[116:119]
	v_mfma_f32_16x16x32_bf16 v[108:111], v[204:207], v[164:167], v[108:111]
	v_mfma_f32_16x16x32_bf16 v[100:103], v[196:199], v[172:175], v[100:103]
	v_mfma_f32_16x16x32_bf16 v[96:99], v[204:207], v[172:175], v[96:99]
	v_mfma_f32_16x16x32_bf16 v[84:87], v[196:199], v[180:183], v[84:87]
	v_mfma_f32_16x16x32_bf16 v[76:79], v[204:207], v[180:183], v[76:79]
	v_mfma_f32_16x16x32_bf16 v[68:71], v[196:199], v[188:191], v[68:71]
	v_mfma_f32_16x16x32_bf16 v[64:67], v[204:207], v[188:191], v[64:67]
	v_mfma_f32_16x16x32_bf16 v[116:119], v[200:203], v[168:171], v[116:119]
	v_mfma_f32_16x16x32_bf16 v[108:111], v[208:211], v[168:171], v[108:111]
	v_mfma_f32_16x16x32_bf16 v[100:103], v[200:203], v[176:179], v[100:103]
	v_mfma_f32_16x16x32_bf16 v[96:99], v[208:211], v[176:179], v[96:99]
	v_mfma_f32_16x16x32_bf16 v[84:87], v[200:203], v[184:187], v[84:87]
	v_mfma_f32_16x16x32_bf16 v[76:79], v[208:211], v[184:187], v[76:79]
	v_mfma_f32_16x16x32_bf16 v[68:71], v[200:203], v[192:195], v[68:71]
	v_mfma_f32_16x16x32_bf16 v[64:67], v[208:211], v[192:195], v[64:67]
	s_setprio 0
	s_barrier
	s_nop 1
	ds_read_b128 v[164:167], v150 offset:16384
	ds_read_b128 v[168:171], v150 offset:17408
	ds_read_b128 v[172:175], v150 offset:18432
	ds_read_b128 v[176:179], v150 offset:19456
	ds_read_b128 v[180:183], v150 offset:20480
	ds_read_b128 v[184:187], v150 offset:21504
	ds_read_b128 v[188:191], v150 offset:22528
	ds_read_b128 v[192:195], v150 offset:23552
	s_add_i32 s30, s45, s7
	v_lshl_add_u64 v[144:145], s[36:37], 0, v[128:129]
	s_mov_b32 m0, s30
	s_nop 0
	global_load_lds_dwordx4 v[144:145], off
	v_lshl_add_u64 v[212:213], s[36:37], 0, v[130:131]
	s_add_i32 m0, s30, 0x2000
	s_nop 0
	global_load_lds_dwordx4 v[212:213], off
	s_mov_b32 m0, s8
	v_lshl_add_u64 v[214:215], s[38:39], 0, v[128:129]
	global_load_lds_dwordx4 v[214:215], off
	v_lshl_add_u64 v[216:217], s[38:39], 0, v[130:131]
	s_mov_b32 m0, s9
	s_nop 0
	global_load_lds_dwordx4 v[216:217], off
	s_add_u32 s30, s36, 0xb0000
	s_addc_u32 s31, s37, 0
	s_add_i32 s75, s46, s7
	v_lshl_add_u64 v[254:255], s[30:31], 0, v[128:129]
	s_mov_b32 m0, s75
	s_nop 0
	global_load_lds_dwordx4 v[254:255], off
	v_lshl_add_u64 v[254:255], s[30:31], 0, v[130:131]
	s_add_i32 m0, s75, 0x2000
	s_nop 0
	global_load_lds_dwordx4 v[254:255], off
	s_waitcnt vmcnt(6)
	s_waitcnt lgkmcnt(0)
	s_barrier
; #define PG8_STAGE(bufoff, gbase, voff) do { _Pragma("unroll") for (int _i = 0; _i < 2; ++_i) \
;         __builtin_amdgcn_global_load_lds((const unsigned*)((const char*)(gbase) + (voff)[_i]), (LAS unsigned*)(lds + (bufoff) + ldsw + _i * 8192), 16, 0, 0); } while (0)
; #define PG8_LDA(dst, b, h) do { _Pragma("unroll") for (int m = 0; m < 4; ++m) _Pragma("unroll") for (int k = 0; k < 2; ++k) dst[m][k] = *(const LAS bf16x8*)(lds + PG8_SA(b, h) + aoff + m * 2048 + k * 1024); } while (0)
; #define PG8_LDB(dst, b, h) do { _Pragma("unroll") for (int n = 0; n < 2; ++n) _Pragma("unroll") for (int k = 0; k < 2; ++k) dst[n][k] = *(const LAS bf16x8*)(lds + PG8_SB(b, h) + boff + n * 2048 + k * 1024); } while (0)
; #define PG8_MMA(ai, bj, At, Bt) do { __builtin_amdgcn_s_setprio(1); _Pragma("unroll") for (int m = 0; m < 4; ++m) _Pragma("unroll") for (int n = 0; n < 2; ++n) _Pragma("unroll") for (int k = 0; k < 2; ++k) \
;         acc[ai][bj][m][n] = __builtin_amdgcn_mfma_f32_16x16x32_bf16(Bt[n][k], At[m][k], acc[ai][bj][m][n], 0, 0, 0); __builtin_amdgcn_s_setprio(0); } while (0)
; #define PG8_WAIT_V(n) asm volatile("s_waitcnt vmcnt(" #n ")" ::: "memory")
; #define PG8_WAIT_L(n) asm volatile("s_waitcnt lgkmcnt(" #n ")" ::: "memory")
; #define PG8_BAR __builtin_amdgcn_s_barrier()
; #define PG8_SCHED __builtin_amdgcn_sched_barrier(0)
; template <class Epi>
; __device__ __forceinline__ void gemm_phase(LAS unsigned char* lds, const Gemm g, const StaticOrder& S, const Epi& E) {
;     ...
;             PG8_WAIT_V(6); PG8_BAR; PG8_MMA(1, 1, At, B1); PG8_BAR;
;             PG8_LDB(B0, 1, 0); PG8_SCHED; PG8_LDA(At, 1, 0); PG8_STAGE(PG8_SA(0, 1), a2 + hstepA, voffA);
;             PG8_WAIT_L(8); PG8_BAR; PG8_WAIT_L(0); PG8_MMA(0, 0, At, B0); PG8_BAR; PG8_SCHED;
;             PG8_LDB(B1, 1, 1); PG8_STAGE(PG8_SB(1, 0), b3, voffB);
;             PG8_BAR; PG8_WAIT_L(0); PG8_MMA(0, 1, At, B1); PG8_BAR;
;             PG8_LDA(At, 1, 1); PG8_STAGE(PG8_SA(1, 0), a3, voffA);
;             PG8_BAR; PG8_WAIT_L(0); PG8_MMA(1, 0, At, B0); PG8_BAR; PG8_SCHED;
	s_setprio 1
	v_mfma_f32_16x16x32_bf16 v[60:63], v[140:143], v[164:167], v[60:63]
	v_mfma_f32_16x16x32_bf16 v[56:59], v[156:159], v[164:167], v[56:59]
	v_mfma_f32_16x16x32_bf16 v[48:51], v[140:143], v[172:175], v[48:51]
	v_mfma_f32_16x16x32_bf16 v[40:43], v[156:159], v[172:175], v[40:43]
	v_mfma_f32_16x16x32_bf16 v[28:31], v[140:143], v[180:183], v[28:31]
	v_mfma_f32_16x16x32_bf16 v[24:27], v[156:159], v[180:183], v[24:27]
	v_mfma_f32_16x16x32_bf16 v[16:19], v[140:143], v[188:191], v[16:19]
	v_mfma_f32_16x16x32_bf16 v[8:11], v[156:159], v[188:191], v[8:11]
	v_mfma_f32_16x16x32_bf16 v[60:63], v[152:155], v[168:171], v[60:63]
	v_mfma_f32_16x16x32_bf16 v[56:59], v[160:163], v[168:171], v[56:59]
	v_mfma_f32_16x16x32_bf16 v[48:51], v[152:155], v[176:179], v[48:51]
	v_mfma_f32_16x16x32_bf16 v[40:43], v[160:163], v[176:179], v[40:43]
	v_mfma_f32_16x16x32_bf16 v[28:31], v[152:155], v[184:187], v[28:31]
	v_mfma_f32_16x16x32_bf16 v[24:27], v[160:163], v[184:187], v[24:27]
	v_mfma_f32_16x16x32_bf16 v[16:19], v[152:155], v[192:195], v[16:19]
	v_mfma_f32_16x16x32_bf16 v[8:11], v[160:163], v[192:195], v[8:11]
	v_mfma_f32_16x16x32_bf16 v[52:55], v[196:199], v[164:167], v[52:55]
	v_mfma_f32_16x16x32_bf16 v[44:47], v[204:207], v[164:167], v[44:47]
	v_mfma_f32_16x16x32_bf16 v[36:39], v[196:199], v[172:175], v[36:39]
	v_mfma_f32_16x16x32_bf16 v[32:35], v[204:207], v[172:175], v[32:35]
	v_mfma_f32_16x16x32_bf16 v[20:23], v[196:199], v[180:183], v[20:23]
	v_mfma_f32_16x16x32_bf16 v[12:15], v[204:207], v[180:183], v[12:15]
	v_mfma_f32_16x16x32_bf16 v[4:7], v[196:199], v[188:191], v[4:7]
	v_mfma_f32_16x16x32_bf16 v[0:3], v[204:207], v[188:191], v[0:3]
	v_mfma_f32_16x16x32_bf16 v[52:55], v[200:203], v[168:171], v[52:55]
	v_mfma_f32_16x16x32_bf16 v[44:47], v[208:211], v[168:171], v[44:47]
	v_mfma_f32_16x16x32_bf16 v[36:39], v[200:203], v[176:179], v[36:39]
	v_mfma_f32_16x16x32_bf16 v[32:35], v[208:211], v[176:179], v[32:35]
	v_mfma_f32_16x16x32_bf16 v[20:23], v[200:203], v[184:187], v[20:23]
	v_mfma_f32_16x16x32_bf16 v[12:15], v[208:211], v[184:187], v[12:15]
	v_mfma_f32_16x16x32_bf16 v[4:7], v[200:203], v[192:195], v[4:7]
	v_mfma_f32_16x16x32_bf16 v[0:3], v[208:211], v[192:195], v[0:3]
	s_setprio 0
	s_add_i32 s75, 0, 0x18000
	v_add_u32_e32 v160, s75, v147
	s_barrier
	ds_read_b128 v[140:143], v160
	ds_read_b128 v[152:155], v160 offset:1024
	ds_read_b128 v[156:159], v160 offset:2048
	ds_read_b128 v[160:163], v160 offset:3072
	s_add_u32 s30, s38, 0xb0000
	s_addc_u32 s31, s39, 0
	s_mov_b32 m0, s40
	v_lshl_add_u64 v[196:197], s[30:31], 0, v[128:129]
	ds_read_b128 v[164:167], v150 offset:32768
	ds_read_b128 v[168:171], v150 offset:33792
	ds_read_b128 v[172:175], v150 offset:34816
	ds_read_b128 v[176:179], v150 offset:35840
	ds_read_b128 v[180:183], v150 offset:36864
	ds_read_b128 v[184:187], v150 offset:37888
	ds_read_b128 v[188:191], v150 offset:38912
	ds_read_b128 v[192:195], v150 offset:39936
	global_load_lds_dwordx4 v[196:197], off
	v_lshl_add_u64 v[196:197], s[30:31], 0, v[130:131]
	s_mov_b32 m0, s41
	s_nop 0
	global_load_lds_dwordx4 v[196:197], off
	s_add_i32 s38, 0, 0x1c000
	v_add_u32_e32 v208, s38, v147
	ds_read_b128 v[196:199], v208
	ds_read_b128 v[200:203], v208 offset:1024
	ds_read_b128 v[204:207], v208 offset:2048
	ds_read_b128 v[208:211], v208 offset:3072
	s_waitcnt lgkmcnt(0)
	s_barrier
	s_setprio 1
	v_mfma_f32_16x16x32_bf16 v[124:127], v[140:143], v[164:167], v[124:127]
	v_mfma_f32_16x16x32_bf16 v[120:123], v[156:159], v[164:167], v[120:123]
	v_mfma_f32_16x16x32_bf16 v[112:115], v[140:143], v[172:175], v[112:115]
	v_mfma_f32_16x16x32_bf16 v[104:107], v[156:159], v[172:175], v[104:107]
	v_mfma_f32_16x16x32_bf16 v[92:95], v[140:143], v[180:183], v[92:95]
	v_mfma_f32_16x16x32_bf16 v[88:91], v[156:159], v[180:183], v[88:91]
	v_mfma_f32_16x16x32_bf16 v[80:83], v[140:143], v[188:191], v[80:83]
	v_mfma_f32_16x16x32_bf16 v[72:75], v[156:159], v[188:191], v[72:75]
	v_mfma_f32_16x16x32_bf16 v[124:127], v[152:155], v[168:171], v[124:127]
	v_mfma_f32_16x16x32_bf16 v[120:123], v[160:163], v[168:171], v[120:123]
	v_mfma_f32_16x16x32_bf16 v[112:115], v[152:155], v[176:179], v[112:115]
	v_mfma_f32_16x16x32_bf16 v[104:107], v[160:163], v[176:179], v[104:107]
	v_mfma_f32_16x16x32_bf16 v[92:95], v[152:155], v[184:187], v[92:95]
	v_mfma_f32_16x16x32_bf16 v[88:91], v[160:163], v[184:187], v[88:91]
	v_mfma_f32_16x16x32_bf16 v[80:83], v[152:155], v[192:195], v[80:83]
	v_mfma_f32_16x16x32_bf16 v[72:75], v[160:163], v[192:195], v[72:75]
	v_mfma_f32_16x16x32_bf16 v[116:119], v[196:199], v[164:167], v[116:119]
	v_mfma_f32_16x16x32_bf16 v[108:111], v[204:207], v[164:167], v[108:111]
	v_mfma_f32_16x16x32_bf16 v[100:103], v[196:199], v[172:175], v[100:103]
	v_mfma_f32_16x16x32_bf16 v[96:99], v[204:207], v[172:175], v[96:99]
	v_mfma_f32_16x16x32_bf16 v[84:87], v[196:199], v[180:183], v[84:87]
	v_mfma_f32_16x16x32_bf16 v[76:79], v[204:207], v[180:183], v[76:79]
	v_mfma_f32_16x16x32_bf16 v[68:71], v[196:199], v[188:191], v[68:71]
	v_mfma_f32_16x16x32_bf16 v[64:67], v[204:207], v[188:191], v[64:67]
	v_mfma_f32_16x16x32_bf16 v[116:119], v[200:203], v[168:171], v[116:119]
	v_mfma_f32_16x16x32_bf16 v[108:111], v[208:211], v[168:171], v[108:111]
	v_mfma_f32_16x16x32_bf16 v[100:103], v[200:203], v[176:179], v[100:103]
	v_mfma_f32_16x16x32_bf16 v[96:99], v[208:211], v[176:179], v[96:99]
	v_mfma_f32_16x16x32_bf16 v[84:87], v[200:203], v[184:187], v[84:87]
	v_mfma_f32_16x16x32_bf16 v[76:79], v[208:211], v[184:187], v[76:79]
	v_mfma_f32_16x16x32_bf16 v[68:71], v[200:203], v[192:195], v[68:71]
	v_mfma_f32_16x16x32_bf16 v[64:67], v[208:211], v[192:195], v[64:67]
	s_setprio 0
	s_barrier
; #define PG8_STAGE(bufoff, gbase, voff) do { _Pragma("unroll") for (int _i = 0; _i < 2; ++_i) \
;         __builtin_amdgcn_global_load_lds((const unsigned*)((const char*)(gbase) + (voff)[_i]), (LAS unsigned*)(lds + (bufoff) + ldsw + _i * 8192), 16, 0, 0); } while (0)
; #define PG8_LDA(dst, b, h) do { _Pragma("unroll") for (int m = 0; m < 4; ++m) _Pragma("unroll") for (int k = 0; k < 2; ++k) dst[m][k] = *(const LAS bf16x8*)(lds + PG8_SA(b, h) + aoff + m * 2048 + k * 1024); } while (0)
; #define PG8_LDB(dst, b, h) do { _Pragma("unroll") for (int n = 0; n < 2; ++n) _Pragma("unroll") for (int k = 0; k < 2; ++k) dst[n][k] = *(const LAS bf16x8*)(lds + PG8_SB(b, h) + boff + n * 2048 + k * 1024); } while (0)
; template <class Epi>
; __device__ __forceinline__ void gemm_phase(LAS unsigned char* lds, const Gemm g, const StaticOrder& S, const Epi& E) {
;     ...
;             PG8_LDB(B1, 1, 1); PG8_STAGE(PG8_SB(1, 0), b3, voffB);
;             PG8_BAR; PG8_WAIT_L(0); PG8_MMA(0, 1, At, B1); PG8_BAR;
;             PG8_LDA(At, 1, 1); PG8_STAGE(PG8_SA(1, 0), a3, voffA);
;             PG8_BAR; PG8_WAIT_L(0); PG8_MMA(1, 0, At, B0); PG8_BAR; PG8_SCHED;
;             PG8_STAGE(PG8_SB(1, 1), b3 + hstepB, voffB);
;             PG8_WAIT_V(6); PG8_BAR; PG8_MMA(1, 1, At, B1); PG8_BAR;
;     __device__ __forceinline__ void operator()(AccRef acc, const Unit& u, int wr, int wc, int fr, int fq) const {
;         const int row0 = u.pm * 256 + wr * 64 + fr, col0 = u.pn * 256 + wc * 32 + 4 * fq;
;         f32x4 sv[2][2], bv[2][2];
; #pragma unroll
;         for (int bj = 0; bj < 2; ++bj)
; #pragma unroll
;             for (int n = 0; n < 2; ++n) {
;                 sv[bj][n] = scale ? *(const f32x4*)(scale + col0 + bj * 128 + n * 16) : (f32x4){1.f, 1.f, 1.f, 1.f};
;                 bv[bj][n] = bias ? *(const f32x4*)(bias + col0 + bj * 128 + n * 16) : (f32x4){0.f, 0.f, 0.f, 0.f}; }
; #pragma unroll
;         for (int ai = 0; ai < 2; ++ai)
; #pragma unroll
;             for (int mh = 0; mh < 2; ++mh) {
;                 f32x4 bs[2][2][2];
; #pragma unroll
;                 for (int m = 0; m < 2; ++m)
; #pragma unroll
;                     for (int bj = 0; bj < 2; ++bj)
; #pragma unroll
;                         for (int n = 0; n < 2; ++n) bs[m][bj][n] = *(const f32x4*)(base + (size_t)(row0 + ai * 128 + (2 * mh + m) * 16) * D + col0 + bj * 128 + n * 16);
	s_nop 1
	ds_read_b128 v[164:167], v150 offset:49152
	ds_read_b128 v[168:171], v150 offset:50176
	ds_read_b128 v[172:175], v150 offset:51200
	ds_read_b128 v[176:179], v150 offset:52224
	ds_read_b128 v[180:183], v150 offset:53248
	ds_read_b128 v[184:187], v150 offset:54272
	ds_read_b128 v[188:191], v150 offset:55296
	ds_read_b128 v[192:195], v150 offset:56320
	s_add_i32 s30, s75, s7
	v_lshl_add_u64 v[254:255], v[144:145], 0, s[22:23]
	s_mov_b32 m0, s30
	s_nop 0
	global_load_lds_dwordx4 v[254:255], off
	v_lshl_add_u64 v[254:255], v[212:213], 0, s[22:23]
	s_add_i32 m0, s30, 0x2000
	s_nop 0
	global_load_lds_dwordx4 v[254:255], off
	s_mov_b32 m0, s43
	v_lshl_add_u64 v[254:255], v[214:215], 0, s[22:23]
	global_load_lds_dwordx4 v[254:255], off
	v_lshl_add_u64 v[144:145], v[216:217], 0, s[22:23]
	s_mov_b32 m0, s44
	s_nop 0
	global_load_lds_dwordx4 v[144:145], off
	s_add_u32 s30, s36, 0xb0080
	s_addc_u32 s31, s37, 0
	s_add_i32 s36, s38, s7
	v_lshl_add_u64 v[254:255], s[30:31], 0, v[128:129]
	s_mov_b32 m0, s36
	s_nop 0
	global_load_lds_dwordx4 v[254:255], off
	v_lshl_add_u64 v[254:255], s[30:31], 0, v[130:131]
	s_add_i32 m0, s36, 0x2000
	s_nop 0
	global_load_lds_dwordx4 v[254:255], off
	s_waitcnt vmcnt(6)
	s_waitcnt lgkmcnt(0)
	s_barrier
	s_setprio 1
	v_mfma_f32_16x16x32_bf16 v[60:63], v[140:143], v[164:167], v[60:63]
	v_mfma_f32_16x16x32_bf16 v[56:59], v[156:159], v[164:167], v[56:59]
	v_mfma_f32_16x16x32_bf16 v[48:51], v[140:143], v[172:175], v[48:51]
	v_mfma_f32_16x16x32_bf16 v[40:43], v[156:159], v[172:175], v[40:43]
	v_mfma_f32_16x16x32_bf16 v[28:31], v[140:143], v[180:183], v[28:31]
	v_mfma_f32_16x16x32_bf16 v[24:27], v[156:159], v[180:183], v[24:27]
	v_mfma_f32_16x16x32_bf16 v[16:19], v[140:143], v[188:191], v[16:19]
	v_mfma_f32_16x16x32_bf16 v[8:11], v[156:159], v[188:191], v[8:11]
	v_mfma_f32_16x16x32_bf16 v[60:63], v[152:155], v[168:171], v[60:63]
	v_mfma_f32_16x16x32_bf16 v[56:59], v[160:163], v[168:171], v[56:59]
	v_mfma_f32_16x16x32_bf16 v[48:51], v[152:155], v[176:179], v[48:51]
	v_mfma_f32_16x16x32_bf16 v[40:43], v[160:163], v[176:179], v[40:43]
	v_mfma_f32_16x16x32_bf16 v[28:31], v[152:155], v[184:187], v[28:31]
	v_mfma_f32_16x16x32_bf16 v[24:27], v[160:163], v[184:187], v[24:27]
	v_mfma_f32_16x16x32_bf16 v[16:19], v[152:155], v[192:195], v[16:19]
	v_mfma_f32_16x16x32_bf16 v[8:11], v[160:163], v[192:195], v[8:11]
	v_mfma_f32_16x16x32_bf16 v[52:55], v[196:199], v[164:167], v[52:55]
	v_mfma_f32_16x16x32_bf16 v[44:47], v[204:207], v[164:167], v[44:47]
	v_mfma_f32_16x16x32_bf16 v[36:39], v[196:199], v[172:175], v[36:39]
	v_mfma_f32_16x16x32_bf16 v[32:35], v[204:207], v[172:175], v[32:35]
	v_mfma_f32_16x16x32_bf16 v[20:23], v[196:199], v[180:183], v[20:23]
	v_mfma_f32_16x16x32_bf16 v[12:15], v[204:207], v[180:183], v[12:15]
	v_mfma_f32_16x16x32_bf16 v[4:7], v[196:199], v[188:191], v[4:7]
	v_mfma_f32_16x16x32_bf16 v[0:3], v[204:207], v[188:191], v[0:3]
	v_mfma_f32_16x16x32_bf16 v[52:55], v[200:203], v[168:171], v[52:55]
	v_mfma_f32_16x16x32_bf16 v[44:47], v[208:211], v[168:171], v[44:47]
	v_mfma_f32_16x16x32_bf16 v[36:39], v[200:203], v[176:179], v[36:39]
	v_mfma_f32_16x16x32_bf16 v[32:35], v[208:211], v[176:179], v[32:35]
	v_mfma_f32_16x16x32_bf16 v[20:23], v[200:203], v[184:187], v[20:23]
	v_mfma_f32_16x16x32_bf16 v[12:15], v[208:211], v[184:187], v[12:15]
	v_mfma_f32_16x16x32_bf16 v[4:7], v[200:203], v[192:195], v[4:7]
	v_mfma_f32_16x16x32_bf16 v[0:3], v[208:211], v[192:195], v[0:3]
	s_setprio 0
	s_add_i32 s74, s74, 2
	s_add_u32 s72, s72, 0x100
	s_addc_u32 s73, s73, 0
	s_cmp_gt_u32 s74, 41
	s_mov_b64 s[30:31], s[34:35]
	s_barrier
	s_cbranch_scc0 .LBB0_1461
	v_lshl_or_b32 v140, s49, 8, v148
	v_ashrrev_i32_e32 v141, 31, v140
	v_lshl_add_u32 v184, s63, 8, v146
	v_lshlrev_b64 v[140:141], 2, v[140:141]
	v_ashrrev_i32_e32 v185, 31, v184
	v_or_b32_e32 v168, 16, v184
	v_lshl_add_u64 v[142:143], s[52:53], 0, v[140:141]
	v_lshlrev_b64 v[144:145], 12, v[184:185]
	v_ashrrev_i32_e32 v169, 31, v168
	v_lshl_add_u64 v[164:165], v[142:143], 0, v[144:145]
	v_lshlrev_b64 v[186:187], 12, v[168:169]
	global_load_dwordx4 v[152:155], v[164:165], off
	global_load_dwordx4 v[156:159], v[164:165], off offset:64
	global_load_dwordx4 v[160:163], v[164:165], off offset:512
	s_nop 0
	global_load_dwordx4 v[164:167], v[164:165], off offset:576
	v_lshl_add_u64 v[180:181], v[142:143], 0, v[186:187]
	global_load_dwordx4 v[168:171], v[180:181], off
	global_load_dwordx4 v[172:175], v[180:181], off offset:64
	global_load_dwordx4 v[176:179], v[180:181], off offset:512
	s_nop 0
	global_load_dwordx4 v[180:183], v[180:181], off offset:576
	v_pk_add_f32 v[198:199], v[96:97], 0 op_sel_hi:[1,0]
	v_or_b32_e32 v96, 32, v184
	v_ashrrev_i32_e32 v97, 31, v96
	v_pk_add_f32 v[126:127], v[126:127], 0 op_sel_hi:[1,0]
	v_pk_add_f32 v[124:125], v[124:125], 0 op_sel_hi:[1,0]
	v_pk_add_f32 v[108:109], v[108:109], 0 op_sel_hi:[1,0]
	v_pk_add_f32 v[196:197], v[98:99], 0 op_sel_hi:[1,0]
	v_lshl_add_u64 v[98:99], s[52:53], 0, v[144:145]
	v_lshlrev_b64 v[200:201], 12, v[96:97]
	v_lshl_add_u64 v[96:97], s[52:53], 0, v[186:187]
	v_pk_add_f32 v[122:123], v[122:123], 0 op_sel_hi:[1,0]
	v_pk_add_f32 v[120:121], v[120:121], 0 op_sel_hi:[1,0]
	v_pk_add_f32 v[118:119], v[118:119], 0 op_sel_hi:[1,0]
	v_pk_add_f32 v[116:117], v[116:117], 0 op_sel_hi:[1,0]
	v_pk_add_f32 v[110:111], v[110:111], 0 op_sel_hi:[1,0]
	v_pk_add_f32 v[114:115], v[114:115], 0 op_sel_hi:[1,0]
	v_pk_add_f32 v[112:113], v[112:113], 0 op_sel_hi:[1,0]
	v_pk_add_f32 v[188:189], v[106:107], 0 op_sel_hi:[1,0]
	v_pk_add_f32 v[190:191], v[104:105], 0 op_sel_hi:[1,0]
	v_pk_add_f32 v[192:193], v[102:103], 0 op_sel_hi:[1,0]
;     __device__ __forceinline__ void operator()(AccRef acc, const Unit& u, int wr, int wc, int fr, int fq) const {
;     ...
;         for (int ai = 0; ai < 2; ++ai)
; #pragma unroll
;             for (int mh = 0; mh < 2; ++mh) {
;                 f32x4 bs[2][2][2];
; #pragma unroll
;                 for (int m = 0; m < 2; ++m)
; #pragma unroll
;                     for (int bj = 0; bj < 2; ++bj)
; #pragma unroll
;                         for (int n = 0; n < 2; ++n) bs[m][bj][n] = *(const f32x4*)(base + (size_t)(row0 + ai * 128 + (2 * mh + m) * 16) * D + col0 + bj * 128 + n * 16);
; #pragma unroll
;                 for (int m = 0; m < 2; ++m)
; #pragma unroll
;                     for (int bj = 0; bj < 2; ++bj)
; #pragma unroll
;                         for (int n = 0; n < 2; ++n) *(f32x4*)(out + (size_t)(row0 + ai * 128 + (2 * mh + m) * 16) * D + col0 + bj * 128 + n * 16) = bs[m][bj][n] + sv[bj][n] * (acc[ai][bj][2 * mh + m][n] + bv[bj][n]);
;                 asm volatile("" ::: "memory"); }
	v_pk_add_f32 v[194:195], v[100:101], 0 op_sel_hi:[1,0]
	v_lshl_add_u64 v[202:203], v[98:99], 0, v[140:141]
	v_lshl_add_u64 v[204:205], v[96:97], 0, v[140:141]
	v_lshl_add_u64 v[186:187], v[142:143], 0, v[200:201]
	v_pk_add_f32 v[94:95], v[94:95], 0 op_sel_hi:[1,0]
	v_pk_add_f32 v[92:93], v[92:93], 0 op_sel_hi:[1,0]
	v_pk_add_f32 v[90:91], v[90:91], 0 op_sel_hi:[1,0]
	v_pk_add_f32 v[88:89], v[88:89], 0 op_sel_hi:[1,0]
	v_pk_add_f32 v[86:87], v[86:87], 0 op_sel_hi:[1,0]
	v_pk_add_f32 v[84:85], v[84:85], 0 op_sel_hi:[1,0]
	v_pk_add_f32 v[78:79], v[78:79], 0 op_sel_hi:[1,0]
	v_pk_add_f32 v[76:77], v[76:77], 0 op_sel_hi:[1,0]
	v_pk_add_f32 v[82:83], v[82:83], 0 op_sel_hi:[1,0]
	v_pk_add_f32 v[80:81], v[80:81], 0 op_sel_hi:[1,0]
	v_pk_add_f32 v[62:63], v[62:63], 0 op_sel_hi:[1,0]
	v_pk_add_f32 v[60:61], v[60:61], 0 op_sel_hi:[1,0]
	v_pk_add_f32 v[58:59], v[58:59], 0 op_sel_hi:[1,0]
	v_pk_add_f32 v[56:57], v[56:57], 0 op_sel_hi:[1,0]
	v_pk_add_f32 v[54:55], v[54:55], 0 op_sel_hi:[1,0]
	v_pk_add_f32 v[52:53], v[52:53], 0 op_sel_hi:[1,0]
	v_pk_add_f32 v[46:47], v[46:47], 0 op_sel_hi:[1,0]
	v_pk_add_f32 v[44:45], v[44:45], 0 op_sel_hi:[1,0]
	v_pk_add_f32 v[50:51], v[50:51], 0 op_sel_hi:[1,0]
	v_pk_add_f32 v[48:49], v[48:49], 0 op_sel_hi:[1,0]
	v_pk_add_f32 v[30:31], v[30:31], 0 op_sel_hi:[1,0]
	v_pk_add_f32 v[28:29], v[28:29], 0 op_sel_hi:[1,0]
	v_pk_add_f32 v[26:27], v[26:27], 0 op_sel_hi:[1,0]
	v_pk_add_f32 v[24:25], v[24:25], 0 op_sel_hi:[1,0]
	v_pk_add_f32 v[22:23], v[22:23], 0 op_sel_hi:[1,0]
	v_pk_add_f32 v[20:21], v[20:21], 0 op_sel_hi:[1,0]
	v_pk_add_f32 v[14:15], v[14:15], 0 op_sel_hi:[1,0]
	v_pk_add_f32 v[12:13], v[12:13], 0 op_sel_hi:[1,0]
	v_pk_add_f32 v[18:19], v[18:19], 0 op_sel_hi:[1,0]
	v_pk_add_f32 v[16:17], v[16:17], 0 op_sel_hi:[1,0]
	s_and_b64 vcc, exec, s[10:11]
	s_mov_b32 s49, s47
	s_mov_b32 s63, s48
	s_mov_b64 s[34:35], s[14:15]
	s_mov_b64 s[30:31], s[12:13]
	s_waitcnt vmcnt(0)
	v_pk_add_f32 v[98:99], v[126:127], v[154:155]
	v_pk_add_f32 v[96:97], v[124:125], v[152:153]
	v_pk_add_f32 v[102:103], v[122:123], v[158:159]
	v_pk_add_f32 v[108:109], v[108:109], v[164:165]
	v_pk_add_f32 v[100:101], v[120:121], v[156:157]
	v_pk_add_f32 v[106:107], v[118:119], v[162:163]
	v_pk_add_f32 v[104:105], v[116:117], v[160:161]
	v_pk_add_f32 v[110:111], v[110:111], v[166:167]
	v_pk_add_f32 v[114:115], v[114:115], v[170:171]
	v_pk_add_f32 v[112:113], v[112:113], v[168:169]
	v_pk_add_f32 v[118:119], v[188:189], v[174:175]
	v_pk_add_f32 v[116:117], v[190:191], v[172:173]
	v_pk_add_f32 v[122:123], v[192:193], v[178:179]
	v_pk_add_f32 v[120:121], v[194:195], v[176:177]
	v_pk_add_f32 v[126:127], v[196:197], v[182:183]
	v_pk_add_f32 v[124:125], v[198:199], v[180:181]
	global_store_dwordx4 v[202:203], v[96:99], off
	global_store_dwordx4 v[202:203], v[100:103], off offset:64
	global_store_dwordx4 v[202:203], v[104:107], off offset:512
	global_store_dwordx4 v[202:203], v[108:111], off offset:576
	global_store_dwordx4 v[204:205], v[112:115], off
	global_store_dwordx4 v[204:205], v[116:119], off offset:64
	global_store_dwordx4 v[204:205], v[120:123], off offset:512
	global_store_dwordx4 v[204:205], v[124:127], off offset:576
	v_or_b32_e32 v108, 48, v184
	v_ashrrev_i32_e32 v109, 31, v108
	v_lshlrev_b64 v[152:153], 12, v[108:109]
	global_load_dwordx4 v[96:99], v[186:187], off
	global_load_dwordx4 v[100:103], v[186:187], off offset:64
	v_lshl_add_u64 v[124:125], v[142:143], 0, v[152:153]
	global_load_dwordx4 v[104:107], v[186:187], off offset:512
	global_load_dwordx4 v[108:111], v[186:187], off offset:576
	global_load_dwordx4 v[112:115], v[124:125], off
	global_load_dwordx4 v[116:119], v[124:125], off offset:64
	global_load_dwordx4 v[120:123], v[124:125], off offset:512
	s_nop 0
	global_load_dwordx4 v[124:127], v[124:125], off offset:576
	v_pk_add_f32 v[162:163], v[66:67], 0 op_sel_hi:[1,0]
	v_pk_add_f32 v[164:165], v[64:65], 0 op_sel_hi:[1,0]
	v_lshl_add_u64 v[64:65], s[52:53], 0, v[200:201]
	v_lshl_add_u64 v[66:67], s[52:53], 0, v[152:153]
	v_pk_add_f32 v[154:155], v[74:75], 0 op_sel_hi:[1,0]
	v_pk_add_f32 v[156:157], v[72:73], 0 op_sel_hi:[1,0]
	v_pk_add_f32 v[158:159], v[70:71], 0 op_sel_hi:[1,0]
	v_pk_add_f32 v[160:161], v[68:69], 0 op_sel_hi:[1,0]
	v_lshl_add_u64 v[168:169], v[64:65], 0, v[140:141]
	v_lshl_add_u64 v[170:171], v[66:67], 0, v[140:141]
	v_lshl_add_u64 v[166:167], v[144:145], 0, s[24:25]
	v_lshl_add_u64 v[152:153], v[142:143], 0, v[166:167]
	s_waitcnt vmcnt(0)
; #define PG8_WAIT_V(n) asm volatile("s_waitcnt vmcnt(" #n ")" ::: "memory")
; #define PG8_BAR __builtin_amdgcn_s_barrier()
; template <class Epi>
; __device__ __forceinline__ void gemm_phase(LAS unsigned char* lds, const Gemm g, const StaticOrder& S, const Epi& E) {
;     ...
;         if (!has_next) break;
;         {
; #pragma unroll
;         for (int a = 0; a < 2; ++a)
; #pragma unroll
;             for (int b = 0; b < 2; ++b)
; #pragma unroll
;                 for (int m = 0; m < 4; ++m)
; #pragma unroll
;                     for (int n = 0; n < 2; ++n) acc[a][b][m][n] = (f32x4){0.f, 0.f, 0.f, 0.f};
;         }
;         cur = nxt; cA = nA; cB = nB; ++ui;
;     }
;     PG8_WAIT_V(0);
;     if (wr == 0) PG8_BAR;
;     PG8_BAR;
;     __device__ __forceinline__ void operator()(AccRef acc, const Unit& u, int wr, int wc, int fr, int fq) const {
;     ...
;                         for (int n = 0; n < 2; ++n) bs[m][bj][n] = *(const f32x4*)(base + (size_t)(row0 + ai * 128 + (2 * mh + m) * 16) * D + col0 + bj * 128 + n * 16);
; #pragma unroll
;                 for (int m = 0; m < 2; ++m)
; #pragma unroll
;                     for (int bj = 0; bj < 2; ++bj)
; #pragma unroll
;                         for (int n = 0; n < 2; ++n) *(f32x4*)(out + (size_t)(row0 + ai * 128 + (2 * mh + m) * 16) * D + col0 + bj * 128 + n * 16) = bs[m][bj][n] + sv[bj][n] * (acc[ai][bj][2 * mh + m][n] + bv[bj][n]);
;                 asm volatile("" ::: "memory"); }
	v_pk_add_f32 v[66:67], v[94:95], v[98:99]
	v_pk_add_f32 v[64:65], v[92:93], v[96:97]
	v_pk_add_f32 v[70:71], v[90:91], v[102:103]
	v_pk_add_f32 v[68:69], v[88:89], v[100:101]
	v_pk_add_f32 v[74:75], v[86:87], v[106:107]
	v_pk_add_f32 v[72:73], v[84:85], v[104:105]
	v_pk_add_f32 v[78:79], v[78:79], v[110:111]
	v_pk_add_f32 v[76:77], v[76:77], v[108:109]
	v_pk_add_f32 v[82:83], v[82:83], v[114:115]
	v_pk_add_f32 v[80:81], v[80:81], v[112:113]
	v_pk_add_f32 v[86:87], v[154:155], v[118:119]
	v_pk_add_f32 v[84:85], v[156:157], v[116:117]
	v_pk_add_f32 v[90:91], v[158:159], v[122:123]
	v_pk_add_f32 v[88:89], v[160:161], v[120:121]
	v_pk_add_f32 v[94:95], v[162:163], v[126:127]
	v_pk_add_f32 v[92:93], v[164:165], v[124:125]
	global_store_dwordx4 v[168:169], v[64:67], off
	global_store_dwordx4 v[168:169], v[68:71], off offset:64
	global_store_dwordx4 v[168:169], v[72:75], off offset:512
	global_store_dwordx4 v[168:169], v[76:79], off offset:576
	global_store_dwordx4 v[170:171], v[80:83], off
	global_store_dwordx4 v[170:171], v[84:87], off offset:64
	global_store_dwordx4 v[170:171], v[88:91], off offset:512
	global_store_dwordx4 v[170:171], v[92:95], off offset:576
	v_lshl_add_u64 v[96:97], v[144:145], 0, s[26:27]
	global_load_dwordx4 v[64:67], v[152:153], off
	global_load_dwordx4 v[68:71], v[152:153], off offset:64
	global_load_dwordx4 v[72:75], v[152:153], off offset:512
	v_lshl_add_u64 v[92:93], v[142:143], 0, v[96:97]
	global_load_dwordx4 v[76:79], v[152:153], off offset:576
	global_load_dwordx4 v[80:83], v[92:93], off
	global_load_dwordx4 v[84:87], v[92:93], off offset:64
	global_load_dwordx4 v[88:91], v[92:93], off offset:512
	s_nop 0
	global_load_dwordx4 v[92:95], v[92:93], off offset:576
	v_pk_add_f32 v[106:107], v[34:35], 0 op_sel_hi:[1,0]
	v_pk_add_f32 v[108:109], v[32:33], 0 op_sel_hi:[1,0]
	v_lshl_add_u64 v[32:33], s[52:53], 0, v[166:167]
	v_lshl_add_u64 v[34:35], s[52:53], 0, v[96:97]
	v_pk_add_f32 v[98:99], v[42:43], 0 op_sel_hi:[1,0]
	v_pk_add_f32 v[100:101], v[40:41], 0 op_sel_hi:[1,0]
	v_pk_add_f32 v[102:103], v[38:39], 0 op_sel_hi:[1,0]
	v_pk_add_f32 v[104:105], v[36:37], 0 op_sel_hi:[1,0]
	v_lshl_add_u64 v[112:113], v[32:33], 0, v[140:141]
	v_lshl_add_u64 v[114:115], v[34:35], 0, v[140:141]
	v_lshl_add_u64 v[110:111], v[144:145], 0, s[28:29]
	v_lshl_add_u64 v[96:97], v[142:143], 0, v[110:111]
	s_waitcnt vmcnt(0)
	v_pk_add_f32 v[34:35], v[62:63], v[66:67]
	v_pk_add_f32 v[32:33], v[60:61], v[64:65]
	v_pk_add_f32 v[38:39], v[58:59], v[70:71]
	v_pk_add_f32 v[36:37], v[56:57], v[68:69]
	v_pk_add_f32 v[42:43], v[54:55], v[74:75]
	v_pk_add_f32 v[40:41], v[52:53], v[72:73]
	v_pk_add_f32 v[46:47], v[46:47], v[78:79]
	v_pk_add_f32 v[44:45], v[44:45], v[76:77]
	v_pk_add_f32 v[50:51], v[50:51], v[82:83]
	v_pk_add_f32 v[48:49], v[48:49], v[80:81]
	v_pk_add_f32 v[54:55], v[98:99], v[86:87]
	v_pk_add_f32 v[52:53], v[100:101], v[84:85]
	v_pk_add_f32 v[58:59], v[102:103], v[90:91]
	v_pk_add_f32 v[56:57], v[104:105], v[88:89]
	v_pk_add_f32 v[62:63], v[106:107], v[94:95]
	v_pk_add_f32 v[60:61], v[108:109], v[92:93]
	global_store_dwordx4 v[112:113], v[32:35], off
	global_store_dwordx4 v[112:113], v[36:39], off offset:64
	global_store_dwordx4 v[112:113], v[40:43], off offset:512
	global_store_dwordx4 v[112:113], v[44:47], off offset:576
	global_store_dwordx4 v[114:115], v[48:51], off
	global_store_dwordx4 v[114:115], v[52:55], off offset:64
	global_store_dwordx4 v[114:115], v[56:59], off offset:512
	global_store_dwordx4 v[114:115], v[60:63], off offset:576
	v_lshl_add_u64 v[64:65], v[144:145], 0, s[16:17]
	global_load_dwordx4 v[32:35], v[96:97], off
	global_load_dwordx4 v[36:39], v[96:97], off offset:64
	global_load_dwordx4 v[40:43], v[96:97], off offset:512
	v_lshl_add_u64 v[60:61], v[142:143], 0, v[64:65]
	global_load_dwordx4 v[44:47], v[96:97], off offset:576
	global_load_dwordx4 v[48:51], v[60:61], off
	global_load_dwordx4 v[52:55], v[60:61], off offset:64
	global_load_dwordx4 v[56:59], v[60:61], off offset:512
	s_nop 0
	global_load_dwordx4 v[60:63], v[60:61], off offset:576
	v_pk_add_f32 v[74:75], v[2:3], 0 op_sel_hi:[1,0]
	v_pk_add_f32 v[76:77], v[0:1], 0 op_sel_hi:[1,0]
	v_lshl_add_u64 v[0:1], s[52:53], 0, v[110:111]
	v_lshl_add_u64 v[2:3], s[52:53], 0, v[64:65]
	v_pk_add_f32 v[66:67], v[10:11], 0 op_sel_hi:[1,0]
	v_pk_add_f32 v[68:69], v[8:9], 0 op_sel_hi:[1,0]
	v_pk_add_f32 v[70:71], v[6:7], 0 op_sel_hi:[1,0]
	v_pk_add_f32 v[72:73], v[4:5], 0 op_sel_hi:[1,0]
	v_lshl_add_u64 v[64:65], v[0:1], 0, v[140:141]
	v_lshl_add_u64 v[78:79], v[2:3], 0, v[140:141]
	s_waitcnt vmcnt(0)
	v_pk_add_f32 v[2:3], v[30:31], v[34:35]
	v_pk_add_f32 v[0:1], v[28:29], v[32:33]
	v_pk_add_f32 v[6:7], v[26:27], v[38:39]
	v_pk_add_f32 v[4:5], v[24:25], v[36:37]
	v_pk_add_f32 v[10:11], v[22:23], v[42:43]
	v_pk_add_f32 v[8:9], v[20:21], v[40:41]
	v_pk_add_f32 v[14:15], v[14:15], v[46:47]
	v_pk_add_f32 v[12:13], v[12:13], v[44:45]
	v_pk_add_f32 v[18:19], v[18:19], v[50:51]
	v_pk_add_f32 v[16:17], v[16:17], v[48:49]
	v_pk_add_f32 v[22:23], v[66:67], v[54:55]
	v_pk_add_f32 v[20:21], v[68:69], v[52:53]
	v_pk_add_f32 v[26:27], v[70:71], v[58:59]
	v_pk_add_f32 v[24:25], v[72:73], v[56:57]
	v_pk_add_f32 v[30:31], v[74:75], v[62:63]
	v_pk_add_f32 v[28:29], v[76:77], v[60:61]
	global_store_dwordx4 v[64:65], v[0:3], off
	global_store_dwordx4 v[64:65], v[4:7], off offset:64
	global_store_dwordx4 v[64:65], v[8:11], off offset:512
	global_store_dwordx4 v[64:65], v[12:15], off offset:576
	global_store_dwordx4 v[78:79], v[16:19], off
	global_store_dwordx4 v[78:79], v[20:23], off offset:64
	global_store_dwordx4 v[78:79], v[24:27], off offset:512
	global_store_dwordx4 v[78:79], v[28:31], off offset:576
	s_cbranch_vccz .LBB0_1450
	s_waitcnt vmcnt(0)
	s_cmpk_gt_u32 s4, 0xff
	s_cbranch_scc1 .LBB0_1465
	s_barrier

; #define PG8_STAGE(bufoff, gbase, voff) do { _Pragma("unroll") for (int _i = 0; _i < 2; ++_i) \
;         __builtin_amdgcn_global_load_lds((const unsigned*)((const char*)(gbase) + (voff)[_i]), (LAS unsigned*)(lds + (bufoff) + ldsw + _i * 8192), 16, 0, 0); } while (0)
; #define PG8_LDA(dst, b, h) do { _Pragma("unroll") for (int m = 0; m < 4; ++m) _Pragma("unroll") for (int k = 0; k < 2; ++k) dst[m][k] = *(const LAS bf16x8*)(lds + PG8_SA(b, h) + aoff + m * 2048 + k * 1024); } while (0)
; #define PG8_LDB(dst, b, h) do { _Pragma("unroll") for (int n = 0; n < 2; ++n) _Pragma("unroll") for (int k = 0; k < 2; ++k) dst[n][k] = *(const LAS bf16x8*)(lds + PG8_SB(b, h) + boff + n * 2048 + k * 1024); } while (0)
; #define PG8_MMA(ai, bj, At, Bt) do { __builtin_amdgcn_s_setprio(1); _Pragma("unroll") for (int m = 0; m < 4; ++m) _Pragma("unroll") for (int n = 0; n < 2; ++n) _Pragma("unroll") for (int k = 0; k < 2; ++k) \
;         acc[ai][bj][m][n] = __builtin_amdgcn_mfma_f32_16x16x32_bf16(Bt[n][k], At[m][k], acc[ai][bj][m][n], 0, 0, 0); __builtin_amdgcn_s_setprio(0); } while (0)
; #define PG8_WAIT_V(n) asm volatile("s_waitcnt vmcnt(" #n ")" ::: "memory")
; #define PG8_WAIT_L(n) asm volatile("s_waitcnt lgkmcnt(" #n ")" ::: "memory")
; #define PG8_BAR __builtin_amdgcn_s_barrier()
; #define PG8_SCHED __builtin_amdgcn_sched_barrier(0)
; template <class Epi>
; __device__ __forceinline__ void gemm_phase(LAS unsigned char* lds, const Gemm g, const StaticOrder& S, const Epi& E) {
;     ...
;             PG8_LDB(B0, 0, 0); PG8_SCHED; PG8_LDA(At, 0, 0); PG8_STAGE(PG8_SA(1, 1), a1 + hstepA, voffA);
;             PG8_WAIT_L(8); PG8_BAR; PG8_WAIT_L(0); PG8_MMA(0, 0, At, B0); PG8_BAR; PG8_SCHED;
;             PG8_LDB(B1, 0, 1); PG8_STAGE(PG8_SB(0, 0), b2, voffB);
;             PG8_BAR; PG8_WAIT_L(0); PG8_MMA(0, 1, At, B1); PG8_BAR;
;             PG8_LDA(At, 0, 1); PG8_STAGE(PG8_SA(0, 0), a2, voffA);
;             PG8_BAR; PG8_WAIT_L(0); PG8_MMA(1, 0, At, B0); PG8_BAR; PG8_SCHED;
;             PG8_STAGE(PG8_SB(0, 1), b2 + hstepB, voffB);
;             PG8_WAIT_V(6); PG8_BAR; PG8_MMA(1, 1, At, B1); PG8_BAR;
.LBB0_1583:
	ds_read_b128 v[80:83], v180
	ds_read_b128 v[84:87], v180 offset:1024
	ds_read_b128 v[88:91], v180 offset:2048
	ds_read_b128 v[92:95], v180 offset:3072
	s_add_u32 s14, s12, 0xfffc0080
	s_addc_u32 s15, s13, -1
	s_cmp_eq_u32 s74, 12
	s_cselect_b32 s37, s25, s15
	s_cselect_b32 s36, s31, s14
	s_cselect_b32 s15, s23, s39
	s_cselect_b32 s14, s35, s38
	v_lshl_add_u64 v[210:211], s[12:13], 0, v[158:159]
	s_add_i32 m0, s8, 0xc000
	ds_read_b128 v[166:169], v181
	ds_read_b128 v[170:173], v181 offset:1024
	ds_read_b128 v[186:189], v181 offset:2048
	ds_read_b128 v[190:193], v181 offset:3072
	ds_read_b128 v[194:197], v181 offset:4096
	ds_read_b128 v[198:201], v181 offset:5120
	ds_read_b128 v[202:205], v181 offset:6144
	ds_read_b128 v[206:209], v181 offset:7168
	global_load_lds_dwordx4 v[210:211], off
	v_lshl_add_u64 v[210:211], s[12:13], 0, v[160:161]
	s_add_i32 m0, s8, 0xe000
	s_nop 0
	global_load_lds_dwordx4 v[210:211], off
	ds_read_b128 v[210:213], v182
	ds_read_b128 v[214:217], v182 offset:1024
	ds_read_b128 v[220:223], v182 offset:2048
	ds_read_b128 v[224:227], v182 offset:3072
	s_waitcnt lgkmcnt(0)
	s_barrier
	s_setprio 1
	v_mfma_f32_16x16x32_bf16 v[140:143], v[80:83], v[166:169], v[140:143]
	v_mfma_f32_16x16x32_bf16 v[136:139], v[88:91], v[166:169], v[136:139]
	v_mfma_f32_16x16x32_bf16 v[124:127], v[80:83], v[186:189], v[124:127]
	v_mfma_f32_16x16x32_bf16 v[120:123], v[88:91], v[186:189], v[120:123]
	v_mfma_f32_16x16x32_bf16 v[108:111], v[80:83], v[194:197], v[108:111]
	v_mfma_f32_16x16x32_bf16 v[104:107], v[88:91], v[194:197], v[104:107]
	v_mfma_f32_16x16x32_bf16 v[76:79], v[80:83], v[202:205], v[76:79]
	v_mfma_f32_16x16x32_bf16 v[72:75], v[88:91], v[202:205], v[72:75]
	v_mfma_f32_16x16x32_bf16 v[140:143], v[84:87], v[170:173], v[140:143]
	v_mfma_f32_16x16x32_bf16 v[136:139], v[92:95], v[170:173], v[136:139]
	v_mfma_f32_16x16x32_bf16 v[124:127], v[84:87], v[190:193], v[124:127]
	v_mfma_f32_16x16x32_bf16 v[120:123], v[92:95], v[190:193], v[120:123]
	v_mfma_f32_16x16x32_bf16 v[108:111], v[84:87], v[198:201], v[108:111]
	v_mfma_f32_16x16x32_bf16 v[104:107], v[92:95], v[198:201], v[104:107]
	v_mfma_f32_16x16x32_bf16 v[76:79], v[84:87], v[206:209], v[76:79]
	v_mfma_f32_16x16x32_bf16 v[72:75], v[92:95], v[206:209], v[72:75]
	v_mfma_f32_16x16x32_bf16 v[132:135], v[210:213], v[166:169], v[132:135]
	v_mfma_f32_16x16x32_bf16 v[128:131], v[220:223], v[166:169], v[128:131]
	v_mfma_f32_16x16x32_bf16 v[116:119], v[210:213], v[186:189], v[116:119]
	v_mfma_f32_16x16x32_bf16 v[112:115], v[220:223], v[186:189], v[112:115]
	v_mfma_f32_16x16x32_bf16 v[100:103], v[210:213], v[194:197], v[100:103]
	v_mfma_f32_16x16x32_bf16 v[96:99], v[220:223], v[194:197], v[96:99]
	v_mfma_f32_16x16x32_bf16 v[68:71], v[210:213], v[202:205], v[68:71]
	v_mfma_f32_16x16x32_bf16 v[64:67], v[220:223], v[202:205], v[64:67]
	v_mfma_f32_16x16x32_bf16 v[132:135], v[214:217], v[170:173], v[132:135]
	v_mfma_f32_16x16x32_bf16 v[128:131], v[224:227], v[170:173], v[128:131]
	v_mfma_f32_16x16x32_bf16 v[116:119], v[214:217], v[190:193], v[116:119]
	v_mfma_f32_16x16x32_bf16 v[112:115], v[224:227], v[190:193], v[112:115]
	v_mfma_f32_16x16x32_bf16 v[100:103], v[214:217], v[198:201], v[100:103]
	v_mfma_f32_16x16x32_bf16 v[96:99], v[224:227], v[198:201], v[96:99]
	v_mfma_f32_16x16x32_bf16 v[68:71], v[214:217], v[206:209], v[68:71]
	v_mfma_f32_16x16x32_bf16 v[64:67], v[224:227], v[206:209], v[64:67]
	s_setprio 0
	s_barrier
	s_nop 1
	ds_read_b128 v[166:169], v181 offset:16384
	ds_read_b128 v[170:173], v181 offset:17408
	ds_read_b128 v[186:189], v181 offset:18432
	ds_read_b128 v[190:193], v181 offset:19456
	ds_read_b128 v[194:197], v181 offset:20480
	ds_read_b128 v[198:201], v181 offset:21504
	ds_read_b128 v[202:205], v181 offset:22528
	ds_read_b128 v[206:209], v181 offset:23552
	s_add_i32 s75, s48, s7
	v_lshl_add_u64 v[228:229], s[14:15], 0, v[146:147]
	s_mov_b32 m0, s75
	s_nop 0
	global_load_lds_dwordx4 v[228:229], off
	v_lshl_add_u64 v[230:231], s[14:15], 0, v[150:151]
	s_add_i32 m0, s75, 0x2000
	s_nop 0
	global_load_lds_dwordx4 v[230:231], off
	s_mov_b32 m0, s8
	v_lshl_add_u64 v[232:233], s[36:37], 0, v[144:145]
	global_load_lds_dwordx4 v[232:233], off
	v_lshl_add_u64 v[236:237], s[36:37], 0, v[148:149]
	s_mov_b32 m0, s9
	s_nop 0
	global_load_lds_dwordx4 v[236:237], off
	s_add_u32 s76, s14, 0x40000
	s_addc_u32 s77, s15, 0
	s_add_i32 s75, s49, s7
	v_lshl_add_u64 v[254:255], s[76:77], 0, v[146:147]
	s_mov_b32 m0, s75
	s_nop 0
	global_load_lds_dwordx4 v[254:255], off
	v_lshl_add_u64 v[254:255], s[76:77], 0, v[150:151]
	s_add_i32 m0, s75, 0x2000
	s_nop 0
	global_load_lds_dwordx4 v[254:255], off
	s_waitcnt vmcnt(6)
	s_waitcnt lgkmcnt(0)
	s_barrier
; #define PG8_STAGE(bufoff, gbase, voff) do { _Pragma("unroll") for (int _i = 0; _i < 2; ++_i) \
;         __builtin_amdgcn_global_load_lds((const unsigned*)((const char*)(gbase) + (voff)[_i]), (LAS unsigned*)(lds + (bufoff) + ldsw + _i * 8192), 16, 0, 0); } while (0)
; #define PG8_LDA(dst, b, h) do { _Pragma("unroll") for (int m = 0; m < 4; ++m) _Pragma("unroll") for (int k = 0; k < 2; ++k) dst[m][k] = *(const LAS bf16x8*)(lds + PG8_SA(b, h) + aoff + m * 2048 + k * 1024); } while (0)
; #define PG8_LDB(dst, b, h) do { _Pragma("unroll") for (int n = 0; n < 2; ++n) _Pragma("unroll") for (int k = 0; k < 2; ++k) dst[n][k] = *(const LAS bf16x8*)(lds + PG8_SB(b, h) + boff + n * 2048 + k * 1024); } while (0)
; #define PG8_MMA(ai, bj, At, Bt) do { __builtin_amdgcn_s_setprio(1); _Pragma("unroll") for (int m = 0; m < 4; ++m) _Pragma("unroll") for (int n = 0; n < 2; ++n) _Pragma("unroll") for (int k = 0; k < 2; ++k) \
;         acc[ai][bj][m][n] = __builtin_amdgcn_mfma_f32_16x16x32_bf16(Bt[n][k], At[m][k], acc[ai][bj][m][n], 0, 0, 0); __builtin_amdgcn_s_setprio(0); } while (0)
; #define PG8_WAIT_V(n) asm volatile("s_waitcnt vmcnt(" #n ")" ::: "memory")
; #define PG8_WAIT_L(n) asm volatile("s_waitcnt lgkmcnt(" #n ")" ::: "memory")
; #define PG8_BAR __builtin_amdgcn_s_barrier()
; #define PG8_SCHED __builtin_amdgcn_sched_barrier(0)
; template <class Epi>
; __device__ __forceinline__ void gemm_phase(LAS unsigned char* lds, const Gemm g, const StaticOrder& S, const Epi& E) {
;     ...
;             PG8_WAIT_V(6); PG8_BAR; PG8_MMA(1, 1, At, B1); PG8_BAR;
;             PG8_LDB(B0, 1, 0); PG8_SCHED; PG8_LDA(At, 1, 0); PG8_STAGE(PG8_SA(0, 1), a2 + hstepA, voffA);
;             PG8_WAIT_L(8); PG8_BAR; PG8_WAIT_L(0); PG8_MMA(0, 0, At, B0); PG8_BAR; PG8_SCHED;
;             PG8_LDB(B1, 1, 1); PG8_STAGE(PG8_SB(1, 0), b3, voffB);
;             PG8_BAR; PG8_WAIT_L(0); PG8_MMA(0, 1, At, B1); PG8_BAR;
;             PG8_LDA(At, 1, 1); PG8_STAGE(PG8_SA(1, 0), a3, voffA);
;             PG8_BAR; PG8_WAIT_L(0); PG8_MMA(1, 0, At, B0); PG8_BAR; PG8_SCHED;
	s_setprio 1
	v_mfma_f32_16x16x32_bf16 v[60:63], v[80:83], v[166:169], v[60:63]
	v_mfma_f32_16x16x32_bf16 v[56:59], v[88:91], v[166:169], v[56:59]
	v_mfma_f32_16x16x32_bf16 v[44:47], v[80:83], v[186:189], v[44:47]
	v_mfma_f32_16x16x32_bf16 v[40:43], v[88:91], v[186:189], v[40:43]
	v_mfma_f32_16x16x32_bf16 v[28:31], v[80:83], v[194:197], v[28:31]
	v_mfma_f32_16x16x32_bf16 v[24:27], v[88:91], v[194:197], v[24:27]
	v_mfma_f32_16x16x32_bf16 v[12:15], v[80:83], v[202:205], v[12:15]
	v_mfma_f32_16x16x32_bf16 v[8:11], v[88:91], v[202:205], v[8:11]
	v_mfma_f32_16x16x32_bf16 v[60:63], v[84:87], v[170:173], v[60:63]
	v_mfma_f32_16x16x32_bf16 v[56:59], v[92:95], v[170:173], v[56:59]
	v_mfma_f32_16x16x32_bf16 v[44:47], v[84:87], v[190:193], v[44:47]
	v_mfma_f32_16x16x32_bf16 v[40:43], v[92:95], v[190:193], v[40:43]
	v_mfma_f32_16x16x32_bf16 v[28:31], v[84:87], v[198:201], v[28:31]
	v_mfma_f32_16x16x32_bf16 v[24:27], v[92:95], v[198:201], v[24:27]
	v_mfma_f32_16x16x32_bf16 v[12:15], v[84:87], v[206:209], v[12:15]
	v_mfma_f32_16x16x32_bf16 v[8:11], v[92:95], v[206:209], v[8:11]
	v_mfma_f32_16x16x32_bf16 v[52:55], v[210:213], v[166:169], v[52:55]
	v_mfma_f32_16x16x32_bf16 v[48:51], v[220:223], v[166:169], v[48:51]
	v_mfma_f32_16x16x32_bf16 v[36:39], v[210:213], v[186:189], v[36:39]
	v_mfma_f32_16x16x32_bf16 v[32:35], v[220:223], v[186:189], v[32:35]
	v_mfma_f32_16x16x32_bf16 v[20:23], v[210:213], v[194:197], v[20:23]
	v_mfma_f32_16x16x32_bf16 v[16:19], v[220:223], v[194:197], v[16:19]
	v_mfma_f32_16x16x32_bf16 v[4:7], v[210:213], v[202:205], v[4:7]
	v_mfma_f32_16x16x32_bf16 v[0:3], v[220:223], v[202:205], v[0:3]
	v_mfma_f32_16x16x32_bf16 v[52:55], v[214:217], v[170:173], v[52:55]
	v_mfma_f32_16x16x32_bf16 v[48:51], v[224:227], v[170:173], v[48:51]
	v_mfma_f32_16x16x32_bf16 v[36:39], v[214:217], v[190:193], v[36:39]
	v_mfma_f32_16x16x32_bf16 v[32:35], v[224:227], v[190:193], v[32:35]
	v_mfma_f32_16x16x32_bf16 v[20:23], v[214:217], v[198:201], v[20:23]
	v_mfma_f32_16x16x32_bf16 v[16:19], v[224:227], v[198:201], v[16:19]
	v_mfma_f32_16x16x32_bf16 v[4:7], v[214:217], v[206:209], v[4:7]
	v_mfma_f32_16x16x32_bf16 v[0:3], v[224:227], v[206:209], v[0:3]
	s_setprio 0
	s_add_i32 s75, 0, 0x18000
	v_add_u32_e32 v92, s75, v175
	s_barrier
	ds_read_b128 v[80:83], v92
	ds_read_b128 v[84:87], v92 offset:1024
	ds_read_b128 v[88:91], v92 offset:2048
	ds_read_b128 v[92:95], v92 offset:3072
	s_add_u32 s36, s36, 0x40000
	s_addc_u32 s37, s37, 0
	s_mov_b32 m0, s40
	v_lshl_add_u64 v[210:211], s[36:37], 0, v[144:145]
	ds_read_b128 v[166:169], v181 offset:32768
	ds_read_b128 v[170:173], v181 offset:33792
	ds_read_b128 v[186:189], v181 offset:34816
	ds_read_b128 v[190:193], v181 offset:35840
	ds_read_b128 v[194:197], v181 offset:36864
	ds_read_b128 v[198:201], v181 offset:37888
	ds_read_b128 v[202:205], v181 offset:38912
	ds_read_b128 v[206:209], v181 offset:39936
	global_load_lds_dwordx4 v[210:211], off
	v_lshl_add_u64 v[210:211], s[36:37], 0, v[148:149]
	s_mov_b32 m0, s41
	s_nop 0
	global_load_lds_dwordx4 v[210:211], off
	s_add_i32 s36, 0, 0x1c000
	v_add_u32_e32 v152, s36, v175
	ds_read_b128 v[210:213], v152
	ds_read_b128 v[214:217], v152 offset:1024
	ds_read_b128 v[220:223], v152 offset:2048
	ds_read_b128 v[224:227], v152 offset:3072
	s_waitcnt lgkmcnt(0)
	s_barrier
	s_setprio 1
	v_mfma_f32_16x16x32_bf16 v[140:143], v[80:83], v[166:169], v[140:143]
	v_mfma_f32_16x16x32_bf16 v[136:139], v[88:91], v[166:169], v[136:139]
	v_mfma_f32_16x16x32_bf16 v[124:127], v[80:83], v[186:189], v[124:127]
	v_mfma_f32_16x16x32_bf16 v[120:123], v[88:91], v[186:189], v[120:123]
	v_mfma_f32_16x16x32_bf16 v[108:111], v[80:83], v[194:197], v[108:111]
	v_mfma_f32_16x16x32_bf16 v[104:107], v[88:91], v[194:197], v[104:107]
	v_mfma_f32_16x16x32_bf16 v[76:79], v[80:83], v[202:205], v[76:79]
	v_mfma_f32_16x16x32_bf16 v[72:75], v[88:91], v[202:205], v[72:75]
	v_mfma_f32_16x16x32_bf16 v[140:143], v[84:87], v[170:173], v[140:143]
	v_mfma_f32_16x16x32_bf16 v[136:139], v[92:95], v[170:173], v[136:139]
	v_mfma_f32_16x16x32_bf16 v[124:127], v[84:87], v[190:193], v[124:127]
	v_mfma_f32_16x16x32_bf16 v[120:123], v[92:95], v[190:193], v[120:123]
	v_mfma_f32_16x16x32_bf16 v[108:111], v[84:87], v[198:201], v[108:111]
	v_mfma_f32_16x16x32_bf16 v[104:107], v[92:95], v[198:201], v[104:107]
	v_mfma_f32_16x16x32_bf16 v[76:79], v[84:87], v[206:209], v[76:79]
	v_mfma_f32_16x16x32_bf16 v[72:75], v[92:95], v[206:209], v[72:75]
	v_mfma_f32_16x16x32_bf16 v[132:135], v[210:213], v[166:169], v[132:135]
	v_mfma_f32_16x16x32_bf16 v[128:131], v[220:223], v[166:169], v[128:131]
	v_mfma_f32_16x16x32_bf16 v[116:119], v[210:213], v[186:189], v[116:119]
	v_mfma_f32_16x16x32_bf16 v[112:115], v[220:223], v[186:189], v[112:115]
	v_mfma_f32_16x16x32_bf16 v[100:103], v[210:213], v[194:197], v[100:103]
	v_mfma_f32_16x16x32_bf16 v[96:99], v[220:223], v[194:197], v[96:99]
	v_mfma_f32_16x16x32_bf16 v[68:71], v[210:213], v[202:205], v[68:71]
	v_mfma_f32_16x16x32_bf16 v[64:67], v[220:223], v[202:205], v[64:67]
	v_mfma_f32_16x16x32_bf16 v[132:135], v[214:217], v[170:173], v[132:135]
	v_mfma_f32_16x16x32_bf16 v[128:131], v[224:227], v[170:173], v[128:131]
	v_mfma_f32_16x16x32_bf16 v[116:119], v[214:217], v[190:193], v[116:119]
	v_mfma_f32_16x16x32_bf16 v[112:115], v[224:227], v[190:193], v[112:115]
	v_mfma_f32_16x16x32_bf16 v[100:103], v[214:217], v[198:201], v[100:103]
	v_mfma_f32_16x16x32_bf16 v[96:99], v[224:227], v[198:201], v[96:99]
	v_mfma_f32_16x16x32_bf16 v[68:71], v[214:217], v[206:209], v[68:71]
	v_mfma_f32_16x16x32_bf16 v[64:67], v[224:227], v[206:209], v[64:67]
	s_setprio 0
	s_barrier
; #define PG8_STAGE(bufoff, gbase, voff) do { _Pragma("unroll") for (int _i = 0; _i < 2; ++_i) \
;         __builtin_amdgcn_global_load_lds((const unsigned*)((const char*)(gbase) + (voff)[_i]), (LAS unsigned*)(lds + (bufoff) + ldsw + _i * 8192), 16, 0, 0); } while (0)
; #define PG8_LDA(dst, b, h) do { _Pragma("unroll") for (int m = 0; m < 4; ++m) _Pragma("unroll") for (int k = 0; k < 2; ++k) dst[m][k] = *(const LAS bf16x8*)(lds + PG8_SA(b, h) + aoff + m * 2048 + k * 1024); } while (0)
; #define PG8_LDB(dst, b, h) do { _Pragma("unroll") for (int n = 0; n < 2; ++n) _Pragma("unroll") for (int k = 0; k < 2; ++k) dst[n][k] = *(const LAS bf16x8*)(lds + PG8_SB(b, h) + boff + n * 2048 + k * 1024); } while (0)
; #define PG8_MMA(ai, bj, At, Bt) do { __builtin_amdgcn_s_setprio(1); _Pragma("unroll") for (int m = 0; m < 4; ++m) _Pragma("unroll") for (int n = 0; n < 2; ++n) _Pragma("unroll") for (int k = 0; k < 2; ++k) \
;         acc[ai][bj][m][n] = __builtin_amdgcn_mfma_f32_16x16x32_bf16(Bt[n][k], At[m][k], acc[ai][bj][m][n], 0, 0, 0); __builtin_amdgcn_s_setprio(0); } while (0)
; #define PG8_WAIT_V(n) asm volatile("s_waitcnt vmcnt(" #n ")" ::: "memory")
; template <class Epi>
; __device__ __forceinline__ void gemm_phase(LAS unsigned char* lds, const Gemm g, const StaticOrder& S, const Epi& E) {
;     ...
;             PG8_LDB(B1, 1, 1); PG8_STAGE(PG8_SB(1, 0), b3, voffB);
;             PG8_BAR; PG8_WAIT_L(0); PG8_MMA(0, 1, At, B1); PG8_BAR;
;             PG8_LDA(At, 1, 1); PG8_STAGE(PG8_SA(1, 0), a3, voffA);
;             PG8_BAR; PG8_WAIT_L(0); PG8_MMA(1, 0, At, B0); PG8_BAR; PG8_SCHED;
;             PG8_STAGE(PG8_SB(1, 1), b3 + hstepB, voffB);
;             PG8_WAIT_V(6); PG8_BAR; PG8_MMA(1, 1, At, B1); PG8_BAR;
;     __device__ __forceinline__ void operator()(AccRef acc, const Unit& u, int wr, int wc, int fr, int fq) const {
;         const int which = u.pn >> 2, row0 = u.pm * 256 + wr * 64 + fr, col0 = (u.pn & 3) * 256 + wc * 64 + 8 * fq;
;         bf16_t* dst = QKV + (size_t)which * ((size_t)T * D);
;         f32x4 gv[2][2];
; #pragma unroll
;         for (int bj = 0; bj < 2; ++bj)
; #pragma unroll
;             for (int n = 0; n < 2; ++n) { const f32x4 a = *(const f32x4*)(qg + 32 * bj + 8 * fq + 4 * n), b = *(const f32x4*)(kg + 32 * bj + 8 * fq + 4 * n);
;                 gv[bj][n] = which == 0 ? a : (which == 1 ? b : (f32x4){1.f, 1.f, 1.f, 1.f}); }
	s_nop 1
	ds_read_b128 v[166:169], v181 offset:49152
	ds_read_b128 v[170:173], v181 offset:50176
	ds_read_b128 v[186:189], v181 offset:51200
	ds_read_b128 v[190:193], v181 offset:52224
	ds_read_b128 v[194:197], v181 offset:53248
	ds_read_b128 v[198:201], v181 offset:54272
	ds_read_b128 v[202:205], v181 offset:55296
	ds_read_b128 v[206:209], v181 offset:56320
	s_add_i32 s37, s75, s7
	v_lshl_add_u64 v[254:255], v[228:229], 0, s[16:17]
	s_mov_b32 m0, s37
	s_nop 0
	global_load_lds_dwordx4 v[254:255], off
	v_lshl_add_u64 v[254:255], v[230:231], 0, s[16:17]
	s_add_i32 m0, s37, 0x2000
	s_nop 0
	global_load_lds_dwordx4 v[254:255], off
	s_mov_b32 m0, s45
	v_lshl_add_u64 v[254:255], v[232:233], 0, s[16:17]
	global_load_lds_dwordx4 v[254:255], off
	v_lshl_add_u64 v[228:229], v[236:237], 0, s[16:17]
	s_mov_b32 m0, s46
	s_nop 0
	global_load_lds_dwordx4 v[228:229], off
	s_add_u32 s14, s14, 0x40080
	s_addc_u32 s15, s15, 0
	s_add_i32 s36, s36, s7
	v_lshl_add_u64 v[254:255], s[14:15], 0, v[146:147]
	s_mov_b32 m0, s36
	s_nop 0
	global_load_lds_dwordx4 v[254:255], off
	v_lshl_add_u64 v[254:255], s[14:15], 0, v[150:151]
	s_add_i32 m0, s36, 0x2000
	s_nop 0
	global_load_lds_dwordx4 v[254:255], off
	s_waitcnt vmcnt(6)
	s_waitcnt lgkmcnt(0)
	s_barrier
	s_setprio 1
	v_mfma_f32_16x16x32_bf16 v[60:63], v[80:83], v[166:169], v[60:63]
	v_mfma_f32_16x16x32_bf16 v[56:59], v[88:91], v[166:169], v[56:59]
	v_mfma_f32_16x16x32_bf16 v[44:47], v[80:83], v[186:189], v[44:47]
	v_mfma_f32_16x16x32_bf16 v[40:43], v[88:91], v[186:189], v[40:43]
	v_mfma_f32_16x16x32_bf16 v[28:31], v[80:83], v[194:197], v[28:31]
	v_mfma_f32_16x16x32_bf16 v[24:27], v[88:91], v[194:197], v[24:27]
	v_mfma_f32_16x16x32_bf16 v[12:15], v[80:83], v[202:205], v[12:15]
	v_mfma_f32_16x16x32_bf16 v[8:11], v[88:91], v[202:205], v[8:11]
	v_mfma_f32_16x16x32_bf16 v[60:63], v[84:87], v[170:173], v[60:63]
	v_mfma_f32_16x16x32_bf16 v[56:59], v[92:95], v[170:173], v[56:59]
	v_mfma_f32_16x16x32_bf16 v[44:47], v[84:87], v[190:193], v[44:47]
	v_mfma_f32_16x16x32_bf16 v[40:43], v[92:95], v[190:193], v[40:43]
	v_mfma_f32_16x16x32_bf16 v[28:31], v[84:87], v[198:201], v[28:31]
	v_mfma_f32_16x16x32_bf16 v[24:27], v[92:95], v[198:201], v[24:27]
	v_mfma_f32_16x16x32_bf16 v[12:15], v[84:87], v[206:209], v[12:15]
	v_mfma_f32_16x16x32_bf16 v[8:11], v[92:95], v[206:209], v[8:11]
	v_mfma_f32_16x16x32_bf16 v[52:55], v[210:213], v[166:169], v[52:55]
	v_mfma_f32_16x16x32_bf16 v[48:51], v[220:223], v[166:169], v[48:51]
	v_mfma_f32_16x16x32_bf16 v[36:39], v[210:213], v[186:189], v[36:39]
	v_mfma_f32_16x16x32_bf16 v[32:35], v[220:223], v[186:189], v[32:35]
	v_mfma_f32_16x16x32_bf16 v[20:23], v[210:213], v[194:197], v[20:23]
	v_mfma_f32_16x16x32_bf16 v[16:19], v[220:223], v[194:197], v[16:19]
	v_mfma_f32_16x16x32_bf16 v[4:7], v[210:213], v[202:205], v[4:7]
	v_mfma_f32_16x16x32_bf16 v[0:3], v[220:223], v[202:205], v[0:3]
	v_mfma_f32_16x16x32_bf16 v[52:55], v[214:217], v[170:173], v[52:55]
	v_mfma_f32_16x16x32_bf16 v[48:51], v[224:227], v[170:173], v[48:51]
	v_mfma_f32_16x16x32_bf16 v[36:39], v[214:217], v[190:193], v[36:39]
	v_mfma_f32_16x16x32_bf16 v[32:35], v[224:227], v[190:193], v[32:35]
	v_mfma_f32_16x16x32_bf16 v[20:23], v[214:217], v[198:201], v[20:23]
	v_mfma_f32_16x16x32_bf16 v[16:19], v[224:227], v[198:201], v[16:19]
	v_mfma_f32_16x16x32_bf16 v[4:7], v[214:217], v[206:209], v[4:7]
	v_mfma_f32_16x16x32_bf16 v[0:3], v[224:227], v[206:209], v[0:3]
	s_setprio 0
	s_add_i32 s74, s74, 2
	s_add_u32 s12, s12, 0x100
	s_addc_u32 s13, s13, 0
	s_add_u32 s38, s38, 0x100
	s_addc_u32 s39, s39, 0
	s_cmp_gt_u32 s74, 13
	s_barrier
	s_cbranch_scc0 .LBB0_1583
	s_ashr_i32 s36, s30, 2
	s_cmp_gt_u32 s30, 3
	s_cselect_b64 s[38:39], -1, 0
	s_cmp_eq_u32 s36, 1
	s_mov_b64 s[14:15], -1
	s_cselect_b64 s[12:13], -1, 0
	s_and_b64 vcc, exec, s[38:39]
	s_cbranch_vccz .LBB0_1586
	global_load_dwordx4 v[80:83], v[154:155], off
	s_mov_b64 s[14:15], 0
	s_waitcnt vmcnt(0)
	v_cndmask_b32_e64 v83, 1.0, v83, s[12:13]
	v_cndmask_b32_e64 v82, 1.0, v82, s[12:13]
	v_cndmask_b32_e64 v81, 1.0, v81, s[12:13]
	v_cndmask_b32_e64 v80, 1.0, v80, s[12:13]

; #define PG8_STAGE(bufoff, gbase, voff) do { _Pragma("unroll") for (int _i = 0; _i < 2; ++_i) \
;         __builtin_amdgcn_global_load_lds((const unsigned*)((const char*)(gbase) + (voff)[_i]), (LAS unsigned*)(lds + (bufoff) + ldsw + _i * 8192), 16, 0, 0); } while (0)
; #define PG8_LDA(dst, b, h) do { _Pragma("unroll") for (int m = 0; m < 4; ++m) _Pragma("unroll") for (int k = 0; k < 2; ++k) dst[m][k] = *(const LAS bf16x8*)(lds + PG8_SA(b, h) + aoff + m * 2048 + k * 1024); } while (0)
; #define PG8_LDB(dst, b, h) do { _Pragma("unroll") for (int n = 0; n < 2; ++n) _Pragma("unroll") for (int k = 0; k < 2; ++k) dst[n][k] = *(const LAS bf16x8*)(lds + PG8_SB(b, h) + boff + n * 2048 + k * 1024); } while (0)
; #define PG8_MMA(ai, bj, At, Bt) do { __builtin_amdgcn_s_setprio(1); _Pragma("unroll") for (int m = 0; m < 4; ++m) _Pragma("unroll") for (int n = 0; n < 2; ++n) _Pragma("unroll") for (int k = 0; k < 2; ++k) \
;         acc[ai][bj][m][n] = __builtin_amdgcn_mfma_f32_16x16x32_bf16(Bt[n][k], At[m][k], acc[ai][bj][m][n], 0, 0, 0); __builtin_amdgcn_s_setprio(0); } while (0)
; #define PG8_WAIT_V(n) asm volatile("s_waitcnt vmcnt(" #n ")" ::: "memory")
; #define PG8_WAIT_L(n) asm volatile("s_waitcnt lgkmcnt(" #n ")" ::: "memory")
; #define PG8_BAR __builtin_amdgcn_s_barrier()
; #define PG8_SCHED __builtin_amdgcn_sched_barrier(0)
; template <class Epi>
; __device__ __forceinline__ void gemm_phase(LAS unsigned char* lds, const Gemm g, const StaticOrder& S, const Epi& E) {
;     ...
;             PG8_LDB(B0, 0, 0); PG8_SCHED; PG8_LDA(At, 0, 0); PG8_STAGE(PG8_SA(1, 1), a1 + hstepA, voffA);
;             PG8_WAIT_L(8); PG8_BAR; PG8_WAIT_L(0); PG8_MMA(0, 0, At, B0); PG8_BAR; PG8_SCHED;
;             PG8_LDB(B1, 0, 1); PG8_STAGE(PG8_SB(0, 0), b2, voffB);
;             PG8_BAR; PG8_WAIT_L(0); PG8_MMA(0, 1, At, B1); PG8_BAR;
;             PG8_LDA(At, 0, 1); PG8_STAGE(PG8_SA(0, 0), a2, voffA);
;             PG8_BAR; PG8_WAIT_L(0); PG8_MMA(1, 0, At, B0); PG8_BAR; PG8_SCHED;
;             PG8_STAGE(PG8_SB(0, 1), b2 + hstepB, voffB);
;             PG8_WAIT_V(6); PG8_BAR; PG8_MMA(1, 1, At, B1); PG8_BAR;
.LBB0_1820:
	ds_read_b128 v[140:143], v149
	ds_read_b128 v[152:155], v149 offset:1024
	ds_read_b128 v[156:159], v149 offset:2048
	ds_read_b128 v[160:163], v149 offset:3072
	s_add_u32 s36, s34, 0xfffc0080
	s_addc_u32 s37, s35, -1
	s_cmp_eq_u32 s70, 12
	s_cselect_b32 s39, s25, s37
	s_cselect_b32 s38, s47, s36
	s_cselect_b32 s37, s23, s63
	s_cselect_b32 s36, s48, s49
	v_lshl_add_u64 v[144:145], s[34:35], 0, v[132:133]
	s_add_i32 m0, s8, 0xc000
	ds_read_b128 v[164:167], v150
	ds_read_b128 v[168:171], v150 offset:1024
	ds_read_b128 v[172:175], v150 offset:2048
	ds_read_b128 v[176:179], v150 offset:3072
	ds_read_b128 v[180:183], v150 offset:4096
	ds_read_b128 v[184:187], v150 offset:5120
	ds_read_b128 v[188:191], v150 offset:6144
	ds_read_b128 v[192:195], v150 offset:7168
	global_load_lds_dwordx4 v[144:145], off
	v_lshl_add_u64 v[144:145], s[34:35], 0, v[134:135]
	s_add_i32 m0, s8, 0xe000
	s_nop 0
	global_load_lds_dwordx4 v[144:145], off
	ds_read_b128 v[196:199], v151
	ds_read_b128 v[200:203], v151 offset:1024
	ds_read_b128 v[204:207], v151 offset:2048
	ds_read_b128 v[208:211], v151 offset:3072
	s_waitcnt lgkmcnt(0)
	s_barrier
	s_setprio 1
	v_mfma_f32_16x16x32_bf16 v[124:127], v[140:143], v[164:167], v[124:127]
	v_mfma_f32_16x16x32_bf16 v[120:123], v[156:159], v[164:167], v[120:123]
	v_mfma_f32_16x16x32_bf16 v[112:115], v[140:143], v[172:175], v[112:115]
	v_mfma_f32_16x16x32_bf16 v[104:107], v[156:159], v[172:175], v[104:107]
	v_mfma_f32_16x16x32_bf16 v[92:95], v[140:143], v[180:183], v[92:95]
	v_mfma_f32_16x16x32_bf16 v[88:91], v[156:159], v[180:183], v[88:91]
	v_mfma_f32_16x16x32_bf16 v[80:83], v[140:143], v[188:191], v[80:83]
	v_mfma_f32_16x16x32_bf16 v[72:75], v[156:159], v[188:191], v[72:75]
	v_mfma_f32_16x16x32_bf16 v[124:127], v[152:155], v[168:171], v[124:127]
	v_mfma_f32_16x16x32_bf16 v[120:123], v[160:163], v[168:171], v[120:123]
	v_mfma_f32_16x16x32_bf16 v[112:115], v[152:155], v[176:179], v[112:115]
	v_mfma_f32_16x16x32_bf16 v[104:107], v[160:163], v[176:179], v[104:107]
	v_mfma_f32_16x16x32_bf16 v[92:95], v[152:155], v[184:187], v[92:95]
	v_mfma_f32_16x16x32_bf16 v[88:91], v[160:163], v[184:187], v[88:91]
	v_mfma_f32_16x16x32_bf16 v[80:83], v[152:155], v[192:195], v[80:83]
	v_mfma_f32_16x16x32_bf16 v[72:75], v[160:163], v[192:195], v[72:75]
	v_mfma_f32_16x16x32_bf16 v[116:119], v[196:199], v[164:167], v[116:119]
	v_mfma_f32_16x16x32_bf16 v[108:111], v[204:207], v[164:167], v[108:111]
	v_mfma_f32_16x16x32_bf16 v[100:103], v[196:199], v[172:175], v[100:103]
	v_mfma_f32_16x16x32_bf16 v[96:99], v[204:207], v[172:175], v[96:99]
	v_mfma_f32_16x16x32_bf16 v[84:87], v[196:199], v[180:183], v[84:87]
	v_mfma_f32_16x16x32_bf16 v[76:79], v[204:207], v[180:183], v[76:79]
	v_mfma_f32_16x16x32_bf16 v[68:71], v[196:199], v[188:191], v[68:71]
	v_mfma_f32_16x16x32_bf16 v[64:67], v[204:207], v[188:191], v[64:67]
	v_mfma_f32_16x16x32_bf16 v[116:119], v[200:203], v[168:171], v[116:119]
	v_mfma_f32_16x16x32_bf16 v[108:111], v[208:211], v[168:171], v[108:111]
	v_mfma_f32_16x16x32_bf16 v[100:103], v[200:203], v[176:179], v[100:103]
	v_mfma_f32_16x16x32_bf16 v[96:99], v[208:211], v[176:179], v[96:99]
	v_mfma_f32_16x16x32_bf16 v[84:87], v[200:203], v[184:187], v[84:87]
	v_mfma_f32_16x16x32_bf16 v[76:79], v[208:211], v[184:187], v[76:79]
	v_mfma_f32_16x16x32_bf16 v[68:71], v[200:203], v[192:195], v[68:71]
	v_mfma_f32_16x16x32_bf16 v[64:67], v[208:211], v[192:195], v[64:67]
	s_setprio 0
	s_barrier
	s_nop 1
	ds_read_b128 v[164:167], v150 offset:16384
	ds_read_b128 v[168:171], v150 offset:17408
	ds_read_b128 v[172:175], v150 offset:18432
	ds_read_b128 v[176:179], v150 offset:19456
	ds_read_b128 v[180:183], v150 offset:20480
	ds_read_b128 v[184:187], v150 offset:21504
	ds_read_b128 v[188:191], v150 offset:22528
	ds_read_b128 v[192:195], v150 offset:23552
	s_add_i32 s71, s44, s7
	v_lshl_add_u64 v[144:145], s[36:37], 0, v[128:129]
	s_mov_b32 m0, s71
	s_nop 0
	global_load_lds_dwordx4 v[144:145], off
	v_lshl_add_u64 v[212:213], s[36:37], 0, v[130:131]
	s_add_i32 m0, s71, 0x2000
	s_nop 0
	global_load_lds_dwordx4 v[212:213], off
	s_mov_b32 m0, s8
	v_lshl_add_u64 v[214:215], s[38:39], 0, v[128:129]
	global_load_lds_dwordx4 v[214:215], off
	v_lshl_add_u64 v[216:217], s[38:39], 0, v[130:131]
	s_mov_b32 m0, s9
	s_nop 0
	global_load_lds_dwordx4 v[216:217], off
	s_add_u32 s72, s36, 0x40000
	s_addc_u32 s73, s37, 0
	s_add_i32 s71, s45, s7
	v_lshl_add_u64 v[254:255], s[72:73], 0, v[128:129]
	s_mov_b32 m0, s71
	s_nop 0
	global_load_lds_dwordx4 v[254:255], off
	v_lshl_add_u64 v[254:255], s[72:73], 0, v[130:131]
	s_add_i32 m0, s71, 0x2000
	s_nop 0
	global_load_lds_dwordx4 v[254:255], off
	s_waitcnt vmcnt(6)
	s_waitcnt lgkmcnt(0)
	s_barrier
; #define PG8_STAGE(bufoff, gbase, voff) do { _Pragma("unroll") for (int _i = 0; _i < 2; ++_i) \
;         __builtin_amdgcn_global_load_lds((const unsigned*)((const char*)(gbase) + (voff)[_i]), (LAS unsigned*)(lds + (bufoff) + ldsw + _i * 8192), 16, 0, 0); } while (0)
; #define PG8_LDA(dst, b, h) do { _Pragma("unroll") for (int m = 0; m < 4; ++m) _Pragma("unroll") for (int k = 0; k < 2; ++k) dst[m][k] = *(const LAS bf16x8*)(lds + PG8_SA(b, h) + aoff + m * 2048 + k * 1024); } while (0)
; #define PG8_LDB(dst, b, h) do { _Pragma("unroll") for (int n = 0; n < 2; ++n) _Pragma("unroll") for (int k = 0; k < 2; ++k) dst[n][k] = *(const LAS bf16x8*)(lds + PG8_SB(b, h) + boff + n * 2048 + k * 1024); } while (0)
; #define PG8_MMA(ai, bj, At, Bt) do { __builtin_amdgcn_s_setprio(1); _Pragma("unroll") for (int m = 0; m < 4; ++m) _Pragma("unroll") for (int n = 0; n < 2; ++n) _Pragma("unroll") for (int k = 0; k < 2; ++k) \
;         acc[ai][bj][m][n] = __builtin_amdgcn_mfma_f32_16x16x32_bf16(Bt[n][k], At[m][k], acc[ai][bj][m][n], 0, 0, 0); __builtin_amdgcn_s_setprio(0); } while (0)
; #define PG8_WAIT_V(n) asm volatile("s_waitcnt vmcnt(" #n ")" ::: "memory")
; #define PG8_WAIT_L(n) asm volatile("s_waitcnt lgkmcnt(" #n ")" ::: "memory")
; #define PG8_BAR __builtin_amdgcn_s_barrier()
; #define PG8_SCHED __builtin_amdgcn_sched_barrier(0)
; template <class Epi>
; __device__ __forceinline__ void gemm_phase(LAS unsigned char* lds, const Gemm g, const StaticOrder& S, const Epi& E) {
;     ...
;             PG8_WAIT_V(6); PG8_BAR; PG8_MMA(1, 1, At, B1); PG8_BAR;
;             PG8_LDB(B0, 1, 0); PG8_SCHED; PG8_LDA(At, 1, 0); PG8_STAGE(PG8_SA(0, 1), a2 + hstepA, voffA);
;             PG8_WAIT_L(8); PG8_BAR; PG8_WAIT_L(0); PG8_MMA(0, 0, At, B0); PG8_BAR; PG8_SCHED;
;             PG8_LDB(B1, 1, 1); PG8_STAGE(PG8_SB(1, 0), b3, voffB);
;             PG8_BAR; PG8_WAIT_L(0); PG8_MMA(0, 1, At, B1); PG8_BAR;
;             PG8_LDA(At, 1, 1); PG8_STAGE(PG8_SA(1, 0), a3, voffA);
;             PG8_BAR; PG8_WAIT_L(0); PG8_MMA(1, 0, At, B0); PG8_BAR; PG8_SCHED;
	s_setprio 1
	v_mfma_f32_16x16x32_bf16 v[60:63], v[140:143], v[164:167], v[60:63]
	v_mfma_f32_16x16x32_bf16 v[56:59], v[156:159], v[164:167], v[56:59]
	v_mfma_f32_16x16x32_bf16 v[48:51], v[140:143], v[172:175], v[48:51]
	v_mfma_f32_16x16x32_bf16 v[40:43], v[156:159], v[172:175], v[40:43]
	v_mfma_f32_16x16x32_bf16 v[28:31], v[140:143], v[180:183], v[28:31]
	v_mfma_f32_16x16x32_bf16 v[24:27], v[156:159], v[180:183], v[24:27]
	v_mfma_f32_16x16x32_bf16 v[16:19], v[140:143], v[188:191], v[16:19]
	v_mfma_f32_16x16x32_bf16 v[8:11], v[156:159], v[188:191], v[8:11]
	v_mfma_f32_16x16x32_bf16 v[60:63], v[152:155], v[168:171], v[60:63]
	v_mfma_f32_16x16x32_bf16 v[56:59], v[160:163], v[168:171], v[56:59]
	v_mfma_f32_16x16x32_bf16 v[48:51], v[152:155], v[176:179], v[48:51]
	v_mfma_f32_16x16x32_bf16 v[40:43], v[160:163], v[176:179], v[40:43]
	v_mfma_f32_16x16x32_bf16 v[28:31], v[152:155], v[184:187], v[28:31]
	v_mfma_f32_16x16x32_bf16 v[24:27], v[160:163], v[184:187], v[24:27]
	v_mfma_f32_16x16x32_bf16 v[16:19], v[152:155], v[192:195], v[16:19]
	v_mfma_f32_16x16x32_bf16 v[8:11], v[160:163], v[192:195], v[8:11]
	v_mfma_f32_16x16x32_bf16 v[52:55], v[196:199], v[164:167], v[52:55]
	v_mfma_f32_16x16x32_bf16 v[44:47], v[204:207], v[164:167], v[44:47]
	v_mfma_f32_16x16x32_bf16 v[36:39], v[196:199], v[172:175], v[36:39]
	v_mfma_f32_16x16x32_bf16 v[32:35], v[204:207], v[172:175], v[32:35]
	v_mfma_f32_16x16x32_bf16 v[20:23], v[196:199], v[180:183], v[20:23]
	v_mfma_f32_16x16x32_bf16 v[12:15], v[204:207], v[180:183], v[12:15]
	v_mfma_f32_16x16x32_bf16 v[4:7], v[196:199], v[188:191], v[4:7]
	v_mfma_f32_16x16x32_bf16 v[0:3], v[204:207], v[188:191], v[0:3]
	v_mfma_f32_16x16x32_bf16 v[52:55], v[200:203], v[168:171], v[52:55]
	v_mfma_f32_16x16x32_bf16 v[44:47], v[208:211], v[168:171], v[44:47]
	v_mfma_f32_16x16x32_bf16 v[36:39], v[200:203], v[176:179], v[36:39]
	v_mfma_f32_16x16x32_bf16 v[32:35], v[208:211], v[176:179], v[32:35]
	v_mfma_f32_16x16x32_bf16 v[20:23], v[200:203], v[184:187], v[20:23]
	v_mfma_f32_16x16x32_bf16 v[12:15], v[208:211], v[184:187], v[12:15]
	v_mfma_f32_16x16x32_bf16 v[4:7], v[200:203], v[192:195], v[4:7]
	v_mfma_f32_16x16x32_bf16 v[0:3], v[208:211], v[192:195], v[0:3]
	s_setprio 0
	s_add_i32 s71, 0, 0x18000
	v_add_u32_e32 v160, s71, v147
	s_barrier
	ds_read_b128 v[140:143], v160
	ds_read_b128 v[152:155], v160 offset:1024
	ds_read_b128 v[156:159], v160 offset:2048
	ds_read_b128 v[160:163], v160 offset:3072
	s_add_u32 s38, s38, 0x40000
	s_addc_u32 s39, s39, 0
	s_mov_b32 m0, s31
	v_lshl_add_u64 v[196:197], s[38:39], 0, v[128:129]
	ds_read_b128 v[164:167], v150 offset:32768
	ds_read_b128 v[168:171], v150 offset:33792
	ds_read_b128 v[172:175], v150 offset:34816
	ds_read_b128 v[176:179], v150 offset:35840
	ds_read_b128 v[180:183], v150 offset:36864
	ds_read_b128 v[184:187], v150 offset:37888
	ds_read_b128 v[188:191], v150 offset:38912
	ds_read_b128 v[192:195], v150 offset:39936
	global_load_lds_dwordx4 v[196:197], off
	v_lshl_add_u64 v[196:197], s[38:39], 0, v[130:131]
	s_mov_b32 m0, s40
	s_nop 0
	global_load_lds_dwordx4 v[196:197], off
	s_add_i32 s38, 0, 0x1c000
	v_add_u32_e32 v208, s38, v147
	ds_read_b128 v[196:199], v208
	ds_read_b128 v[200:203], v208 offset:1024
	ds_read_b128 v[204:207], v208 offset:2048
	ds_read_b128 v[208:211], v208 offset:3072
	s_waitcnt lgkmcnt(0)
	s_barrier
	s_setprio 1
	v_mfma_f32_16x16x32_bf16 v[124:127], v[140:143], v[164:167], v[124:127]
	v_mfma_f32_16x16x32_bf16 v[120:123], v[156:159], v[164:167], v[120:123]
	v_mfma_f32_16x16x32_bf16 v[112:115], v[140:143], v[172:175], v[112:115]
	v_mfma_f32_16x16x32_bf16 v[104:107], v[156:159], v[172:175], v[104:107]
	v_mfma_f32_16x16x32_bf16 v[92:95], v[140:143], v[180:183], v[92:95]
	v_mfma_f32_16x16x32_bf16 v[88:91], v[156:159], v[180:183], v[88:91]
	v_mfma_f32_16x16x32_bf16 v[80:83], v[140:143], v[188:191], v[80:83]
	v_mfma_f32_16x16x32_bf16 v[72:75], v[156:159], v[188:191], v[72:75]
	v_mfma_f32_16x16x32_bf16 v[124:127], v[152:155], v[168:171], v[124:127]
	v_mfma_f32_16x16x32_bf16 v[120:123], v[160:163], v[168:171], v[120:123]
	v_mfma_f32_16x16x32_bf16 v[112:115], v[152:155], v[176:179], v[112:115]
	v_mfma_f32_16x16x32_bf16 v[104:107], v[160:163], v[176:179], v[104:107]
	v_mfma_f32_16x16x32_bf16 v[92:95], v[152:155], v[184:187], v[92:95]
	v_mfma_f32_16x16x32_bf16 v[88:91], v[160:163], v[184:187], v[88:91]
	v_mfma_f32_16x16x32_bf16 v[80:83], v[152:155], v[192:195], v[80:83]
	v_mfma_f32_16x16x32_bf16 v[72:75], v[160:163], v[192:195], v[72:75]
	v_mfma_f32_16x16x32_bf16 v[116:119], v[196:199], v[164:167], v[116:119]
	v_mfma_f32_16x16x32_bf16 v[108:111], v[204:207], v[164:167], v[108:111]
	v_mfma_f32_16x16x32_bf16 v[100:103], v[196:199], v[172:175], v[100:103]
	v_mfma_f32_16x16x32_bf16 v[96:99], v[204:207], v[172:175], v[96:99]
	v_mfma_f32_16x16x32_bf16 v[84:87], v[196:199], v[180:183], v[84:87]
	v_mfma_f32_16x16x32_bf16 v[76:79], v[204:207], v[180:183], v[76:79]
	v_mfma_f32_16x16x32_bf16 v[68:71], v[196:199], v[188:191], v[68:71]
	v_mfma_f32_16x16x32_bf16 v[64:67], v[204:207], v[188:191], v[64:67]
	v_mfma_f32_16x16x32_bf16 v[116:119], v[200:203], v[168:171], v[116:119]
	v_mfma_f32_16x16x32_bf16 v[108:111], v[208:211], v[168:171], v[108:111]
	v_mfma_f32_16x16x32_bf16 v[100:103], v[200:203], v[176:179], v[100:103]
	v_mfma_f32_16x16x32_bf16 v[96:99], v[208:211], v[176:179], v[96:99]
	v_mfma_f32_16x16x32_bf16 v[84:87], v[200:203], v[184:187], v[84:87]
	v_mfma_f32_16x16x32_bf16 v[76:79], v[208:211], v[184:187], v[76:79]
	v_mfma_f32_16x16x32_bf16 v[68:71], v[200:203], v[192:195], v[68:71]
	v_mfma_f32_16x16x32_bf16 v[64:67], v[208:211], v[192:195], v[64:67]
	s_setprio 0
	s_barrier
; #define PG8_STAGE(bufoff, gbase, voff) do { _Pragma("unroll") for (int _i = 0; _i < 2; ++_i) \
;         __builtin_amdgcn_global_load_lds((const unsigned*)((const char*)(gbase) + (voff)[_i]), (LAS unsigned*)(lds + (bufoff) + ldsw + _i * 8192), 16, 0, 0); } while (0)
; #define PG8_LDA(dst, b, h) do { _Pragma("unroll") for (int m = 0; m < 4; ++m) _Pragma("unroll") for (int k = 0; k < 2; ++k) dst[m][k] = *(const LAS bf16x8*)(lds + PG8_SA(b, h) + aoff + m * 2048 + k * 1024); } while (0)
; #define PG8_MMA(ai, bj, At, Bt) do { __builtin_amdgcn_s_setprio(1); _Pragma("unroll") for (int m = 0; m < 4; ++m) _Pragma("unroll") for (int n = 0; n < 2; ++n) _Pragma("unroll") for (int k = 0; k < 2; ++k) \
;         acc[ai][bj][m][n] = __builtin_amdgcn_mfma_f32_16x16x32_bf16(Bt[n][k], At[m][k], acc[ai][bj][m][n], 0, 0, 0); __builtin_amdgcn_s_setprio(0); } while (0)
; template <class Epi>
; __device__ __forceinline__ void gemm_phase(LAS unsigned char* lds, const Gemm g, const StaticOrder& S, const Epi& E) {
;     ...
;             PG8_LDA(At, 1, 1); PG8_STAGE(PG8_SA(1, 0), a3, voffA);
;             PG8_BAR; PG8_WAIT_L(0); PG8_MMA(1, 0, At, B0); PG8_BAR; PG8_SCHED;
;             PG8_STAGE(PG8_SB(1, 1), b3 + hstepB, voffB);
;             PG8_WAIT_V(6); PG8_BAR; PG8_MMA(1, 1, At, B1); PG8_BAR;
;     __device__ __forceinline__ void operator()(AccRef acc, const Unit& u, int wr, int wc, int fr, int fq) const {
;         const int row0 = u.pm * 256 + wr * 64 + fr, col0 = u.pn * 256 + wc * 32 + 4 * fq;
;         f32x4 sv[2][2], bv[2][2];
; #pragma unroll
;         for (int bj = 0; bj < 2; ++bj)
; #pragma unroll
;             for (int n = 0; n < 2; ++n) {
;                 sv[bj][n] = scale ? *(const f32x4*)(scale + col0 + bj * 128 + n * 16) : (f32x4){1.f, 1.f, 1.f, 1.f};
;                 bv[bj][n] = bias ? *(const f32x4*)(bias + col0 + bj * 128 + n * 16) : (f32x4){0.f, 0.f, 0.f, 0.f}; }
; #pragma unroll
;         for (int ai = 0; ai < 2; ++ai)
; #pragma unroll
;             for (int mh = 0; mh < 2; ++mh) {
;                 f32x4 bs[2][2][2];
; #pragma unroll
;                 for (int m = 0; m < 2; ++m)
; #pragma unroll
;                     for (int bj = 0; bj < 2; ++bj)
; #pragma unroll
;                         for (int n = 0; n < 2; ++n) bs[m][bj][n] = *(const f32x4*)(base + (size_t)(row0 + ai * 128 + (2 * mh + m) * 16) * D + col0 + bj * 128 + n * 16);
	s_nop 1
	ds_read_b128 v[164:167], v150 offset:49152
	ds_read_b128 v[168:171], v150 offset:50176
	ds_read_b128 v[172:175], v150 offset:51200
	ds_read_b128 v[176:179], v150 offset:52224
	ds_read_b128 v[180:183], v150 offset:53248
	ds_read_b128 v[184:187], v150 offset:54272
	ds_read_b128 v[188:191], v150 offset:55296
	ds_read_b128 v[192:195], v150 offset:56320
	s_add_i32 s39, s71, s7
	v_lshl_add_u64 v[254:255], v[144:145], 0, s[12:13]
	s_mov_b32 m0, s39
	s_nop 0
	global_load_lds_dwordx4 v[254:255], off
	v_lshl_add_u64 v[254:255], v[212:213], 0, s[12:13]
	s_add_i32 m0, s39, 0x2000
	s_nop 0
	global_load_lds_dwordx4 v[254:255], off
	s_mov_b32 m0, s42
	v_lshl_add_u64 v[254:255], v[214:215], 0, s[12:13]
	global_load_lds_dwordx4 v[254:255], off
	v_lshl_add_u64 v[144:145], v[216:217], 0, s[12:13]
	s_mov_b32 m0, s43
	s_nop 0
	global_load_lds_dwordx4 v[144:145], off
	s_add_u32 s36, s36, 0x40080
	s_addc_u32 s37, s37, 0
	s_add_i32 s38, s38, s7
	v_lshl_add_u64 v[254:255], s[36:37], 0, v[128:129]
	s_mov_b32 m0, s38
	s_nop 0
	global_load_lds_dwordx4 v[254:255], off
	v_lshl_add_u64 v[254:255], s[36:37], 0, v[130:131]
	s_add_i32 m0, s38, 0x2000
	s_nop 0
	global_load_lds_dwordx4 v[254:255], off
	s_waitcnt vmcnt(6)
	s_waitcnt lgkmcnt(0)
	s_barrier
	s_setprio 1
	v_mfma_f32_16x16x32_bf16 v[60:63], v[140:143], v[164:167], v[60:63]
	v_mfma_f32_16x16x32_bf16 v[56:59], v[156:159], v[164:167], v[56:59]
	v_mfma_f32_16x16x32_bf16 v[48:51], v[140:143], v[172:175], v[48:51]
	v_mfma_f32_16x16x32_bf16 v[40:43], v[156:159], v[172:175], v[40:43]
	v_mfma_f32_16x16x32_bf16 v[28:31], v[140:143], v[180:183], v[28:31]
	v_mfma_f32_16x16x32_bf16 v[24:27], v[156:159], v[180:183], v[24:27]
	v_mfma_f32_16x16x32_bf16 v[16:19], v[140:143], v[188:191], v[16:19]
	v_mfma_f32_16x16x32_bf16 v[8:11], v[156:159], v[188:191], v[8:11]
	v_mfma_f32_16x16x32_bf16 v[60:63], v[152:155], v[168:171], v[60:63]
	v_mfma_f32_16x16x32_bf16 v[56:59], v[160:163], v[168:171], v[56:59]
	v_mfma_f32_16x16x32_bf16 v[48:51], v[152:155], v[176:179], v[48:51]
	v_mfma_f32_16x16x32_bf16 v[40:43], v[160:163], v[176:179], v[40:43]
	v_mfma_f32_16x16x32_bf16 v[28:31], v[152:155], v[184:187], v[28:31]
	v_mfma_f32_16x16x32_bf16 v[24:27], v[160:163], v[184:187], v[24:27]
	v_mfma_f32_16x16x32_bf16 v[16:19], v[152:155], v[192:195], v[16:19]
	v_mfma_f32_16x16x32_bf16 v[8:11], v[160:163], v[192:195], v[8:11]
	v_mfma_f32_16x16x32_bf16 v[52:55], v[196:199], v[164:167], v[52:55]
	v_mfma_f32_16x16x32_bf16 v[44:47], v[204:207], v[164:167], v[44:47]
	v_mfma_f32_16x16x32_bf16 v[36:39], v[196:199], v[172:175], v[36:39]
	v_mfma_f32_16x16x32_bf16 v[32:35], v[204:207], v[172:175], v[32:35]
	v_mfma_f32_16x16x32_bf16 v[20:23], v[196:199], v[180:183], v[20:23]
	v_mfma_f32_16x16x32_bf16 v[12:15], v[204:207], v[180:183], v[12:15]
	v_mfma_f32_16x16x32_bf16 v[4:7], v[196:199], v[188:191], v[4:7]
	v_mfma_f32_16x16x32_bf16 v[0:3], v[204:207], v[188:191], v[0:3]
	v_mfma_f32_16x16x32_bf16 v[52:55], v[200:203], v[168:171], v[52:55]
	v_mfma_f32_16x16x32_bf16 v[44:47], v[208:211], v[168:171], v[44:47]
	v_mfma_f32_16x16x32_bf16 v[36:39], v[200:203], v[176:179], v[36:39]
	v_mfma_f32_16x16x32_bf16 v[32:35], v[208:211], v[176:179], v[32:35]
	v_mfma_f32_16x16x32_bf16 v[20:23], v[200:203], v[184:187], v[20:23]
	v_mfma_f32_16x16x32_bf16 v[12:15], v[208:211], v[184:187], v[12:15]
	v_mfma_f32_16x16x32_bf16 v[4:7], v[200:203], v[192:195], v[4:7]
	v_mfma_f32_16x16x32_bf16 v[0:3], v[208:211], v[192:195], v[0:3]
	s_setprio 0
	s_add_i32 s70, s70, 2
	s_add_u32 s34, s34, 0x100
	s_addc_u32 s35, s35, 0
	s_add_u32 s49, s49, 0x100
	s_addc_u32 s63, s63, 0
	s_cmp_gt_u32 s70, 13
	s_barrier
	s_cbranch_scc0 .LBB0_1820
	v_lshl_or_b32 v140, s46, 8, v148
	v_ashrrev_i32_e32 v141, 31, v140
	v_lshl_add_u32 v184, s30, 8, v146
	v_lshlrev_b64 v[140:141], 2, v[140:141]
	v_ashrrev_i32_e32 v185, 31, v184
	v_or_b32_e32 v168, 16, v184
	v_lshl_add_u64 v[142:143], s[52:53], 0, v[140:141]
	v_lshlrev_b64 v[144:145], 12, v[184:185]
	v_ashrrev_i32_e32 v169, 31, v168
	v_lshl_add_u64 v[164:165], v[142:143], 0, v[144:145]
	v_lshlrev_b64 v[186:187], 12, v[168:169]
	global_load_dwordx4 v[152:155], v[164:165], off
	global_load_dwordx4 v[156:159], v[164:165], off offset:64
	global_load_dwordx4 v[160:163], v[164:165], off offset:512
	s_nop 0
	global_load_dwordx4 v[164:167], v[164:165], off offset:576
	v_lshl_add_u64 v[180:181], v[142:143], 0, v[186:187]
	global_load_dwordx4 v[168:171], v[180:181], off
	global_load_dwordx4 v[172:175], v[180:181], off offset:64
	global_load_dwordx4 v[176:179], v[180:181], off offset:512
	s_nop 0
	global_load_dwordx4 v[180:183], v[180:181], off offset:576
	v_pk_add_f32 v[198:199], v[96:97], 0 op_sel_hi:[1,0]
	v_or_b32_e32 v96, 32, v184
	v_ashrrev_i32_e32 v97, 31, v96
	v_pk_add_f32 v[126:127], v[126:127], 0 op_sel_hi:[1,0]
	v_pk_add_f32 v[124:125], v[124:125], 0 op_sel_hi:[1,0]
	v_pk_add_f32 v[108:109], v[108:109], 0 op_sel_hi:[1,0]
	v_pk_add_f32 v[196:197], v[98:99], 0 op_sel_hi:[1,0]
	v_lshl_add_u64 v[98:99], s[52:53], 0, v[144:145]
	v_lshlrev_b64 v[200:201], 12, v[96:97]
	v_lshl_add_u64 v[96:97], s[52:53], 0, v[186:187]
	v_pk_add_f32 v[122:123], v[122:123], 0 op_sel_hi:[1,0]
	v_pk_add_f32 v[120:121], v[120:121], 0 op_sel_hi:[1,0]
	v_pk_add_f32 v[118:119], v[118:119], 0 op_sel_hi:[1,0]
	v_pk_add_f32 v[116:117], v[116:117], 0 op_sel_hi:[1,0]
	v_pk_add_f32 v[110:111], v[110:111], 0 op_sel_hi:[1,0]
	v_pk_add_f32 v[114:115], v[114:115], 0 op_sel_hi:[1,0]
	v_pk_add_f32 v[112:113], v[112:113], 0 op_sel_hi:[1,0]
	v_pk_add_f32 v[188:189], v[106:107], 0 op_sel_hi:[1,0]
	v_pk_add_f32 v[190:191], v[104:105], 0 op_sel_hi:[1,0]
	v_pk_add_f32 v[192:193], v[102:103], 0 op_sel_hi:[1,0]
;     __device__ __forceinline__ void operator()(AccRef acc, const Unit& u, int wr, int wc, int fr, int fq) const {
;     ...
;         for (int ai = 0; ai < 2; ++ai)
; #pragma unroll
;             for (int mh = 0; mh < 2; ++mh) {
;                 f32x4 bs[2][2][2];
; #pragma unroll
;                 for (int m = 0; m < 2; ++m)
; #pragma unroll
;                     for (int bj = 0; bj < 2; ++bj)
; #pragma unroll
;                         for (int n = 0; n < 2; ++n) bs[m][bj][n] = *(const f32x4*)(base + (size_t)(row0 + ai * 128 + (2 * mh + m) * 16) * D + col0 + bj * 128 + n * 16);
; #pragma unroll
;                 for (int m = 0; m < 2; ++m)
; #pragma unroll
;                     for (int bj = 0; bj < 2; ++bj)
; #pragma unroll
;                         for (int n = 0; n < 2; ++n) *(f32x4*)(out + (size_t)(row0 + ai * 128 + (2 * mh + m) * 16) * D + col0 + bj * 128 + n * 16) = bs[m][bj][n] + sv[bj][n] * (acc[ai][bj][2 * mh + m][n] + bv[bj][n]);
	v_pk_add_f32 v[194:195], v[100:101], 0 op_sel_hi:[1,0]
	v_lshl_add_u64 v[202:203], v[98:99], 0, v[140:141]
	v_lshl_add_u64 v[204:205], v[96:97], 0, v[140:141]
	v_lshl_add_u64 v[186:187], v[142:143], 0, v[200:201]
	v_pk_add_f32 v[94:95], v[94:95], 0 op_sel_hi:[1,0]
	v_pk_add_f32 v[92:93], v[92:93], 0 op_sel_hi:[1,0]
	v_pk_add_f32 v[90:91], v[90:91], 0 op_sel_hi:[1,0]
	v_pk_add_f32 v[88:89], v[88:89], 0 op_sel_hi:[1,0]
	v_pk_add_f32 v[86:87], v[86:87], 0 op_sel_hi:[1,0]
	v_pk_add_f32 v[84:85], v[84:85], 0 op_sel_hi:[1,0]
	v_pk_add_f32 v[78:79], v[78:79], 0 op_sel_hi:[1,0]
	v_pk_add_f32 v[76:77], v[76:77], 0 op_sel_hi:[1,0]
	v_pk_add_f32 v[82:83], v[82:83], 0 op_sel_hi:[1,0]
	v_pk_add_f32 v[80:81], v[80:81], 0 op_sel_hi:[1,0]
	v_pk_add_f32 v[62:63], v[62:63], 0 op_sel_hi:[1,0]
	v_pk_add_f32 v[60:61], v[60:61], 0 op_sel_hi:[1,0]
	v_pk_add_f32 v[58:59], v[58:59], 0 op_sel_hi:[1,0]
	v_pk_add_f32 v[56:57], v[56:57], 0 op_sel_hi:[1,0]
	v_pk_add_f32 v[54:55], v[54:55], 0 op_sel_hi:[1,0]
	v_pk_add_f32 v[52:53], v[52:53], 0 op_sel_hi:[1,0]
	v_pk_add_f32 v[46:47], v[46:47], 0 op_sel_hi:[1,0]
	v_pk_add_f32 v[44:45], v[44:45], 0 op_sel_hi:[1,0]
	v_pk_add_f32 v[50:51], v[50:51], 0 op_sel_hi:[1,0]
	v_pk_add_f32 v[48:49], v[48:49], 0 op_sel_hi:[1,0]
	v_pk_add_f32 v[30:31], v[30:31], 0 op_sel_hi:[1,0]
	v_pk_add_f32 v[28:29], v[28:29], 0 op_sel_hi:[1,0]
	v_pk_add_f32 v[26:27], v[26:27], 0 op_sel_hi:[1,0]
	v_pk_add_f32 v[24:25], v[24:25], 0 op_sel_hi:[1,0]
	v_pk_add_f32 v[22:23], v[22:23], 0 op_sel_hi:[1,0]
	v_pk_add_f32 v[20:21], v[20:21], 0 op_sel_hi:[1,0]
	v_pk_add_f32 v[14:15], v[14:15], 0 op_sel_hi:[1,0]
	v_pk_add_f32 v[12:13], v[12:13], 0 op_sel_hi:[1,0]
	v_pk_add_f32 v[18:19], v[18:19], 0 op_sel_hi:[1,0]
	v_pk_add_f32 v[16:17], v[16:17], 0 op_sel_hi:[1,0]
	s_and_b64 vcc, exec, s[10:11]
	s_mov_b32 s46, s22
	s_mov_b32 s30, s24
	s_mov_b64 s[36:37], s[28:29]
	s_mov_b64 s[34:35], s[26:27]
	s_waitcnt vmcnt(0)
	v_pk_add_f32 v[98:99], v[126:127], v[154:155]
	v_pk_add_f32 v[96:97], v[124:125], v[152:153]
	v_pk_add_f32 v[102:103], v[122:123], v[158:159]
	v_pk_add_f32 v[108:109], v[108:109], v[164:165]
	v_pk_add_f32 v[100:101], v[120:121], v[156:157]
	v_pk_add_f32 v[106:107], v[118:119], v[162:163]
	v_pk_add_f32 v[104:105], v[116:117], v[160:161]
	v_pk_add_f32 v[110:111], v[110:111], v[166:167]
	v_pk_add_f32 v[114:115], v[114:115], v[170:171]
	v_pk_add_f32 v[112:113], v[112:113], v[168:169]
	v_pk_add_f32 v[118:119], v[188:189], v[174:175]
	v_pk_add_f32 v[116:117], v[190:191], v[172:173]
	v_pk_add_f32 v[122:123], v[192:193], v[178:179]
	v_pk_add_f32 v[120:121], v[194:195], v[176:177]
	v_pk_add_f32 v[126:127], v[196:197], v[182:183]
	v_pk_add_f32 v[124:125], v[198:199], v[180:181]
	global_store_dwordx4 v[202:203], v[96:99], off
	global_store_dwordx4 v[202:203], v[100:103], off offset:64
	global_store_dwordx4 v[202:203], v[104:107], off offset:512
	global_store_dwordx4 v[202:203], v[108:111], off offset:576
	global_store_dwordx4 v[204:205], v[112:115], off
	global_store_dwordx4 v[204:205], v[116:119], off offset:64
	global_store_dwordx4 v[204:205], v[120:123], off offset:512
	global_store_dwordx4 v[204:205], v[124:127], off offset:576
	v_or_b32_e32 v108, 48, v184
	v_ashrrev_i32_e32 v109, 31, v108
	v_lshlrev_b64 v[152:153], 12, v[108:109]
	global_load_dwordx4 v[96:99], v[186:187], off
	global_load_dwordx4 v[100:103], v[186:187], off offset:64
	v_lshl_add_u64 v[124:125], v[142:143], 0, v[152:153]
	global_load_dwordx4 v[104:107], v[186:187], off offset:512
	global_load_dwordx4 v[108:111], v[186:187], off offset:576
	global_load_dwordx4 v[112:115], v[124:125], off
	global_load_dwordx4 v[116:119], v[124:125], off offset:64
	global_load_dwordx4 v[120:123], v[124:125], off offset:512
	s_nop 0
	global_load_dwordx4 v[124:127], v[124:125], off offset:576
	v_pk_add_f32 v[162:163], v[66:67], 0 op_sel_hi:[1,0]
	v_pk_add_f32 v[164:165], v[64:65], 0 op_sel_hi:[1,0]
	v_lshl_add_u64 v[64:65], s[52:53], 0, v[200:201]
	v_lshl_add_u64 v[66:67], s[52:53], 0, v[152:153]
	v_pk_add_f32 v[154:155], v[74:75], 0 op_sel_hi:[1,0]
	v_pk_add_f32 v[156:157], v[72:73], 0 op_sel_hi:[1,0]
	v_pk_add_f32 v[158:159], v[70:71], 0 op_sel_hi:[1,0]
	v_pk_add_f32 v[160:161], v[68:69], 0 op_sel_hi:[1,0]
	v_lshl_add_u64 v[168:169], v[64:65], 0, v[140:141]
	v_lshl_add_u64 v[170:171], v[66:67], 0, v[140:141]
	v_lshl_add_u64 v[166:167], v[144:145], 0, s[14:15]
	v_lshl_add_u64 v[152:153], v[142:143], 0, v[166:167]
	s_waitcnt vmcnt(0)
;     __device__ __forceinline__ void operator()(AccRef acc, const Unit& u, int wr, int wc, int fr, int fq) const {
;     ...
;         for (int ai = 0; ai < 2; ++ai)
; #pragma unroll
;             for (int mh = 0; mh < 2; ++mh) {
;                 f32x4 bs[2][2][2];
; #pragma unroll
;                 for (int m = 0; m < 2; ++m)
; #pragma unroll
;                     for (int bj = 0; bj < 2; ++bj)
; #pragma unroll
;                         for (int n = 0; n < 2; ++n) bs[m][bj][n] = *(const f32x4*)(base + (size_t)(row0 + ai * 128 + (2 * mh + m) * 16) * D + col0 + bj * 128 + n * 16);
; #pragma unroll
;                 for (int m = 0; m < 2; ++m)
; #pragma unroll
;                     for (int bj = 0; bj < 2; ++bj)
; #pragma unroll
;                         for (int n = 0; n < 2; ++n) *(f32x4*)(out + (size_t)(row0 + ai * 128 + (2 * mh + m) * 16) * D + col0 + bj * 128 + n * 16) = bs[m][bj][n] + sv[bj][n] * (acc[ai][bj][2 * mh + m][n] + bv[bj][n]);
;                 asm volatile("" ::: "memory"); }
	v_pk_add_f32 v[66:67], v[94:95], v[98:99]
	v_pk_add_f32 v[64:65], v[92:93], v[96:97]
	v_pk_add_f32 v[70:71], v[90:91], v[102:103]
	v_pk_add_f32 v[68:69], v[88:89], v[100:101]
	v_pk_add_f32 v[74:75], v[86:87], v[106:107]
	v_pk_add_f32 v[72:73], v[84:85], v[104:105]
	v_pk_add_f32 v[78:79], v[78:79], v[110:111]
	v_pk_add_f32 v[76:77], v[76:77], v[108:109]
	v_pk_add_f32 v[82:83], v[82:83], v[114:115]
	v_pk_add_f32 v[80:81], v[80:81], v[112:113]
	v_pk_add_f32 v[86:87], v[154:155], v[118:119]
	v_pk_add_f32 v[84:85], v[156:157], v[116:117]
	v_pk_add_f32 v[90:91], v[158:159], v[122:123]
	v_pk_add_f32 v[88:89], v[160:161], v[120:121]
	v_pk_add_f32 v[94:95], v[162:163], v[126:127]
	v_pk_add_f32 v[92:93], v[164:165], v[124:125]
	global_store_dwordx4 v[168:169], v[64:67], off
	global_store_dwordx4 v[168:169], v[68:71], off offset:64
	global_store_dwordx4 v[168:169], v[72:75], off offset:512
	global_store_dwordx4 v[168:169], v[76:79], off offset:576
	global_store_dwordx4 v[170:171], v[80:83], off
	global_store_dwordx4 v[170:171], v[84:87], off offset:64
	global_store_dwordx4 v[170:171], v[88:91], off offset:512
	global_store_dwordx4 v[170:171], v[92:95], off offset:576
	v_lshl_add_u64 v[96:97], v[144:145], 0, s[16:17]
	global_load_dwordx4 v[64:67], v[152:153], off
	global_load_dwordx4 v[68:71], v[152:153], off offset:64
	global_load_dwordx4 v[72:75], v[152:153], off offset:512
	v_lshl_add_u64 v[92:93], v[142:143], 0, v[96:97]
	global_load_dwordx4 v[76:79], v[152:153], off offset:576
	global_load_dwordx4 v[80:83], v[92:93], off
	global_load_dwordx4 v[84:87], v[92:93], off offset:64
	global_load_dwordx4 v[88:91], v[92:93], off offset:512
	s_nop 0
	global_load_dwordx4 v[92:95], v[92:93], off offset:576
	v_pk_add_f32 v[106:107], v[34:35], 0 op_sel_hi:[1,0]
	v_pk_add_f32 v[108:109], v[32:33], 0 op_sel_hi:[1,0]
	v_lshl_add_u64 v[32:33], s[52:53], 0, v[166:167]
	v_lshl_add_u64 v[34:35], s[52:53], 0, v[96:97]
	v_pk_add_f32 v[98:99], v[42:43], 0 op_sel_hi:[1,0]
	v_pk_add_f32 v[100:101], v[40:41], 0 op_sel_hi:[1,0]
	v_pk_add_f32 v[102:103], v[38:39], 0 op_sel_hi:[1,0]
	v_pk_add_f32 v[104:105], v[36:37], 0 op_sel_hi:[1,0]
	v_lshl_add_u64 v[112:113], v[32:33], 0, v[140:141]
	v_lshl_add_u64 v[114:115], v[34:35], 0, v[140:141]
	v_lshl_add_u64 v[110:111], v[144:145], 0, s[18:19]
	v_lshl_add_u64 v[96:97], v[142:143], 0, v[110:111]
	s_waitcnt vmcnt(0)
	v_pk_add_f32 v[34:35], v[62:63], v[66:67]
	v_pk_add_f32 v[32:33], v[60:61], v[64:65]
	v_pk_add_f32 v[38:39], v[58:59], v[70:71]
	v_pk_add_f32 v[36:37], v[56:57], v[68:69]
	v_pk_add_f32 v[42:43], v[54:55], v[74:75]
	v_pk_add_f32 v[40:41], v[52:53], v[72:73]
	v_pk_add_f32 v[46:47], v[46:47], v[78:79]
	v_pk_add_f32 v[44:45], v[44:45], v[76:77]
	v_pk_add_f32 v[50:51], v[50:51], v[82:83]
	v_pk_add_f32 v[48:49], v[48:49], v[80:81]
	v_pk_add_f32 v[54:55], v[98:99], v[86:87]
	v_pk_add_f32 v[52:53], v[100:101], v[84:85]
	v_pk_add_f32 v[58:59], v[102:103], v[90:91]
	v_pk_add_f32 v[56:57], v[104:105], v[88:89]
	v_pk_add_f32 v[62:63], v[106:107], v[94:95]
	v_pk_add_f32 v[60:61], v[108:109], v[92:93]
	global_store_dwordx4 v[112:113], v[32:35], off
	global_store_dwordx4 v[112:113], v[36:39], off offset:64
	global_store_dwordx4 v[112:113], v[40:43], off offset:512
	global_store_dwordx4 v[112:113], v[44:47], off offset:576
	global_store_dwordx4 v[114:115], v[48:51], off
	global_store_dwordx4 v[114:115], v[52:55], off offset:64
	global_store_dwordx4 v[114:115], v[56:59], off offset:512
	global_store_dwordx4 v[114:115], v[60:63], off offset:576
	v_lshl_add_u64 v[64:65], v[144:145], 0, s[20:21]
	global_load_dwordx4 v[32:35], v[96:97], off
	global_load_dwordx4 v[36:39], v[96:97], off offset:64
	global_load_dwordx4 v[40:43], v[96:97], off offset:512
	v_lshl_add_u64 v[60:61], v[142:143], 0, v[64:65]
	global_load_dwordx4 v[44:47], v[96:97], off offset:576
	global_load_dwordx4 v[48:51], v[60:61], off
	global_load_dwordx4 v[52:55], v[60:61], off offset:64
	global_load_dwordx4 v[56:59], v[60:61], off offset:512
	s_nop 0
	global_load_dwordx4 v[60:63], v[60:61], off offset:576
	v_pk_add_f32 v[74:75], v[2:3], 0 op_sel_hi:[1,0]
	v_pk_add_f32 v[76:77], v[0:1], 0 op_sel_hi:[1,0]
	v_lshl_add_u64 v[0:1], s[52:53], 0, v[110:111]
	v_lshl_add_u64 v[2:3], s[52:53], 0, v[64:65]
	v_pk_add_f32 v[66:67], v[10:11], 0 op_sel_hi:[1,0]
	v_pk_add_f32 v[68:69], v[8:9], 0 op_sel_hi:[1,0]
	v_pk_add_f32 v[70:71], v[6:7], 0 op_sel_hi:[1,0]
	v_pk_add_f32 v[72:73], v[4:5], 0 op_sel_hi:[1,0]
	v_lshl_add_u64 v[64:65], v[0:1], 0, v[140:141]
	v_lshl_add_u64 v[78:79], v[2:3], 0, v[140:141]
	s_waitcnt vmcnt(0)
	v_pk_add_f32 v[2:3], v[30:31], v[34:35]
	v_pk_add_f32 v[0:1], v[28:29], v[32:33]
	v_pk_add_f32 v[6:7], v[26:27], v[38:39]
	v_pk_add_f32 v[4:5], v[24:25], v[36:37]
	v_pk_add_f32 v[10:11], v[22:23], v[42:43]
	v_pk_add_f32 v[8:9], v[20:21], v[40:41]
	v_pk_add_f32 v[14:15], v[14:15], v[46:47]
	v_pk_add_f32 v[12:13], v[12:13], v[44:45]
	v_pk_add_f32 v[18:19], v[18:19], v[50:51]
	v_pk_add_f32 v[16:17], v[16:17], v[48:49]
	v_pk_add_f32 v[22:23], v[66:67], v[54:55]
	v_pk_add_f32 v[20:21], v[68:69], v[52:53]
	v_pk_add_f32 v[26:27], v[70:71], v[58:59]
	v_pk_add_f32 v[24:25], v[72:73], v[56:57]
	v_pk_add_f32 v[30:31], v[74:75], v[62:63]
	v_pk_add_f32 v[28:29], v[76:77], v[60:61]
	global_store_dwordx4 v[64:65], v[0:3], off
	global_store_dwordx4 v[64:65], v[4:7], off offset:64
	global_store_dwordx4 v[64:65], v[8:11], off offset:512
	global_store_dwordx4 v[64:65], v[12:15], off offset:576
	global_store_dwordx4 v[78:79], v[16:19], off
	global_store_dwordx4 v[78:79], v[20:23], off offset:64
	global_store_dwordx4 v[78:79], v[24:27], off offset:512
	global_store_dwordx4 v[78:79], v[28:31], off offset:576
	s_cbranch_vccz .LBB0_1813
	s_waitcnt vmcnt(0)
	s_cmpk_gt_u32 s4, 0xff
	s_cbranch_scc1 .LBB0_1824
	s_barrier

; #define PG8_STAGE(bufoff, gbase, voff) do { _Pragma("unroll") for (int _i = 0; _i < 2; ++_i) \
;         __builtin_amdgcn_global_load_lds((const unsigned*)((const char*)(gbase) + (voff)[_i]), (LAS unsigned*)(lds + (bufoff) + ldsw + _i * 8192), 16, 0, 0); } while (0)
; #define PG8_LDA(dst, b, h) do { _Pragma("unroll") for (int m = 0; m < 4; ++m) _Pragma("unroll") for (int k = 0; k < 2; ++k) dst[m][k] = *(const LAS bf16x8*)(lds + PG8_SA(b, h) + aoff + m * 2048 + k * 1024); } while (0)
; #define PG8_LDB(dst, b, h) do { _Pragma("unroll") for (int n = 0; n < 2; ++n) _Pragma("unroll") for (int k = 0; k < 2; ++k) dst[n][k] = *(const LAS bf16x8*)(lds + PG8_SB(b, h) + boff + n * 2048 + k * 1024); } while (0)
; #define PG8_MMA(ai, bj, At, Bt) do { __builtin_amdgcn_s_setprio(1); _Pragma("unroll") for (int m = 0; m < 4; ++m) _Pragma("unroll") for (int n = 0; n < 2; ++n) _Pragma("unroll") for (int k = 0; k < 2; ++k) \
;         acc[ai][bj][m][n] = __builtin_amdgcn_mfma_f32_16x16x32_bf16(Bt[n][k], At[m][k], acc[ai][bj][m][n], 0, 0, 0); __builtin_amdgcn_s_setprio(0); } while (0)
; #define PG8_WAIT_V(n) asm volatile("s_waitcnt vmcnt(" #n ")" ::: "memory")
; #define PG8_WAIT_L(n) asm volatile("s_waitcnt lgkmcnt(" #n ")" ::: "memory")
; #define PG8_BAR __builtin_amdgcn_s_barrier()
; #define PG8_SCHED __builtin_amdgcn_sched_barrier(0)
; template <class Epi>
; __device__ __forceinline__ void gemm_phase(LAS unsigned char* lds, const Gemm g, const StaticOrder& S, const Epi& E) {
;     ...
;             PG8_LDB(B0, 0, 0); PG8_SCHED; PG8_LDA(At, 0, 0); PG8_STAGE(PG8_SA(1, 1), a1 + hstepA, voffA);
;             PG8_WAIT_L(8); PG8_BAR; PG8_WAIT_L(0); PG8_MMA(0, 0, At, B0); PG8_BAR; PG8_SCHED;
;             PG8_LDB(B1, 0, 1); PG8_STAGE(PG8_SB(0, 0), b2, voffB);
;             PG8_BAR; PG8_WAIT_L(0); PG8_MMA(0, 1, At, B1); PG8_BAR;
;             PG8_LDA(At, 0, 1); PG8_STAGE(PG8_SA(0, 0), a2, voffA);
;             PG8_BAR; PG8_WAIT_L(0); PG8_MMA(1, 0, At, B0); PG8_BAR; PG8_SCHED;
;             PG8_STAGE(PG8_SB(0, 1), b2 + hstepB, voffB);
;             PG8_WAIT_V(6); PG8_BAR; PG8_MMA(1, 1, At, B1); PG8_BAR;
.LBB0_2042:
	ds_read_b128 v[140:143], v149
	ds_read_b128 v[152:155], v149 offset:1024
	ds_read_b128 v[156:159], v149 offset:2048
	ds_read_b128 v[160:163], v149 offset:3072
	s_add_u32 s20, s18, 0x100
	s_addc_u32 s21, s19, 0
	s_cmp_eq_u32 s46, 40
	s_cselect_b32 s25, s5, s21
	s_cselect_b32 s24, s4, s20
	s_cselect_b32 s23, s7, s45
	s_cselect_b32 s22, s6, s44
	v_lshl_add_u64 v[144:145], s[18:19], 0, v[132:133]
	s_add_i32 m0, s30, 0xc000
	ds_read_b128 v[164:167], v150
	ds_read_b128 v[168:171], v150 offset:1024
	ds_read_b128 v[172:175], v150 offset:2048
	ds_read_b128 v[176:179], v150 offset:3072
	ds_read_b128 v[180:183], v150 offset:4096
	ds_read_b128 v[184:187], v150 offset:5120
	ds_read_b128 v[188:191], v150 offset:6144
	ds_read_b128 v[192:195], v150 offset:7168
	global_load_lds_dwordx4 v[144:145], off
	v_lshl_add_u64 v[144:145], s[18:19], 0, v[134:135]
	s_add_i32 m0, s30, 0xe000
	s_nop 0
	global_load_lds_dwordx4 v[144:145], off
	ds_read_b128 v[196:199], v151
	ds_read_b128 v[200:203], v151 offset:1024
	ds_read_b128 v[204:207], v151 offset:2048
	ds_read_b128 v[208:211], v151 offset:3072
	s_waitcnt lgkmcnt(0)
	s_barrier
	s_setprio 1
	v_mfma_f32_16x16x32_bf16 v[124:127], v[140:143], v[164:167], v[124:127]
	v_mfma_f32_16x16x32_bf16 v[120:123], v[156:159], v[164:167], v[120:123]
	v_mfma_f32_16x16x32_bf16 v[112:115], v[140:143], v[172:175], v[112:115]
	v_mfma_f32_16x16x32_bf16 v[104:107], v[156:159], v[172:175], v[104:107]
	v_mfma_f32_16x16x32_bf16 v[92:95], v[140:143], v[180:183], v[92:95]
	v_mfma_f32_16x16x32_bf16 v[88:91], v[156:159], v[180:183], v[88:91]
	v_mfma_f32_16x16x32_bf16 v[80:83], v[140:143], v[188:191], v[80:83]
	v_mfma_f32_16x16x32_bf16 v[72:75], v[156:159], v[188:191], v[72:75]
	v_mfma_f32_16x16x32_bf16 v[124:127], v[152:155], v[168:171], v[124:127]
	v_mfma_f32_16x16x32_bf16 v[120:123], v[160:163], v[168:171], v[120:123]
	v_mfma_f32_16x16x32_bf16 v[112:115], v[152:155], v[176:179], v[112:115]
	v_mfma_f32_16x16x32_bf16 v[104:107], v[160:163], v[176:179], v[104:107]
	v_mfma_f32_16x16x32_bf16 v[92:95], v[152:155], v[184:187], v[92:95]
	v_mfma_f32_16x16x32_bf16 v[88:91], v[160:163], v[184:187], v[88:91]
	v_mfma_f32_16x16x32_bf16 v[80:83], v[152:155], v[192:195], v[80:83]
	v_mfma_f32_16x16x32_bf16 v[72:75], v[160:163], v[192:195], v[72:75]
	v_mfma_f32_16x16x32_bf16 v[116:119], v[196:199], v[164:167], v[116:119]
	v_mfma_f32_16x16x32_bf16 v[108:111], v[204:207], v[164:167], v[108:111]
	v_mfma_f32_16x16x32_bf16 v[100:103], v[196:199], v[172:175], v[100:103]
	v_mfma_f32_16x16x32_bf16 v[96:99], v[204:207], v[172:175], v[96:99]
	v_mfma_f32_16x16x32_bf16 v[84:87], v[196:199], v[180:183], v[84:87]
	v_mfma_f32_16x16x32_bf16 v[76:79], v[204:207], v[180:183], v[76:79]
	v_mfma_f32_16x16x32_bf16 v[68:71], v[196:199], v[188:191], v[68:71]
	v_mfma_f32_16x16x32_bf16 v[64:67], v[204:207], v[188:191], v[64:67]
	v_mfma_f32_16x16x32_bf16 v[116:119], v[200:203], v[168:171], v[116:119]
	v_mfma_f32_16x16x32_bf16 v[108:111], v[208:211], v[168:171], v[108:111]
	v_mfma_f32_16x16x32_bf16 v[100:103], v[200:203], v[176:179], v[100:103]
	v_mfma_f32_16x16x32_bf16 v[96:99], v[208:211], v[176:179], v[96:99]
	v_mfma_f32_16x16x32_bf16 v[84:87], v[200:203], v[184:187], v[84:87]
	v_mfma_f32_16x16x32_bf16 v[76:79], v[208:211], v[184:187], v[76:79]
	v_mfma_f32_16x16x32_bf16 v[68:71], v[200:203], v[192:195], v[68:71]
	v_mfma_f32_16x16x32_bf16 v[64:67], v[208:211], v[192:195], v[64:67]
	s_setprio 0
	s_barrier
	s_nop 1
	ds_read_b128 v[164:167], v150 offset:16384
	ds_read_b128 v[168:171], v150 offset:17408
	ds_read_b128 v[172:175], v150 offset:18432
	ds_read_b128 v[176:179], v150 offset:19456
	ds_read_b128 v[180:183], v150 offset:20480
	ds_read_b128 v[184:187], v150 offset:21504
	ds_read_b128 v[188:191], v150 offset:22528
	ds_read_b128 v[192:195], v150 offset:23552
	s_add_i32 s18, s38, s29
	v_lshl_add_u64 v[144:145], s[22:23], 0, v[128:129]
	s_mov_b32 m0, s18
	s_nop 0
	global_load_lds_dwordx4 v[144:145], off
	v_lshl_add_u64 v[212:213], s[22:23], 0, v[130:131]
	s_add_i32 m0, s18, 0x2000
	s_nop 0
	global_load_lds_dwordx4 v[212:213], off
	s_mov_b32 m0, s30
	v_lshl_add_u64 v[214:215], s[24:25], 0, v[128:129]
	global_load_lds_dwordx4 v[214:215], off
	v_lshl_add_u64 v[216:217], s[24:25], 0, v[130:131]
	s_mov_b32 m0, s31
	s_nop 0
	global_load_lds_dwordx4 v[216:217], off
	s_add_u32 s18, s22, 0xb0000
	s_addc_u32 s19, s23, 0
	s_add_i32 s47, s39, s29
	v_lshl_add_u64 v[254:255], s[18:19], 0, v[128:129]
	s_mov_b32 m0, s47
	s_nop 0
	global_load_lds_dwordx4 v[254:255], off
	v_lshl_add_u64 v[254:255], s[18:19], 0, v[130:131]
	s_add_i32 m0, s47, 0x2000
	s_nop 0
	global_load_lds_dwordx4 v[254:255], off
	s_waitcnt vmcnt(6)
	s_waitcnt lgkmcnt(0)
	s_barrier
; #define PG8_STAGE(bufoff, gbase, voff) do { _Pragma("unroll") for (int _i = 0; _i < 2; ++_i) \
;         __builtin_amdgcn_global_load_lds((const unsigned*)((const char*)(gbase) + (voff)[_i]), (LAS unsigned*)(lds + (bufoff) + ldsw + _i * 8192), 16, 0, 0); } while (0)
; #define PG8_LDA(dst, b, h) do { _Pragma("unroll") for (int m = 0; m < 4; ++m) _Pragma("unroll") for (int k = 0; k < 2; ++k) dst[m][k] = *(const LAS bf16x8*)(lds + PG8_SA(b, h) + aoff + m * 2048 + k * 1024); } while (0)
; #define PG8_LDB(dst, b, h) do { _Pragma("unroll") for (int n = 0; n < 2; ++n) _Pragma("unroll") for (int k = 0; k < 2; ++k) dst[n][k] = *(const LAS bf16x8*)(lds + PG8_SB(b, h) + boff + n * 2048 + k * 1024); } while (0)
; #define PG8_MMA(ai, bj, At, Bt) do { __builtin_amdgcn_s_setprio(1); _Pragma("unroll") for (int m = 0; m < 4; ++m) _Pragma("unroll") for (int n = 0; n < 2; ++n) _Pragma("unroll") for (int k = 0; k < 2; ++k) \
;         acc[ai][bj][m][n] = __builtin_amdgcn_mfma_f32_16x16x32_bf16(Bt[n][k], At[m][k], acc[ai][bj][m][n], 0, 0, 0); __builtin_amdgcn_s_setprio(0); } while (0)
; #define PG8_WAIT_V(n) asm volatile("s_waitcnt vmcnt(" #n ")" ::: "memory")
; #define PG8_WAIT_L(n) asm volatile("s_waitcnt lgkmcnt(" #n ")" ::: "memory")
; #define PG8_BAR __builtin_amdgcn_s_barrier()
; #define PG8_SCHED __builtin_amdgcn_sched_barrier(0)
; template <class Epi>
; __device__ __forceinline__ void gemm_phase(LAS unsigned char* lds, const Gemm g, const StaticOrder& S, const Epi& E) {
;     ...
;             PG8_WAIT_V(6); PG8_BAR; PG8_MMA(1, 1, At, B1); PG8_BAR;
;             PG8_LDB(B0, 1, 0); PG8_SCHED; PG8_LDA(At, 1, 0); PG8_STAGE(PG8_SA(0, 1), a2 + hstepA, voffA);
;             PG8_WAIT_L(8); PG8_BAR; PG8_WAIT_L(0); PG8_MMA(0, 0, At, B0); PG8_BAR; PG8_SCHED;
;             PG8_LDB(B1, 1, 1); PG8_STAGE(PG8_SB(1, 0), b3, voffB);
;             PG8_BAR; PG8_WAIT_L(0); PG8_MMA(0, 1, At, B1); PG8_BAR;
;             PG8_LDA(At, 1, 1); PG8_STAGE(PG8_SA(1, 0), a3, voffA);
;             PG8_BAR; PG8_WAIT_L(0); PG8_MMA(1, 0, At, B0); PG8_BAR; PG8_SCHED;
	s_setprio 1
	v_mfma_f32_16x16x32_bf16 v[60:63], v[140:143], v[164:167], v[60:63]
	v_mfma_f32_16x16x32_bf16 v[56:59], v[156:159], v[164:167], v[56:59]
	v_mfma_f32_16x16x32_bf16 v[48:51], v[140:143], v[172:175], v[48:51]
	v_mfma_f32_16x16x32_bf16 v[40:43], v[156:159], v[172:175], v[40:43]
	v_mfma_f32_16x16x32_bf16 v[28:31], v[140:143], v[180:183], v[28:31]
	v_mfma_f32_16x16x32_bf16 v[24:27], v[156:159], v[180:183], v[24:27]
	v_mfma_f32_16x16x32_bf16 v[16:19], v[140:143], v[188:191], v[16:19]
	v_mfma_f32_16x16x32_bf16 v[8:11], v[156:159], v[188:191], v[8:11]
	v_mfma_f32_16x16x32_bf16 v[60:63], v[152:155], v[168:171], v[60:63]
	v_mfma_f32_16x16x32_bf16 v[56:59], v[160:163], v[168:171], v[56:59]
	v_mfma_f32_16x16x32_bf16 v[48:51], v[152:155], v[176:179], v[48:51]
	v_mfma_f32_16x16x32_bf16 v[40:43], v[160:163], v[176:179], v[40:43]
	v_mfma_f32_16x16x32_bf16 v[28:31], v[152:155], v[184:187], v[28:31]
	v_mfma_f32_16x16x32_bf16 v[24:27], v[160:163], v[184:187], v[24:27]
	v_mfma_f32_16x16x32_bf16 v[16:19], v[152:155], v[192:195], v[16:19]
	v_mfma_f32_16x16x32_bf16 v[8:11], v[160:163], v[192:195], v[8:11]
	v_mfma_f32_16x16x32_bf16 v[52:55], v[196:199], v[164:167], v[52:55]
	v_mfma_f32_16x16x32_bf16 v[44:47], v[204:207], v[164:167], v[44:47]
	v_mfma_f32_16x16x32_bf16 v[36:39], v[196:199], v[172:175], v[36:39]
	v_mfma_f32_16x16x32_bf16 v[32:35], v[204:207], v[172:175], v[32:35]
	v_mfma_f32_16x16x32_bf16 v[20:23], v[196:199], v[180:183], v[20:23]
	v_mfma_f32_16x16x32_bf16 v[12:15], v[204:207], v[180:183], v[12:15]
	v_mfma_f32_16x16x32_bf16 v[4:7], v[196:199], v[188:191], v[4:7]
	v_mfma_f32_16x16x32_bf16 v[0:3], v[204:207], v[188:191], v[0:3]
	v_mfma_f32_16x16x32_bf16 v[52:55], v[200:203], v[168:171], v[52:55]
	v_mfma_f32_16x16x32_bf16 v[44:47], v[208:211], v[168:171], v[44:47]
	v_mfma_f32_16x16x32_bf16 v[36:39], v[200:203], v[176:179], v[36:39]
	v_mfma_f32_16x16x32_bf16 v[32:35], v[208:211], v[176:179], v[32:35]
	v_mfma_f32_16x16x32_bf16 v[20:23], v[200:203], v[184:187], v[20:23]
	v_mfma_f32_16x16x32_bf16 v[12:15], v[208:211], v[184:187], v[12:15]
	v_mfma_f32_16x16x32_bf16 v[4:7], v[200:203], v[192:195], v[4:7]
	v_mfma_f32_16x16x32_bf16 v[0:3], v[208:211], v[192:195], v[0:3]
	s_setprio 0
	s_add_i32 s47, 0, 0x18000
	v_add_u32_e32 v160, s47, v147
	s_barrier
	ds_read_b128 v[140:143], v160
	ds_read_b128 v[152:155], v160 offset:1024
	ds_read_b128 v[156:159], v160 offset:2048
	ds_read_b128 v[160:163], v160 offset:3072
	s_add_u32 s18, s24, 0xb0000
	s_addc_u32 s19, s25, 0
	s_mov_b32 m0, s33
	v_lshl_add_u64 v[196:197], s[18:19], 0, v[128:129]
	ds_read_b128 v[164:167], v150 offset:32768
	ds_read_b128 v[168:171], v150 offset:33792
	ds_read_b128 v[172:175], v150 offset:34816
	ds_read_b128 v[176:179], v150 offset:35840
	ds_read_b128 v[180:183], v150 offset:36864
	ds_read_b128 v[184:187], v150 offset:37888
	ds_read_b128 v[188:191], v150 offset:38912
	ds_read_b128 v[192:195], v150 offset:39936
	global_load_lds_dwordx4 v[196:197], off
	v_lshl_add_u64 v[196:197], s[18:19], 0, v[130:131]
	s_mov_b32 m0, s34
	s_nop 0
	global_load_lds_dwordx4 v[196:197], off
	s_add_i32 s24, 0, 0x1c000
	v_add_u32_e32 v208, s24, v147
	ds_read_b128 v[196:199], v208
	ds_read_b128 v[200:203], v208 offset:1024
	ds_read_b128 v[204:207], v208 offset:2048
	ds_read_b128 v[208:211], v208 offset:3072
	s_waitcnt lgkmcnt(0)
	s_barrier
	s_setprio 1
	v_mfma_f32_16x16x32_bf16 v[124:127], v[140:143], v[164:167], v[124:127]
	v_mfma_f32_16x16x32_bf16 v[120:123], v[156:159], v[164:167], v[120:123]
	v_mfma_f32_16x16x32_bf16 v[112:115], v[140:143], v[172:175], v[112:115]
	v_mfma_f32_16x16x32_bf16 v[104:107], v[156:159], v[172:175], v[104:107]
	v_mfma_f32_16x16x32_bf16 v[92:95], v[140:143], v[180:183], v[92:95]
	v_mfma_f32_16x16x32_bf16 v[88:91], v[156:159], v[180:183], v[88:91]
	v_mfma_f32_16x16x32_bf16 v[80:83], v[140:143], v[188:191], v[80:83]
	v_mfma_f32_16x16x32_bf16 v[72:75], v[156:159], v[188:191], v[72:75]
	v_mfma_f32_16x16x32_bf16 v[124:127], v[152:155], v[168:171], v[124:127]
	v_mfma_f32_16x16x32_bf16 v[120:123], v[160:163], v[168:171], v[120:123]
	v_mfma_f32_16x16x32_bf16 v[112:115], v[152:155], v[176:179], v[112:115]
	v_mfma_f32_16x16x32_bf16 v[104:107], v[160:163], v[176:179], v[104:107]
	v_mfma_f32_16x16x32_bf16 v[92:95], v[152:155], v[184:187], v[92:95]
	v_mfma_f32_16x16x32_bf16 v[88:91], v[160:163], v[184:187], v[88:91]
	v_mfma_f32_16x16x32_bf16 v[80:83], v[152:155], v[192:195], v[80:83]
	v_mfma_f32_16x16x32_bf16 v[72:75], v[160:163], v[192:195], v[72:75]
	v_mfma_f32_16x16x32_bf16 v[116:119], v[196:199], v[164:167], v[116:119]
	v_mfma_f32_16x16x32_bf16 v[108:111], v[204:207], v[164:167], v[108:111]
	v_mfma_f32_16x16x32_bf16 v[100:103], v[196:199], v[172:175], v[100:103]
	v_mfma_f32_16x16x32_bf16 v[96:99], v[204:207], v[172:175], v[96:99]
	v_mfma_f32_16x16x32_bf16 v[84:87], v[196:199], v[180:183], v[84:87]
	v_mfma_f32_16x16x32_bf16 v[76:79], v[204:207], v[180:183], v[76:79]
	v_mfma_f32_16x16x32_bf16 v[68:71], v[196:199], v[188:191], v[68:71]
	v_mfma_f32_16x16x32_bf16 v[64:67], v[204:207], v[188:191], v[64:67]
	v_mfma_f32_16x16x32_bf16 v[116:119], v[200:203], v[168:171], v[116:119]
	v_mfma_f32_16x16x32_bf16 v[108:111], v[208:211], v[168:171], v[108:111]
	v_mfma_f32_16x16x32_bf16 v[100:103], v[200:203], v[176:179], v[100:103]
	v_mfma_f32_16x16x32_bf16 v[96:99], v[208:211], v[176:179], v[96:99]
	v_mfma_f32_16x16x32_bf16 v[84:87], v[200:203], v[184:187], v[84:87]
	v_mfma_f32_16x16x32_bf16 v[76:79], v[208:211], v[184:187], v[76:79]
	v_mfma_f32_16x16x32_bf16 v[68:71], v[200:203], v[192:195], v[68:71]
	v_mfma_f32_16x16x32_bf16 v[64:67], v[208:211], v[192:195], v[64:67]
	s_setprio 0
	s_barrier
; #define PG8_STAGE(bufoff, gbase, voff) do { _Pragma("unroll") for (int _i = 0; _i < 2; ++_i) \
;         __builtin_amdgcn_global_load_lds((const unsigned*)((const char*)(gbase) + (voff)[_i]), (LAS unsigned*)(lds + (bufoff) + ldsw + _i * 8192), 16, 0, 0); } while (0)
; #define PG8_LDA(dst, b, h) do { _Pragma("unroll") for (int m = 0; m < 4; ++m) _Pragma("unroll") for (int k = 0; k < 2; ++k) dst[m][k] = *(const LAS bf16x8*)(lds + PG8_SA(b, h) + aoff + m * 2048 + k * 1024); } while (0)
; #define PG8_MMA(ai, bj, At, Bt) do { __builtin_amdgcn_s_setprio(1); _Pragma("unroll") for (int m = 0; m < 4; ++m) _Pragma("unroll") for (int n = 0; n < 2; ++n) _Pragma("unroll") for (int k = 0; k < 2; ++k) \
;         acc[ai][bj][m][n] = __builtin_amdgcn_mfma_f32_16x16x32_bf16(Bt[n][k], At[m][k], acc[ai][bj][m][n], 0, 0, 0); __builtin_amdgcn_s_setprio(0); } while (0)
; template <class Epi>
; __device__ __forceinline__ void gemm_phase(LAS unsigned char* lds, const Gemm g, const StaticOrder& S, const Epi& E) {
;     ...
;             PG8_LDA(At, 1, 1); PG8_STAGE(PG8_SA(1, 0), a3, voffA);
;             PG8_BAR; PG8_WAIT_L(0); PG8_MMA(1, 0, At, B0); PG8_BAR; PG8_SCHED;
;             PG8_STAGE(PG8_SB(1, 1), b3 + hstepB, voffB);
;             PG8_WAIT_V(6); PG8_BAR; PG8_MMA(1, 1, At, B1); PG8_BAR;
;     __device__ __forceinline__ void operator()(AccRef acc, const Unit& u, int wr, int wc, int fr, int fq) const {
;         const int row0 = u.pm * 256 + wr * 64 + fr, col0 = u.pn * 256 + wc * 32 + 4 * fq;
;         f32x4 sv[2][2], bv[2][2];
; #pragma unroll
;         for (int bj = 0; bj < 2; ++bj)
; #pragma unroll
;             for (int n = 0; n < 2; ++n) {
;                 sv[bj][n] = scale ? *(const f32x4*)(scale + col0 + bj * 128 + n * 16) : (f32x4){1.f, 1.f, 1.f, 1.f};
;                 bv[bj][n] = bias ? *(const f32x4*)(bias + col0 + bj * 128 + n * 16) : (f32x4){0.f, 0.f, 0.f, 0.f}; }
; #pragma unroll
;         for (int ai = 0; ai < 2; ++ai)
; #pragma unroll
;             for (int mh = 0; mh < 2; ++mh) {
;                 f32x4 bs[2][2][2];
; #pragma unroll
;                 for (int m = 0; m < 2; ++m)
; #pragma unroll
;                     for (int bj = 0; bj < 2; ++bj)
; #pragma unroll
;                         for (int n = 0; n < 2; ++n) bs[m][bj][n] = *(const f32x4*)(base + (size_t)(row0 + ai * 128 + (2 * mh + m) * 16) * D + col0 + bj * 128 + n * 16);
	s_nop 1
	ds_read_b128 v[164:167], v150 offset:49152
	ds_read_b128 v[168:171], v150 offset:50176
	ds_read_b128 v[172:175], v150 offset:51200
	ds_read_b128 v[176:179], v150 offset:52224
	ds_read_b128 v[180:183], v150 offset:53248
	ds_read_b128 v[184:187], v150 offset:54272
	ds_read_b128 v[188:191], v150 offset:55296
	ds_read_b128 v[192:195], v150 offset:56320
	s_add_i32 s18, s47, s29
	v_lshl_add_u64 v[254:255], v[144:145], 0, s[10:11]
	s_mov_b32 m0, s18
	s_nop 0
	global_load_lds_dwordx4 v[254:255], off
	v_lshl_add_u64 v[254:255], v[212:213], 0, s[10:11]
	s_add_i32 m0, s18, 0x2000
	s_nop 0
	global_load_lds_dwordx4 v[254:255], off
	s_mov_b32 m0, s36
	v_lshl_add_u64 v[254:255], v[214:215], 0, s[10:11]
	global_load_lds_dwordx4 v[254:255], off
	v_lshl_add_u64 v[144:145], v[216:217], 0, s[10:11]
	s_mov_b32 m0, s37
	s_nop 0
	global_load_lds_dwordx4 v[144:145], off
	s_add_u32 s18, s22, 0xb0080
	s_addc_u32 s19, s23, 0
	s_add_i32 s22, s24, s29
	v_lshl_add_u64 v[254:255], s[18:19], 0, v[128:129]
	s_mov_b32 m0, s22
	s_nop 0
	global_load_lds_dwordx4 v[254:255], off
	v_lshl_add_u64 v[254:255], s[18:19], 0, v[130:131]
	s_add_i32 m0, s22, 0x2000
	s_nop 0
	global_load_lds_dwordx4 v[254:255], off
	s_waitcnt vmcnt(6)
	s_waitcnt lgkmcnt(0)
	s_barrier
	s_setprio 1
	v_mfma_f32_16x16x32_bf16 v[60:63], v[140:143], v[164:167], v[60:63]
	v_mfma_f32_16x16x32_bf16 v[56:59], v[156:159], v[164:167], v[56:59]
	v_mfma_f32_16x16x32_bf16 v[48:51], v[140:143], v[172:175], v[48:51]
	v_mfma_f32_16x16x32_bf16 v[40:43], v[156:159], v[172:175], v[40:43]
	v_mfma_f32_16x16x32_bf16 v[28:31], v[140:143], v[180:183], v[28:31]
	v_mfma_f32_16x16x32_bf16 v[24:27], v[156:159], v[180:183], v[24:27]
	v_mfma_f32_16x16x32_bf16 v[16:19], v[140:143], v[188:191], v[16:19]
	v_mfma_f32_16x16x32_bf16 v[8:11], v[156:159], v[188:191], v[8:11]
	v_mfma_f32_16x16x32_bf16 v[60:63], v[152:155], v[168:171], v[60:63]
	v_mfma_f32_16x16x32_bf16 v[56:59], v[160:163], v[168:171], v[56:59]
	v_mfma_f32_16x16x32_bf16 v[48:51], v[152:155], v[176:179], v[48:51]
	v_mfma_f32_16x16x32_bf16 v[40:43], v[160:163], v[176:179], v[40:43]
	v_mfma_f32_16x16x32_bf16 v[28:31], v[152:155], v[184:187], v[28:31]
	v_mfma_f32_16x16x32_bf16 v[24:27], v[160:163], v[184:187], v[24:27]
	v_mfma_f32_16x16x32_bf16 v[16:19], v[152:155], v[192:195], v[16:19]
	v_mfma_f32_16x16x32_bf16 v[8:11], v[160:163], v[192:195], v[8:11]
	v_mfma_f32_16x16x32_bf16 v[52:55], v[196:199], v[164:167], v[52:55]
	v_mfma_f32_16x16x32_bf16 v[44:47], v[204:207], v[164:167], v[44:47]
	v_mfma_f32_16x16x32_bf16 v[36:39], v[196:199], v[172:175], v[36:39]
	v_mfma_f32_16x16x32_bf16 v[32:35], v[204:207], v[172:175], v[32:35]
	v_mfma_f32_16x16x32_bf16 v[20:23], v[196:199], v[180:183], v[20:23]
	v_mfma_f32_16x16x32_bf16 v[12:15], v[204:207], v[180:183], v[12:15]
	v_mfma_f32_16x16x32_bf16 v[4:7], v[196:199], v[188:191], v[4:7]
	v_mfma_f32_16x16x32_bf16 v[0:3], v[204:207], v[188:191], v[0:3]
	v_mfma_f32_16x16x32_bf16 v[52:55], v[200:203], v[168:171], v[52:55]
	v_mfma_f32_16x16x32_bf16 v[44:47], v[208:211], v[168:171], v[44:47]
	v_mfma_f32_16x16x32_bf16 v[36:39], v[200:203], v[176:179], v[36:39]
	v_mfma_f32_16x16x32_bf16 v[32:35], v[208:211], v[176:179], v[32:35]
	v_mfma_f32_16x16x32_bf16 v[20:23], v[200:203], v[184:187], v[20:23]
	v_mfma_f32_16x16x32_bf16 v[12:15], v[208:211], v[184:187], v[12:15]
	v_mfma_f32_16x16x32_bf16 v[4:7], v[200:203], v[192:195], v[4:7]
	v_mfma_f32_16x16x32_bf16 v[0:3], v[208:211], v[192:195], v[0:3]
	s_setprio 0
	s_add_i32 s46, s46, 2
	s_add_u32 s44, s44, 0x100
	s_addc_u32 s45, s45, 0
	s_cmp_gt_u32 s46, 41
	s_mov_b64 s[18:19], s[20:21]
	s_barrier
	s_cbranch_scc0 .LBB0_2042
	v_lshl_or_b32 v140, s42, 8, v148
	v_ashrrev_i32_e32 v141, 31, v140
	v_lshl_add_u32 v184, s43, 8, v146
	v_lshlrev_b64 v[140:141], 2, v[140:141]
	v_ashrrev_i32_e32 v185, 31, v184
	v_or_b32_e32 v168, 16, v184
	v_lshl_add_u64 v[142:143], s[52:53], 0, v[140:141]
	v_lshlrev_b64 v[144:145], 12, v[184:185]
	v_ashrrev_i32_e32 v169, 31, v168
	v_lshl_add_u64 v[164:165], v[142:143], 0, v[144:145]
	v_lshlrev_b64 v[186:187], 12, v[168:169]
	global_load_dwordx4 v[152:155], v[164:165], off
	global_load_dwordx4 v[156:159], v[164:165], off offset:64
	global_load_dwordx4 v[160:163], v[164:165], off offset:512
	s_nop 0
	global_load_dwordx4 v[164:167], v[164:165], off offset:576
	v_lshl_add_u64 v[180:181], v[142:143], 0, v[186:187]
	global_load_dwordx4 v[168:171], v[180:181], off
	global_load_dwordx4 v[172:175], v[180:181], off offset:64
	global_load_dwordx4 v[176:179], v[180:181], off offset:512
	s_nop 0
	global_load_dwordx4 v[180:183], v[180:181], off offset:576
	v_pk_add_f32 v[198:199], v[96:97], 0 op_sel_hi:[1,0]
	v_or_b32_e32 v96, 32, v184
	v_ashrrev_i32_e32 v97, 31, v96
	v_pk_add_f32 v[126:127], v[126:127], 0 op_sel_hi:[1,0]
	v_pk_add_f32 v[124:125], v[124:125], 0 op_sel_hi:[1,0]
	v_pk_add_f32 v[108:109], v[108:109], 0 op_sel_hi:[1,0]
	v_pk_add_f32 v[196:197], v[98:99], 0 op_sel_hi:[1,0]
	v_lshl_add_u64 v[98:99], s[52:53], 0, v[144:145]
	v_lshlrev_b64 v[200:201], 12, v[96:97]
	v_lshl_add_u64 v[96:97], s[52:53], 0, v[186:187]
	v_pk_add_f32 v[122:123], v[122:123], 0 op_sel_hi:[1,0]
	v_pk_add_f32 v[120:121], v[120:121], 0 op_sel_hi:[1,0]
	v_pk_add_f32 v[118:119], v[118:119], 0 op_sel_hi:[1,0]
	v_pk_add_f32 v[116:117], v[116:117], 0 op_sel_hi:[1,0]
	v_pk_add_f32 v[110:111], v[110:111], 0 op_sel_hi:[1,0]
	v_pk_add_f32 v[114:115], v[114:115], 0 op_sel_hi:[1,0]
	v_pk_add_f32 v[112:113], v[112:113], 0 op_sel_hi:[1,0]
	v_pk_add_f32 v[188:189], v[106:107], 0 op_sel_hi:[1,0]
	v_pk_add_f32 v[190:191], v[104:105], 0 op_sel_hi:[1,0]
	v_pk_add_f32 v[192:193], v[102:103], 0 op_sel_hi:[1,0]
;     __device__ __forceinline__ void operator()(AccRef acc, const Unit& u, int wr, int wc, int fr, int fq) const {
;     ...
;         for (int ai = 0; ai < 2; ++ai)
; #pragma unroll
;             for (int mh = 0; mh < 2; ++mh) {
;                 f32x4 bs[2][2][2];
; #pragma unroll
;                 for (int m = 0; m < 2; ++m)
; #pragma unroll
;                     for (int bj = 0; bj < 2; ++bj)
; #pragma unroll
;                         for (int n = 0; n < 2; ++n) bs[m][bj][n] = *(const f32x4*)(base + (size_t)(row0 + ai * 128 + (2 * mh + m) * 16) * D + col0 + bj * 128 + n * 16);
; #pragma unroll
;                 for (int m = 0; m < 2; ++m)
; #pragma unroll
;                     for (int bj = 0; bj < 2; ++bj)
; #pragma unroll
;                         for (int n = 0; n < 2; ++n) *(f32x4*)(out + (size_t)(row0 + ai * 128 + (2 * mh + m) * 16) * D + col0 + bj * 128 + n * 16) = bs[m][bj][n] + sv[bj][n] * (acc[ai][bj][2 * mh + m][n] + bv[bj][n]);
	v_pk_add_f32 v[194:195], v[100:101], 0 op_sel_hi:[1,0]
	v_lshl_add_u64 v[202:203], v[98:99], 0, v[140:141]
	v_lshl_add_u64 v[204:205], v[96:97], 0, v[140:141]
	v_lshl_add_u64 v[186:187], v[142:143], 0, v[200:201]
	v_pk_add_f32 v[94:95], v[94:95], 0 op_sel_hi:[1,0]
	v_pk_add_f32 v[92:93], v[92:93], 0 op_sel_hi:[1,0]
	v_pk_add_f32 v[90:91], v[90:91], 0 op_sel_hi:[1,0]
	v_pk_add_f32 v[88:89], v[88:89], 0 op_sel_hi:[1,0]
	v_pk_add_f32 v[86:87], v[86:87], 0 op_sel_hi:[1,0]
	v_pk_add_f32 v[84:85], v[84:85], 0 op_sel_hi:[1,0]
	v_pk_add_f32 v[78:79], v[78:79], 0 op_sel_hi:[1,0]
	v_pk_add_f32 v[76:77], v[76:77], 0 op_sel_hi:[1,0]
	v_pk_add_f32 v[82:83], v[82:83], 0 op_sel_hi:[1,0]
	v_pk_add_f32 v[80:81], v[80:81], 0 op_sel_hi:[1,0]
	v_pk_add_f32 v[62:63], v[62:63], 0 op_sel_hi:[1,0]
	v_pk_add_f32 v[60:61], v[60:61], 0 op_sel_hi:[1,0]
	v_pk_add_f32 v[58:59], v[58:59], 0 op_sel_hi:[1,0]
	v_pk_add_f32 v[56:57], v[56:57], 0 op_sel_hi:[1,0]
	v_pk_add_f32 v[54:55], v[54:55], 0 op_sel_hi:[1,0]
	v_pk_add_f32 v[52:53], v[52:53], 0 op_sel_hi:[1,0]
	v_pk_add_f32 v[46:47], v[46:47], 0 op_sel_hi:[1,0]
	v_pk_add_f32 v[44:45], v[44:45], 0 op_sel_hi:[1,0]
	v_pk_add_f32 v[50:51], v[50:51], 0 op_sel_hi:[1,0]
	v_pk_add_f32 v[48:49], v[48:49], 0 op_sel_hi:[1,0]
	v_pk_add_f32 v[30:31], v[30:31], 0 op_sel_hi:[1,0]
	v_pk_add_f32 v[28:29], v[28:29], 0 op_sel_hi:[1,0]
	v_pk_add_f32 v[26:27], v[26:27], 0 op_sel_hi:[1,0]
	v_pk_add_f32 v[24:25], v[24:25], 0 op_sel_hi:[1,0]
	v_pk_add_f32 v[22:23], v[22:23], 0 op_sel_hi:[1,0]
	v_pk_add_f32 v[20:21], v[20:21], 0 op_sel_hi:[1,0]
	v_pk_add_f32 v[14:15], v[14:15], 0 op_sel_hi:[1,0]
	v_pk_add_f32 v[12:13], v[12:13], 0 op_sel_hi:[1,0]
	v_pk_add_f32 v[18:19], v[18:19], 0 op_sel_hi:[1,0]
	v_pk_add_f32 v[16:17], v[16:17], 0 op_sel_hi:[1,0]
	s_and_b64 vcc, exec, s[0:1]
	s_mov_b32 s42, s40
	s_mov_b32 s43, s41
	s_mov_b64 s[20:21], s[6:7]
	s_mov_b64 s[18:19], s[4:5]
	s_waitcnt vmcnt(0)
	v_pk_add_f32 v[98:99], v[126:127], v[154:155]
	v_pk_add_f32 v[96:97], v[124:125], v[152:153]
	v_pk_add_f32 v[102:103], v[122:123], v[158:159]
	v_pk_add_f32 v[108:109], v[108:109], v[164:165]
	v_pk_add_f32 v[100:101], v[120:121], v[156:157]
	v_pk_add_f32 v[106:107], v[118:119], v[162:163]
	v_pk_add_f32 v[104:105], v[116:117], v[160:161]
	v_pk_add_f32 v[110:111], v[110:111], v[166:167]
	v_pk_add_f32 v[114:115], v[114:115], v[170:171]
	v_pk_add_f32 v[112:113], v[112:113], v[168:169]
	v_pk_add_f32 v[118:119], v[188:189], v[174:175]
	v_pk_add_f32 v[116:117], v[190:191], v[172:173]
	v_pk_add_f32 v[122:123], v[192:193], v[178:179]
	v_pk_add_f32 v[120:121], v[194:195], v[176:177]
	v_pk_add_f32 v[126:127], v[196:197], v[182:183]
	v_pk_add_f32 v[124:125], v[198:199], v[180:181]
	global_store_dwordx4 v[202:203], v[96:99], off
	global_store_dwordx4 v[202:203], v[100:103], off offset:64
	global_store_dwordx4 v[202:203], v[104:107], off offset:512
	global_store_dwordx4 v[202:203], v[108:111], off offset:576
	global_store_dwordx4 v[204:205], v[112:115], off
	global_store_dwordx4 v[204:205], v[116:119], off offset:64
	global_store_dwordx4 v[204:205], v[120:123], off offset:512
	global_store_dwordx4 v[204:205], v[124:127], off offset:576
	v_or_b32_e32 v108, 48, v184
	v_ashrrev_i32_e32 v109, 31, v108
	v_lshlrev_b64 v[152:153], 12, v[108:109]
	global_load_dwordx4 v[96:99], v[186:187], off
	global_load_dwordx4 v[100:103], v[186:187], off offset:64
	v_lshl_add_u64 v[124:125], v[142:143], 0, v[152:153]
	global_load_dwordx4 v[104:107], v[186:187], off offset:512
	global_load_dwordx4 v[108:111], v[186:187], off offset:576
	global_load_dwordx4 v[112:115], v[124:125], off
	global_load_dwordx4 v[116:119], v[124:125], off offset:64
	global_load_dwordx4 v[120:123], v[124:125], off offset:512
	s_nop 0
	global_load_dwordx4 v[124:127], v[124:125], off offset:576
	v_pk_add_f32 v[162:163], v[66:67], 0 op_sel_hi:[1,0]
	v_pk_add_f32 v[164:165], v[64:65], 0 op_sel_hi:[1,0]
	v_lshl_add_u64 v[64:65], s[52:53], 0, v[200:201]
	v_lshl_add_u64 v[66:67], s[52:53], 0, v[152:153]
	v_pk_add_f32 v[154:155], v[74:75], 0 op_sel_hi:[1,0]
	v_pk_add_f32 v[156:157], v[72:73], 0 op_sel_hi:[1,0]
	v_pk_add_f32 v[158:159], v[70:71], 0 op_sel_hi:[1,0]
	v_pk_add_f32 v[160:161], v[68:69], 0 op_sel_hi:[1,0]
	v_lshl_add_u64 v[168:169], v[64:65], 0, v[140:141]
	v_lshl_add_u64 v[170:171], v[66:67], 0, v[140:141]
	v_lshl_add_u64 v[166:167], v[144:145], 0, s[12:13]
	v_lshl_add_u64 v[152:153], v[142:143], 0, v[166:167]
	s_waitcnt vmcnt(0)
;     __device__ __forceinline__ void operator()(AccRef acc, const Unit& u, int wr, int wc, int fr, int fq) const {
;     ...
;         for (int ai = 0; ai < 2; ++ai)
; #pragma unroll
;             for (int mh = 0; mh < 2; ++mh) {
;                 f32x4 bs[2][2][2];
; #pragma unroll
;                 for (int m = 0; m < 2; ++m)
; #pragma unroll
;                     for (int bj = 0; bj < 2; ++bj)
; #pragma unroll
;                         for (int n = 0; n < 2; ++n) bs[m][bj][n] = *(const f32x4*)(base + (size_t)(row0 + ai * 128 + (2 * mh + m) * 16) * D + col0 + bj * 128 + n * 16);
; #pragma unroll
;                 for (int m = 0; m < 2; ++m)
; #pragma unroll
;                     for (int bj = 0; bj < 2; ++bj)
; #pragma unroll
;                         for (int n = 0; n < 2; ++n) *(f32x4*)(out + (size_t)(row0 + ai * 128 + (2 * mh + m) * 16) * D + col0 + bj * 128 + n * 16) = bs[m][bj][n] + sv[bj][n] * (acc[ai][bj][2 * mh + m][n] + bv[bj][n]);
;                 asm volatile("" ::: "memory"); }
	v_pk_add_f32 v[66:67], v[94:95], v[98:99]
	v_pk_add_f32 v[64:65], v[92:93], v[96:97]
	v_pk_add_f32 v[70:71], v[90:91], v[102:103]
	v_pk_add_f32 v[68:69], v[88:89], v[100:101]
	v_pk_add_f32 v[74:75], v[86:87], v[106:107]
	v_pk_add_f32 v[72:73], v[84:85], v[104:105]
	v_pk_add_f32 v[78:79], v[78:79], v[110:111]
	v_pk_add_f32 v[76:77], v[76:77], v[108:109]
	v_pk_add_f32 v[82:83], v[82:83], v[114:115]
	v_pk_add_f32 v[80:81], v[80:81], v[112:113]
	v_pk_add_f32 v[86:87], v[154:155], v[118:119]
	v_pk_add_f32 v[84:85], v[156:157], v[116:117]
	v_pk_add_f32 v[90:91], v[158:159], v[122:123]
	v_pk_add_f32 v[88:89], v[160:161], v[120:121]
	v_pk_add_f32 v[94:95], v[162:163], v[126:127]
	v_pk_add_f32 v[92:93], v[164:165], v[124:125]
	global_store_dwordx4 v[168:169], v[64:67], off
	global_store_dwordx4 v[168:169], v[68:71], off offset:64
	global_store_dwordx4 v[168:169], v[72:75], off offset:512
	global_store_dwordx4 v[168:169], v[76:79], off offset:576
	global_store_dwordx4 v[170:171], v[80:83], off
	global_store_dwordx4 v[170:171], v[84:87], off offset:64
	global_store_dwordx4 v[170:171], v[88:91], off offset:512
	global_store_dwordx4 v[170:171], v[92:95], off offset:576
	v_lshl_add_u64 v[96:97], v[144:145], 0, s[14:15]
	v_lshl_add_u64 v[98:99], v[142:143], 0, v[96:97]
	global_load_dwordx4 v[64:67], v[152:153], off
	global_load_dwordx4 v[68:71], v[152:153], off offset:64
	global_load_dwordx4 v[72:75], v[152:153], off offset:512
	global_load_dwordx4 v[76:79], v[152:153], off offset:576
	global_load_dwordx4 v[80:83], v[98:99], off
	global_load_dwordx4 v[84:87], v[98:99], off offset:64
	global_load_dwordx4 v[88:91], v[98:99], off offset:512
	global_load_dwordx4 v[92:95], v[98:99], off offset:576
	v_pk_add_f32 v[106:107], v[34:35], 0 op_sel_hi:[1,0]
	v_pk_add_f32 v[108:109], v[32:33], 0 op_sel_hi:[1,0]
	v_lshl_add_u64 v[32:33], s[52:53], 0, v[166:167]
	v_lshl_add_u64 v[34:35], s[52:53], 0, v[96:97]
	v_pk_add_f32 v[98:99], v[42:43], 0 op_sel_hi:[1,0]
	v_pk_add_f32 v[100:101], v[40:41], 0 op_sel_hi:[1,0]
	v_pk_add_f32 v[102:103], v[38:39], 0 op_sel_hi:[1,0]
	v_pk_add_f32 v[104:105], v[36:37], 0 op_sel_hi:[1,0]
	v_lshl_add_u64 v[112:113], v[32:33], 0, v[140:141]
	v_lshl_add_u64 v[114:115], v[34:35], 0, v[140:141]
	v_lshl_add_u64 v[110:111], v[144:145], 0, s[16:17]
	v_lshl_add_u64 v[96:97], v[142:143], 0, v[110:111]
	s_waitcnt vmcnt(0)
	v_pk_add_f32 v[34:35], v[62:63], v[66:67]
	v_pk_add_f32 v[32:33], v[60:61], v[64:65]
	v_pk_add_f32 v[38:39], v[58:59], v[70:71]
	v_pk_add_f32 v[36:37], v[56:57], v[68:69]
	v_pk_add_f32 v[42:43], v[54:55], v[74:75]
	v_pk_add_f32 v[40:41], v[52:53], v[72:73]
	v_pk_add_f32 v[46:47], v[46:47], v[78:79]
	v_pk_add_f32 v[44:45], v[44:45], v[76:77]
	v_pk_add_f32 v[50:51], v[50:51], v[82:83]
	v_pk_add_f32 v[48:49], v[48:49], v[80:81]
	v_pk_add_f32 v[54:55], v[98:99], v[86:87]
	v_pk_add_f32 v[52:53], v[100:101], v[84:85]
	v_pk_add_f32 v[58:59], v[102:103], v[90:91]
	v_pk_add_f32 v[56:57], v[104:105], v[88:89]
	v_pk_add_f32 v[62:63], v[106:107], v[94:95]
	v_pk_add_f32 v[60:61], v[108:109], v[92:93]
	global_store_dwordx4 v[112:113], v[32:35], off
	global_store_dwordx4 v[112:113], v[36:39], off offset:64
	global_store_dwordx4 v[112:113], v[40:43], off offset:512
	global_store_dwordx4 v[112:113], v[44:47], off offset:576
	global_store_dwordx4 v[114:115], v[48:51], off
	global_store_dwordx4 v[114:115], v[52:55], off offset:64
	global_store_dwordx4 v[114:115], v[56:59], off offset:512
	global_store_dwordx4 v[114:115], v[60:63], off offset:576
	v_lshl_add_u64 v[64:65], v[144:145], 0, s[8:9]
	v_lshl_add_u64 v[66:67], v[142:143], 0, v[64:65]
	global_load_dwordx4 v[32:35], v[96:97], off
	global_load_dwordx4 v[36:39], v[96:97], off offset:64
	global_load_dwordx4 v[40:43], v[96:97], off offset:512
	global_load_dwordx4 v[44:47], v[96:97], off offset:576
	global_load_dwordx4 v[48:51], v[66:67], off
	global_load_dwordx4 v[52:55], v[66:67], off offset:64
	global_load_dwordx4 v[56:59], v[66:67], off offset:512
	global_load_dwordx4 v[60:63], v[66:67], off offset:576
	v_pk_add_f32 v[74:75], v[2:3], 0 op_sel_hi:[1,0]
	v_pk_add_f32 v[76:77], v[0:1], 0 op_sel_hi:[1,0]
	v_lshl_add_u64 v[0:1], s[52:53], 0, v[110:111]
	v_lshl_add_u64 v[2:3], s[52:53], 0, v[64:65]
	v_pk_add_f32 v[66:67], v[10:11], 0 op_sel_hi:[1,0]
	v_pk_add_f32 v[68:69], v[8:9], 0 op_sel_hi:[1,0]
	v_pk_add_f32 v[70:71], v[6:7], 0 op_sel_hi:[1,0]
	v_pk_add_f32 v[72:73], v[4:5], 0 op_sel_hi:[1,0]
	v_lshl_add_u64 v[64:65], v[0:1], 0, v[140:141]
	v_lshl_add_u64 v[78:79], v[2:3], 0, v[140:141]
	s_waitcnt vmcnt(0)
	v_pk_add_f32 v[2:3], v[30:31], v[34:35]
	v_pk_add_f32 v[0:1], v[28:29], v[32:33]
	v_pk_add_f32 v[6:7], v[26:27], v[38:39]
	v_pk_add_f32 v[4:5], v[24:25], v[36:37]
	v_pk_add_f32 v[10:11], v[22:23], v[42:43]
	v_pk_add_f32 v[8:9], v[20:21], v[40:41]
	v_pk_add_f32 v[14:15], v[14:15], v[46:47]
	v_pk_add_f32 v[12:13], v[12:13], v[44:45]
	v_pk_add_f32 v[18:19], v[18:19], v[50:51]
	v_pk_add_f32 v[16:17], v[16:17], v[48:49]
	v_pk_add_f32 v[22:23], v[66:67], v[54:55]
	v_pk_add_f32 v[20:21], v[68:69], v[52:53]
	v_pk_add_f32 v[26:27], v[70:71], v[58:59]
	v_pk_add_f32 v[24:25], v[72:73], v[56:57]
	v_pk_add_f32 v[30:31], v[74:75], v[62:63]
	v_pk_add_f32 v[28:29], v[76:77], v[60:61]
	global_store_dwordx4 v[64:65], v[0:3], off
	global_store_dwordx4 v[64:65], v[4:7], off offset:64
	global_store_dwordx4 v[64:65], v[8:11], off offset:512
	global_store_dwordx4 v[64:65], v[12:15], off offset:576
	global_store_dwordx4 v[78:79], v[16:19], off
	global_store_dwordx4 v[78:79], v[20:23], off offset:64
	global_store_dwordx4 v[78:79], v[24:27], off offset:512
	global_store_dwordx4 v[78:79], v[28:31], off offset:576
	s_cbranch_vccz .LBB0_2031
	s_waitcnt vmcnt(0)
	s_cmpk_gt_u32 s26, 0xff
	s_cbranch_scc1 .LBB0_2046
	s_barrier
